# GEMM: tighter MMA hand-off around barriers; up-proj epilogue: removed dead DPP old-value inits (+hazard pads), first-iteration MFMAs take srcC=0 instead of zeroing accumulators; attention: L2 prefetch
# speedup vs baseline: 1.0059x; 1.0059x over previous
.LBB0_693:
.LBB0_694:
	s_add_i32 s19, 0, 0x10000
	s_add_i32 s36, 0, 0x14000
	v_add_u32_e32 v12, s19, v214
	v_add_u32_e32 v28, s36, v214
	ds_read_b128 v[0:3], v12
	ds_read_b128 v[4:7], v12 offset:1024
	ds_read_b128 v[8:11], v12 offset:2048
	ds_read_b128 v[12:15], v12 offset:3072
	ds_read_b128 v[16:19], v28
	ds_read_b128 v[20:23], v28 offset:1024
	ds_read_b128 v[24:27], v28 offset:2048
	ds_read_b128 v[28:31], v28 offset:3072
	s_add_u32 s4, s82, 0x40080
	s_addc_u32 s5, s83, 0
	v_lshl_add_u64 v[68:69], s[4:5], 0, v[50:51]
	s_add_i32 m0, s23, 0xc000
	ds_read_b128 v[32:35], v215
	ds_read_b128 v[36:39], v215 offset:1024
	ds_read_b128 v[40:43], v215 offset:2048
	ds_read_b128 v[44:47], v215 offset:3072
	ds_read_b128 v[52:55], v215 offset:4096
	ds_read_b128 v[56:59], v215 offset:5120
	ds_read_b128 v[60:63], v215 offset:6144
	ds_read_b128 v[64:67], v215 offset:7168
	global_load_lds_dwordx4 v[68:69], off
	v_lshl_add_u64 v[68:69], s[4:5], 0, v[120:121]
	s_add_i32 m0, s23, 0xe000
	s_nop 0
	global_load_lds_dwordx4 v[68:69], off
	s_waitcnt vmcnt(40) lgkmcnt(0)
	s_setprio 1
	s_barrier
	v_mfma_f32_16x16x32_bf16 v[68:71], v[0:3], v[32:35], 0
	v_mfma_f32_16x16x32_bf16 v[72:75], v[8:11], v[32:35], 0
	v_mfma_f32_16x16x32_bf16 v[76:79], v[0:3], v[40:43], 0
	v_mfma_f32_16x16x32_bf16 v[80:83], v[8:11], v[40:43], 0
	v_mfma_f32_16x16x32_bf16 v[84:87], v[0:3], v[52:55], 0
	v_mfma_f32_16x16x32_bf16 v[88:91], v[8:11], v[52:55], 0
	v_mfma_f32_16x16x32_bf16 v[92:95], v[0:3], v[60:63], 0
	v_mfma_f32_16x16x32_bf16 v[96:99], v[8:11], v[60:63], 0
	v_mfma_f32_16x16x32_bf16 v[68:71], v[4:7], v[36:39], v[68:71]
	v_mfma_f32_16x16x32_bf16 v[72:75], v[12:15], v[36:39], v[72:75]
	v_mfma_f32_16x16x32_bf16 v[76:79], v[4:7], v[44:47], v[76:79]
	v_mfma_f32_16x16x32_bf16 v[80:83], v[12:15], v[44:47], v[80:83]
	v_mfma_f32_16x16x32_bf16 v[84:87], v[4:7], v[56:59], v[84:87]
	v_mfma_f32_16x16x32_bf16 v[88:91], v[12:15], v[56:59], v[88:91]
	v_mfma_f32_16x16x32_bf16 v[92:95], v[4:7], v[64:67], v[92:95]
	v_mfma_f32_16x16x32_bf16 v[96:99], v[12:15], v[64:67], v[96:99]
	s_setprio 0
	s_setprio 1
	v_mfma_f32_16x16x32_bf16 v[100:103], v[16:19], v[32:35], 0
	v_mfma_f32_16x16x32_bf16 v[32:35], v[24:27], v[32:35], 0
	v_mfma_f32_16x16x32_bf16 v[122:125], v[20:23], v[36:39], v[100:103]
	v_mfma_f32_16x16x32_bf16 v[32:35], v[28:31], v[36:39], v[32:35]
	v_mfma_f32_16x16x32_bf16 v[36:39], v[16:19], v[40:43], 0
	v_mfma_f32_16x16x32_bf16 v[40:43], v[24:27], v[40:43], 0
	v_mfma_f32_16x16x32_bf16 v[36:39], v[20:23], v[44:47], v[36:39]
	v_mfma_f32_16x16x32_bf16 v[40:43], v[28:31], v[44:47], v[40:43]
	v_mfma_f32_16x16x32_bf16 v[44:47], v[16:19], v[52:55], 0
	v_mfma_f32_16x16x32_bf16 v[52:55], v[24:27], v[52:55], 0
	v_mfma_f32_16x16x32_bf16 v[126:129], v[28:31], v[56:59], v[52:55]
	v_mfma_f32_16x16x32_bf16 v[52:55], v[16:19], v[60:63], 0
	v_mfma_f32_16x16x32_bf16 v[44:47], v[20:23], v[56:59], v[44:47]
	v_mfma_f32_16x16x32_bf16 v[130:133], v[20:23], v[64:67], v[52:55]
	v_mfma_f32_16x16x32_bf16 v[52:55], v[24:27], v[60:63], 0
	v_mfma_f32_16x16x32_bf16 v[134:137], v[28:31], v[64:67], v[52:55]
	s_barrier
	s_setprio 0
	v_lshl_add_u64 v[154:155], s[24:25], 0, v[48:49]
	s_add_i32 s4, s19, s88
	v_lshl_add_u64 v[116:117], v[154:155], 0, s[16:17]
	s_mov_b32 m0, s4
	s_nop 0
	ds_read_b128 v[52:55], v215 offset:16384
	ds_read_b128 v[56:59], v215 offset:17408
	ds_read_b128 v[60:63], v215 offset:18432
	ds_read_b128 v[64:67], v215 offset:19456
	ds_read_b128 v[100:103], v215 offset:20480
	ds_read_b128 v[104:107], v215 offset:21504
	ds_read_b128 v[108:111], v215 offset:22528
	ds_read_b128 v[112:115], v215 offset:23552
	global_load_lds_dwordx4 v[116:117], off
	s_add_i32 m0, s4, 0x2000
	v_lshl_add_u64 v[190:191], s[24:25], 0, v[160:161]
	s_add_u32 s4, s24, 0x10100
	v_lshl_add_u64 v[116:117], v[190:191], 0, s[16:17]
	s_addc_u32 s5, s25, 0
	s_add_i32 s19, s36, s88
	global_load_lds_dwordx4 v[116:117], off
	v_lshl_add_u64 v[116:117], s[4:5], 0, v[48:49]
	s_mov_b32 m0, s19
	v_lshl_add_u64 v[248:249], s[82:83], 0, v[50:51]
	global_load_lds_dwordx4 v[116:117], off
	v_lshl_add_u64 v[116:117], s[4:5], 0, v[160:161]
	s_add_i32 m0, s19, 0x2000
	v_mov_b32_e32 v252, v253
	global_load_lds_dwordx4 v[116:117], off
	v_lshl_add_u64 v[116:117], v[248:249], 0, s[16:17]
	s_mov_b32 m0, s23
	v_mov_b32_e32 v253, v250
	v_lshl_add_u64 v[250:251], s[82:83], 0, v[120:121]
	global_load_lds_dwordx4 v[116:117], off
	v_lshl_add_u64 v[116:117], v[250:251], 0, s[16:17]
	s_mov_b32 m0, s91
	s_nop 0
	global_load_lds_dwordx4 v[116:117], off
	s_waitcnt vmcnt(40) lgkmcnt(0)
	s_setprio 1
	s_barrier
	v_mfma_f32_16x16x32_bf16 v[116:119], v[0:3], v[52:55], 0
	v_mfma_f32_16x16x32_bf16 v[138:141], v[4:7], v[56:59], v[116:119]
	v_mfma_f32_16x16x32_bf16 v[116:119], v[8:11], v[52:55], 0
	v_mfma_f32_16x16x32_bf16 v[142:145], v[12:15], v[56:59], v[116:119]
	v_mfma_f32_16x16x32_bf16 v[116:119], v[0:3], v[60:63], 0
	v_mfma_f32_16x16x32_bf16 v[146:149], v[4:7], v[64:67], v[116:119]
	v_mfma_f32_16x16x32_bf16 v[116:119], v[8:11], v[60:63], 0
	v_mfma_f32_16x16x32_bf16 v[150:153], v[12:15], v[64:67], v[116:119]
	v_mfma_f32_16x16x32_bf16 v[116:119], v[0:3], v[100:103], 0
	v_mfma_f32_16x16x32_bf16 v[0:3], v[0:3], v[108:111], 0
	v_mfma_f32_16x16x32_bf16 v[162:165], v[4:7], v[104:107], v[116:119]
	v_mfma_f32_16x16x32_bf16 v[0:3], v[4:7], v[112:115], v[0:3]
	v_mfma_f32_16x16x32_bf16 v[4:7], v[8:11], v[108:111], 0
	v_mfma_f32_16x16x32_bf16 v[116:119], v[8:11], v[100:103], 0
	v_mfma_f32_16x16x32_bf16 v[4:7], v[12:15], v[112:115], v[4:7]
	v_mfma_f32_16x16x32_bf16 v[170:173], v[12:15], v[104:107], v[116:119]
	s_setprio 0
	s_setprio 1
	v_mfma_f32_16x16x32_bf16 v[8:11], v[16:19], v[52:55], 0
	v_mfma_f32_16x16x32_bf16 v[12:15], v[24:27], v[52:55], 0
	v_mfma_f32_16x16x32_bf16 v[52:55], v[16:19], v[60:63], 0
	v_mfma_f32_16x16x32_bf16 v[178:181], v[20:23], v[64:67], v[52:55]
	v_mfma_f32_16x16x32_bf16 v[52:55], v[24:27], v[60:63], 0
	v_mfma_f32_16x16x32_bf16 v[182:185], v[28:31], v[64:67], v[52:55]
	v_mfma_f32_16x16x32_bf16 v[52:55], v[16:19], v[100:103], 0
	v_mfma_f32_16x16x32_bf16 v[16:19], v[16:19], v[108:111], 0
	v_mfma_f32_16x16x32_bf16 v[8:11], v[20:23], v[56:59], v[8:11]
	v_mfma_f32_16x16x32_bf16 v[12:15], v[28:31], v[56:59], v[12:15]
	v_mfma_f32_16x16x32_bf16 v[186:189], v[20:23], v[104:107], v[52:55]
	v_mfma_f32_16x16x32_bf16 v[52:55], v[24:27], v[100:103], 0
	v_mfma_f32_16x16x32_bf16 v[198:201], v[20:23], v[112:115], v[16:19]
	v_mfma_f32_16x16x32_bf16 v[16:19], v[24:27], v[108:111], 0
	v_mfma_f32_16x16x32_bf16 v[194:197], v[28:31], v[104:107], v[52:55]
	v_mfma_f32_16x16x32_bf16 v[202:205], v[28:31], v[112:115], v[16:19]
	s_barrier
	s_setprio 0
	s_add_i32 s19, 0, 0x18000
	s_add_i32 s36, 0, 0x1c000
	v_add_u32_e32 v28, s19, v214
	v_add_u32_e32 v52, s36, v214
	ds_read_b128 v[16:19], v28
	ds_read_b128 v[20:23], v28 offset:1024
	ds_read_b128 v[24:27], v28 offset:2048
	ds_read_b128 v[28:31], v28 offset:3072
	ds_read_b128 v[206:209], v52
	ds_read_b128 v[210:213], v52 offset:1024
	ds_read_b128 v[216:219], v52 offset:2048
	ds_read_b128 v[220:223], v52 offset:3072
	s_add_u32 s4, s82, 0x40100
	s_addc_u32 s5, s83, 0
	s_mov_b32 m0, s38
	v_lshl_add_u64 v[60:61], s[4:5], 0, v[50:51]
	ds_read_b128 v[52:55], v215 offset:32768
	ds_read_b128 v[56:59], v215 offset:33792
	ds_read_b128 v[224:227], v215 offset:34816
	ds_read_b128 v[228:231], v215 offset:35840
	ds_read_b128 v[232:235], v215 offset:36864
	ds_read_b128 v[236:239], v215 offset:37888
	ds_read_b128 v[240:243], v215 offset:38912
	ds_read_b128 v[244:247], v215 offset:39936
	global_load_lds_dwordx4 v[60:61], off
	v_lshl_add_u64 v[60:61], s[4:5], 0, v[120:121]
	s_mov_b32 m0, s39
	s_nop 0
	global_load_lds_dwordx4 v[60:61], off
	s_waitcnt vmcnt(8) lgkmcnt(0)
	s_setprio 1
	s_barrier
	v_mfma_f32_16x16x32_bf16 v[60:63], v[16:19], v[52:55], v[68:71]
	v_mfma_f32_16x16x32_bf16 v[174:177], v[20:23], v[56:59], v[60:63]
	v_mfma_f32_16x16x32_bf16 v[60:63], v[24:27], v[52:55], v[72:75]
	v_mfma_f32_16x16x32_bf16 v[166:169], v[28:31], v[56:59], v[60:63]
	v_mfma_f32_16x16x32_bf16 v[60:63], v[16:19], v[224:227], v[76:79]
	v_mfma_f32_16x16x32_bf16 v[156:159], v[20:23], v[228:231], v[60:63]
	v_mfma_f32_16x16x32_bf16 v[60:63], v[24:27], v[224:227], v[80:83]
	v_mfma_f32_16x16x32_bf16 v[116:119], v[28:31], v[228:231], v[60:63]
	v_mfma_f32_16x16x32_bf16 v[60:63], v[16:19], v[232:235], v[84:87]
	v_mfma_f32_16x16x32_bf16 v[112:115], v[20:23], v[236:239], v[60:63]
	v_mfma_f32_16x16x32_bf16 v[60:63], v[24:27], v[232:235], v[88:91]
	v_mfma_f32_16x16x32_bf16 v[108:111], v[28:31], v[236:239], v[60:63]
	v_mfma_f32_16x16x32_bf16 v[60:63], v[16:19], v[240:243], v[92:95]
	v_mfma_f32_16x16x32_bf16 v[104:107], v[20:23], v[244:247], v[60:63]
	v_mfma_f32_16x16x32_bf16 v[60:63], v[24:27], v[240:243], v[96:99]
	v_mfma_f32_16x16x32_bf16 v[100:103], v[28:31], v[244:247], v[60:63]
	s_setprio 0
	s_setprio 1
	v_mfma_f32_16x16x32_bf16 v[60:63], v[206:209], v[52:55], v[122:125]
	v_mfma_f32_16x16x32_bf16 v[32:35], v[216:219], v[52:55], v[32:35]
	v_mfma_f32_16x16x32_bf16 v[64:67], v[210:213], v[56:59], v[60:63]
	v_mfma_f32_16x16x32_bf16 v[60:63], v[220:223], v[56:59], v[32:35]
	v_mfma_f32_16x16x32_bf16 v[32:35], v[206:209], v[224:227], v[36:39]
	v_mfma_f32_16x16x32_bf16 v[56:59], v[210:213], v[228:231], v[32:35]
	v_mfma_f32_16x16x32_bf16 v[32:35], v[216:219], v[224:227], v[40:43]
	v_mfma_f32_16x16x32_bf16 v[52:55], v[220:223], v[228:231], v[32:35]
	v_mfma_f32_16x16x32_bf16 v[32:35], v[206:209], v[232:235], v[44:47]
	v_mfma_f32_16x16x32_bf16 v[44:47], v[210:213], v[236:239], v[32:35]
	v_mfma_f32_16x16x32_bf16 v[32:35], v[216:219], v[232:235], v[126:129]
	v_mfma_f32_16x16x32_bf16 v[40:43], v[220:223], v[236:239], v[32:35]
	v_mfma_f32_16x16x32_bf16 v[32:35], v[206:209], v[240:243], v[130:133]
	v_mfma_f32_16x16x32_bf16 v[36:39], v[210:213], v[244:247], v[32:35]
	v_mfma_f32_16x16x32_bf16 v[32:35], v[216:219], v[240:243], v[134:137]
	v_mov_b32_e32 v241, 0x7f
	v_mov_b64_e32 v[242:243], 0x400
	v_mfma_f32_16x16x32_bf16 v[32:35], v[220:223], v[244:247], v[32:35]
	v_mov_b32_e32 v247, 0x77
	v_mov_b32_e32 v246, 0x7c
	v_mov_b32_e32 v245, 0x7d
	v_mov_b32_e32 v244, 0x7e
	s_setprio 0
	s_barrier
	s_mov_b64 s[42:43], 0x180
	s_add_i32 s4, s19, s88
	v_lshl_add_u64 v[68:69], v[154:155], 0, s[42:43]
	s_mov_b32 m0, s4
	ds_read_b128 v[122:125], v215 offset:49152
	ds_read_b128 v[126:129], v215 offset:50176
	ds_read_b128 v[130:133], v215 offset:51200
	ds_read_b128 v[134:137], v215 offset:52224
	ds_read_b128 v[224:227], v215 offset:53248
	ds_read_b128 v[228:231], v215 offset:54272
	ds_read_b128 v[232:235], v215 offset:55296
	ds_read_b128 v[236:239], v215 offset:56320
	global_load_lds_dwordx4 v[68:69], off
	s_add_i32 m0, s4, 0x2000
	s_add_u32 s4, s24, 0x10180
	v_lshl_add_u64 v[68:69], v[190:191], 0, s[42:43]
	s_addc_u32 s5, s25, 0
	s_add_i32 s19, s36, s88
	global_load_lds_dwordx4 v[68:69], off
	v_lshl_add_u64 v[68:69], s[4:5], 0, v[48:49]
	s_mov_b32 m0, s19
	s_nop 0
	global_load_lds_dwordx4 v[68:69], off
	v_lshl_add_u64 v[68:69], s[4:5], 0, v[160:161]
	s_add_i32 m0, s19, 0x2000
	s_nop 0
	global_load_lds_dwordx4 v[68:69], off
	v_lshl_add_u64 v[68:69], v[248:249], 0, s[42:43]
	s_mov_b32 m0, s49
	v_mov_b32_e32 v248, 0x260
	global_load_lds_dwordx4 v[68:69], off
	v_lshl_add_u64 v[68:69], v[250:251], 0, s[42:43]
	s_mov_b32 m0, s52
	v_mov_b32_e32 v250, v253
	global_load_lds_dwordx4 v[68:69], off
	s_waitcnt vmcnt(8)
	s_waitcnt lgkmcnt(0)
	v_mov_b32_e32 v253, v252
	s_barrier
	s_setprio 1
	s_waitcnt lgkmcnt(0)
	v_mfma_f32_16x16x32_bf16 v[68:71], v[16:19], v[122:125], v[138:141]
	v_mfma_f32_16x16x32_bf16 v[96:99], v[20:23], v[126:129], v[68:71]
	v_mfma_f32_16x16x32_bf16 v[68:71], v[24:27], v[122:125], v[142:145]
	v_mfma_f32_16x16x32_bf16 v[92:95], v[28:31], v[126:129], v[68:71]
	v_mfma_f32_16x16x32_bf16 v[68:71], v[16:19], v[130:133], v[146:149]
	v_mfma_f32_16x16x32_bf16 v[88:91], v[20:23], v[134:137], v[68:71]
	v_mfma_f32_16x16x32_bf16 v[68:71], v[24:27], v[130:133], v[150:153]
	v_mfma_f32_16x16x32_bf16 v[84:87], v[28:31], v[134:137], v[68:71]
	v_mfma_f32_16x16x32_bf16 v[68:71], v[16:19], v[224:227], v[162:165]
	v_mfma_f32_16x16x32_bf16 v[0:3], v[16:19], v[232:235], v[0:3]
	v_mfma_f32_16x16x32_bf16 v[80:83], v[20:23], v[228:231], v[68:71]
	v_mfma_f32_16x16x32_bf16 v[68:71], v[24:27], v[224:227], v[170:173]
	v_mfma_f32_16x16x32_bf16 v[72:75], v[20:23], v[236:239], v[0:3]
	v_mfma_f32_16x16x32_bf16 v[0:3], v[24:27], v[232:235], v[4:7]
	v_mfma_f32_16x16x32_bf16 v[76:79], v[28:31], v[228:231], v[68:71]
	v_mfma_f32_16x16x32_bf16 v[68:71], v[28:31], v[236:239], v[0:3]
	s_setprio 0
	s_setprio 1
	v_mfma_f32_16x16x32_bf16 v[0:3], v[206:209], v[122:125], v[8:11]
	v_mfma_f32_16x16x32_bf16 v[28:31], v[210:213], v[126:129], v[0:3]
	v_mfma_f32_16x16x32_bf16 v[0:3], v[216:219], v[122:125], v[12:15]
	v_mfma_f32_16x16x32_bf16 v[24:27], v[220:223], v[126:129], v[0:3]
	v_mfma_f32_16x16x32_bf16 v[0:3], v[206:209], v[130:133], v[178:181]
	v_mfma_f32_16x16x32_bf16 v[20:23], v[210:213], v[134:137], v[0:3]
	v_mfma_f32_16x16x32_bf16 v[0:3], v[216:219], v[130:133], v[182:185]
	v_mfma_f32_16x16x32_bf16 v[16:19], v[220:223], v[134:137], v[0:3]
	v_mfma_f32_16x16x32_bf16 v[0:3], v[206:209], v[224:227], v[186:189]
	v_mfma_f32_16x16x32_bf16 v[12:15], v[210:213], v[228:231], v[0:3]
	v_mfma_f32_16x16x32_bf16 v[0:3], v[216:219], v[224:227], v[194:197]
	v_mfma_f32_16x16x32_bf16 v[8:11], v[220:223], v[228:231], v[0:3]
	v_mfma_f32_16x16x32_bf16 v[0:3], v[206:209], v[232:235], v[198:201]
	v_mfma_f32_16x16x32_bf16 v[4:7], v[210:213], v[236:239], v[0:3]
	v_mfma_f32_16x16x32_bf16 v[0:3], v[216:219], v[232:235], v[202:205]
	v_mfma_f32_16x16x32_bf16 v[0:3], v[220:223], v[236:239], v[0:3]
	s_barrier
	s_setprio 0
	s_mov_b32 s19, 2

.LBB0_696:
	s_add_i32 s92, s19, 2
	s_or_b32 s94, s19, 1
	s_lshl_b64 s[4:5], s[92:93], 7
	s_add_u32 s42, s82, s4
	s_addc_u32 s43, s83, s5
	s_add_u32 s4, s24, s4
	s_addc_u32 s5, s25, s5
	s_add_i32 s80, 0, 0x10000
	s_cmp_eq_u32 s19, 2
	s_cselect_b32 s43, s77, s43
	s_cselect_b32 s42, s76, s42
	s_cselect_b32 s5, s36, s5
	s_cselect_b32 s4, s37, s4
	s_add_i32 s81, 0, 0x14000
	v_add_u32_e32 v134, s80, v214
	v_add_u32_e32 v150, s81, v214
	ds_read_b128 v[122:125], v134
	ds_read_b128 v[126:129], v134 offset:1024
	ds_read_b128 v[130:133], v134 offset:2048
	ds_read_b128 v[134:137], v134 offset:3072
	ds_read_b128 v[138:141], v150
	ds_read_b128 v[142:145], v150 offset:1024
	ds_read_b128 v[146:149], v150 offset:2048
	ds_read_b128 v[150:153], v150 offset:3072
	s_mov_b32 s95, s93
	s_lshl_b64 s[94:95], s[94:95], 7
	s_add_u32 s94, s73, s94
	s_addc_u32 s95, s75, s95
	v_lshl_add_u64 v[154:155], s[94:95], 0, v[50:51]
	s_add_i32 m0, s23, 0xc000
	ds_read_b128 v[162:165], v215
	ds_read_b128 v[170:173], v215 offset:1024
	ds_read_b128 v[178:181], v215 offset:2048
	ds_read_b128 v[182:185], v215 offset:3072
	ds_read_b128 v[186:189], v215 offset:4096
	ds_read_b128 v[194:197], v215 offset:5120
	ds_read_b128 v[198:201], v215 offset:6144
	ds_read_b128 v[202:205], v215 offset:7168
	global_load_lds_dwordx4 v[154:155], off
	v_lshl_add_u64 v[154:155], s[94:95], 0, v[120:121]
	s_add_i32 m0, s23, 0xe000
	s_nop 0
	global_load_lds_dwordx4 v[154:155], off
	s_waitcnt vmcnt(8) lgkmcnt(0)
	s_setprio 1
	s_barrier
	v_mfma_f32_16x16x32_bf16 v[174:177], v[122:125], v[162:165], v[174:177]
	v_mfma_f32_16x16x32_bf16 v[166:169], v[130:133], v[162:165], v[166:169]
	v_mfma_f32_16x16x32_bf16 v[154:157], v[122:125], v[178:181], v[156:159]
	v_mfma_f32_16x16x32_bf16 v[116:119], v[130:133], v[178:181], v[116:119]
	v_mfma_f32_16x16x32_bf16 v[112:115], v[122:125], v[186:189], v[112:115]
	v_mfma_f32_16x16x32_bf16 v[108:111], v[130:133], v[186:189], v[108:111]
	v_mfma_f32_16x16x32_bf16 v[104:107], v[122:125], v[198:201], v[104:107]
	v_mfma_f32_16x16x32_bf16 v[100:103], v[130:133], v[198:201], v[100:103]
	v_mfma_f32_16x16x32_bf16 v[174:177], v[126:129], v[170:173], v[174:177]
	v_mfma_f32_16x16x32_bf16 v[166:169], v[134:137], v[170:173], v[166:169]
	v_mfma_f32_16x16x32_bf16 v[154:157], v[126:129], v[182:185], v[154:157]
	v_mfma_f32_16x16x32_bf16 v[116:119], v[134:137], v[182:185], v[116:119]
	v_mfma_f32_16x16x32_bf16 v[112:115], v[126:129], v[194:197], v[112:115]
	v_mfma_f32_16x16x32_bf16 v[108:111], v[134:137], v[194:197], v[108:111]
	v_mfma_f32_16x16x32_bf16 v[104:107], v[126:129], v[202:205], v[104:107]
	v_mfma_f32_16x16x32_bf16 v[100:103], v[134:137], v[202:205], v[100:103]
	s_setprio 0
	s_setprio 1
	v_mfma_f32_16x16x32_bf16 v[64:67], v[138:141], v[162:165], v[64:67]
	v_mfma_f32_16x16x32_bf16 v[60:63], v[146:149], v[162:165], v[60:63]
	v_mfma_f32_16x16x32_bf16 v[56:59], v[138:141], v[178:181], v[56:59]
	v_mfma_f32_16x16x32_bf16 v[52:55], v[146:149], v[178:181], v[52:55]
	v_mfma_f32_16x16x32_bf16 v[44:47], v[138:141], v[186:189], v[44:47]
	v_mfma_f32_16x16x32_bf16 v[40:43], v[146:149], v[186:189], v[40:43]
	v_mfma_f32_16x16x32_bf16 v[36:39], v[138:141], v[198:201], v[36:39]
	v_mfma_f32_16x16x32_bf16 v[32:35], v[146:149], v[198:201], v[32:35]
	v_mfma_f32_16x16x32_bf16 v[64:67], v[142:145], v[170:173], v[64:67]
	v_mfma_f32_16x16x32_bf16 v[60:63], v[150:153], v[170:173], v[60:63]
	v_mfma_f32_16x16x32_bf16 v[56:59], v[142:145], v[182:185], v[56:59]
	v_mfma_f32_16x16x32_bf16 v[52:55], v[150:153], v[182:185], v[52:55]
	v_mfma_f32_16x16x32_bf16 v[44:47], v[142:145], v[194:197], v[44:47]
	v_mfma_f32_16x16x32_bf16 v[40:43], v[150:153], v[194:197], v[40:43]
	v_mfma_f32_16x16x32_bf16 v[36:39], v[142:145], v[202:205], v[36:39]
	v_mfma_f32_16x16x32_bf16 v[32:35], v[150:153], v[202:205], v[32:35]
	s_barrier
	s_setprio 0
	s_add_i32 s80, s80, s88
	v_lshl_add_u64 v[190:191], s[4:5], 0, v[48:49]
	s_mov_b32 m0, s80
	ds_read_b128 v[162:165], v215 offset:16384
	ds_read_b128 v[170:173], v215 offset:17408
	ds_read_b128 v[178:181], v215 offset:18432
	ds_read_b128 v[182:185], v215 offset:19456
	ds_read_b128 v[186:189], v215 offset:20480
	ds_read_b128 v[194:197], v215 offset:21504
	ds_read_b128 v[198:201], v215 offset:22528
	ds_read_b128 v[202:205], v215 offset:23552
	global_load_lds_dwordx4 v[190:191], off
	s_add_i32 m0, s80, 0x2000
	s_add_u32 s94, s4, 0x10000
	v_lshl_add_u64 v[206:207], s[4:5], 0, v[160:161]
	s_addc_u32 s95, s5, 0
	s_add_i32 s80, s81, s88
	global_load_lds_dwordx4 v[206:207], off
	v_lshl_add_u64 v[158:159], s[94:95], 0, v[48:49]
	s_mov_b32 m0, s80
	v_lshl_add_u64 v[208:209], s[42:43], 0, v[50:51]
	global_load_lds_dwordx4 v[158:159], off
	v_lshl_add_u64 v[158:159], s[94:95], 0, v[160:161]
	s_add_i32 m0, s80, 0x2000
	v_lshl_add_u64 v[210:211], s[42:43], 0, v[120:121]
	global_load_lds_dwordx4 v[158:159], off
	s_mov_b32 m0, s23
	s_nop 0
	global_load_lds_dwordx4 v[208:209], off
	s_mov_b32 m0, s91
	s_nop 0
	global_load_lds_dwordx4 v[210:211], off
	s_waitcnt vmcnt(8) lgkmcnt(0)
	s_setprio 1
	s_barrier
	v_mfma_f32_16x16x32_bf16 v[96:99], v[122:125], v[162:165], v[96:99]
	v_mfma_f32_16x16x32_bf16 v[92:95], v[130:133], v[162:165], v[92:95]
	v_mfma_f32_16x16x32_bf16 v[88:91], v[122:125], v[178:181], v[88:91]
	v_mfma_f32_16x16x32_bf16 v[84:87], v[130:133], v[178:181], v[84:87]
	v_mfma_f32_16x16x32_bf16 v[80:83], v[122:125], v[186:189], v[80:83]
	v_mfma_f32_16x16x32_bf16 v[76:79], v[130:133], v[186:189], v[76:79]
	v_mfma_f32_16x16x32_bf16 v[72:75], v[122:125], v[198:201], v[72:75]
	v_mfma_f32_16x16x32_bf16 v[68:71], v[130:133], v[198:201], v[68:71]
	v_mfma_f32_16x16x32_bf16 v[96:99], v[126:129], v[170:173], v[96:99]
	v_mfma_f32_16x16x32_bf16 v[92:95], v[134:137], v[170:173], v[92:95]
	v_mfma_f32_16x16x32_bf16 v[88:91], v[126:129], v[182:185], v[88:91]
	v_mfma_f32_16x16x32_bf16 v[84:87], v[134:137], v[182:185], v[84:87]
	v_mfma_f32_16x16x32_bf16 v[80:83], v[126:129], v[194:197], v[80:83]
	v_mfma_f32_16x16x32_bf16 v[76:79], v[134:137], v[194:197], v[76:79]
	v_mfma_f32_16x16x32_bf16 v[72:75], v[126:129], v[202:205], v[72:75]
	v_mfma_f32_16x16x32_bf16 v[68:71], v[134:137], v[202:205], v[68:71]
	s_setprio 0
	s_setprio 1
	v_mfma_f32_16x16x32_bf16 v[28:31], v[138:141], v[162:165], v[28:31]
	v_mfma_f32_16x16x32_bf16 v[24:27], v[146:149], v[162:165], v[24:27]
	v_mfma_f32_16x16x32_bf16 v[20:23], v[138:141], v[178:181], v[20:23]
	v_mfma_f32_16x16x32_bf16 v[16:19], v[146:149], v[178:181], v[16:19]
	v_mfma_f32_16x16x32_bf16 v[12:15], v[138:141], v[186:189], v[12:15]
	v_mfma_f32_16x16x32_bf16 v[8:11], v[146:149], v[186:189], v[8:11]
	v_mfma_f32_16x16x32_bf16 v[4:7], v[138:141], v[198:201], v[4:7]
	v_mfma_f32_16x16x32_bf16 v[0:3], v[146:149], v[198:201], v[0:3]
	v_mfma_f32_16x16x32_bf16 v[28:31], v[142:145], v[170:173], v[28:31]
	v_mfma_f32_16x16x32_bf16 v[24:27], v[150:153], v[170:173], v[24:27]
	v_mfma_f32_16x16x32_bf16 v[20:23], v[142:145], v[182:185], v[20:23]
	v_mfma_f32_16x16x32_bf16 v[16:19], v[150:153], v[182:185], v[16:19]
	v_mfma_f32_16x16x32_bf16 v[12:15], v[142:145], v[194:197], v[12:15]
	v_mfma_f32_16x16x32_bf16 v[8:11], v[150:153], v[194:197], v[8:11]
	v_mfma_f32_16x16x32_bf16 v[4:7], v[142:145], v[202:205], v[4:7]
	v_mfma_f32_16x16x32_bf16 v[0:3], v[150:153], v[202:205], v[0:3]
	s_barrier
	s_setprio 0
	s_add_i32 s80, 0, 0x18000
	s_add_i32 s81, 0, 0x1c000
	v_add_u32_e32 v134, s80, v214
	v_add_u32_e32 v150, s81, v214
	ds_read_b128 v[122:125], v134
	ds_read_b128 v[126:129], v134 offset:1024
	ds_read_b128 v[130:133], v134 offset:2048
	ds_read_b128 v[134:137], v134 offset:3072
	ds_read_b128 v[138:141], v150
	ds_read_b128 v[142:145], v150 offset:1024
	ds_read_b128 v[146:149], v150 offset:2048
	ds_read_b128 v[150:153], v150 offset:3072
	s_add_u32 s42, s42, 0x40000
	s_addc_u32 s43, s43, 0
	s_mov_b32 m0, s38
	v_lshl_add_u64 v[158:159], s[42:43], 0, v[50:51]
	ds_read_b128 v[162:165], v215 offset:32768
	ds_read_b128 v[170:173], v215 offset:33792
	ds_read_b128 v[178:181], v215 offset:34816
	ds_read_b128 v[182:185], v215 offset:35840
	ds_read_b128 v[186:189], v215 offset:36864
	ds_read_b128 v[194:197], v215 offset:37888
	ds_read_b128 v[198:201], v215 offset:38912
	ds_read_b128 v[202:205], v215 offset:39936
	global_load_lds_dwordx4 v[158:159], off
	v_lshl_add_u64 v[158:159], s[42:43], 0, v[120:121]
	s_mov_b32 m0, s39
	s_nop 0
	global_load_lds_dwordx4 v[158:159], off
	s_waitcnt vmcnt(8) lgkmcnt(0)
	s_setprio 1
	s_barrier
	v_mfma_f32_16x16x32_bf16 v[174:177], v[122:125], v[162:165], v[174:177]
	v_mfma_f32_16x16x32_bf16 v[166:169], v[130:133], v[162:165], v[166:169]
	v_mfma_f32_16x16x32_bf16 v[154:157], v[122:125], v[178:181], v[154:157]
	v_mfma_f32_16x16x32_bf16 v[116:119], v[130:133], v[178:181], v[116:119]
	v_mfma_f32_16x16x32_bf16 v[112:115], v[122:125], v[186:189], v[112:115]
	v_mfma_f32_16x16x32_bf16 v[108:111], v[130:133], v[186:189], v[108:111]
	v_mfma_f32_16x16x32_bf16 v[104:107], v[122:125], v[198:201], v[104:107]
	v_mfma_f32_16x16x32_bf16 v[100:103], v[130:133], v[198:201], v[100:103]
	v_mfma_f32_16x16x32_bf16 v[174:177], v[126:129], v[170:173], v[174:177]
	v_mfma_f32_16x16x32_bf16 v[166:169], v[134:137], v[170:173], v[166:169]
	v_mfma_f32_16x16x32_bf16 v[156:159], v[126:129], v[182:185], v[154:157]
	v_mfma_f32_16x16x32_bf16 v[116:119], v[134:137], v[182:185], v[116:119]
	v_mfma_f32_16x16x32_bf16 v[112:115], v[126:129], v[194:197], v[112:115]
	v_mfma_f32_16x16x32_bf16 v[108:111], v[134:137], v[194:197], v[108:111]
	v_mfma_f32_16x16x32_bf16 v[104:107], v[126:129], v[202:205], v[104:107]
	v_mfma_f32_16x16x32_bf16 v[100:103], v[134:137], v[202:205], v[100:103]
	s_setprio 0
	s_setprio 1
	v_mfma_f32_16x16x32_bf16 v[64:67], v[138:141], v[162:165], v[64:67]
	v_mfma_f32_16x16x32_bf16 v[60:63], v[146:149], v[162:165], v[60:63]
	v_mfma_f32_16x16x32_bf16 v[56:59], v[138:141], v[178:181], v[56:59]
	v_mfma_f32_16x16x32_bf16 v[52:55], v[146:149], v[178:181], v[52:55]
	v_mfma_f32_16x16x32_bf16 v[44:47], v[138:141], v[186:189], v[44:47]
	v_mfma_f32_16x16x32_bf16 v[40:43], v[146:149], v[186:189], v[40:43]
	v_mfma_f32_16x16x32_bf16 v[36:39], v[138:141], v[198:201], v[36:39]
	v_mfma_f32_16x16x32_bf16 v[32:35], v[146:149], v[198:201], v[32:35]
	v_mfma_f32_16x16x32_bf16 v[64:67], v[142:145], v[170:173], v[64:67]
	v_mfma_f32_16x16x32_bf16 v[60:63], v[150:153], v[170:173], v[60:63]
	v_mfma_f32_16x16x32_bf16 v[56:59], v[142:145], v[182:185], v[56:59]
	v_mfma_f32_16x16x32_bf16 v[52:55], v[150:153], v[182:185], v[52:55]
	v_mfma_f32_16x16x32_bf16 v[44:47], v[142:145], v[194:197], v[44:47]
	v_mfma_f32_16x16x32_bf16 v[40:43], v[150:153], v[194:197], v[40:43]
	v_mfma_f32_16x16x32_bf16 v[36:39], v[142:145], v[202:205], v[36:39]
	v_mfma_f32_16x16x32_bf16 v[32:35], v[150:153], v[202:205], v[32:35]
	s_barrier
	s_setprio 0
	s_add_i32 s42, s80, s88
	v_lshl_add_u64 v[154:155], v[190:191], 0, s[14:15]
	s_mov_b32 m0, s42
	ds_read_b128 v[162:165], v215 offset:49152
	ds_read_b128 v[170:173], v215 offset:50176
	ds_read_b128 v[178:181], v215 offset:51200
	ds_read_b128 v[182:185], v215 offset:52224
	ds_read_b128 v[186:189], v215 offset:53248
	ds_read_b128 v[194:197], v215 offset:54272
	ds_read_b128 v[198:201], v215 offset:55296
	ds_read_b128 v[202:205], v215 offset:56320
	global_load_lds_dwordx4 v[154:155], off
	s_add_i32 m0, s42, 0x2000
	s_add_u32 s4, s4, 0x10080
	v_lshl_add_u64 v[154:155], v[206:207], 0, s[14:15]
	s_addc_u32 s5, s5, 0
	s_add_i32 s42, s81, s88
	global_load_lds_dwordx4 v[154:155], off
	v_lshl_add_u64 v[154:155], s[4:5], 0, v[48:49]
	s_mov_b32 m0, s42
	s_nop 0
	global_load_lds_dwordx4 v[154:155], off
	v_lshl_add_u64 v[154:155], s[4:5], 0, v[160:161]
	s_add_i32 m0, s42, 0x2000
	s_nop 0
	global_load_lds_dwordx4 v[154:155], off
	v_lshl_add_u64 v[154:155], v[208:209], 0, s[14:15]
	s_mov_b32 m0, s49
	s_nop 0
	global_load_lds_dwordx4 v[154:155], off
	v_lshl_add_u64 v[154:155], v[210:211], 0, s[14:15]
	s_mov_b32 m0, s52
	s_nop 0
	global_load_lds_dwordx4 v[154:155], off
	s_waitcnt vmcnt(8) lgkmcnt(0)
	s_setprio 1
	s_barrier
	v_mfma_f32_16x16x32_bf16 v[96:99], v[122:125], v[162:165], v[96:99]
	v_mfma_f32_16x16x32_bf16 v[92:95], v[130:133], v[162:165], v[92:95]
	v_mfma_f32_16x16x32_bf16 v[88:91], v[122:125], v[178:181], v[88:91]
	v_mfma_f32_16x16x32_bf16 v[84:87], v[130:133], v[178:181], v[84:87]
	v_mfma_f32_16x16x32_bf16 v[80:83], v[122:125], v[186:189], v[80:83]
	v_mfma_f32_16x16x32_bf16 v[76:79], v[130:133], v[186:189], v[76:79]
	v_mfma_f32_16x16x32_bf16 v[72:75], v[122:125], v[198:201], v[72:75]
	v_mfma_f32_16x16x32_bf16 v[68:71], v[130:133], v[198:201], v[68:71]
	v_mfma_f32_16x16x32_bf16 v[96:99], v[126:129], v[170:173], v[96:99]
	v_mfma_f32_16x16x32_bf16 v[92:95], v[134:137], v[170:173], v[92:95]
	v_mfma_f32_16x16x32_bf16 v[88:91], v[126:129], v[182:185], v[88:91]
	v_mfma_f32_16x16x32_bf16 v[84:87], v[134:137], v[182:185], v[84:87]
	v_mfma_f32_16x16x32_bf16 v[80:83], v[126:129], v[194:197], v[80:83]
	v_mfma_f32_16x16x32_bf16 v[76:79], v[134:137], v[194:197], v[76:79]
	v_mfma_f32_16x16x32_bf16 v[72:75], v[126:129], v[202:205], v[72:75]
	v_mfma_f32_16x16x32_bf16 v[68:71], v[134:137], v[202:205], v[68:71]
	s_setprio 0
	s_setprio 1
	v_mfma_f32_16x16x32_bf16 v[28:31], v[138:141], v[162:165], v[28:31]
	v_mfma_f32_16x16x32_bf16 v[24:27], v[146:149], v[162:165], v[24:27]
	v_mfma_f32_16x16x32_bf16 v[20:23], v[138:141], v[178:181], v[20:23]
	v_mfma_f32_16x16x32_bf16 v[16:19], v[146:149], v[178:181], v[16:19]
	v_mfma_f32_16x16x32_bf16 v[12:15], v[138:141], v[186:189], v[12:15]
	v_mfma_f32_16x16x32_bf16 v[8:11], v[146:149], v[186:189], v[8:11]
	v_mfma_f32_16x16x32_bf16 v[4:7], v[138:141], v[198:201], v[4:7]
	v_mfma_f32_16x16x32_bf16 v[0:3], v[146:149], v[198:201], v[0:3]
	v_mfma_f32_16x16x32_bf16 v[28:31], v[142:145], v[170:173], v[28:31]
	v_mfma_f32_16x16x32_bf16 v[24:27], v[150:153], v[170:173], v[24:27]
	v_mfma_f32_16x16x32_bf16 v[20:23], v[142:145], v[182:185], v[20:23]
	v_mfma_f32_16x16x32_bf16 v[16:19], v[150:153], v[182:185], v[16:19]
	v_mfma_f32_16x16x32_bf16 v[12:15], v[142:145], v[194:197], v[12:15]
	v_mfma_f32_16x16x32_bf16 v[8:11], v[150:153], v[194:197], v[8:11]
	v_mfma_f32_16x16x32_bf16 v[4:7], v[142:145], v[202:205], v[4:7]
	v_mfma_f32_16x16x32_bf16 v[0:3], v[150:153], v[202:205], v[0:3]
	s_barrier
	s_setprio 0
	s_cmp_lg_u32 s19, 0
	s_mov_b32 s19, 2
	s_cbranch_scc0 .LBB0_696
	s_and_b64 vcc, exec, s[68:69]
	s_cbranch_vccz .LBB0_699
	s_barrier

.LBB0_786:
.LBB0_787:
	s_add_i32 s9, 0, 0x10000
	s_add_i32 s19, 0, 0x14000
	v_add_u32_e32 v12, s9, v175
	v_add_u32_e32 v28, s19, v175
	ds_read_b128 v[0:3], v12
	ds_read_b128 v[4:7], v12 offset:1024
	ds_read_b128 v[8:11], v12 offset:2048
	ds_read_b128 v[12:15], v12 offset:3072
	ds_read_b128 v[16:19], v28
	ds_read_b128 v[20:23], v28 offset:1024
	ds_read_b128 v[24:27], v28 offset:2048
	ds_read_b128 v[28:31], v28 offset:3072
	s_add_u32 s36, s24, 0x40080
	s_addc_u32 s37, s25, 0
	v_lshl_add_u64 v[64:65], s[36:37], 0, v[122:123]
	s_add_i32 m0, s88, 0xc000
	ds_read_b128 v[32:35], v179
	ds_read_b128 v[36:39], v179 offset:1024
	ds_read_b128 v[40:43], v179 offset:2048
	ds_read_b128 v[44:47], v179 offset:3072
	ds_read_b128 v[48:51], v179 offset:4096
	ds_read_b128 v[52:55], v179 offset:5120
	ds_read_b128 v[56:59], v179 offset:6144
	ds_read_b128 v[60:63], v179 offset:7168
	global_load_lds_dwordx4 v[64:65], off
	v_lshl_add_u64 v[64:65], s[36:37], 0, v[124:125]
	s_add_i32 m0, s88, 0xe000
	s_nop 0
	global_load_lds_dwordx4 v[64:65], off
	s_waitcnt vmcnt(32) lgkmcnt(0)
	s_setprio 1
	s_barrier
	v_mfma_f32_16x16x32_bf16 v[64:67], v[0:3], v[32:35], 0
	v_mfma_f32_16x16x32_bf16 v[68:71], v[8:11], v[32:35], 0
	v_mfma_f32_16x16x32_bf16 v[72:75], v[0:3], v[40:43], 0
	v_mfma_f32_16x16x32_bf16 v[76:79], v[8:11], v[40:43], 0
	v_mfma_f32_16x16x32_bf16 v[80:83], v[0:3], v[48:51], 0
	v_mfma_f32_16x16x32_bf16 v[84:87], v[8:11], v[48:51], 0
	v_mfma_f32_16x16x32_bf16 v[88:91], v[0:3], v[56:59], 0
	v_mfma_f32_16x16x32_bf16 v[92:95], v[8:11], v[56:59], 0
	v_mfma_f32_16x16x32_bf16 v[116:119], v[4:7], v[36:39], v[64:67]
	v_mfma_f32_16x16x32_bf16 v[68:71], v[12:15], v[36:39], v[68:71]
	v_mfma_f32_16x16x32_bf16 v[72:75], v[4:7], v[44:47], v[72:75]
	v_mfma_f32_16x16x32_bf16 v[76:79], v[12:15], v[44:47], v[76:79]
	v_mfma_f32_16x16x32_bf16 v[80:83], v[4:7], v[52:55], v[80:83]
	v_mfma_f32_16x16x32_bf16 v[84:87], v[12:15], v[52:55], v[84:87]
	v_mfma_f32_16x16x32_bf16 v[88:91], v[4:7], v[60:63], v[88:91]
	v_mfma_f32_16x16x32_bf16 v[92:95], v[12:15], v[60:63], v[92:95]
	s_setprio 0
	s_setprio 1
	v_mfma_f32_16x16x32_bf16 v[96:99], v[16:19], v[32:35], 0
	v_mfma_f32_16x16x32_bf16 v[32:35], v[24:27], v[32:35], 0
	v_mfma_f32_16x16x32_bf16 v[126:129], v[20:23], v[36:39], v[96:99]
	v_mfma_f32_16x16x32_bf16 v[32:35], v[28:31], v[36:39], v[32:35]
	v_mfma_f32_16x16x32_bf16 v[36:39], v[16:19], v[40:43], 0
	v_mfma_f32_16x16x32_bf16 v[40:43], v[24:27], v[40:43], 0
	v_mfma_f32_16x16x32_bf16 v[36:39], v[20:23], v[44:47], v[36:39]
	v_mfma_f32_16x16x32_bf16 v[40:43], v[28:31], v[44:47], v[40:43]
	v_mfma_f32_16x16x32_bf16 v[44:47], v[16:19], v[48:51], 0
	v_mfma_f32_16x16x32_bf16 v[48:51], v[24:27], v[48:51], 0
	v_mfma_f32_16x16x32_bf16 v[130:133], v[28:31], v[52:55], v[48:51]
	v_mfma_f32_16x16x32_bf16 v[48:51], v[16:19], v[56:59], 0
	v_mfma_f32_16x16x32_bf16 v[44:47], v[20:23], v[52:55], v[44:47]
	v_mfma_f32_16x16x32_bf16 v[134:137], v[20:23], v[60:63], v[48:51]
	v_mfma_f32_16x16x32_bf16 v[48:51], v[24:27], v[56:59], 0
	v_mfma_f32_16x16x32_bf16 v[138:141], v[28:31], v[60:63], v[48:51]
	s_barrier
	s_setprio 0
	v_lshl_add_u64 v[158:159], s[22:23], 0, v[120:121]
	s_add_i32 s9, s9, s87
	v_lshl_add_u64 v[112:113], v[158:159], 0, s[16:17]
	s_mov_b32 m0, s9
	s_nop 0
	ds_read_b128 v[48:51], v179 offset:16384
	ds_read_b128 v[52:55], v179 offset:17408
	ds_read_b128 v[56:59], v179 offset:18432
	ds_read_b128 v[60:63], v179 offset:19456
	ds_read_b128 v[96:99], v179 offset:20480
	ds_read_b128 v[100:103], v179 offset:21504
	ds_read_b128 v[104:107], v179 offset:22528
	ds_read_b128 v[108:111], v179 offset:23552
	global_load_lds_dwordx4 v[112:113], off
	s_add_i32 m0, s9, 0x2000
	v_lshl_add_u64 v[176:177], s[22:23], 0, v[160:161]
	s_add_u32 s36, s22, 0x40100
	v_lshl_add_u64 v[112:113], v[176:177], 0, s[16:17]
	s_addc_u32 s37, s23, 0
	s_add_i32 s9, s19, s87
	global_load_lds_dwordx4 v[112:113], off
	v_lshl_add_u64 v[112:113], s[36:37], 0, v[120:121]
	s_mov_b32 m0, s9
	v_lshl_add_u64 v[188:189], s[24:25], 0, v[122:123]
	global_load_lds_dwordx4 v[112:113], off
	v_lshl_add_u64 v[112:113], s[36:37], 0, v[160:161]
	s_add_i32 m0, s9, 0x2000
	v_lshl_add_u64 v[190:191], s[24:25], 0, v[124:125]
	global_load_lds_dwordx4 v[112:113], off
	v_lshl_add_u64 v[112:113], v[188:189], 0, s[16:17]
	s_mov_b32 m0, s88
	s_nop 0
	global_load_lds_dwordx4 v[112:113], off
	v_lshl_add_u64 v[112:113], v[190:191], 0, s[16:17]
	s_mov_b32 m0, s89
	s_nop 0
	global_load_lds_dwordx4 v[112:113], off
	s_waitcnt vmcnt(32) lgkmcnt(0)
	s_setprio 1
	s_barrier
	v_mfma_f32_16x16x32_bf16 v[112:115], v[0:3], v[48:51], 0
	v_mfma_f32_16x16x32_bf16 v[142:145], v[4:7], v[52:55], v[112:115]
	v_mfma_f32_16x16x32_bf16 v[112:115], v[8:11], v[48:51], 0
	v_mfma_f32_16x16x32_bf16 v[146:149], v[12:15], v[52:55], v[112:115]
	v_mfma_f32_16x16x32_bf16 v[112:115], v[0:3], v[56:59], 0
	v_mfma_f32_16x16x32_bf16 v[150:153], v[4:7], v[60:63], v[112:115]
	v_mfma_f32_16x16x32_bf16 v[112:115], v[8:11], v[56:59], 0
	v_mfma_f32_16x16x32_bf16 v[154:157], v[12:15], v[60:63], v[112:115]
	v_mfma_f32_16x16x32_bf16 v[112:115], v[0:3], v[96:99], 0
	v_mfma_f32_16x16x32_bf16 v[0:3], v[0:3], v[104:107], 0
	v_mfma_f32_16x16x32_bf16 v[162:165], v[4:7], v[100:103], v[112:115]
	v_mfma_f32_16x16x32_bf16 v[0:3], v[4:7], v[108:111], v[0:3]
	v_mfma_f32_16x16x32_bf16 v[4:7], v[8:11], v[104:107], 0
	v_mfma_f32_16x16x32_bf16 v[112:115], v[8:11], v[96:99], 0
	v_mfma_f32_16x16x32_bf16 v[4:7], v[12:15], v[108:111], v[4:7]
	v_mfma_f32_16x16x32_bf16 v[166:169], v[12:15], v[100:103], v[112:115]
	s_setprio 0
	s_setprio 1
	v_mfma_f32_16x16x32_bf16 v[12:15], v[24:27], v[48:51], 0
	v_mfma_f32_16x16x32_bf16 v[170:173], v[28:31], v[52:55], v[12:15]
	v_mfma_f32_16x16x32_bf16 v[12:15], v[16:19], v[56:59], 0
	v_mfma_f32_16x16x32_bf16 v[180:183], v[20:23], v[60:63], v[12:15]
	v_mfma_f32_16x16x32_bf16 v[12:15], v[24:27], v[56:59], 0
	v_mfma_f32_16x16x32_bf16 v[184:187], v[28:31], v[60:63], v[12:15]
	v_mfma_f32_16x16x32_bf16 v[12:15], v[16:19], v[96:99], 0
	v_mfma_f32_16x16x32_bf16 v[194:197], v[20:23], v[100:103], v[12:15]
	v_mfma_f32_16x16x32_bf16 v[12:15], v[24:27], v[96:99], 0
	v_mfma_f32_16x16x32_bf16 v[8:11], v[16:19], v[48:51], 0
	v_mfma_f32_16x16x32_bf16 v[198:201], v[28:31], v[100:103], v[12:15]
	v_mfma_f32_16x16x32_bf16 v[12:15], v[16:19], v[104:107], 0
	v_mfma_f32_16x16x32_bf16 v[8:11], v[20:23], v[52:55], v[8:11]
	v_mfma_f32_16x16x32_bf16 v[202:205], v[20:23], v[108:111], v[12:15]
	v_mfma_f32_16x16x32_bf16 v[12:15], v[24:27], v[104:107], 0
	v_mfma_f32_16x16x32_bf16 v[206:209], v[28:31], v[108:111], v[12:15]
	s_barrier
	s_setprio 0
	s_add_i32 s9, 0, 0x18000
	s_nop 3
	v_add_u32_e32 v12, s9, v175
	s_add_i32 s19, 0, 0x1c000
	ds_read_b128 v[16:19], v12
	ds_read_b128 v[24:27], v12 offset:1024
	ds_read_b128 v[28:31], v12 offset:2048
	ds_read_b128 v[210:213], v12 offset:3072
	v_add_u32_e32 v12, s19, v175
	ds_read_b128 v[214:217], v12
	ds_read_b128 v[218:221], v12 offset:1024
	ds_read_b128 v[222:225], v12 offset:2048
	ds_read_b128 v[226:229], v12 offset:3072
	s_add_u32 s36, s24, 0x40100
	s_addc_u32 s37, s25, 0
	s_mov_b32 m0, s90
	v_lshl_add_u64 v[12:13], s[36:37], 0, v[122:123]
	ds_read_b128 v[48:51], v179 offset:32768
	ds_read_b128 v[52:55], v179 offset:33792
	ds_read_b128 v[234:237], v179 offset:34816
	v_mov_b32_e32 v174, v192
	v_mov_b32_e32 v192, v250
	v_mov_b32_e32 v66, v253
	ds_read_b128 v[250:253], v179 offset:35840
	ds_read_b128 v[238:241], v179 offset:36864
	ds_read_b128 v[242:245], v179 offset:37888
	ds_read_b128 v[230:233], v179 offset:38912
	ds_read_b128 v[246:249], v179 offset:39936
	global_load_lds_dwordx4 v[12:13], off
	v_lshl_add_u64 v[12:13], s[36:37], 0, v[124:125]
	s_mov_b32 m0, s91
	s_nop 0
	global_load_lds_dwordx4 v[12:13], off
	s_waitcnt vmcnt(8) lgkmcnt(0)
	s_setprio 1
	s_barrier
	v_mfma_f32_16x16x32_bf16 v[56:59], v[16:19], v[234:237], v[72:75]
	v_mfma_f32_16x16x32_bf16 v[12:15], v[16:19], v[48:51], v[116:119]
	v_mfma_f32_16x16x32_bf16 v[116:119], v[24:27], v[250:253], v[56:59]
	v_mfma_f32_16x16x32_bf16 v[56:59], v[28:31], v[234:237], v[76:79]
	v_mfma_f32_16x16x32_bf16 v[112:115], v[210:213], v[250:253], v[56:59]
	v_mfma_f32_16x16x32_bf16 v[56:59], v[16:19], v[238:241], v[80:83]
	v_mfma_f32_16x16x32_bf16 v[104:107], v[24:27], v[242:245], v[56:59]
	v_mfma_f32_16x16x32_bf16 v[56:59], v[28:31], v[238:241], v[84:87]
	v_mfma_f32_16x16x32_bf16 v[108:111], v[210:213], v[242:245], v[56:59]
	v_mfma_f32_16x16x32_bf16 v[56:59], v[16:19], v[230:233], v[88:91]
	v_mfma_f32_16x16x32_bf16 v[20:23], v[24:27], v[52:55], v[12:15]
	v_mfma_f32_16x16x32_bf16 v[12:15], v[28:31], v[48:51], v[68:71]
	v_mfma_f32_16x16x32_bf16 v[96:99], v[24:27], v[246:249], v[56:59]
	v_mfma_f32_16x16x32_bf16 v[56:59], v[28:31], v[230:233], v[92:95]
	v_mfma_f32_16x16x32_bf16 v[12:15], v[210:213], v[52:55], v[12:15]
	v_mfma_f32_16x16x32_bf16 v[100:103], v[210:213], v[246:249], v[56:59]
	s_setprio 0
	s_setprio 1
	v_mfma_f32_16x16x32_bf16 v[56:59], v[214:217], v[48:51], v[126:129]
	v_mfma_f32_16x16x32_bf16 v[32:35], v[222:225], v[48:51], v[32:35]
	v_mfma_f32_16x16x32_bf16 v[60:63], v[218:221], v[52:55], v[56:59]
	v_mfma_f32_16x16x32_bf16 v[56:59], v[226:229], v[52:55], v[32:35]
	v_mfma_f32_16x16x32_bf16 v[32:35], v[214:217], v[234:237], v[36:39]
	v_mfma_f32_16x16x32_bf16 v[52:55], v[218:221], v[250:253], v[32:35]
	v_mfma_f32_16x16x32_bf16 v[32:35], v[222:225], v[234:237], v[40:43]
	v_mfma_f32_16x16x32_bf16 v[48:51], v[226:229], v[250:253], v[32:35]
	v_mov_b32_e32 v253, v66
	v_mov_b32_e32 v250, v192
	v_mov_b32_e32 v192, v174
	v_mfma_f32_16x16x32_bf16 v[32:35], v[214:217], v[238:241], v[44:47]
	v_mfma_f32_16x16x32_bf16 v[44:47], v[218:221], v[242:245], v[32:35]
	v_mfma_f32_16x16x32_bf16 v[32:35], v[222:225], v[238:241], v[130:133]
	v_mfma_f32_16x16x32_bf16 v[40:43], v[226:229], v[242:245], v[32:35]
	v_mfma_f32_16x16x32_bf16 v[32:35], v[214:217], v[230:233], v[134:137]
	v_mfma_f32_16x16x32_bf16 v[36:39], v[218:221], v[246:249], v[32:35]
	v_mfma_f32_16x16x32_bf16 v[32:35], v[222:225], v[230:233], v[138:141]
	v_mfma_f32_16x16x32_bf16 v[32:35], v[226:229], v[246:249], v[32:35]
	v_mov_b32_e32 v247, 0x77
	v_mov_b32_e32 v246, 0x7c
	v_mov_b32_e32 v248, 0x260
	s_setprio 0
	s_barrier
	s_mov_b64 s[40:41], 0x180
	s_add_i32 s9, s9, s87
	v_lshl_add_u64 v[64:65], v[158:159], 0, s[40:41]
	s_mov_b32 m0, s9
	ds_read_b128 v[126:129], v179 offset:49152
	ds_read_b128 v[130:133], v179 offset:50176
	ds_read_b128 v[134:137], v179 offset:51200
	ds_read_b128 v[138:141], v179 offset:52224
	ds_read_b128 v[230:233], v179 offset:53248
	ds_read_b128 v[234:237], v179 offset:54272
	ds_read_b128 v[238:241], v179 offset:55296
	ds_read_b128 v[242:245], v179 offset:56320
	global_load_lds_dwordx4 v[64:65], off
	s_add_i32 m0, s9, 0x2000
	s_add_u32 s36, s22, 0x40180
	v_lshl_add_u64 v[64:65], v[176:177], 0, s[40:41]
	s_addc_u32 s37, s23, 0
	s_add_i32 s9, s19, s87
	global_load_lds_dwordx4 v[64:65], off
	v_lshl_add_u64 v[64:65], s[36:37], 0, v[120:121]
	s_mov_b32 m0, s9
	s_nop 0
	global_load_lds_dwordx4 v[64:65], off
	v_lshl_add_u64 v[64:65], s[36:37], 0, v[160:161]
	s_add_i32 m0, s9, 0x2000
	s_nop 0
	global_load_lds_dwordx4 v[64:65], off
	v_lshl_add_u64 v[64:65], v[188:189], 0, s[40:41]
	s_mov_b32 m0, s63
	s_nop 0
	global_load_lds_dwordx4 v[64:65], off
	v_lshl_add_u64 v[64:65], v[190:191], 0, s[40:41]
	s_mov_b32 m0, s64
	s_nop 0
	global_load_lds_dwordx4 v[64:65], off
	s_waitcnt vmcnt(8) lgkmcnt(0)
	s_setprio 1
	s_barrier
	v_mfma_f32_16x16x32_bf16 v[64:67], v[16:19], v[126:129], v[142:145]
	v_mfma_f32_16x16x32_bf16 v[88:91], v[24:27], v[130:133], v[64:67]
	v_mfma_f32_16x16x32_bf16 v[64:67], v[28:31], v[126:129], v[146:149]
	v_mfma_f32_16x16x32_bf16 v[92:95], v[210:213], v[130:133], v[64:67]
	v_mfma_f32_16x16x32_bf16 v[64:67], v[16:19], v[134:137], v[150:153]
	v_mfma_f32_16x16x32_bf16 v[80:83], v[24:27], v[138:141], v[64:67]
	v_mfma_f32_16x16x32_bf16 v[64:67], v[28:31], v[134:137], v[154:157]
	v_mfma_f32_16x16x32_bf16 v[84:87], v[210:213], v[138:141], v[64:67]
	v_mfma_f32_16x16x32_bf16 v[64:67], v[16:19], v[230:233], v[162:165]
	v_mfma_f32_16x16x32_bf16 v[72:75], v[24:27], v[234:237], v[64:67]
	v_mfma_f32_16x16x32_bf16 v[64:67], v[28:31], v[230:233], v[166:169]
	v_mfma_f32_16x16x32_bf16 v[0:3], v[16:19], v[238:241], v[0:3]
	v_mfma_f32_16x16x32_bf16 v[76:79], v[210:213], v[234:237], v[64:67]
	v_mfma_f32_16x16x32_bf16 v[64:67], v[24:27], v[242:245], v[0:3]
	v_mfma_f32_16x16x32_bf16 v[0:3], v[28:31], v[238:241], v[4:7]
	v_mfma_f32_16x16x32_bf16 v[68:71], v[210:213], v[242:245], v[0:3]
	s_setprio 0
	s_setprio 1
	v_mfma_f32_16x16x32_bf16 v[0:3], v[214:217], v[126:129], v[8:11]
	v_mfma_f32_16x16x32_bf16 v[28:31], v[218:221], v[130:133], v[0:3]
	v_mfma_f32_16x16x32_bf16 v[0:3], v[222:225], v[126:129], v[170:173]
	v_mfma_f32_16x16x32_bf16 v[24:27], v[226:229], v[130:133], v[0:3]
	v_mfma_f32_16x16x32_bf16 v[0:3], v[214:217], v[134:137], v[180:183]
	v_mfma_f32_16x16x32_bf16 v[16:19], v[218:221], v[138:141], v[0:3]
	v_mfma_f32_16x16x32_bf16 v[0:3], v[222:225], v[134:137], v[184:187]
	v_mfma_f32_16x16x32_bf16 v[126:129], v[214:217], v[238:241], v[202:205]
	v_mfma_f32_16x16x32_bf16 v[8:11], v[226:229], v[138:141], v[0:3]
	v_mfma_f32_16x16x32_bf16 v[0:3], v[214:217], v[230:233], v[194:197]
	v_mfma_f32_16x16x32_bf16 v[4:7], v[222:225], v[230:233], v[198:201]
	v_mfma_f32_16x16x32_bf16 v[132:135], v[218:221], v[242:245], v[126:129]
	v_mfma_f32_16x16x32_bf16 v[126:129], v[222:225], v[238:241], v[206:209]
	v_mov_b32_e32 v241, 0x7f
	v_mfma_f32_16x16x32_bf16 v[0:3], v[218:221], v[234:237], v[0:3]
	v_mfma_f32_16x16x32_bf16 v[4:7], v[226:229], v[234:237], v[4:7]
	v_mfma_f32_16x16x32_bf16 v[128:131], v[226:229], v[242:245], v[126:129]
	v_mov_b32_e32 v245, 0x7d
	v_mov_b32_e32 v244, 0x7e
	v_mov_b64_e32 v[242:243], 0x400
	s_setprio 0
	s_barrier
	s_mov_b32 s40, 2

.LBB0_789:
	s_add_u32 s24, s43, s92
	s_addc_u32 s25, s69, 0
	s_add_u32 s94, s81, s92
	s_addc_u32 s95, vcc_lo, 0
	s_add_i32 vcc_hi, 0, 0x10000
	s_cmp_eq_u32 s92, s22
	s_cselect_b32 s41, s9, s25
	s_cselect_b32 s40, s19, s24
	s_cselect_b32 s25, s36, s95
	s_cselect_b32 s24, s37, s94
	s_add_i32 s80, 0, 0x14000
	v_add_u32_e32 v150, vcc_hi, v175
	v_add_u32_e32 v158, s80, v175
	ds_read_b128 v[138:141], v150
	ds_read_b128 v[142:145], v150 offset:1024
	ds_read_b128 v[146:149], v150 offset:2048
	ds_read_b128 v[150:153], v150 offset:3072
	ds_read_b128 v[154:157], v158
	ds_read_b128 v[162:165], v158 offset:1024
	ds_read_b128 v[166:169], v158 offset:2048
	ds_read_b128 v[170:173], v158 offset:3072
	v_lshl_add_u64 v[158:159], v[126:127], 0, s[92:93]
	s_add_i32 m0, s88, 0xc000
	ds_read_b128 v[180:183], v179
	ds_read_b128 v[184:187], v179 offset:1024
	ds_read_b128 v[194:197], v179 offset:2048
	ds_read_b128 v[198:201], v179 offset:3072
	ds_read_b128 v[202:205], v179 offset:4096
	ds_read_b128 v[206:209], v179 offset:5120
	ds_read_b128 v[210:213], v179 offset:6144
	ds_read_b128 v[214:217], v179 offset:7168
	global_load_lds_dwordx4 v[158:159], off
	v_lshl_add_u64 v[158:159], v[136:137], 0, s[92:93]
	s_add_i32 m0, s88, 0xe000
	s_nop 0
	global_load_lds_dwordx4 v[158:159], off
	s_waitcnt vmcnt(8) lgkmcnt(0)
	s_setprio 1
	s_barrier
	v_mfma_f32_16x16x32_bf16 v[20:23], v[138:141], v[180:183], v[20:23]
	v_mfma_f32_16x16x32_bf16 v[12:15], v[146:149], v[180:183], v[12:15]
	v_mfma_f32_16x16x32_bf16 v[116:119], v[138:141], v[194:197], v[116:119]
	v_mfma_f32_16x16x32_bf16 v[112:115], v[146:149], v[194:197], v[112:115]
	v_mfma_f32_16x16x32_bf16 v[104:107], v[138:141], v[202:205], v[104:107]
	v_mfma_f32_16x16x32_bf16 v[108:111], v[146:149], v[202:205], v[108:111]
	v_mfma_f32_16x16x32_bf16 v[96:99], v[138:141], v[210:213], v[96:99]
	v_mfma_f32_16x16x32_bf16 v[100:103], v[146:149], v[210:213], v[100:103]
	v_mfma_f32_16x16x32_bf16 v[20:23], v[142:145], v[184:187], v[20:23]
	v_mfma_f32_16x16x32_bf16 v[12:15], v[150:153], v[184:187], v[12:15]
	v_mfma_f32_16x16x32_bf16 v[116:119], v[142:145], v[198:201], v[116:119]
	v_mfma_f32_16x16x32_bf16 v[112:115], v[150:153], v[198:201], v[112:115]
	v_mfma_f32_16x16x32_bf16 v[104:107], v[142:145], v[206:209], v[104:107]
	v_mfma_f32_16x16x32_bf16 v[108:111], v[150:153], v[206:209], v[108:111]
	v_mfma_f32_16x16x32_bf16 v[96:99], v[142:145], v[214:217], v[96:99]
	v_mfma_f32_16x16x32_bf16 v[100:103], v[150:153], v[214:217], v[100:103]
	s_setprio 0
	s_setprio 1
	v_mfma_f32_16x16x32_bf16 v[60:63], v[154:157], v[180:183], v[60:63]
	v_mfma_f32_16x16x32_bf16 v[56:59], v[166:169], v[180:183], v[56:59]
	v_mfma_f32_16x16x32_bf16 v[52:55], v[154:157], v[194:197], v[52:55]
	v_mfma_f32_16x16x32_bf16 v[48:51], v[166:169], v[194:197], v[48:51]
	v_mfma_f32_16x16x32_bf16 v[44:47], v[154:157], v[202:205], v[44:47]
	v_mfma_f32_16x16x32_bf16 v[40:43], v[166:169], v[202:205], v[40:43]
	v_mfma_f32_16x16x32_bf16 v[36:39], v[154:157], v[210:213], v[36:39]
	v_mfma_f32_16x16x32_bf16 v[32:35], v[166:169], v[210:213], v[32:35]
	v_mfma_f32_16x16x32_bf16 v[60:63], v[162:165], v[184:187], v[60:63]
	v_mfma_f32_16x16x32_bf16 v[56:59], v[170:173], v[184:187], v[56:59]
	v_mfma_f32_16x16x32_bf16 v[52:55], v[162:165], v[198:201], v[52:55]
	v_mfma_f32_16x16x32_bf16 v[48:51], v[170:173], v[198:201], v[48:51]
	v_mfma_f32_16x16x32_bf16 v[44:47], v[162:165], v[206:209], v[44:47]
	v_mfma_f32_16x16x32_bf16 v[40:43], v[170:173], v[206:209], v[40:43]
	v_mfma_f32_16x16x32_bf16 v[36:39], v[162:165], v[214:217], v[36:39]
	v_mfma_f32_16x16x32_bf16 v[32:35], v[170:173], v[214:217], v[32:35]
	s_barrier
	s_setprio 0
	s_add_i32 s94, vcc_hi, s87
	v_lshl_add_u64 v[158:159], s[24:25], 0, v[120:121]
	s_mov_b32 m0, s94
	ds_read_b128 v[180:183], v179 offset:16384
	ds_read_b128 v[184:187], v179 offset:17408
	ds_read_b128 v[194:197], v179 offset:18432
	ds_read_b128 v[198:201], v179 offset:19456
	ds_read_b128 v[202:205], v179 offset:20480
	ds_read_b128 v[206:209], v179 offset:21504
	ds_read_b128 v[210:213], v179 offset:22528
	ds_read_b128 v[214:217], v179 offset:23552
	global_load_lds_dwordx4 v[158:159], off
	s_add_i32 m0, s94, 0x2000
	s_add_u32 s94, s24, 0x40000
	v_lshl_add_u64 v[176:177], s[24:25], 0, v[160:161]
	s_addc_u32 s95, s25, 0
	s_add_i32 s80, s80, s87
	global_load_lds_dwordx4 v[176:177], off
	v_lshl_add_u64 v[188:189], s[94:95], 0, v[120:121]
	s_mov_b32 m0, s80
	v_lshl_add_u64 v[190:191], s[40:41], 0, v[124:125]
	global_load_lds_dwordx4 v[188:189], off
	v_lshl_add_u64 v[188:189], s[94:95], 0, v[160:161]
	s_add_i32 m0, s80, 0x2000
	s_nop 0
	global_load_lds_dwordx4 v[188:189], off
	v_lshl_add_u64 v[188:189], s[40:41], 0, v[122:123]
	s_mov_b32 m0, s88
	s_nop 0
	global_load_lds_dwordx4 v[188:189], off
	s_mov_b32 m0, s89
	s_nop 0
	global_load_lds_dwordx4 v[190:191], off
	s_waitcnt vmcnt(8) lgkmcnt(0)
	s_setprio 1
	s_barrier
	v_mfma_f32_16x16x32_bf16 v[88:91], v[138:141], v[180:183], v[88:91]
	v_mfma_f32_16x16x32_bf16 v[92:95], v[146:149], v[180:183], v[92:95]
	v_mfma_f32_16x16x32_bf16 v[80:83], v[138:141], v[194:197], v[80:83]
	v_mfma_f32_16x16x32_bf16 v[84:87], v[146:149], v[194:197], v[84:87]
	v_mfma_f32_16x16x32_bf16 v[72:75], v[138:141], v[202:205], v[72:75]
	v_mfma_f32_16x16x32_bf16 v[76:79], v[146:149], v[202:205], v[76:79]
	v_mfma_f32_16x16x32_bf16 v[64:67], v[138:141], v[210:213], v[64:67]
	v_mfma_f32_16x16x32_bf16 v[68:71], v[146:149], v[210:213], v[68:71]
	v_mfma_f32_16x16x32_bf16 v[88:91], v[142:145], v[184:187], v[88:91]
	v_mfma_f32_16x16x32_bf16 v[92:95], v[150:153], v[184:187], v[92:95]
	v_mfma_f32_16x16x32_bf16 v[80:83], v[142:145], v[198:201], v[80:83]
	v_mfma_f32_16x16x32_bf16 v[84:87], v[150:153], v[198:201], v[84:87]
	v_mfma_f32_16x16x32_bf16 v[72:75], v[142:145], v[206:209], v[72:75]
	v_mfma_f32_16x16x32_bf16 v[76:79], v[150:153], v[206:209], v[76:79]
	v_mfma_f32_16x16x32_bf16 v[64:67], v[142:145], v[214:217], v[64:67]
	v_mfma_f32_16x16x32_bf16 v[68:71], v[150:153], v[214:217], v[68:71]
	s_setprio 0
	s_setprio 1
	v_mfma_f32_16x16x32_bf16 v[28:31], v[154:157], v[180:183], v[28:31]
	v_mfma_f32_16x16x32_bf16 v[24:27], v[166:169], v[180:183], v[24:27]
	v_mfma_f32_16x16x32_bf16 v[16:19], v[154:157], v[194:197], v[16:19]
	v_mfma_f32_16x16x32_bf16 v[8:11], v[166:169], v[194:197], v[8:11]
	v_mfma_f32_16x16x32_bf16 v[0:3], v[154:157], v[202:205], v[0:3]
	v_mfma_f32_16x16x32_bf16 v[4:7], v[166:169], v[202:205], v[4:7]
	v_mfma_f32_16x16x32_bf16 v[132:135], v[154:157], v[210:213], v[132:135]
	v_mfma_f32_16x16x32_bf16 v[128:131], v[166:169], v[210:213], v[128:131]
	v_mfma_f32_16x16x32_bf16 v[28:31], v[162:165], v[184:187], v[28:31]
	v_mfma_f32_16x16x32_bf16 v[24:27], v[170:173], v[184:187], v[24:27]
	v_mfma_f32_16x16x32_bf16 v[16:19], v[162:165], v[198:201], v[16:19]
	v_mfma_f32_16x16x32_bf16 v[8:11], v[170:173], v[198:201], v[8:11]
	v_mfma_f32_16x16x32_bf16 v[0:3], v[162:165], v[206:209], v[0:3]
	v_mfma_f32_16x16x32_bf16 v[4:7], v[170:173], v[206:209], v[4:7]
	v_mfma_f32_16x16x32_bf16 v[132:135], v[162:165], v[214:217], v[132:135]
	v_mfma_f32_16x16x32_bf16 v[128:131], v[170:173], v[214:217], v[128:131]
	s_barrier
	s_setprio 0
	s_add_i32 s80, 0, 0x18000
	s_add_i32 s94, 0, 0x1c000
	v_add_u32_e32 v150, s80, v175
	v_add_u32_e32 v170, s94, v175
	ds_read_b128 v[138:141], v150
	ds_read_b128 v[142:145], v150 offset:1024
	ds_read_b128 v[146:149], v150 offset:2048
	ds_read_b128 v[150:153], v150 offset:3072
	ds_read_b128 v[154:157], v170
	ds_read_b128 v[162:165], v170 offset:1024
	ds_read_b128 v[166:169], v170 offset:2048
	ds_read_b128 v[170:173], v170 offset:3072
	s_add_u32 s40, s40, 0x40000
	s_addc_u32 s41, s41, 0
	s_mov_b32 m0, s90
	v_lshl_add_u64 v[218:219], s[40:41], 0, v[122:123]
	ds_read_b128 v[180:183], v179 offset:32768
	ds_read_b128 v[184:187], v179 offset:33792
	ds_read_b128 v[194:197], v179 offset:34816
	ds_read_b128 v[198:201], v179 offset:35840
	ds_read_b128 v[202:205], v179 offset:36864
	ds_read_b128 v[206:209], v179 offset:37888
	ds_read_b128 v[210:213], v179 offset:38912
	ds_read_b128 v[214:217], v179 offset:39936
	global_load_lds_dwordx4 v[218:219], off
	v_lshl_add_u64 v[218:219], s[40:41], 0, v[124:125]
	s_mov_b32 m0, s91
	s_nop 0
	global_load_lds_dwordx4 v[218:219], off
	s_waitcnt vmcnt(8) lgkmcnt(0)
	s_setprio 1
	s_barrier
	v_mfma_f32_16x16x32_bf16 v[20:23], v[138:141], v[180:183], v[20:23]
	v_mfma_f32_16x16x32_bf16 v[12:15], v[146:149], v[180:183], v[12:15]
	v_mfma_f32_16x16x32_bf16 v[116:119], v[138:141], v[194:197], v[116:119]
	v_mfma_f32_16x16x32_bf16 v[112:115], v[146:149], v[194:197], v[112:115]
	v_mfma_f32_16x16x32_bf16 v[104:107], v[138:141], v[202:205], v[104:107]
	v_mfma_f32_16x16x32_bf16 v[108:111], v[146:149], v[202:205], v[108:111]
	v_mfma_f32_16x16x32_bf16 v[96:99], v[138:141], v[210:213], v[96:99]
	v_mfma_f32_16x16x32_bf16 v[100:103], v[146:149], v[210:213], v[100:103]
	v_mfma_f32_16x16x32_bf16 v[20:23], v[142:145], v[184:187], v[20:23]
	v_mfma_f32_16x16x32_bf16 v[12:15], v[150:153], v[184:187], v[12:15]
	v_mfma_f32_16x16x32_bf16 v[116:119], v[142:145], v[198:201], v[116:119]
	v_mfma_f32_16x16x32_bf16 v[112:115], v[150:153], v[198:201], v[112:115]
	v_mfma_f32_16x16x32_bf16 v[104:107], v[142:145], v[206:209], v[104:107]
	v_mfma_f32_16x16x32_bf16 v[108:111], v[150:153], v[206:209], v[108:111]
	v_mfma_f32_16x16x32_bf16 v[96:99], v[142:145], v[214:217], v[96:99]
	v_mfma_f32_16x16x32_bf16 v[100:103], v[150:153], v[214:217], v[100:103]
	s_setprio 0
	s_setprio 1
	v_mfma_f32_16x16x32_bf16 v[60:63], v[154:157], v[180:183], v[60:63]
	v_mfma_f32_16x16x32_bf16 v[56:59], v[166:169], v[180:183], v[56:59]
	v_mfma_f32_16x16x32_bf16 v[52:55], v[154:157], v[194:197], v[52:55]
	v_mfma_f32_16x16x32_bf16 v[48:51], v[166:169], v[194:197], v[48:51]
	v_mfma_f32_16x16x32_bf16 v[44:47], v[154:157], v[202:205], v[44:47]
	v_mfma_f32_16x16x32_bf16 v[40:43], v[166:169], v[202:205], v[40:43]
	v_mfma_f32_16x16x32_bf16 v[36:39], v[154:157], v[210:213], v[36:39]
	v_mfma_f32_16x16x32_bf16 v[32:35], v[166:169], v[210:213], v[32:35]
	v_mfma_f32_16x16x32_bf16 v[60:63], v[162:165], v[184:187], v[60:63]
	v_mfma_f32_16x16x32_bf16 v[56:59], v[170:173], v[184:187], v[56:59]
	v_mfma_f32_16x16x32_bf16 v[52:55], v[162:165], v[198:201], v[52:55]
	v_mfma_f32_16x16x32_bf16 v[48:51], v[170:173], v[198:201], v[48:51]
	v_mfma_f32_16x16x32_bf16 v[44:47], v[162:165], v[206:209], v[44:47]
	v_mfma_f32_16x16x32_bf16 v[40:43], v[170:173], v[206:209], v[40:43]
	v_mfma_f32_16x16x32_bf16 v[36:39], v[162:165], v[214:217], v[36:39]
	v_mfma_f32_16x16x32_bf16 v[32:35], v[170:173], v[214:217], v[32:35]
	s_barrier
	s_setprio 0
	s_add_i32 s40, s80, s87
	v_lshl_add_u64 v[158:159], v[158:159], 0, s[14:15]
	s_mov_b32 m0, s40
	ds_read_b128 v[180:183], v179 offset:49152
	ds_read_b128 v[184:187], v179 offset:50176
	ds_read_b128 v[194:197], v179 offset:51200
	ds_read_b128 v[198:201], v179 offset:52224
	ds_read_b128 v[202:205], v179 offset:53248
	ds_read_b128 v[206:209], v179 offset:54272
	ds_read_b128 v[210:213], v179 offset:55296
	ds_read_b128 v[214:217], v179 offset:56320
	global_load_lds_dwordx4 v[158:159], off
	s_add_i32 m0, s40, 0x2000
	s_add_u32 s24, s24, 0x40080
	v_lshl_add_u64 v[158:159], v[176:177], 0, s[14:15]
	s_addc_u32 s25, s25, 0
	s_add_i32 s40, s94, s87
	global_load_lds_dwordx4 v[158:159], off
	v_lshl_add_u64 v[158:159], s[24:25], 0, v[120:121]
	s_mov_b32 m0, s40
	s_nop 0
	global_load_lds_dwordx4 v[158:159], off
	v_lshl_add_u64 v[158:159], s[24:25], 0, v[160:161]
	s_add_i32 m0, s40, 0x2000
	s_nop 0
	global_load_lds_dwordx4 v[158:159], off
	v_lshl_add_u64 v[158:159], v[188:189], 0, s[14:15]
	s_mov_b32 m0, s63
	s_nop 0
	global_load_lds_dwordx4 v[158:159], off
	v_lshl_add_u64 v[158:159], v[190:191], 0, s[14:15]
	s_mov_b32 m0, s64
	s_nop 0
	global_load_lds_dwordx4 v[158:159], off
	s_waitcnt vmcnt(8) lgkmcnt(0)
	s_setprio 1
	s_barrier
	v_mfma_f32_16x16x32_bf16 v[88:91], v[138:141], v[180:183], v[88:91]
	v_mfma_f32_16x16x32_bf16 v[92:95], v[146:149], v[180:183], v[92:95]
	v_mfma_f32_16x16x32_bf16 v[80:83], v[138:141], v[194:197], v[80:83]
	v_mfma_f32_16x16x32_bf16 v[84:87], v[146:149], v[194:197], v[84:87]
	v_mfma_f32_16x16x32_bf16 v[72:75], v[138:141], v[202:205], v[72:75]
	v_mfma_f32_16x16x32_bf16 v[76:79], v[146:149], v[202:205], v[76:79]
	v_mfma_f32_16x16x32_bf16 v[64:67], v[138:141], v[210:213], v[64:67]
	v_mfma_f32_16x16x32_bf16 v[68:71], v[146:149], v[210:213], v[68:71]
	v_mfma_f32_16x16x32_bf16 v[88:91], v[142:145], v[184:187], v[88:91]
	v_mfma_f32_16x16x32_bf16 v[92:95], v[150:153], v[184:187], v[92:95]
	v_mfma_f32_16x16x32_bf16 v[80:83], v[142:145], v[198:201], v[80:83]
	v_mfma_f32_16x16x32_bf16 v[84:87], v[150:153], v[198:201], v[84:87]
	v_mfma_f32_16x16x32_bf16 v[72:75], v[142:145], v[206:209], v[72:75]
	v_mfma_f32_16x16x32_bf16 v[76:79], v[150:153], v[206:209], v[76:79]
	v_mfma_f32_16x16x32_bf16 v[64:67], v[142:145], v[214:217], v[64:67]
	v_mfma_f32_16x16x32_bf16 v[68:71], v[150:153], v[214:217], v[68:71]
	s_setprio 0
	s_setprio 1
	v_mfma_f32_16x16x32_bf16 v[28:31], v[154:157], v[180:183], v[28:31]
	v_mfma_f32_16x16x32_bf16 v[24:27], v[166:169], v[180:183], v[24:27]
	v_mfma_f32_16x16x32_bf16 v[16:19], v[154:157], v[194:197], v[16:19]
	v_mfma_f32_16x16x32_bf16 v[8:11], v[166:169], v[194:197], v[8:11]
	v_mfma_f32_16x16x32_bf16 v[0:3], v[154:157], v[202:205], v[0:3]
	v_mfma_f32_16x16x32_bf16 v[4:7], v[166:169], v[202:205], v[4:7]
	v_mfma_f32_16x16x32_bf16 v[132:135], v[154:157], v[210:213], v[132:135]
	v_mfma_f32_16x16x32_bf16 v[128:131], v[166:169], v[210:213], v[128:131]
	v_mfma_f32_16x16x32_bf16 v[28:31], v[162:165], v[184:187], v[28:31]
	v_mfma_f32_16x16x32_bf16 v[24:27], v[170:173], v[184:187], v[24:27]
	v_mfma_f32_16x16x32_bf16 v[16:19], v[162:165], v[198:201], v[16:19]
	v_mfma_f32_16x16x32_bf16 v[8:11], v[170:173], v[198:201], v[8:11]
	v_mfma_f32_16x16x32_bf16 v[0:3], v[162:165], v[206:209], v[0:3]
	v_mfma_f32_16x16x32_bf16 v[4:7], v[170:173], v[206:209], v[4:7]
	v_mfma_f32_16x16x32_bf16 v[132:135], v[162:165], v[214:217], v[132:135]
	v_mfma_f32_16x16x32_bf16 v[128:131], v[170:173], v[214:217], v[128:131]
	s_barrier
	s_setprio 0
	s_add_i32 s42, s42, 2
	s_add_u32 s43, s43, 0x100
	s_addc_u32 s69, s69, 0
	s_add_u32 s81, s81, 0x100
	s_addc_u32 vcc_lo, vcc_lo, 0
	s_add_u32 s22, s22, 0xffffff00
	s_addc_u32 s23, s23, -1
	v_lshl_add_u64 v[126:127], v[126:127], 0, s[16:17]
	s_cmp_gt_u32 s42, 13
	v_lshl_add_u64 v[136:137], v[136:137], 0, s[16:17]
	s_cbranch_scc0 .LBB0_789
	s_and_b64 vcc, exec, s[44:45]
	s_cbranch_vccz .LBB0_792
	s_barrier

.LBB0_1066:
	s_or_b64 exec, exec, s[4:5]
	s_ashr_i32 s8, s18, 6
	s_ashr_i32 s4, s19, 7
	s_mul_i32 s24, s8, 0x2400
	s_sub_i32 s7, 7, s4
	s_and_b32 s9, s8, 3
	s_lshl_b32 s5, s19, 9
	s_add_i32 s24, s24, 0
	s_and_b32 s23, s5, 0xf800
	s_lshl_b32 s19, s7, 8
	s_lshl_b32 s5, s9, 5
	s_add_i32 s24, s24, 0x12800
	v_and_b32_e32 v1, 31, v0
	s_or_b32 s41, s5, s19
	v_mov_b32_e32 v3, s24
	s_movk_i32 s24, 0x90
	v_mad_u32_u24 v3, v1, s24, v3
	s_add_i32 s24, s41, s23
	v_or_b32_e32 v160, s24, v1
	v_mov_b64_e32 v[4:5], s[44:45]
	s_ashr_i32 s22, s18, 8
	s_or_b32 s19, s41, 0x80
	v_mad_u64_u32 v[6:7], s[24:25], v160, s3, v[4:5]
	s_lshl_b32 s24, s22, 6
	s_add_i32 s36, s19, s23
	s_lshl_b32 s92, s6, 8
	s_ashr_i32 s25, s24, 31
	v_or_b32_e32 v178, s36, v1
	v_bfe_u32 v2, v0, 5, 1
	v_lshl_add_u64 v[6:7], v[6:7], 0, s[92:93]
	s_lshl_b64 s[24:25], s[24:25], 1
	v_mad_u64_u32 v[4:5], s[36:37], v178, s3, v[4:5]
	v_lshlrev_b32_e32 v180, 4, v2
	v_lshl_add_u64 v[6:7], v[6:7], 0, s[24:25]
	v_mov_b32_e32 v181, v161
	v_lshl_add_u64 v[4:5], v[4:5], 0, s[92:93]
	v_lshl_add_u64 v[6:7], v[6:7], 0, v[180:181]
	v_lshl_add_u64 v[4:5], v[4:5], 0, s[24:25]
	v_lshl_add_u64 v[10:11], v[4:5], 0, v[180:181]
	v_add_co_u32_e32 v4, vcc, s72, v6
	s_mov_b64 s[52:53], 0x1000
	s_nop 0
	v_addc_co_u32_e32 v5, vcc, 0, v7, vcc
	v_lshl_add_u64 v[8:9], v[6:7], 0, s[52:53]
	global_load_dwordx4 v[32:35], v[4:5], off
	v_add_u32_e32 v195, v3, v180
	v_lshl_add_u64 v[12:13], v[10:11], 0, s[52:53]
	v_add_co_u32_e32 v14, vcc, s72, v10
	s_nop 1
	v_addc_co_u32_e32 v15, vcc, 0, v11, vcc
	global_load_dwordx4 v[36:39], v[14:15], off
	global_load_dwordx4 v[40:43], v[8:9], off offset:32
	global_load_dwordx4 v[44:47], v[12:13], off offset:32
	global_load_dwordx4 v[48:51], v[8:9], off offset:64
	global_load_dwordx4 v[52:55], v[12:13], off offset:64
	global_load_dwordx4 v[56:59], v[8:9], off offset:96
	global_load_dwordx4 v[60:63], v[12:13], off offset:96
	s_add_u32 s24, s44, s92
	v_lshlrev_b32_e32 v3, 4, v0
	s_addc_u32 s25, s45, 0
	v_and_b32_e32 v20, 0xf0, v3
	v_mov_b32_e32 v21, v161
	v_ashrrev_i32_e32 v184, 4, v0
	v_lshl_add_u64 v[182:183], s[24:25], 0, v[20:21]
	v_add_u32_e32 v3, s23, v184
	v_add_u32_e32 v250, 0, v20
	s_or_b32 s36, s23, 64
	v_mov_b32_e32 v249, 0x5800
	v_mov_b32_e32 v240, 0x3d800000
	v_mov_b32_e32 v192, 0x358637bd
	s_cmp_lt_i32 s8, 4
	v_mad_i64_i32 v[4:5], s[24:25], v3, s3, v[182:183]
	v_add_u32_e32 v3, 0x200, v0
	v_ashrrev_i32_e32 v186, 4, v3
	v_add_co_u32_e32 v8, vcc, s72, v4
	v_add_u32_e32 v3, s23, v186
	s_nop 0
	v_addc_co_u32_e32 v9, vcc, 0, v5, vcc
	v_mad_i64_i32 v[12:13], s[24:25], v3, s3, v[182:183]
	global_load_dwordx4 v[4:7], v[8:9], off offset:1024
	s_nop 0
	global_load_dwordx4 v[8:11], v[8:9], off offset:2048
	v_add_co_u32_e32 v16, vcc, s72, v12
	s_movk_i32 s24, 0x110
	s_nop 0
	v_addc_co_u32_e32 v17, vcc, 0, v13, vcc
	global_load_dwordx4 v[12:15], v[16:17], off offset:1024
	s_nop 0
	global_load_dwordx4 v[16:19], v[16:17], off offset:2048
	v_mul_lo_u32 v251, v184, s24
	s_movk_i32 s25, 0x140
	v_add_u32_e32 v3, v250, v251
	v_mul_lo_u32 v252, v184, s25
	v_mul_lo_u32 v253, v186, s24
	v_mul_lo_u32 v236, v186, s25
	s_waitcnt vmcnt(4)
	ds_write_b128 v195, v[32:35]
	ds_write_b128 v195, v[36:39] offset:4608
	ds_write_b128 v195, v[40:43] offset:32
	ds_write_b128 v195, v[44:47] offset:4640
	ds_write_b128 v195, v[48:51] offset:64
	ds_write_b128 v195, v[52:55] offset:4672
	ds_write_b128 v195, v[56:59] offset:96
	ds_write_b128 v195, v[60:63] offset:4704
	s_waitcnt vmcnt(3)
	ds_write_b128 v3, v[4:7]
	v_add_u32_e32 v3, v250, v252
	s_waitcnt vmcnt(2)
	ds_write_b128 v3, v[8:11] offset:17408
	v_add_u32_e32 v3, v250, v253
	s_waitcnt vmcnt(1)
	ds_write_b128 v3, v[12:15]
	v_add_u32_e32 v3, v250, v236
	s_waitcnt vmcnt(0)
	ds_write_b128 v3, v[16:19] offset:17408
	v_add_u32_e32 v3, s36, v184
	v_mad_i64_i32 v[4:5], s[24:25], v3, s3, v[182:183]
	v_add_co_u32_e32 v4, vcc, s72, v4
	v_add_u32_e32 v3, s36, v186
	s_nop 0
	v_addc_co_u32_e32 v5, vcc, 0, v5, vcc
	global_load_dwordx4 v[162:165], v[4:5], off offset:1024
	global_load_dwordx4 v[166:169], v[4:5], off offset:2048
	v_mad_i64_i32 v[4:5], s[24:25], v3, s3, v[182:183]
	v_add_co_u32_e32 v4, vcc, 0x1000, v4
	s_nop 1
	v_addc_co_u32_e32 v5, vcc, 0, v5, vcc
	global_load_dwordx4 v[170:173], v[4:5], off offset:1024
	global_load_dwordx4 v[174:177], v[4:5], off offset:2048
	s_mov_b64 s[24:25], 0x38000
	v_lshl_add_u64 v[8:9], v[4:5], 0, s[24:25]
	s_mov_b64 s[24:25], 0x70000
	v_lshl_add_u64 v[10:11], v[4:5], 0, s[24:25]
	global_load_dword v239, v[8:9], off offset:1024
	global_load_dword v239, v[8:9], off offset:2048
	global_load_dword v239, v[10:11], off offset:1024
	global_load_dword v239, v[10:11], off offset:2048
	s_waitcnt lgkmcnt(0)
	s_barrier
	s_cbranch_scc1 .LBB0_1068
	s_setprio 1

.LBB0_1070:
	s_cmp_gt_u32 s52, s24
	s_cbranch_scc1 .LBB0_1080
	s_bitcmp1_b32 s52, 0
	s_cselect_b32 s4, 0x9400, 0
	s_add_i32 s6, s4, 0
	s_add_i32 s4, s6, s37
	v_add3_u32 v190, s4, v180, v233
	ds_read_b128 v[144:147], v195
	ds_read_b128 v[148:151], v190
	ds_read_b128 v[196:199], v195 offset:32
	ds_read_b128 v[152:155], v190 offset:32
	ds_read_b128 v[200:203], v195 offset:64
	ds_read_b128 v[156:159], v190 offset:64
	ds_read_b128 v[204:207], v195 offset:96
	ds_read_b128 v[208:211], v190 offset:96
	ds_read_b128 v[212:215], v190 offset:8704
	ds_read_b128 v[216:219], v190 offset:8736
	ds_read_b128 v[220:223], v190 offset:8768
	ds_read_b128 v[224:227], v190 offset:8800
	s_add_i32 s7, s53, 0xffffffbf
	s_mov_b64 s[4:5], -1
	s_cmp_le_i32 s7, s40
	s_waitcnt lgkmcnt(10)
	v_mfma_f32_32x32x16_bf16 v[128:143], v[148:151], v[144:147], 0
	s_waitcnt lgkmcnt(8)
	v_mfma_f32_32x32x16_bf16 v[128:143], v[152:155], v[196:199], v[128:143]
	s_waitcnt lgkmcnt(6)
	v_mfma_f32_32x32x16_bf16 v[128:143], v[156:159], v[200:203], v[128:143]
	s_waitcnt lgkmcnt(4)
	v_mfma_f32_32x32x16_bf16 v[128:143], v[208:211], v[204:207], v[128:143]
	s_waitcnt lgkmcnt(3)
	v_mfma_f32_32x32x16_bf16 v[144:159], v[212:215], v[144:147], 0
	s_waitcnt lgkmcnt(2)
	v_mfma_f32_32x32x16_bf16 v[144:159], v[216:219], v[196:199], v[144:159]
	s_waitcnt lgkmcnt(1)
	v_mfma_f32_32x32x16_bf16 v[144:159], v[220:223], v[200:203], v[144:159]
	s_waitcnt lgkmcnt(0)
	v_mfma_f32_32x32x16_bf16 v[144:159], v[224:227], v[204:207], v[144:159]
	s_cbranch_scc0 .LBB0_1073
	s_add_i32 s4, 0, 0x27a00
	v_mov_b32_e32 v190, s4
	ds_read_b32 v190, v190
	s_mov_b64 s[4:5], 0
	v_mbcnt_lo_u32_b32 v191, -1, 0
	v_mbcnt_hi_u32_b32 v191, -1, v191
	v_lshlrev_b32_e32 v191, 2, v191
	v_xor_b32_e32 v191, 0x80, v191
	v_max3_f32 v196, v128, v129, v130
	v_max3_f32 v196, v196, v131, v132
	v_max3_f32 v196, v196, v133, v134
	v_max3_f32 v196, v196, v135, v136
	v_max3_f32 v196, v196, v137, v138
	v_max3_f32 v196, v196, v139, v140
	v_max3_f32 v196, v196, v141, v142
	v_max3_f32 v196, v196, v143, v144
	v_max3_f32 v196, v196, v145, v146
	v_max3_f32 v196, v196, v147, v148
	v_max3_f32 v196, v196, v149, v150
	v_max3_f32 v196, v196, v151, v152
	v_max3_f32 v196, v196, v153, v154
	v_max3_f32 v196, v196, v155, v156
	v_max3_f32 v196, v196, v157, v158
	v_max_f32_e32 v196, v196, v159
	ds_bpermute_b32 v191, v191, v196
	s_waitcnt lgkmcnt(0)
	v_max_f32_e32 v196, v196, v191
	v_fma_f32 v196, v196, s28, v190
	v_add_f32_e32 v197, 0x41000000, v194
	v_cmp_gt_f32_e32 vcc, v196, v197
	s_cbranch_vccz .Lat_far_nors_1
	v_max_f32_e32 v197, v194, v196
	v_sub_f32_e32 v198, v194, v197
	v_exp_f32_e32 v198, v198
	v_mov_b32_e32 v194, v197
	v_mul_f32_e32 v238, v238, v198
	v_pk_mul_f32 v[126:127], v[126:127], v[198:199] op_sel_hi:[1,0]
	v_pk_mul_f32 v[124:125], v[124:125], v[198:199] op_sel_hi:[1,0]
	v_pk_mul_f32 v[122:123], v[122:123], v[198:199] op_sel_hi:[1,0]
	v_pk_mul_f32 v[120:121], v[120:121], v[198:199] op_sel_hi:[1,0]
	v_pk_mul_f32 v[118:119], v[118:119], v[198:199] op_sel_hi:[1,0]
	v_pk_mul_f32 v[116:117], v[116:117], v[198:199] op_sel_hi:[1,0]
	v_pk_mul_f32 v[114:115], v[114:115], v[198:199] op_sel_hi:[1,0]
	v_pk_mul_f32 v[112:113], v[112:113], v[198:199] op_sel_hi:[1,0]
	v_pk_mul_f32 v[94:95], v[94:95], v[198:199] op_sel_hi:[1,0]
	v_pk_mul_f32 v[92:93], v[92:93], v[198:199] op_sel_hi:[1,0]
	v_pk_mul_f32 v[90:91], v[90:91], v[198:199] op_sel_hi:[1,0]
	v_pk_mul_f32 v[88:89], v[88:89], v[198:199] op_sel_hi:[1,0]
	v_pk_mul_f32 v[86:87], v[86:87], v[198:199] op_sel_hi:[1,0]
	v_pk_mul_f32 v[84:85], v[84:85], v[198:199] op_sel_hi:[1,0]
	v_pk_mul_f32 v[82:83], v[82:83], v[198:199] op_sel_hi:[1,0]
	v_pk_mul_f32 v[80:81], v[80:81], v[198:199] op_sel_hi:[1,0]
	v_pk_mul_f32 v[62:63], v[62:63], v[198:199] op_sel_hi:[1,0]
	v_pk_mul_f32 v[60:61], v[60:61], v[198:199] op_sel_hi:[1,0]
	v_pk_mul_f32 v[58:59], v[58:59], v[198:199] op_sel_hi:[1,0]
	v_pk_mul_f32 v[56:57], v[56:57], v[198:199] op_sel_hi:[1,0]
	v_pk_mul_f32 v[54:55], v[54:55], v[198:199] op_sel_hi:[1,0]
	v_pk_mul_f32 v[52:53], v[52:53], v[198:199] op_sel_hi:[1,0]
	v_pk_mul_f32 v[50:51], v[50:51], v[198:199] op_sel_hi:[1,0]
	v_pk_mul_f32 v[48:49], v[48:49], v[198:199] op_sel_hi:[1,0]
	v_pk_mul_f32 v[30:31], v[30:31], v[198:199] op_sel_hi:[1,0]
	v_pk_mul_f32 v[28:29], v[28:29], v[198:199] op_sel_hi:[1,0]
	v_pk_mul_f32 v[26:27], v[26:27], v[198:199] op_sel_hi:[1,0]
	v_pk_mul_f32 v[24:25], v[24:25], v[198:199] op_sel_hi:[1,0]
	v_pk_mul_f32 v[22:23], v[22:23], v[198:199] op_sel_hi:[1,0]
	v_pk_mul_f32 v[20:21], v[20:21], v[198:199] op_sel_hi:[1,0]
	v_pk_mul_f32 v[18:19], v[18:19], v[198:199] op_sel_hi:[1,0]
	v_pk_mul_f32 v[16:17], v[16:17], v[198:199] op_sel_hi:[1,0]
.Lat_far_nors_1:
	v_sub_f32_e32 v191, v190, v194
	v_fma_f32 v226, v128, s28, v191
	v_fma_f32 v227, v129, s28, v191
	v_fma_f32 v224, v130, s28, v191
	v_fma_f32 v225, v131, s28, v191
	v_fma_f32 v222, v132, s28, v191
	v_fma_f32 v223, v133, s28, v191
	v_fma_f32 v220, v134, s28, v191
	v_fma_f32 v221, v135, s28, v191
	v_fma_f32 v218, v136, s28, v191
	v_fma_f32 v219, v137, s28, v191
	v_fma_f32 v216, v138, s28, v191
	v_fma_f32 v217, v139, s28, v191
	v_fma_f32 v214, v140, s28, v191
	v_fma_f32 v215, v141, s28, v191
	v_fma_f32 v212, v142, s28, v191
	v_fma_f32 v213, v143, s28, v191
	v_fma_f32 v210, v144, s28, v191
	v_fma_f32 v211, v145, s28, v191
	v_fma_f32 v208, v146, s28, v191
	v_fma_f32 v209, v147, s28, v191
	v_fma_f32 v206, v148, s28, v191
	v_fma_f32 v207, v149, s28, v191
	v_fma_f32 v204, v150, s28, v191
	v_fma_f32 v205, v151, s28, v191
	v_fma_f32 v202, v152, s28, v191
	v_fma_f32 v203, v153, s28, v191
	v_fma_f32 v200, v154, s28, v191
	v_fma_f32 v201, v155, s28, v191
	v_fma_f32 v198, v156, s28, v191
	v_fma_f32 v199, v157, s28, v191
	v_fma_f32 v196, v158, s28, v191
	v_fma_f32 v197, v159, s28, v191
	s_branch .Lat_tail_1

.LBB0_1077:
	v_sub_f32_e32 v226, v226, v194
	v_sub_f32_e32 v227, v227, v194
	v_sub_f32_e32 v224, v224, v194
	v_sub_f32_e32 v225, v225, v194
	v_sub_f32_e32 v222, v222, v194
	v_sub_f32_e32 v223, v223, v194
	v_sub_f32_e32 v220, v220, v194
	v_sub_f32_e32 v221, v221, v194
	v_sub_f32_e32 v218, v218, v194
	v_sub_f32_e32 v219, v219, v194
	v_sub_f32_e32 v216, v216, v194
	v_sub_f32_e32 v217, v217, v194
	v_sub_f32_e32 v214, v214, v194
	v_sub_f32_e32 v215, v215, v194
	v_sub_f32_e32 v212, v212, v194
	v_sub_f32_e32 v213, v213, v194
	v_sub_f32_e32 v210, v210, v194
	v_sub_f32_e32 v211, v211, v194
	v_sub_f32_e32 v208, v208, v194
	v_sub_f32_e32 v209, v209, v194
	v_sub_f32_e32 v206, v206, v194
	v_sub_f32_e32 v207, v207, v194
	v_sub_f32_e32 v204, v204, v194
	v_sub_f32_e32 v205, v205, v194
	v_sub_f32_e32 v202, v202, v194
	v_sub_f32_e32 v203, v203, v194
	v_sub_f32_e32 v200, v200, v194
	v_sub_f32_e32 v201, v201, v194
	v_sub_f32_e32 v198, v198, v194
	v_sub_f32_e32 v199, v199, v194
	v_sub_f32_e32 v196, v196, v194
	v_sub_f32_e32 v197, v197, v194
.Lat_tail_1:
	v_exp_f32_e32 v128, v226
	v_exp_f32_e32 v129, v227
	v_exp_f32_e32 v156, v224
	v_exp_f32_e32 v157, v225
	v_exp_f32_e32 v158, v222
	v_exp_f32_e32 v159, v223
	v_add_f32_e32 v130, v128, v156
	v_add_f32_e32 v131, v129, v157
	v_exp_f32_e32 v190, v220
	v_exp_f32_e32 v191, v221
	v_add_f32_e32 v130, v158, v130
	v_add_f32_e32 v131, v159, v131
	v_exp_f32_e32 v148, v218
	v_exp_f32_e32 v149, v219
	v_add_f32_e32 v130, v190, v130
	v_add_f32_e32 v131, v191, v131
	v_exp_f32_e32 v150, v216
	v_exp_f32_e32 v151, v217
	v_add_f32_e32 v130, v148, v130
	v_add_f32_e32 v131, v149, v131
	v_exp_f32_e32 v152, v214
	v_exp_f32_e32 v153, v215
	v_add_f32_e32 v130, v150, v130
	v_add_f32_e32 v131, v151, v131
	v_exp_f32_e32 v154, v212
	v_exp_f32_e32 v155, v213
	v_add_f32_e32 v130, v152, v130
	v_add_f32_e32 v131, v153, v131
	v_exp_f32_e32 v140, v210
	v_exp_f32_e32 v141, v211
	v_add_f32_e32 v130, v154, v130
	v_add_f32_e32 v131, v155, v131
	v_exp_f32_e32 v142, v208
	v_exp_f32_e32 v143, v209
	v_add_f32_e32 v130, v140, v130
	v_add_f32_e32 v131, v141, v131
	v_exp_f32_e32 v144, v206
	v_exp_f32_e32 v145, v207
	v_add_f32_e32 v130, v142, v130
	v_add_f32_e32 v131, v143, v131
	v_exp_f32_e32 v146, v204
	v_exp_f32_e32 v147, v205
	v_add_f32_e32 v130, v144, v130
	v_add_f32_e32 v131, v145, v131
	v_exp_f32_e32 v132, v202
	v_exp_f32_e32 v133, v203
	v_add_f32_e32 v130, v146, v130
	v_add_f32_e32 v131, v147, v131
	v_exp_f32_e32 v134, v200
	v_exp_f32_e32 v135, v201
	v_add_f32_e32 v130, v132, v130
	v_add_f32_e32 v131, v133, v131
	v_exp_f32_e32 v136, v198
	v_exp_f32_e32 v137, v199
	v_add_f32_e32 v130, v134, v130
	v_add_f32_e32 v131, v135, v131
	v_exp_f32_e32 v138, v196
	v_exp_f32_e32 v139, v197
	v_add_f32_e32 v130, v136, v130
	v_add_f32_e32 v131, v137, v131
	v_add_f32_e32 v130, v138, v130
	v_add_f32_e32 v131, v139, v131
	v_add_f32_e32 v130, v130, v131
	v_cvt_pk_bf16_f32 v128, v128, v129
	v_cvt_pk_bf16_f32 v129, v156, v157
	v_cvt_pk_bf16_f32 v131, v190, v191
	v_add3_u32 v190, s6, v235, v234
	v_add_f32_e32 v238, v238, v130
	v_cvt_pk_bf16_f32 v130, v158, v159
	ds_read_b64_tr_b16 v[156:157], v190 offset:17408
	ds_read_b64_tr_b16 v[158:159], v190 offset:19968
	v_cvt_pk_bf16_f32 v148, v148, v149
	v_cvt_pk_bf16_f32 v149, v150, v151
	v_cvt_pk_bf16_f32 v150, v152, v153
	v_cvt_pk_bf16_f32 v151, v154, v155
	ds_read_b64_tr_b16 v[152:153], v190 offset:17472
	ds_read_b64_tr_b16 v[154:155], v190 offset:20032
	v_cvt_pk_bf16_f32 v140, v140, v141
	v_cvt_pk_bf16_f32 v141, v142, v143
	v_cvt_pk_bf16_f32 v142, v144, v145
	v_cvt_pk_bf16_f32 v143, v146, v147
	ds_read_b64_tr_b16 v[144:145], v190 offset:17536
	ds_read_b64_tr_b16 v[146:147], v190 offset:20096
	v_cvt_pk_bf16_f32 v132, v132, v133
	v_cvt_pk_bf16_f32 v133, v134, v135
	v_cvt_pk_bf16_f32 v134, v136, v137
	v_cvt_pk_bf16_f32 v135, v138, v139
	ds_read_b64_tr_b16 v[136:137], v190 offset:17600
	ds_read_b64_tr_b16 v[138:139], v190 offset:20160
	s_waitcnt lgkmcnt(6)
	v_mfma_f32_32x32x16_bf16 v[112:127], v[156:159], v[128:131], v[112:127]
	ds_read_b64_tr_b16 v[156:157], v190 offset:22528
	ds_read_b64_tr_b16 v[158:159], v190 offset:25088
	s_waitcnt lgkmcnt(6)
	v_mfma_f32_32x32x16_bf16 v[80:95], v[152:155], v[128:131], v[80:95]
	ds_read_b64_tr_b16 v[152:153], v190 offset:22592
	ds_read_b64_tr_b16 v[154:155], v190 offset:25152
	s_waitcnt lgkmcnt(6)
	v_mfma_f32_32x32x16_bf16 v[48:63], v[144:147], v[128:131], v[48:63]
	ds_read_b64_tr_b16 v[144:145], v190 offset:22656
	ds_read_b64_tr_b16 v[146:147], v190 offset:25216
	s_waitcnt lgkmcnt(6)
	v_mfma_f32_32x32x16_bf16 v[16:31], v[136:139], v[128:131], v[16:31]
	ds_read_b64_tr_b16 v[136:137], v190 offset:22720
	ds_read_b64_tr_b16 v[138:139], v190 offset:25280
	s_waitcnt lgkmcnt(6)
	v_mfma_f32_32x32x16_bf16 v[112:127], v[156:159], v[148:151], v[112:127]
	ds_read_b64_tr_b16 v[156:157], v190 offset:27648
	ds_read_b64_tr_b16 v[158:159], v190 offset:30208
	s_waitcnt lgkmcnt(6)
	v_mfma_f32_32x32x16_bf16 v[80:95], v[152:155], v[148:151], v[80:95]
	ds_read_b64_tr_b16 v[152:153], v190 offset:27712
	ds_read_b64_tr_b16 v[154:155], v190 offset:30272
	s_waitcnt lgkmcnt(6)
	v_mfma_f32_32x32x16_bf16 v[48:63], v[144:147], v[148:151], v[48:63]
	ds_read_b64_tr_b16 v[144:145], v190 offset:27776
	ds_read_b64_tr_b16 v[146:147], v190 offset:30336
	s_waitcnt lgkmcnt(6)
	v_mfma_f32_32x32x16_bf16 v[16:31], v[136:139], v[148:151], v[16:31]
	ds_read_b64_tr_b16 v[136:137], v190 offset:27840
	ds_read_b64_tr_b16 v[138:139], v190 offset:30400
	s_waitcnt lgkmcnt(6)
	v_mfma_f32_32x32x16_bf16 v[112:127], v[156:159], v[140:143], v[112:127]
	ds_read_b64_tr_b16 v[156:157], v190 offset:32768
	ds_read_b64_tr_b16 v[158:159], v190 offset:35328
	s_waitcnt lgkmcnt(6)
	v_mfma_f32_32x32x16_bf16 v[80:95], v[152:155], v[140:143], v[80:95]
	ds_read_b64_tr_b16 v[152:153], v190 offset:32832
	ds_read_b64_tr_b16 v[154:155], v190 offset:35392
	s_waitcnt lgkmcnt(6)
	v_mfma_f32_32x32x16_bf16 v[48:63], v[144:147], v[140:143], v[48:63]
	ds_read_b64_tr_b16 v[144:145], v190 offset:32896
	ds_read_b64_tr_b16 v[146:147], v190 offset:35456
	s_waitcnt lgkmcnt(6)
	v_mfma_f32_32x32x16_bf16 v[16:31], v[136:139], v[140:143], v[16:31]
	ds_read_b64_tr_b16 v[136:137], v190 offset:32960
	ds_read_b64_tr_b16 v[138:139], v190 offset:35520
	s_waitcnt lgkmcnt(6)
	v_mfma_f32_32x32x16_bf16 v[112:127], v[156:159], v[132:135], v[112:127]
	s_waitcnt lgkmcnt(4)
	v_mfma_f32_32x32x16_bf16 v[80:95], v[152:155], v[132:135], v[80:95]
	s_waitcnt lgkmcnt(2)
	v_mfma_f32_32x32x16_bf16 v[48:63], v[144:147], v[132:135], v[48:63]
	s_waitcnt lgkmcnt(0)
	v_mfma_f32_32x32x16_bf16 v[16:31], v[136:139], v[132:135], v[16:31]
	s_cmp_gt_u32 s52, s25
	s_cbranch_scc0 .LBB0_1081

.LBB0_1079:
	s_bitcmp1_b32 s52, 0
	s_cselect_b32 s4, 0x9400, 0
	v_add_u32_e32 v128, s4, v250
	v_add_u32_e32 v129, v128, v251
	v_add_u32_e32 v130, v128, v252
	v_add_u32_e32 v131, v128, v253
	v_add_u32_e32 v128, v128, v236
	s_waitcnt vmcnt(7)
	ds_write_b128 v129, v[162:165]
	s_waitcnt vmcnt(6)
	ds_write_b128 v130, v[166:169] offset:17408
	s_waitcnt vmcnt(5)
	ds_write_b128 v131, v[170:173]
	s_waitcnt vmcnt(4)
	ds_write_b128 v128, v[174:177] offset:17408
	s_add_i32 s4, s52, 1
	s_cmp_ge_u32 s4, s36
	s_cbranch_scc1 .LBB0_1069
	s_branch .LBB0_1089

.LBB0_1081:
	s_bitcmp1_b32 s52, 0
	s_cselect_b32 s4, 0x9400, 0
	s_add_i32 s6, s4, 0
	s_add_i32 s4, s6, s37
	v_add3_u32 v190, s4, v180, v233
	ds_read_b128 v[144:147], v195 offset:4608
	ds_read_b128 v[148:151], v190
	ds_read_b128 v[196:199], v195 offset:4640
	ds_read_b128 v[152:155], v190 offset:32
	ds_read_b128 v[200:203], v195 offset:4672
	ds_read_b128 v[156:159], v190 offset:64
	ds_read_b128 v[204:207], v195 offset:4704
	ds_read_b128 v[208:211], v190 offset:96
	ds_read_b128 v[212:215], v190 offset:8704
	ds_read_b128 v[216:219], v190 offset:8736
	ds_read_b128 v[220:223], v190 offset:8768
	ds_read_b128 v[224:227], v190 offset:8800
	s_add_i32 s7, s53, 0xffffffbf
	s_mov_b64 s[4:5], -1
	s_cmp_le_u32 s7, s41
	s_waitcnt lgkmcnt(10)
	v_mfma_f32_32x32x16_bf16 v[128:143], v[148:151], v[144:147], 0
	s_waitcnt lgkmcnt(8)
	v_mfma_f32_32x32x16_bf16 v[128:143], v[152:155], v[196:199], v[128:143]
	s_waitcnt lgkmcnt(6)
	v_mfma_f32_32x32x16_bf16 v[128:143], v[156:159], v[200:203], v[128:143]
	s_waitcnt lgkmcnt(4)
	v_mfma_f32_32x32x16_bf16 v[128:143], v[208:211], v[204:207], v[128:143]
	s_waitcnt lgkmcnt(3)
	v_mfma_f32_32x32x16_bf16 v[144:159], v[212:215], v[144:147], 0
	s_waitcnt lgkmcnt(2)
	v_mfma_f32_32x32x16_bf16 v[144:159], v[216:219], v[196:199], v[144:159]
	s_waitcnt lgkmcnt(1)
	v_mfma_f32_32x32x16_bf16 v[144:159], v[220:223], v[200:203], v[144:159]
	s_waitcnt lgkmcnt(0)
	v_mfma_f32_32x32x16_bf16 v[144:159], v[224:227], v[204:207], v[144:159]
	s_cbranch_scc0 .LBB0_1083
	s_add_i32 s4, 0, 0x27a00
	v_mov_b32_e32 v190, s4
	ds_read_b32 v190, v190
	s_mov_b64 s[4:5], 0
	v_mbcnt_lo_u32_b32 v191, -1, 0
	v_mbcnt_hi_u32_b32 v191, -1, v191
	v_lshlrev_b32_e32 v191, 2, v191
	v_xor_b32_e32 v191, 0x80, v191
	v_max3_f32 v196, v128, v129, v130
	v_max3_f32 v196, v196, v131, v132
	v_max3_f32 v196, v196, v133, v134
	v_max3_f32 v196, v196, v135, v136
	v_max3_f32 v196, v196, v137, v138
	v_max3_f32 v196, v196, v139, v140
	v_max3_f32 v196, v196, v141, v142
	v_max3_f32 v196, v196, v143, v144
	v_max3_f32 v196, v196, v145, v146
	v_max3_f32 v196, v196, v147, v148
	v_max3_f32 v196, v196, v149, v150
	v_max3_f32 v196, v196, v151, v152
	v_max3_f32 v196, v196, v153, v154
	v_max3_f32 v196, v196, v155, v156
	v_max3_f32 v196, v196, v157, v158
	v_max_f32_e32 v196, v196, v159
	ds_bpermute_b32 v191, v191, v196
	s_waitcnt lgkmcnt(0)
	v_max_f32_e32 v196, v196, v191
	v_fma_f32 v196, v196, s28, v190
	v_add_f32_e32 v197, 0x41000000, v188
	v_cmp_gt_f32_e32 vcc, v196, v197
	s_cbranch_vccz .Lat_far_nors_2
	v_max_f32_e32 v197, v188, v196
	v_sub_f32_e32 v198, v188, v197
	v_exp_f32_e32 v198, v198
	v_mov_b32_e32 v188, v197
	v_mul_f32_e32 v237, v237, v198
	v_pk_mul_f32 v[110:111], v[110:111], v[198:199] op_sel_hi:[1,0]
	v_pk_mul_f32 v[108:109], v[108:109], v[198:199] op_sel_hi:[1,0]
	v_pk_mul_f32 v[106:107], v[106:107], v[198:199] op_sel_hi:[1,0]
	v_pk_mul_f32 v[104:105], v[104:105], v[198:199] op_sel_hi:[1,0]
	v_pk_mul_f32 v[102:103], v[102:103], v[198:199] op_sel_hi:[1,0]
	v_pk_mul_f32 v[100:101], v[100:101], v[198:199] op_sel_hi:[1,0]
	v_pk_mul_f32 v[98:99], v[98:99], v[198:199] op_sel_hi:[1,0]
	v_pk_mul_f32 v[96:97], v[96:97], v[198:199] op_sel_hi:[1,0]
	v_pk_mul_f32 v[78:79], v[78:79], v[198:199] op_sel_hi:[1,0]
	v_pk_mul_f32 v[76:77], v[76:77], v[198:199] op_sel_hi:[1,0]
	v_pk_mul_f32 v[74:75], v[74:75], v[198:199] op_sel_hi:[1,0]
	v_pk_mul_f32 v[72:73], v[72:73], v[198:199] op_sel_hi:[1,0]
	v_pk_mul_f32 v[70:71], v[70:71], v[198:199] op_sel_hi:[1,0]
	v_pk_mul_f32 v[68:69], v[68:69], v[198:199] op_sel_hi:[1,0]
	v_pk_mul_f32 v[66:67], v[66:67], v[198:199] op_sel_hi:[1,0]
	v_pk_mul_f32 v[64:65], v[64:65], v[198:199] op_sel_hi:[1,0]
	v_pk_mul_f32 v[46:47], v[46:47], v[198:199] op_sel_hi:[1,0]
	v_pk_mul_f32 v[44:45], v[44:45], v[198:199] op_sel_hi:[1,0]
	v_pk_mul_f32 v[42:43], v[42:43], v[198:199] op_sel_hi:[1,0]
	v_pk_mul_f32 v[40:41], v[40:41], v[198:199] op_sel_hi:[1,0]
	v_pk_mul_f32 v[38:39], v[38:39], v[198:199] op_sel_hi:[1,0]
	v_pk_mul_f32 v[36:37], v[36:37], v[198:199] op_sel_hi:[1,0]
	v_pk_mul_f32 v[34:35], v[34:35], v[198:199] op_sel_hi:[1,0]
	v_pk_mul_f32 v[32:33], v[32:33], v[198:199] op_sel_hi:[1,0]
	v_pk_mul_f32 v[14:15], v[14:15], v[198:199] op_sel_hi:[1,0]
	v_pk_mul_f32 v[12:13], v[12:13], v[198:199] op_sel_hi:[1,0]
	v_pk_mul_f32 v[10:11], v[10:11], v[198:199] op_sel_hi:[1,0]
	v_pk_mul_f32 v[8:9], v[8:9], v[198:199] op_sel_hi:[1,0]
	v_pk_mul_f32 v[6:7], v[6:7], v[198:199] op_sel_hi:[1,0]
	v_pk_mul_f32 v[4:5], v[4:5], v[198:199] op_sel_hi:[1,0]
	v_pk_mul_f32 v[2:3], v[2:3], v[198:199] op_sel_hi:[1,0]
	v_pk_mul_f32 v[0:1], v[0:1], v[198:199] op_sel_hi:[1,0]
.Lat_far_nors_2:
	v_sub_f32_e32 v191, v190, v188
	v_fma_f32 v226, v128, s28, v191
	v_fma_f32 v227, v129, s28, v191
	v_fma_f32 v224, v130, s28, v191
	v_fma_f32 v225, v131, s28, v191
	v_fma_f32 v222, v132, s28, v191
	v_fma_f32 v223, v133, s28, v191
	v_fma_f32 v220, v134, s28, v191
	v_fma_f32 v221, v135, s28, v191
	v_fma_f32 v218, v136, s28, v191
	v_fma_f32 v219, v137, s28, v191
	v_fma_f32 v216, v138, s28, v191
	v_fma_f32 v217, v139, s28, v191
	v_fma_f32 v214, v140, s28, v191
	v_fma_f32 v215, v141, s28, v191
	v_fma_f32 v212, v142, s28, v191
	v_fma_f32 v213, v143, s28, v191
	v_fma_f32 v210, v144, s28, v191
	v_fma_f32 v211, v145, s28, v191
	v_fma_f32 v208, v146, s28, v191
	v_fma_f32 v209, v147, s28, v191
	v_fma_f32 v206, v148, s28, v191
	v_fma_f32 v207, v149, s28, v191
	v_fma_f32 v204, v150, s28, v191
	v_fma_f32 v205, v151, s28, v191
	v_fma_f32 v202, v152, s28, v191
	v_fma_f32 v203, v153, s28, v191
	v_fma_f32 v200, v154, s28, v191
	v_fma_f32 v201, v155, s28, v191
	v_fma_f32 v198, v156, s28, v191
	v_fma_f32 v199, v157, s28, v191
	v_fma_f32 v196, v158, s28, v191
	v_fma_f32 v197, v159, s28, v191
	s_branch .Lat_tail_2

.LBB0_1087:
	v_sub_f32_e32 v226, v226, v188
	v_sub_f32_e32 v227, v227, v188
	v_sub_f32_e32 v224, v224, v188
	v_sub_f32_e32 v225, v225, v188
	v_sub_f32_e32 v222, v222, v188
	v_sub_f32_e32 v223, v223, v188
	v_sub_f32_e32 v220, v220, v188
	v_sub_f32_e32 v221, v221, v188
	v_sub_f32_e32 v218, v218, v188
	v_sub_f32_e32 v219, v219, v188
	v_sub_f32_e32 v216, v216, v188
	v_sub_f32_e32 v217, v217, v188
	v_sub_f32_e32 v214, v214, v188
	v_sub_f32_e32 v215, v215, v188
	v_sub_f32_e32 v212, v212, v188
	v_sub_f32_e32 v213, v213, v188
	v_sub_f32_e32 v210, v210, v188
	v_sub_f32_e32 v211, v211, v188
	v_sub_f32_e32 v208, v208, v188
	v_sub_f32_e32 v209, v209, v188
	v_sub_f32_e32 v206, v206, v188
	v_sub_f32_e32 v207, v207, v188
	v_sub_f32_e32 v204, v204, v188
	v_sub_f32_e32 v205, v205, v188
	v_sub_f32_e32 v202, v202, v188
	v_sub_f32_e32 v203, v203, v188
	v_sub_f32_e32 v200, v200, v188
	v_sub_f32_e32 v201, v201, v188
	v_sub_f32_e32 v198, v198, v188
	v_sub_f32_e32 v199, v199, v188
	v_sub_f32_e32 v196, v196, v188
	v_sub_f32_e32 v197, v197, v188
.Lat_tail_2:
	v_exp_f32_e32 v128, v226
	v_exp_f32_e32 v129, v227
	v_exp_f32_e32 v156, v224
	v_exp_f32_e32 v157, v225
	v_exp_f32_e32 v158, v222
	v_exp_f32_e32 v159, v223
	v_add_f32_e32 v130, v128, v156
	v_add_f32_e32 v131, v129, v157
	v_exp_f32_e32 v190, v220
	v_exp_f32_e32 v191, v221
	v_add_f32_e32 v130, v158, v130
	v_add_f32_e32 v131, v159, v131
	v_exp_f32_e32 v148, v218
	v_exp_f32_e32 v149, v219
	v_add_f32_e32 v130, v190, v130
	v_add_f32_e32 v131, v191, v131
	v_exp_f32_e32 v150, v216
	v_exp_f32_e32 v151, v217
	v_add_f32_e32 v130, v148, v130
	v_add_f32_e32 v131, v149, v131
	v_exp_f32_e32 v152, v214
	v_exp_f32_e32 v153, v215
	v_add_f32_e32 v130, v150, v130
	v_add_f32_e32 v131, v151, v131
	v_exp_f32_e32 v154, v212
	v_exp_f32_e32 v155, v213
	v_add_f32_e32 v130, v152, v130
	v_add_f32_e32 v131, v153, v131
	v_exp_f32_e32 v140, v210
	v_exp_f32_e32 v141, v211
	v_add_f32_e32 v130, v154, v130
	v_add_f32_e32 v131, v155, v131
	v_exp_f32_e32 v142, v208
	v_exp_f32_e32 v143, v209
	v_add_f32_e32 v130, v140, v130
	v_add_f32_e32 v131, v141, v131
	v_exp_f32_e32 v144, v206
	v_exp_f32_e32 v145, v207
	v_add_f32_e32 v130, v142, v130
	v_add_f32_e32 v131, v143, v131
	v_exp_f32_e32 v146, v204
	v_exp_f32_e32 v147, v205
	v_add_f32_e32 v130, v144, v130
	v_add_f32_e32 v131, v145, v131
	v_exp_f32_e32 v132, v202
	v_exp_f32_e32 v133, v203
	v_add_f32_e32 v130, v146, v130
	v_add_f32_e32 v131, v147, v131
	v_exp_f32_e32 v134, v200
	v_exp_f32_e32 v135, v201
	v_add_f32_e32 v130, v132, v130
	v_add_f32_e32 v131, v133, v131
	v_exp_f32_e32 v136, v198
	v_exp_f32_e32 v137, v199
	v_add_f32_e32 v130, v134, v130
	v_add_f32_e32 v131, v135, v131
	v_exp_f32_e32 v138, v196
	v_exp_f32_e32 v139, v197
	v_add_f32_e32 v130, v136, v130
	v_add_f32_e32 v131, v137, v131
	v_add_f32_e32 v130, v138, v130
	v_add_f32_e32 v131, v139, v131
	v_add_f32_e32 v130, v130, v131
	v_cvt_pk_bf16_f32 v128, v128, v129
	v_cvt_pk_bf16_f32 v129, v156, v157
	v_cvt_pk_bf16_f32 v131, v190, v191
	v_add3_u32 v190, s6, v235, v234
	v_add_f32_e32 v237, v237, v130
	v_cvt_pk_bf16_f32 v130, v158, v159
	ds_read_b64_tr_b16 v[156:157], v190 offset:17408
	ds_read_b64_tr_b16 v[158:159], v190 offset:19968
	v_cvt_pk_bf16_f32 v148, v148, v149
	v_cvt_pk_bf16_f32 v149, v150, v151
	v_cvt_pk_bf16_f32 v150, v152, v153
	v_cvt_pk_bf16_f32 v151, v154, v155
	ds_read_b64_tr_b16 v[152:153], v190 offset:17472
	ds_read_b64_tr_b16 v[154:155], v190 offset:20032
	v_cvt_pk_bf16_f32 v140, v140, v141
	v_cvt_pk_bf16_f32 v141, v142, v143
	v_cvt_pk_bf16_f32 v142, v144, v145
	v_cvt_pk_bf16_f32 v143, v146, v147
	ds_read_b64_tr_b16 v[144:145], v190 offset:17536
	ds_read_b64_tr_b16 v[146:147], v190 offset:20096
	v_cvt_pk_bf16_f32 v132, v132, v133
	v_cvt_pk_bf16_f32 v133, v134, v135
	v_cvt_pk_bf16_f32 v134, v136, v137
	v_cvt_pk_bf16_f32 v135, v138, v139
	ds_read_b64_tr_b16 v[136:137], v190 offset:17600
	ds_read_b64_tr_b16 v[138:139], v190 offset:20160
	s_waitcnt lgkmcnt(6)
	v_mfma_f32_32x32x16_bf16 v[96:111], v[156:159], v[128:131], v[96:111]
	ds_read_b64_tr_b16 v[156:157], v190 offset:22528
	ds_read_b64_tr_b16 v[158:159], v190 offset:25088
	s_waitcnt lgkmcnt(6)
	v_mfma_f32_32x32x16_bf16 v[64:79], v[152:155], v[128:131], v[64:79]
	ds_read_b64_tr_b16 v[152:153], v190 offset:22592
	ds_read_b64_tr_b16 v[154:155], v190 offset:25152
	s_waitcnt lgkmcnt(6)
	v_mfma_f32_32x32x16_bf16 v[32:47], v[144:147], v[128:131], v[32:47]
	ds_read_b64_tr_b16 v[144:145], v190 offset:22656
	ds_read_b64_tr_b16 v[146:147], v190 offset:25216
	s_waitcnt lgkmcnt(6)
	v_mfma_f32_32x32x16_bf16 v[0:15], v[136:139], v[128:131], v[0:15]
	ds_read_b64_tr_b16 v[136:137], v190 offset:22720
	ds_read_b64_tr_b16 v[138:139], v190 offset:25280
	s_waitcnt lgkmcnt(6)
	v_mfma_f32_32x32x16_bf16 v[96:111], v[156:159], v[148:151], v[96:111]
	ds_read_b64_tr_b16 v[156:157], v190 offset:27648
	ds_read_b64_tr_b16 v[158:159], v190 offset:30208
	s_waitcnt lgkmcnt(6)
	v_mfma_f32_32x32x16_bf16 v[64:79], v[152:155], v[148:151], v[64:79]
	ds_read_b64_tr_b16 v[152:153], v190 offset:27712
	ds_read_b64_tr_b16 v[154:155], v190 offset:30272
	s_waitcnt lgkmcnt(6)
	v_mfma_f32_32x32x16_bf16 v[32:47], v[144:147], v[148:151], v[32:47]
	ds_read_b64_tr_b16 v[144:145], v190 offset:27776
	ds_read_b64_tr_b16 v[146:147], v190 offset:30336
	s_waitcnt lgkmcnt(6)
	v_mfma_f32_32x32x16_bf16 v[0:15], v[136:139], v[148:151], v[0:15]
	ds_read_b64_tr_b16 v[136:137], v190 offset:27840
	ds_read_b64_tr_b16 v[138:139], v190 offset:30400
	s_waitcnt lgkmcnt(6)
	v_mfma_f32_32x32x16_bf16 v[96:111], v[156:159], v[140:143], v[96:111]
	ds_read_b64_tr_b16 v[156:157], v190 offset:32768
	ds_read_b64_tr_b16 v[158:159], v190 offset:35328
	s_waitcnt lgkmcnt(6)
	v_mfma_f32_32x32x16_bf16 v[64:79], v[152:155], v[140:143], v[64:79]
	ds_read_b64_tr_b16 v[152:153], v190 offset:32832
	ds_read_b64_tr_b16 v[154:155], v190 offset:35392
	s_waitcnt lgkmcnt(6)
	v_mfma_f32_32x32x16_bf16 v[32:47], v[144:147], v[140:143], v[32:47]
	ds_read_b64_tr_b16 v[144:145], v190 offset:32896
	ds_read_b64_tr_b16 v[146:147], v190 offset:35456
	s_waitcnt lgkmcnt(6)
	v_mfma_f32_32x32x16_bf16 v[0:15], v[136:139], v[140:143], v[0:15]
	ds_read_b64_tr_b16 v[136:137], v190 offset:32960
	ds_read_b64_tr_b16 v[138:139], v190 offset:35520
	s_waitcnt lgkmcnt(6)
	v_mfma_f32_32x32x16_bf16 v[96:111], v[156:159], v[132:135], v[96:111]
	s_waitcnt lgkmcnt(4)
	v_mfma_f32_32x32x16_bf16 v[64:79], v[152:155], v[132:135], v[64:79]
	s_waitcnt lgkmcnt(2)
	v_mfma_f32_32x32x16_bf16 v[32:47], v[144:147], v[132:135], v[32:47]
	s_waitcnt lgkmcnt(0)
	v_mfma_f32_32x32x16_bf16 v[0:15], v[136:139], v[132:135], v[0:15]
	s_add_i32 s52, s52, 1
	s_cmp_ge_u32 s52, s36
	s_cbranch_scc0 .LBB0_1079

.LBB0_1089:
	s_add_i32 s92, s23, s53
	s_mov_b64 s[6:7], 0x70000
	v_lshl_add_u64 v[128:129], s[92:93], 0, v[184:185]
	v_mad_u64_u32 v[130:131], s[4:5], v128, s3, v[182:183]
	v_mad_i32_i24 v129, v129, s3, v131
	v_add_co_u32_e32 v128, vcc, 0x1000, v130
	s_nop 1
	v_addc_co_u32_e32 v129, vcc, 0, v129, vcc
	global_load_dwordx4 v[162:165], v[128:129], off offset:1024
	global_load_dwordx4 v[166:169], v[128:129], off offset:2048
	v_lshl_add_u64 v[132:133], v[128:129], 0, s[6:7]
	v_lshl_add_u64 v[128:129], s[92:93], 0, v[186:187]
	v_mad_u64_u32 v[130:131], s[4:5], v128, s3, v[182:183]
	v_mad_i32_i24 v129, v129, s3, v131
	v_add_co_u32_e32 v128, vcc, 0x1000, v130
	s_nop 1
	v_addc_co_u32_e32 v129, vcc, 0, v129, vcc
	global_load_dwordx4 v[170:173], v[128:129], off offset:1024
	global_load_dwordx4 v[174:177], v[128:129], off offset:2048
	v_lshl_add_u64 v[134:135], v[128:129], 0, s[6:7]
	global_load_dword v239, v[132:133], off offset:1024
	global_load_dword v239, v[132:133], off offset:2048
	global_load_dword v239, v[134:135], off offset:1024
	global_load_dword v239, v[134:135], off offset:2048
	s_branch .LBB0_1069

.LBB0_1211:
.LBB0_1212:
	s_add_i32 s19, 0, 0x10000
	s_add_i32 s36, 0, 0x14000
	v_add_u32_e32 v12, s19, v203
	v_add_u32_e32 v28, s36, v203
	ds_read_b128 v[0:3], v12
	ds_read_b128 v[4:7], v12 offset:1024
	ds_read_b128 v[8:11], v12 offset:2048
	ds_read_b128 v[12:15], v12 offset:3072
	ds_read_b128 v[16:19], v28
	ds_read_b128 v[20:23], v28 offset:1024
	ds_read_b128 v[24:27], v28 offset:2048
	ds_read_b128 v[28:31], v28 offset:3072
	s_add_u32 s4, s40, 0x40080
	s_addc_u32 s5, s41, 0
	v_lshl_add_u64 v[64:65], s[4:5], 0, v[130:131]
	s_add_i32 m0, s23, 0xc000
	ds_read_b128 v[32:35], v204
	ds_read_b128 v[36:39], v204 offset:1024
	ds_read_b128 v[40:43], v204 offset:2048
	ds_read_b128 v[44:47], v204 offset:3072
	ds_read_b128 v[48:51], v204 offset:4096
	ds_read_b128 v[52:55], v204 offset:5120
	ds_read_b128 v[56:59], v204 offset:6144
	ds_read_b128 v[60:63], v204 offset:7168
	global_load_lds_dwordx4 v[64:65], off
	v_lshl_add_u64 v[64:65], s[4:5], 0, v[132:133]
	s_add_i32 m0, s23, 0xe000
	s_nop 0
	global_load_lds_dwordx4 v[64:65], off
	s_waitcnt vmcnt(40) lgkmcnt(0)
	s_setprio 1
	s_barrier
	v_mfma_f32_16x16x32_bf16 v[64:67], v[0:3], v[32:35], 0
	v_mfma_f32_16x16x32_bf16 v[68:71], v[8:11], v[32:35], 0
	v_mfma_f32_16x16x32_bf16 v[72:75], v[0:3], v[40:43], 0
	v_mfma_f32_16x16x32_bf16 v[76:79], v[8:11], v[40:43], 0
	v_mfma_f32_16x16x32_bf16 v[80:83], v[0:3], v[48:51], 0
	v_mfma_f32_16x16x32_bf16 v[84:87], v[8:11], v[48:51], 0
	v_mfma_f32_16x16x32_bf16 v[88:91], v[0:3], v[56:59], 0
	v_mfma_f32_16x16x32_bf16 v[92:95], v[8:11], v[56:59], 0
	v_mfma_f32_16x16x32_bf16 v[64:67], v[4:7], v[36:39], v[64:67]
	v_mfma_f32_16x16x32_bf16 v[68:71], v[12:15], v[36:39], v[68:71]
	v_mfma_f32_16x16x32_bf16 v[72:75], v[4:7], v[44:47], v[72:75]
	v_mfma_f32_16x16x32_bf16 v[76:79], v[12:15], v[44:47], v[76:79]
	v_mfma_f32_16x16x32_bf16 v[80:83], v[4:7], v[52:55], v[80:83]
	v_mfma_f32_16x16x32_bf16 v[84:87], v[12:15], v[52:55], v[84:87]
	v_mfma_f32_16x16x32_bf16 v[88:91], v[4:7], v[60:63], v[88:91]
	v_mfma_f32_16x16x32_bf16 v[92:95], v[12:15], v[60:63], v[92:95]
	s_setprio 0
	s_setprio 1
	v_mfma_f32_16x16x32_bf16 v[96:99], v[16:19], v[32:35], 0
	v_mfma_f32_16x16x32_bf16 v[32:35], v[24:27], v[32:35], 0
	v_mfma_f32_16x16x32_bf16 v[96:99], v[20:23], v[36:39], v[96:99]
	v_mfma_f32_16x16x32_bf16 v[32:35], v[28:31], v[36:39], v[32:35]
	v_mfma_f32_16x16x32_bf16 v[36:39], v[16:19], v[40:43], 0
	v_mfma_f32_16x16x32_bf16 v[40:43], v[24:27], v[40:43], 0
	v_mfma_f32_16x16x32_bf16 v[36:39], v[20:23], v[44:47], v[36:39]
	v_mfma_f32_16x16x32_bf16 v[40:43], v[28:31], v[44:47], v[40:43]
	v_mfma_f32_16x16x32_bf16 v[44:47], v[16:19], v[48:51], 0
	v_mfma_f32_16x16x32_bf16 v[48:51], v[24:27], v[48:51], 0
	v_mfma_f32_16x16x32_bf16 v[100:103], v[28:31], v[52:55], v[48:51]
	v_mfma_f32_16x16x32_bf16 v[48:51], v[16:19], v[56:59], 0
	v_mfma_f32_16x16x32_bf16 v[104:107], v[20:23], v[60:63], v[48:51]
	v_mfma_f32_16x16x32_bf16 v[48:51], v[24:27], v[56:59], 0
	v_mfma_f32_16x16x32_bf16 v[44:47], v[20:23], v[52:55], v[44:47]
	v_mfma_f32_16x16x32_bf16 v[108:111], v[28:31], v[60:63], v[48:51]
	s_barrier
	s_setprio 0
	v_lshl_add_u64 v[158:159], s[24:25], 0, v[128:129]
	s_add_i32 s4, s19, s74
	v_lshl_add_u64 v[134:135], v[158:159], 0, s[16:17]
	s_mov_b32 m0, s4
	ds_read_b128 v[48:51], v204 offset:16384
	ds_read_b128 v[52:55], v204 offset:17408
	ds_read_b128 v[56:59], v204 offset:18432
	ds_read_b128 v[60:63], v204 offset:19456
	ds_read_b128 v[112:115], v204 offset:20480
	ds_read_b128 v[116:119], v204 offset:21504
	ds_read_b128 v[120:123], v204 offset:22528
	ds_read_b128 v[124:127], v204 offset:23552
	global_load_lds_dwordx4 v[134:135], off
	s_add_i32 m0, s4, 0x2000
	v_lshl_add_u64 v[188:189], s[24:25], 0, v[160:161]
	s_add_u32 s4, s24, 0x40100
	v_lshl_add_u64 v[134:135], v[188:189], 0, s[16:17]
	s_addc_u32 s5, s25, 0
	s_add_i32 s19, s36, s74
	global_load_lds_dwordx4 v[134:135], off
	v_lshl_add_u64 v[134:135], s[4:5], 0, v[128:129]
	s_mov_b32 m0, s19
	v_lshl_add_u64 v[190:191], s[40:41], 0, v[130:131]
	global_load_lds_dwordx4 v[134:135], off
	v_lshl_add_u64 v[134:135], s[4:5], 0, v[160:161]
	s_add_i32 m0, s19, 0x2000
	v_mov_b32_e32 v202, v250
	global_load_lds_dwordx4 v[134:135], off
	v_lshl_add_u64 v[134:135], v[190:191], 0, s[16:17]
	s_mov_b32 m0, s23
	v_lshl_add_u64 v[250:251], s[40:41], 0, v[132:133]
	global_load_lds_dwordx4 v[134:135], off
	v_lshl_add_u64 v[134:135], v[250:251], 0, s[16:17]
	s_mov_b32 m0, s77
	s_nop 0
	global_load_lds_dwordx4 v[134:135], off
	s_waitcnt vmcnt(40) lgkmcnt(0)
	s_setprio 1
	s_barrier
	v_mfma_f32_16x16x32_bf16 v[134:137], v[0:3], v[48:51], 0
	v_mfma_f32_16x16x32_bf16 v[142:145], v[0:3], v[56:59], 0
	v_mfma_f32_16x16x32_bf16 v[150:153], v[0:3], v[112:115], 0
	v_mfma_f32_16x16x32_bf16 v[0:3], v[0:3], v[120:123], 0
	v_mfma_f32_16x16x32_bf16 v[134:137], v[4:7], v[52:55], v[134:137]
	v_mfma_f32_16x16x32_bf16 v[142:145], v[4:7], v[60:63], v[142:145]
	v_mfma_f32_16x16x32_bf16 v[150:153], v[4:7], v[116:119], v[150:153]
	v_mfma_f32_16x16x32_bf16 v[0:3], v[4:7], v[124:127], v[0:3]
	v_mfma_f32_16x16x32_bf16 v[4:7], v[8:11], v[120:123], 0
	v_mfma_f32_16x16x32_bf16 v[138:141], v[8:11], v[48:51], 0
	v_mfma_f32_16x16x32_bf16 v[146:149], v[8:11], v[56:59], 0
	v_mfma_f32_16x16x32_bf16 v[154:157], v[8:11], v[112:115], 0
	v_mfma_f32_16x16x32_bf16 v[4:7], v[12:15], v[124:127], v[4:7]
	v_mfma_f32_16x16x32_bf16 v[138:141], v[12:15], v[52:55], v[138:141]
	v_mfma_f32_16x16x32_bf16 v[146:149], v[12:15], v[60:63], v[146:149]
	v_mfma_f32_16x16x32_bf16 v[154:157], v[12:15], v[116:119], v[154:157]
	s_setprio 0
	s_setprio 1
	v_mfma_f32_16x16x32_bf16 v[8:11], v[16:19], v[48:51], 0
	v_mfma_f32_16x16x32_bf16 v[12:15], v[24:27], v[48:51], 0
	v_mfma_f32_16x16x32_bf16 v[48:51], v[16:19], v[56:59], 0
	v_mfma_f32_16x16x32_bf16 v[162:165], v[20:23], v[60:63], v[48:51]
	v_mfma_f32_16x16x32_bf16 v[48:51], v[24:27], v[56:59], 0
	v_mfma_f32_16x16x32_bf16 v[166:169], v[28:31], v[60:63], v[48:51]
	v_mfma_f32_16x16x32_bf16 v[48:51], v[16:19], v[112:115], 0
	v_mfma_f32_16x16x32_bf16 v[16:19], v[16:19], v[120:123], 0
	v_mfma_f32_16x16x32_bf16 v[8:11], v[20:23], v[52:55], v[8:11]
	v_mfma_f32_16x16x32_bf16 v[12:15], v[28:31], v[52:55], v[12:15]
	v_mfma_f32_16x16x32_bf16 v[170:173], v[20:23], v[116:119], v[48:51]
	v_mfma_f32_16x16x32_bf16 v[48:51], v[24:27], v[112:115], 0
	v_mfma_f32_16x16x32_bf16 v[180:183], v[20:23], v[124:127], v[16:19]
	v_mfma_f32_16x16x32_bf16 v[16:19], v[24:27], v[120:123], 0
	v_mfma_f32_16x16x32_bf16 v[174:177], v[28:31], v[116:119], v[48:51]
	v_mfma_f32_16x16x32_bf16 v[184:187], v[28:31], v[124:127], v[16:19]
	s_barrier
	s_setprio 0
	s_add_i32 s19, 0, 0x18000
	v_add_u32_e32 v28, s19, v203
	s_add_i32 s36, 0, 0x1c000
	s_nop 0
	ds_read_b128 v[16:19], v28
	ds_read_b128 v[20:23], v28 offset:1024
	ds_read_b128 v[24:27], v28 offset:2048
	ds_read_b128 v[194:197], v28 offset:3072
	v_add_u32_e32 v28, s36, v203
	ds_read_b128 v[198:201], v28
	ds_read_b128 v[206:209], v28 offset:1024
	ds_read_b128 v[210:213], v28 offset:2048
	ds_read_b128 v[214:217], v28 offset:3072
	s_add_u32 s4, s40, 0x40100
	s_addc_u32 s5, s41, 0
	s_mov_b32 m0, s78
	v_lshl_add_u64 v[48:49], s[4:5], 0, v[130:131]
	ds_read_b128 v[28:31], v204 offset:32768
	ds_read_b128 v[52:55], v204 offset:33792
	ds_read_b128 v[218:221], v204 offset:34816
	ds_read_b128 v[222:225], v204 offset:35840
	ds_read_b128 v[226:229], v204 offset:36864
	ds_read_b128 v[230:233], v204 offset:37888
	ds_read_b128 v[234:237], v204 offset:38912
	ds_read_b128 v[238:241], v204 offset:39936
	global_load_lds_dwordx4 v[48:49], off
	v_lshl_add_u64 v[48:49], s[4:5], 0, v[132:133]
	s_mov_b32 m0, s79
	s_nop 0
	global_load_lds_dwordx4 v[48:49], off
	s_waitcnt vmcnt(8) lgkmcnt(0)
	s_setprio 1
	s_barrier
	v_mfma_f32_16x16x32_bf16 v[56:59], v[16:19], v[218:221], v[72:75]
	v_mfma_f32_16x16x32_bf16 v[48:51], v[16:19], v[28:31], v[64:67]
	v_mfma_f32_16x16x32_bf16 v[120:123], v[20:23], v[222:225], v[56:59]
	v_mfma_f32_16x16x32_bf16 v[56:59], v[24:27], v[218:221], v[76:79]
	v_mfma_f32_16x16x32_bf16 v[124:127], v[20:23], v[52:55], v[48:51]
	v_mfma_f32_16x16x32_bf16 v[48:51], v[24:27], v[28:31], v[68:71]
	v_mfma_f32_16x16x32_bf16 v[68:71], v[194:197], v[222:225], v[56:59]
	v_mfma_f32_16x16x32_bf16 v[56:59], v[16:19], v[226:229], v[80:83]
	v_mfma_f32_16x16x32_bf16 v[116:119], v[20:23], v[230:233], v[56:59]
	v_mfma_f32_16x16x32_bf16 v[56:59], v[24:27], v[226:229], v[84:87]
	v_mfma_f32_16x16x32_bf16 v[72:75], v[194:197], v[230:233], v[56:59]
	v_mfma_f32_16x16x32_bf16 v[56:59], v[16:19], v[234:237], v[88:91]
	v_mfma_f32_16x16x32_bf16 v[112:115], v[20:23], v[238:241], v[56:59]
	v_mfma_f32_16x16x32_bf16 v[56:59], v[24:27], v[234:237], v[92:95]
	v_mfma_f32_16x16x32_bf16 v[48:51], v[194:197], v[52:55], v[48:51]
	v_mfma_f32_16x16x32_bf16 v[92:95], v[194:197], v[238:241], v[56:59]
	s_setprio 0
	s_setprio 1
	v_mfma_f32_16x16x32_bf16 v[56:59], v[198:201], v[28:31], v[96:99]
	v_mfma_f32_16x16x32_bf16 v[28:31], v[210:213], v[28:31], v[32:35]
	v_mfma_f32_16x16x32_bf16 v[60:63], v[214:217], v[52:55], v[28:31]
	v_mfma_f32_16x16x32_bf16 v[28:31], v[198:201], v[218:221], v[36:39]
	v_mfma_f32_16x16x32_bf16 v[64:67], v[206:209], v[52:55], v[56:59]
	v_mfma_f32_16x16x32_bf16 v[56:59], v[206:209], v[222:225], v[28:31]
	v_mfma_f32_16x16x32_bf16 v[28:31], v[210:213], v[218:221], v[40:43]
	v_mfma_f32_16x16x32_bf16 v[52:55], v[214:217], v[222:225], v[28:31]
	v_mfma_f32_16x16x32_bf16 v[28:31], v[198:201], v[226:229], v[44:47]
	v_mfma_f32_16x16x32_bf16 v[44:47], v[206:209], v[230:233], v[28:31]
	v_mfma_f32_16x16x32_bf16 v[28:31], v[210:213], v[226:229], v[100:103]
	v_mfma_f32_16x16x32_bf16 v[40:43], v[214:217], v[230:233], v[28:31]
	v_mfma_f32_16x16x32_bf16 v[28:31], v[198:201], v[234:237], v[104:107]
	v_mfma_f32_16x16x32_bf16 v[36:39], v[206:209], v[238:241], v[28:31]
	v_mfma_f32_16x16x32_bf16 v[28:31], v[210:213], v[234:237], v[108:111]
	v_mfma_f32_16x16x32_bf16 v[28:31], v[214:217], v[238:241], v[28:31]
	s_barrier
	s_setprio 0
	s_mov_b64 s[66:67], 0x180
	s_add_i32 s4, s19, s74
	v_lshl_add_u64 v[32:33], v[158:159], 0, s[66:67]
	s_mov_b32 m0, s4
	ds_read_b128 v[218:221], v204 offset:49152
	ds_read_b128 v[222:225], v204 offset:50176
	ds_read_b128 v[226:229], v204 offset:51200
	ds_read_b128 v[230:233], v204 offset:52224
	ds_read_b128 v[234:237], v204 offset:53248
	ds_read_b128 v[238:241], v204 offset:54272
	ds_read_b128 v[242:245], v204 offset:55296
	ds_read_b128 v[246:249], v204 offset:56320
	global_load_lds_dwordx4 v[32:33], off
	s_add_i32 m0, s4, 0x2000
	s_add_u32 s4, s24, 0x40180
	v_lshl_add_u64 v[32:33], v[188:189], 0, s[66:67]
	s_addc_u32 s5, s25, 0
	s_add_i32 s19, s36, s74
	global_load_lds_dwordx4 v[32:33], off
	v_lshl_add_u64 v[32:33], s[4:5], 0, v[128:129]
	s_mov_b32 m0, s19
	s_nop 0
	global_load_lds_dwordx4 v[32:33], off
	v_lshl_add_u64 v[32:33], s[4:5], 0, v[160:161]
	s_add_i32 m0, s19, 0x2000
	s_nop 0
	global_load_lds_dwordx4 v[32:33], off
	v_lshl_add_u64 v[32:33], v[190:191], 0, s[66:67]
	s_mov_b32 m0, s83
	s_nop 0
	global_load_lds_dwordx4 v[32:33], off
	v_lshl_add_u64 v[32:33], v[250:251], 0, s[66:67]
	s_mov_b32 m0, s84
	v_mov_b32_e32 v250, v202
	global_load_lds_dwordx4 v[32:33], off
	s_waitcnt vmcnt(8) lgkmcnt(0)
	s_setprio 1
	s_barrier
	v_mfma_f32_16x16x32_bf16 v[32:35], v[16:19], v[218:221], v[134:137]
	v_mfma_f32_16x16x32_bf16 v[108:111], v[20:23], v[222:225], v[32:35]
	v_mfma_f32_16x16x32_bf16 v[32:35], v[24:27], v[218:221], v[138:141]
	v_mfma_f32_16x16x32_bf16 v[104:107], v[194:197], v[222:225], v[32:35]
	v_mfma_f32_16x16x32_bf16 v[32:35], v[16:19], v[226:229], v[142:145]
	v_mfma_f32_16x16x32_bf16 v[100:103], v[20:23], v[230:233], v[32:35]
	v_mfma_f32_16x16x32_bf16 v[32:35], v[24:27], v[226:229], v[146:149]
	v_mfma_f32_16x16x32_bf16 v[96:99], v[194:197], v[230:233], v[32:35]
	v_mfma_f32_16x16x32_bf16 v[32:35], v[16:19], v[234:237], v[150:153]
	v_mfma_f32_16x16x32_bf16 v[0:3], v[16:19], v[242:245], v[0:3]
	v_mfma_f32_16x16x32_bf16 v[80:83], v[20:23], v[238:241], v[32:35]
	v_mfma_f32_16x16x32_bf16 v[32:35], v[24:27], v[234:237], v[154:157]
	v_mfma_f32_16x16x32_bf16 v[88:91], v[20:23], v[246:249], v[0:3]
	v_mfma_f32_16x16x32_bf16 v[0:3], v[24:27], v[242:245], v[4:7]
	v_mfma_f32_16x16x32_bf16 v[76:79], v[194:197], v[238:241], v[32:35]
	v_mfma_f32_16x16x32_bf16 v[84:87], v[194:197], v[246:249], v[0:3]
	s_setprio 0
	s_setprio 1
	v_mfma_f32_16x16x32_bf16 v[0:3], v[198:201], v[218:221], v[8:11]
	v_mfma_f32_16x16x32_bf16 v[32:35], v[206:209], v[222:225], v[0:3]
	v_mfma_f32_16x16x32_bf16 v[0:3], v[210:213], v[218:221], v[12:15]
	v_mfma_f32_16x16x32_bf16 v[24:27], v[214:217], v[222:225], v[0:3]
	v_mfma_f32_16x16x32_bf16 v[0:3], v[198:201], v[226:229], v[162:165]
	v_mfma_f32_16x16x32_bf16 v[20:23], v[206:209], v[230:233], v[0:3]
	v_mfma_f32_16x16x32_bf16 v[0:3], v[210:213], v[226:229], v[166:169]
	v_mfma_f32_16x16x32_bf16 v[16:19], v[214:217], v[230:233], v[0:3]
	v_mfma_f32_16x16x32_bf16 v[0:3], v[198:201], v[234:237], v[170:173]
	v_mfma_f32_16x16x32_bf16 v[12:15], v[206:209], v[238:241], v[0:3]
	v_mfma_f32_16x16x32_bf16 v[0:3], v[210:213], v[234:237], v[174:177]
	v_mfma_f32_16x16x32_bf16 v[8:11], v[214:217], v[238:241], v[0:3]
	v_mov_b32_e32 v241, 0x7f
	v_mfma_f32_16x16x32_bf16 v[0:3], v[198:201], v[242:245], v[180:183]
	v_mfma_f32_16x16x32_bf16 v[4:7], v[206:209], v[246:249], v[0:3]
	v_mfma_f32_16x16x32_bf16 v[0:3], v[210:213], v[242:245], v[184:187]
	v_mov_b32_e32 v245, 0x7d
	v_mov_b32_e32 v244, 0x7e
	v_mov_b64_e32 v[242:243], 0x400
	v_mfma_f32_16x16x32_bf16 v[0:3], v[214:217], v[246:249], v[0:3]
	v_mov_b32_e32 v247, 0x77
	v_mov_b32_e32 v246, 0x7c
	v_mov_b32_e32 v248, 0x260
	s_setprio 0
	s_barrier
	s_mov_b32 s4, 2

.LBB0_1214:
	s_add_u32 s24, s90, s92
	s_addc_u32 s25, s91, 0
	s_add_u32 s80, vcc_lo, s92
	s_addc_u32 s94, vcc_hi, 0
	s_add_i32 s95, 0, 0x10000
	s_cmp_eq_u32 s92, s4
	s_cselect_b32 s41, s19, s25
	s_cselect_b32 s40, s36, s24
	s_cselect_b32 s25, s37, s94
	s_cselect_b32 s24, s63, s80
	s_add_i32 s80, 0, 0x14000
	v_add_u32_e32 v150, s95, v203
	v_add_u32_e32 v158, s80, v203
	ds_read_b128 v[138:141], v150
	ds_read_b128 v[142:145], v150 offset:1024
	ds_read_b128 v[146:149], v150 offset:2048
	ds_read_b128 v[150:153], v150 offset:3072
	ds_read_b128 v[154:157], v158
	ds_read_b128 v[162:165], v158 offset:1024
	ds_read_b128 v[166:169], v158 offset:2048
	ds_read_b128 v[170:173], v158 offset:3072
	v_lshl_add_u64 v[158:159], v[134:135], 0, s[92:93]
	s_add_i32 m0, s23, 0xc000
	ds_read_b128 v[174:177], v204
	ds_read_b128 v[180:183], v204 offset:1024
	ds_read_b128 v[184:187], v204 offset:2048
	ds_read_b128 v[194:197], v204 offset:3072
	ds_read_b128 v[198:201], v204 offset:4096
	ds_read_b128 v[206:209], v204 offset:5120
	ds_read_b128 v[210:213], v204 offset:6144
	ds_read_b128 v[214:217], v204 offset:7168
	global_load_lds_dwordx4 v[158:159], off
	v_lshl_add_u64 v[158:159], v[136:137], 0, s[92:93]
	s_add_i32 m0, s23, 0xe000
	s_nop 0
	global_load_lds_dwordx4 v[158:159], off
	s_waitcnt vmcnt(8) lgkmcnt(0)
	s_setprio 1
	s_barrier
	v_mfma_f32_16x16x32_bf16 v[124:127], v[138:141], v[174:177], v[124:127]
	v_mfma_f32_16x16x32_bf16 v[48:51], v[146:149], v[174:177], v[48:51]
	v_mfma_f32_16x16x32_bf16 v[120:123], v[138:141], v[184:187], v[120:123]
	v_mfma_f32_16x16x32_bf16 v[68:71], v[146:149], v[184:187], v[68:71]
	v_mfma_f32_16x16x32_bf16 v[116:119], v[138:141], v[198:201], v[116:119]
	v_mfma_f32_16x16x32_bf16 v[72:75], v[146:149], v[198:201], v[72:75]
	v_mfma_f32_16x16x32_bf16 v[112:115], v[138:141], v[210:213], v[112:115]
	v_mfma_f32_16x16x32_bf16 v[92:95], v[146:149], v[210:213], v[92:95]
	v_mfma_f32_16x16x32_bf16 v[124:127], v[142:145], v[180:183], v[124:127]
	v_mfma_f32_16x16x32_bf16 v[48:51], v[150:153], v[180:183], v[48:51]
	v_mfma_f32_16x16x32_bf16 v[120:123], v[142:145], v[194:197], v[120:123]
	v_mfma_f32_16x16x32_bf16 v[68:71], v[150:153], v[194:197], v[68:71]
	v_mfma_f32_16x16x32_bf16 v[116:119], v[142:145], v[206:209], v[116:119]
	v_mfma_f32_16x16x32_bf16 v[72:75], v[150:153], v[206:209], v[72:75]
	v_mfma_f32_16x16x32_bf16 v[112:115], v[142:145], v[214:217], v[112:115]
	v_mfma_f32_16x16x32_bf16 v[92:95], v[150:153], v[214:217], v[92:95]
	s_setprio 0
	s_setprio 1
	v_mfma_f32_16x16x32_bf16 v[64:67], v[154:157], v[174:177], v[64:67]
	v_mfma_f32_16x16x32_bf16 v[60:63], v[166:169], v[174:177], v[60:63]
	v_mfma_f32_16x16x32_bf16 v[56:59], v[154:157], v[184:187], v[56:59]
	v_mfma_f32_16x16x32_bf16 v[52:55], v[166:169], v[184:187], v[52:55]
	v_mfma_f32_16x16x32_bf16 v[44:47], v[154:157], v[198:201], v[44:47]
	v_mfma_f32_16x16x32_bf16 v[40:43], v[166:169], v[198:201], v[40:43]
	v_mfma_f32_16x16x32_bf16 v[36:39], v[154:157], v[210:213], v[36:39]
	v_mfma_f32_16x16x32_bf16 v[28:31], v[166:169], v[210:213], v[28:31]
	v_mfma_f32_16x16x32_bf16 v[64:67], v[162:165], v[180:183], v[64:67]
	v_mfma_f32_16x16x32_bf16 v[60:63], v[170:173], v[180:183], v[60:63]
	v_mfma_f32_16x16x32_bf16 v[56:59], v[162:165], v[194:197], v[56:59]
	v_mfma_f32_16x16x32_bf16 v[52:55], v[170:173], v[194:197], v[52:55]
	v_mfma_f32_16x16x32_bf16 v[44:47], v[162:165], v[206:209], v[44:47]
	v_mfma_f32_16x16x32_bf16 v[40:43], v[170:173], v[206:209], v[40:43]
	v_mfma_f32_16x16x32_bf16 v[36:39], v[162:165], v[214:217], v[36:39]
	v_mfma_f32_16x16x32_bf16 v[28:31], v[170:173], v[214:217], v[28:31]
	s_barrier
	s_setprio 0
	s_add_i32 s94, s95, s74
	v_lshl_add_u64 v[158:159], s[24:25], 0, v[128:129]
	s_mov_b32 m0, s94
	ds_read_b128 v[174:177], v204 offset:16384
	ds_read_b128 v[180:183], v204 offset:17408
	ds_read_b128 v[184:187], v204 offset:18432
	ds_read_b128 v[194:197], v204 offset:19456
	ds_read_b128 v[198:201], v204 offset:20480
	ds_read_b128 v[206:209], v204 offset:21504
	ds_read_b128 v[210:213], v204 offset:22528
	ds_read_b128 v[214:217], v204 offset:23552
	global_load_lds_dwordx4 v[158:159], off
	s_add_i32 m0, s94, 0x2000
	s_add_u32 s94, s24, 0x40000
	v_lshl_add_u64 v[188:189], s[24:25], 0, v[160:161]
	s_addc_u32 s95, s25, 0
	s_add_i32 s80, s80, s74
	global_load_lds_dwordx4 v[188:189], off
	v_lshl_add_u64 v[190:191], s[94:95], 0, v[128:129]
	s_mov_b32 m0, s80
	v_lshl_add_u64 v[218:219], s[40:41], 0, v[132:133]
	global_load_lds_dwordx4 v[190:191], off
	v_lshl_add_u64 v[190:191], s[94:95], 0, v[160:161]
	s_add_i32 m0, s80, 0x2000
	s_nop 0
	global_load_lds_dwordx4 v[190:191], off
	v_lshl_add_u64 v[190:191], s[40:41], 0, v[130:131]
	s_mov_b32 m0, s23
	s_nop 0
	global_load_lds_dwordx4 v[190:191], off
	s_mov_b32 m0, s77
	s_nop 0
	global_load_lds_dwordx4 v[218:219], off
	s_waitcnt vmcnt(8) lgkmcnt(0)
	s_setprio 1
	s_barrier
	v_mfma_f32_16x16x32_bf16 v[108:111], v[138:141], v[174:177], v[108:111]
	v_mfma_f32_16x16x32_bf16 v[104:107], v[146:149], v[174:177], v[104:107]
	v_mfma_f32_16x16x32_bf16 v[100:103], v[138:141], v[184:187], v[100:103]
	v_mfma_f32_16x16x32_bf16 v[96:99], v[146:149], v[184:187], v[96:99]
	v_mfma_f32_16x16x32_bf16 v[80:83], v[138:141], v[198:201], v[80:83]
	v_mfma_f32_16x16x32_bf16 v[76:79], v[146:149], v[198:201], v[76:79]
	v_mfma_f32_16x16x32_bf16 v[88:91], v[138:141], v[210:213], v[88:91]
	v_mfma_f32_16x16x32_bf16 v[84:87], v[146:149], v[210:213], v[84:87]
	v_mfma_f32_16x16x32_bf16 v[108:111], v[142:145], v[180:183], v[108:111]
	v_mfma_f32_16x16x32_bf16 v[104:107], v[150:153], v[180:183], v[104:107]
	v_mfma_f32_16x16x32_bf16 v[100:103], v[142:145], v[194:197], v[100:103]
	v_mfma_f32_16x16x32_bf16 v[96:99], v[150:153], v[194:197], v[96:99]
	v_mfma_f32_16x16x32_bf16 v[80:83], v[142:145], v[206:209], v[80:83]
	v_mfma_f32_16x16x32_bf16 v[76:79], v[150:153], v[206:209], v[76:79]
	v_mfma_f32_16x16x32_bf16 v[88:91], v[142:145], v[214:217], v[88:91]
	v_mfma_f32_16x16x32_bf16 v[84:87], v[150:153], v[214:217], v[84:87]
	s_setprio 0
	s_setprio 1
	v_mfma_f32_16x16x32_bf16 v[32:35], v[154:157], v[174:177], v[32:35]
	v_mfma_f32_16x16x32_bf16 v[24:27], v[166:169], v[174:177], v[24:27]
	v_mfma_f32_16x16x32_bf16 v[20:23], v[154:157], v[184:187], v[20:23]
	v_mfma_f32_16x16x32_bf16 v[16:19], v[166:169], v[184:187], v[16:19]
	v_mfma_f32_16x16x32_bf16 v[12:15], v[154:157], v[198:201], v[12:15]
	v_mfma_f32_16x16x32_bf16 v[8:11], v[166:169], v[198:201], v[8:11]
	v_mfma_f32_16x16x32_bf16 v[4:7], v[154:157], v[210:213], v[4:7]
	v_mfma_f32_16x16x32_bf16 v[0:3], v[166:169], v[210:213], v[0:3]
	v_mfma_f32_16x16x32_bf16 v[32:35], v[162:165], v[180:183], v[32:35]
	v_mfma_f32_16x16x32_bf16 v[24:27], v[170:173], v[180:183], v[24:27]
	v_mfma_f32_16x16x32_bf16 v[20:23], v[162:165], v[194:197], v[20:23]
	v_mfma_f32_16x16x32_bf16 v[16:19], v[170:173], v[194:197], v[16:19]
	v_mfma_f32_16x16x32_bf16 v[12:15], v[162:165], v[206:209], v[12:15]
	v_mfma_f32_16x16x32_bf16 v[8:11], v[170:173], v[206:209], v[8:11]
	v_mfma_f32_16x16x32_bf16 v[4:7], v[162:165], v[214:217], v[4:7]
	v_mfma_f32_16x16x32_bf16 v[0:3], v[170:173], v[214:217], v[0:3]
	s_barrier
	s_setprio 0
	s_add_i32 s80, 0, 0x18000
	s_add_i32 s94, 0, 0x1c000
	v_add_u32_e32 v150, s80, v203
	v_add_u32_e32 v170, s94, v203
	ds_read_b128 v[138:141], v150
	ds_read_b128 v[142:145], v150 offset:1024
	ds_read_b128 v[146:149], v150 offset:2048
	ds_read_b128 v[150:153], v150 offset:3072
	ds_read_b128 v[154:157], v170
	ds_read_b128 v[162:165], v170 offset:1024
	ds_read_b128 v[166:169], v170 offset:2048
	ds_read_b128 v[170:173], v170 offset:3072
	s_add_u32 s40, s40, 0x40000
	s_addc_u32 s41, s41, 0
	s_mov_b32 m0, s78
	v_lshl_add_u64 v[220:221], s[40:41], 0, v[130:131]
	ds_read_b128 v[174:177], v204 offset:32768
	ds_read_b128 v[180:183], v204 offset:33792
	ds_read_b128 v[184:187], v204 offset:34816
	ds_read_b128 v[194:197], v204 offset:35840
	ds_read_b128 v[198:201], v204 offset:36864
	ds_read_b128 v[206:209], v204 offset:37888
	ds_read_b128 v[210:213], v204 offset:38912
	ds_read_b128 v[214:217], v204 offset:39936
	global_load_lds_dwordx4 v[220:221], off
	v_lshl_add_u64 v[220:221], s[40:41], 0, v[132:133]
	s_mov_b32 m0, s79
	s_nop 0
	global_load_lds_dwordx4 v[220:221], off
	s_waitcnt vmcnt(8) lgkmcnt(0)
	s_setprio 1
	s_barrier
	v_mfma_f32_16x16x32_bf16 v[124:127], v[138:141], v[174:177], v[124:127]
	v_mfma_f32_16x16x32_bf16 v[48:51], v[146:149], v[174:177], v[48:51]
	v_mfma_f32_16x16x32_bf16 v[120:123], v[138:141], v[184:187], v[120:123]
	v_mfma_f32_16x16x32_bf16 v[68:71], v[146:149], v[184:187], v[68:71]
	v_mfma_f32_16x16x32_bf16 v[116:119], v[138:141], v[198:201], v[116:119]
	v_mfma_f32_16x16x32_bf16 v[72:75], v[146:149], v[198:201], v[72:75]
	v_mfma_f32_16x16x32_bf16 v[112:115], v[138:141], v[210:213], v[112:115]
	v_mfma_f32_16x16x32_bf16 v[92:95], v[146:149], v[210:213], v[92:95]
	v_mfma_f32_16x16x32_bf16 v[124:127], v[142:145], v[180:183], v[124:127]
	v_mfma_f32_16x16x32_bf16 v[48:51], v[150:153], v[180:183], v[48:51]
	v_mfma_f32_16x16x32_bf16 v[120:123], v[142:145], v[194:197], v[120:123]
	v_mfma_f32_16x16x32_bf16 v[68:71], v[150:153], v[194:197], v[68:71]
	v_mfma_f32_16x16x32_bf16 v[116:119], v[142:145], v[206:209], v[116:119]
	v_mfma_f32_16x16x32_bf16 v[72:75], v[150:153], v[206:209], v[72:75]
	v_mfma_f32_16x16x32_bf16 v[112:115], v[142:145], v[214:217], v[112:115]
	v_mfma_f32_16x16x32_bf16 v[92:95], v[150:153], v[214:217], v[92:95]
	s_setprio 0
	s_setprio 1
	v_mfma_f32_16x16x32_bf16 v[64:67], v[154:157], v[174:177], v[64:67]
	v_mfma_f32_16x16x32_bf16 v[60:63], v[166:169], v[174:177], v[60:63]
	v_mfma_f32_16x16x32_bf16 v[56:59], v[154:157], v[184:187], v[56:59]
	v_mfma_f32_16x16x32_bf16 v[52:55], v[166:169], v[184:187], v[52:55]
	v_mfma_f32_16x16x32_bf16 v[44:47], v[154:157], v[198:201], v[44:47]
	v_mfma_f32_16x16x32_bf16 v[40:43], v[166:169], v[198:201], v[40:43]
	v_mfma_f32_16x16x32_bf16 v[36:39], v[154:157], v[210:213], v[36:39]
	v_mfma_f32_16x16x32_bf16 v[28:31], v[166:169], v[210:213], v[28:31]
	v_mfma_f32_16x16x32_bf16 v[64:67], v[162:165], v[180:183], v[64:67]
	v_mfma_f32_16x16x32_bf16 v[60:63], v[170:173], v[180:183], v[60:63]
	v_mfma_f32_16x16x32_bf16 v[56:59], v[162:165], v[194:197], v[56:59]
	v_mfma_f32_16x16x32_bf16 v[52:55], v[170:173], v[194:197], v[52:55]
	v_mfma_f32_16x16x32_bf16 v[44:47], v[162:165], v[206:209], v[44:47]
	v_mfma_f32_16x16x32_bf16 v[40:43], v[170:173], v[206:209], v[40:43]
	v_mfma_f32_16x16x32_bf16 v[36:39], v[162:165], v[214:217], v[36:39]
	v_mfma_f32_16x16x32_bf16 v[28:31], v[170:173], v[214:217], v[28:31]
	s_barrier
	s_setprio 0
	s_add_i32 s40, s80, s74
	v_lshl_add_u64 v[158:159], v[158:159], 0, s[14:15]
	s_mov_b32 m0, s40
	ds_read_b128 v[174:177], v204 offset:49152
	ds_read_b128 v[180:183], v204 offset:50176
	ds_read_b128 v[184:187], v204 offset:51200
	ds_read_b128 v[194:197], v204 offset:52224
	ds_read_b128 v[198:201], v204 offset:53248
	ds_read_b128 v[206:209], v204 offset:54272
	ds_read_b128 v[210:213], v204 offset:55296
	ds_read_b128 v[214:217], v204 offset:56320
	global_load_lds_dwordx4 v[158:159], off
	s_add_i32 m0, s40, 0x2000
	s_add_u32 s24, s24, 0x40080
	v_lshl_add_u64 v[158:159], v[188:189], 0, s[14:15]
	s_addc_u32 s25, s25, 0
	s_add_i32 s40, s94, s74
	global_load_lds_dwordx4 v[158:159], off
	v_lshl_add_u64 v[158:159], s[24:25], 0, v[128:129]
	s_mov_b32 m0, s40
	s_nop 0
	global_load_lds_dwordx4 v[158:159], off
	v_lshl_add_u64 v[158:159], s[24:25], 0, v[160:161]
	s_add_i32 m0, s40, 0x2000
	s_nop 0
	global_load_lds_dwordx4 v[158:159], off
	v_lshl_add_u64 v[158:159], v[190:191], 0, s[14:15]
	s_mov_b32 m0, s83
	s_nop 0
	global_load_lds_dwordx4 v[158:159], off
	v_lshl_add_u64 v[158:159], v[218:219], 0, s[14:15]
	s_mov_b32 m0, s84
	s_nop 0
	global_load_lds_dwordx4 v[158:159], off
	s_waitcnt vmcnt(8) lgkmcnt(0)
	s_setprio 1
	s_barrier
	v_mfma_f32_16x16x32_bf16 v[108:111], v[138:141], v[174:177], v[108:111]
	v_mfma_f32_16x16x32_bf16 v[104:107], v[146:149], v[174:177], v[104:107]
	v_mfma_f32_16x16x32_bf16 v[100:103], v[138:141], v[184:187], v[100:103]
	v_mfma_f32_16x16x32_bf16 v[96:99], v[146:149], v[184:187], v[96:99]
	v_mfma_f32_16x16x32_bf16 v[80:83], v[138:141], v[198:201], v[80:83]
	v_mfma_f32_16x16x32_bf16 v[76:79], v[146:149], v[198:201], v[76:79]
	v_mfma_f32_16x16x32_bf16 v[88:91], v[138:141], v[210:213], v[88:91]
	v_mfma_f32_16x16x32_bf16 v[84:87], v[146:149], v[210:213], v[84:87]
	v_mfma_f32_16x16x32_bf16 v[108:111], v[142:145], v[180:183], v[108:111]
	v_mfma_f32_16x16x32_bf16 v[104:107], v[150:153], v[180:183], v[104:107]
	v_mfma_f32_16x16x32_bf16 v[100:103], v[142:145], v[194:197], v[100:103]
	v_mfma_f32_16x16x32_bf16 v[96:99], v[150:153], v[194:197], v[96:99]
	v_mfma_f32_16x16x32_bf16 v[80:83], v[142:145], v[206:209], v[80:83]
	v_mfma_f32_16x16x32_bf16 v[76:79], v[150:153], v[206:209], v[76:79]
	v_mfma_f32_16x16x32_bf16 v[88:91], v[142:145], v[214:217], v[88:91]
	v_mfma_f32_16x16x32_bf16 v[84:87], v[150:153], v[214:217], v[84:87]
	s_setprio 0
	s_setprio 1
	v_mfma_f32_16x16x32_bf16 v[32:35], v[154:157], v[174:177], v[32:35]
	v_mfma_f32_16x16x32_bf16 v[24:27], v[166:169], v[174:177], v[24:27]
	v_mfma_f32_16x16x32_bf16 v[20:23], v[154:157], v[184:187], v[20:23]
	v_mfma_f32_16x16x32_bf16 v[16:19], v[166:169], v[184:187], v[16:19]
	v_mfma_f32_16x16x32_bf16 v[12:15], v[154:157], v[198:201], v[12:15]
	v_mfma_f32_16x16x32_bf16 v[8:11], v[166:169], v[198:201], v[8:11]
	v_mfma_f32_16x16x32_bf16 v[4:7], v[154:157], v[210:213], v[4:7]
	v_mfma_f32_16x16x32_bf16 v[0:3], v[166:169], v[210:213], v[0:3]
	v_mfma_f32_16x16x32_bf16 v[32:35], v[162:165], v[180:183], v[32:35]
	v_mfma_f32_16x16x32_bf16 v[24:27], v[170:173], v[180:183], v[24:27]
	v_mfma_f32_16x16x32_bf16 v[20:23], v[162:165], v[194:197], v[20:23]
	v_mfma_f32_16x16x32_bf16 v[16:19], v[170:173], v[194:197], v[16:19]
	v_mfma_f32_16x16x32_bf16 v[12:15], v[162:165], v[206:209], v[12:15]
	v_mfma_f32_16x16x32_bf16 v[8:11], v[170:173], v[206:209], v[8:11]
	v_mfma_f32_16x16x32_bf16 v[4:7], v[162:165], v[214:217], v[4:7]
	v_mfma_f32_16x16x32_bf16 v[0:3], v[170:173], v[214:217], v[0:3]
	s_barrier
	s_setprio 0
	s_add_i32 s81, s81, 2
	s_add_u32 s90, s90, 0x100
	s_addc_u32 s91, s91, 0
	s_add_u32 vcc_lo, vcc_lo, 0x100
	s_addc_u32 vcc_hi, vcc_hi, 0
	s_add_u32 s4, s4, 0xffffff00
	s_addc_u32 s5, s5, -1
	v_lshl_add_u64 v[134:135], v[134:135], 0, s[16:17]
	s_cmp_gt_u32 s81, 13
	v_lshl_add_u64 v[136:137], v[136:137], 0, s[16:17]
	s_cbranch_scc0 .LBB0_1214
	s_and_b64 vcc, exec, s[58:59]
	s_cbranch_vccz .LBB0_1217
	s_barrier

.LBB0_1368:
	v_add_u32_e32 v0, s0, v2
	v_ashrrev_i32_e32 v2, 31, v0
	v_lshrrev_b32_e32 v2, 26, v2
	v_lshlrev_b32_e32 v1, 4, v0
	v_add_u32_e32 v2, v0, v2
	v_bfe_i32 v0, v0, 27, 1
	v_lshrrev_b32_e32 v0, 22, v0
	v_add_u32_e32 v0, v1, v0
	v_and_b32_e32 v0, 0xfffffc00, v0
	v_sub_u32_e32 v0, v1, v0
	v_lshrrev_b32_e32 v3, 4, v0
	v_bitop3_b32 v0, v3, v0, 32 bitop3:0x6c
	v_ashrrev_i32_e32 v4, 31, v0
	v_ashrrev_i32_e32 v2, 6, v2
	v_lshrrev_b32_e32 v4, 26, v4
	v_lshlrev_b32_e32 v3, 3, v2
	v_add_u32_e32 v4, v0, v4
	v_and_b32_e32 v3, -16, v3
	v_ashrrev_i32_e32 v5, 6, v4
	v_and_b32_e32 v4, 0xc0, v4
	v_add_u32_e32 v3, v5, v3
	v_sub_u32_e32 v0, v0, v4
	v_mov_b32_e32 v7, 1
	v_lshlrev_b32_e32 v2, 5, v2
	v_ashrrev_i16_sdwa v0, v7, sext(v0) dst_sel:DWORD dst_unused:UNUSED_PAD src0_sel:DWORD src1_sel:BYTE_0
	v_lshlrev_b32_e32 v4, 1, v3
	v_lshrrev_b32_e32 v6, 2, v3
	v_and_b32_e32 v5, 3, v5
	v_and_b32_e32 v2, 32, v2
	v_bfe_i32 v0, v0, 0, 16
	v_and_b32_e32 v4, 24, v4
	v_and_b32_e32 v6, 4, v6
	v_and_or_b32 v5, v3, s2, v5
	v_or3_b32 v4, v5, v6, v4
	v_add_lshl_u32 v0, v2, v0, 1
	v_lshl_add_u32 v166, v3, 11, v0
	v_lshl_add_u32 v172, v4, 11, v0
	v_add_u32_e32 v0, 0x2000, v1
	v_ashrrev_i32_e32 v1, 31, v0
	v_lshrrev_b32_e32 v1, 22, v1
	v_add_u32_e32 v1, v0, v1
	v_ashrrev_i32_e32 v1, 10, v1
	v_mul_i32_i24_e32 v2, 0x400, v1
	v_sub_u32_e32 v0, v0, v2
	v_lshrrev_b32_e32 v2, 4, v0
	v_bitop3_b32 v0, v2, v0, 32 bitop3:0x6c
	v_ashrrev_i32_e32 v3, 31, v0
	v_lshrrev_b32_e32 v3, 26, v3
	v_lshlrev_b32_e32 v2, 3, v1
	v_add_u32_e32 v3, v0, v3
	v_and_b32_e32 v2, -16, v2
	v_ashrrev_i32_e32 v4, 6, v3
	v_and_b32_e32 v3, 0xc0, v3
	v_add_u32_e32 v2, v4, v2
	v_sub_u32_e32 v0, v0, v3
	v_lshlrev_b32_e32 v1, 5, v1
	v_ashrrev_i16_sdwa v0, v7, sext(v0) dst_sel:DWORD dst_unused:UNUSED_PAD src0_sel:DWORD src1_sel:BYTE_0
	v_lshlrev_b32_e32 v3, 1, v2
	v_lshrrev_b32_e32 v5, 2, v2
	v_and_b32_e32 v4, 3, v4
	v_and_b32_e32 v1, 32, v1
	v_bfe_i32 v0, v0, 0, 16
	v_and_b32_e32 v3, 24, v3
	v_and_b32_e32 v5, 4, v5
	v_and_or_b32 v4, v2, s2, v4
	v_or3_b32 v3, v4, v5, v3
	v_add_lshl_u32 v0, v1, v0, 1
	v_mov_b32_e32 v160, v161
	v_lshl_add_u32 v168, v2, 11, v0
	v_lshl_add_u32 v170, v3, 11, v0
	v_mov_b32_e32 v162, v161
	v_mov_b32_e32 v163, v161
	s_mov_b32 s66, s65
	s_mov_b64 s[78:79], s[6:7]
	s_mov_b64 s[76:77], s[84:85]
	s_mov_b32 s54, s72
	s_mov_b32 s56, s74

.LBB0_1379:
	s_add_i32 s6, 0, 0x10000
	s_add_i32 s7, 0, 0x14000
	v_add_u32_e32 v140, s6, v182
	v_add_u32_e32 v156, s7, v182
	ds_read_b128 v[128:131], v140
	ds_read_b128 v[132:135], v140 offset:1024
	ds_read_b128 v[136:139], v140 offset:2048
	ds_read_b128 v[140:143], v140 offset:3072
	ds_read_b128 v[144:147], v156
	ds_read_b128 v[148:151], v156 offset:1024
	ds_read_b128 v[152:155], v156 offset:2048
	ds_read_b128 v[156:159], v156 offset:3072
	s_add_u32 s4, s78, 0x40080
	s_addc_u32 s5, s79, 0
	v_lshl_add_u64 v[188:189], s[4:5], 0, v[166:167]
	s_add_i32 m0, s55, 0xc000
	ds_read_b128 v[162:165], v183
	ds_read_b128 v[174:177], v183 offset:1024
	ds_read_b128 v[178:181], v183 offset:2048
	ds_read_b128 v[184:187], v183 offset:3072
	ds_read_b128 v[194:197], v183 offset:4096
	ds_read_b128 v[198:201], v183 offset:5120
	ds_read_b128 v[202:205], v183 offset:6144
	ds_read_b128 v[206:209], v183 offset:7168
	global_load_lds_dwordx4 v[188:189], off
	v_lshl_add_u64 v[188:189], s[4:5], 0, v[168:169]
	s_add_i32 m0, s55, 0xe000
	s_nop 0
	global_load_lds_dwordx4 v[188:189], off
	s_waitcnt vmcnt(16) lgkmcnt(0)
	s_setprio 1
	s_barrier
	v_mfma_f32_16x16x32_bf16 v[124:127], v[128:131], v[162:165], 0
	v_mfma_f32_16x16x32_bf16 v[120:123], v[136:139], v[162:165], 0
	v_mfma_f32_16x16x32_bf16 v[116:119], v[128:131], v[178:181], 0
	v_mfma_f32_16x16x32_bf16 v[112:115], v[136:139], v[178:181], 0
	v_mfma_f32_16x16x32_bf16 v[108:111], v[128:131], v[194:197], 0
	v_mfma_f32_16x16x32_bf16 v[104:107], v[136:139], v[194:197], 0
	v_mfma_f32_16x16x32_bf16 v[100:103], v[128:131], v[202:205], 0
	v_mfma_f32_16x16x32_bf16 v[96:99], v[136:139], v[202:205], 0
	v_mfma_f32_16x16x32_bf16 v[124:127], v[132:135], v[174:177], v[124:127]
	v_mfma_f32_16x16x32_bf16 v[120:123], v[140:143], v[174:177], v[120:123]
	v_mfma_f32_16x16x32_bf16 v[116:119], v[132:135], v[184:187], v[116:119]
	v_mfma_f32_16x16x32_bf16 v[112:115], v[140:143], v[184:187], v[112:115]
	v_mfma_f32_16x16x32_bf16 v[108:111], v[132:135], v[198:201], v[108:111]
	v_mfma_f32_16x16x32_bf16 v[104:107], v[140:143], v[198:201], v[104:107]
	v_mfma_f32_16x16x32_bf16 v[100:103], v[132:135], v[206:209], v[100:103]
	v_mfma_f32_16x16x32_bf16 v[96:99], v[140:143], v[206:209], v[96:99]
	s_setprio 0
	s_setprio 1
	v_mfma_f32_16x16x32_bf16 v[92:95], v[144:147], v[162:165], 0
	v_mfma_f32_16x16x32_bf16 v[88:91], v[152:155], v[162:165], 0
	v_mfma_f32_16x16x32_bf16 v[84:87], v[144:147], v[178:181], 0
	v_mfma_f32_16x16x32_bf16 v[80:83], v[152:155], v[178:181], 0
	v_mfma_f32_16x16x32_bf16 v[76:79], v[144:147], v[194:197], 0
	v_mfma_f32_16x16x32_bf16 v[72:75], v[152:155], v[194:197], 0
	v_mfma_f32_16x16x32_bf16 v[68:71], v[144:147], v[202:205], 0
	v_mfma_f32_16x16x32_bf16 v[64:67], v[152:155], v[202:205], 0
	v_mfma_f32_16x16x32_bf16 v[92:95], v[148:151], v[174:177], v[92:95]
	v_mfma_f32_16x16x32_bf16 v[88:91], v[156:159], v[174:177], v[88:91]
	v_mfma_f32_16x16x32_bf16 v[84:87], v[148:151], v[184:187], v[84:87]
	v_mfma_f32_16x16x32_bf16 v[80:83], v[156:159], v[184:187], v[80:83]
	v_mfma_f32_16x16x32_bf16 v[76:79], v[148:151], v[198:201], v[76:79]
	v_mfma_f32_16x16x32_bf16 v[72:75], v[156:159], v[198:201], v[72:75]
	v_mfma_f32_16x16x32_bf16 v[68:71], v[148:151], v[206:209], v[68:71]
	v_mfma_f32_16x16x32_bf16 v[64:67], v[156:159], v[206:209], v[64:67]
	s_barrier
	s_setprio 0
	v_lshl_add_u64 v[188:189], s[76:77], 0, v[172:173]
	s_add_i32 s4, s6, s58
	v_lshl_add_u64 v[190:191], v[188:189], 0, s[16:17]
	s_mov_b32 m0, s4
	ds_read_b128 v[162:165], v183 offset:16384
	ds_read_b128 v[174:177], v183 offset:17408
	ds_read_b128 v[178:181], v183 offset:18432
	ds_read_b128 v[184:187], v183 offset:19456
	ds_read_b128 v[194:197], v183 offset:20480
	ds_read_b128 v[198:201], v183 offset:21504
	ds_read_b128 v[202:205], v183 offset:22528
	ds_read_b128 v[206:209], v183 offset:23552
	global_load_lds_dwordx4 v[190:191], off
	s_add_i32 m0, s4, 0x2000
	v_lshl_add_u64 v[190:191], s[76:77], 0, v[170:171]
	s_add_u32 s4, s76, 0x40100
	v_lshl_add_u64 v[210:211], v[190:191], 0, s[16:17]
	s_addc_u32 s5, s77, 0
	s_add_i32 s6, s7, s58
	global_load_lds_dwordx4 v[210:211], off
	v_lshl_add_u64 v[210:211], s[4:5], 0, v[172:173]
	s_mov_b32 m0, s6
	s_nop 0
	global_load_lds_dwordx4 v[210:211], off
	v_lshl_add_u64 v[210:211], s[4:5], 0, v[170:171]
	s_add_i32 m0, s6, 0x2000
	s_nop 0
	global_load_lds_dwordx4 v[210:211], off
	v_lshl_add_u64 v[210:211], s[78:79], 0, v[166:167]
	v_lshl_add_u64 v[212:213], v[210:211], 0, s[16:17]
	s_mov_b32 m0, s55
	s_nop 0
	global_load_lds_dwordx4 v[212:213], off
	v_lshl_add_u64 v[212:213], s[78:79], 0, v[168:169]
	v_lshl_add_u64 v[214:215], v[212:213], 0, s[16:17]
	s_mov_b32 m0, s59
	s_nop 0
	global_load_lds_dwordx4 v[214:215], off
	s_waitcnt vmcnt(16) lgkmcnt(0)
	s_setprio 1
	s_barrier
	v_mfma_f32_16x16x32_bf16 v[60:63], v[128:131], v[162:165], 0
	v_mfma_f32_16x16x32_bf16 v[56:59], v[136:139], v[162:165], 0
	v_mfma_f32_16x16x32_bf16 v[52:55], v[128:131], v[178:181], 0
	v_mfma_f32_16x16x32_bf16 v[48:51], v[136:139], v[178:181], 0
	v_mfma_f32_16x16x32_bf16 v[44:47], v[128:131], v[194:197], 0
	v_mfma_f32_16x16x32_bf16 v[40:43], v[136:139], v[194:197], 0
	v_mfma_f32_16x16x32_bf16 v[36:39], v[128:131], v[202:205], 0
	v_mfma_f32_16x16x32_bf16 v[32:35], v[136:139], v[202:205], 0
	v_mfma_f32_16x16x32_bf16 v[60:63], v[132:135], v[174:177], v[60:63]
	v_mfma_f32_16x16x32_bf16 v[56:59], v[140:143], v[174:177], v[56:59]
	v_mfma_f32_16x16x32_bf16 v[52:55], v[132:135], v[184:187], v[52:55]
	v_mfma_f32_16x16x32_bf16 v[48:51], v[140:143], v[184:187], v[48:51]
	v_mfma_f32_16x16x32_bf16 v[44:47], v[132:135], v[198:201], v[44:47]
	v_mfma_f32_16x16x32_bf16 v[40:43], v[140:143], v[198:201], v[40:43]
	v_mfma_f32_16x16x32_bf16 v[36:39], v[132:135], v[206:209], v[36:39]
	v_mfma_f32_16x16x32_bf16 v[32:35], v[140:143], v[206:209], v[32:35]
	s_setprio 0
	s_setprio 1
	v_mfma_f32_16x16x32_bf16 v[28:31], v[144:147], v[162:165], 0
	v_mfma_f32_16x16x32_bf16 v[24:27], v[152:155], v[162:165], 0
	v_mfma_f32_16x16x32_bf16 v[20:23], v[144:147], v[178:181], 0
	v_mfma_f32_16x16x32_bf16 v[16:19], v[152:155], v[178:181], 0
	v_mfma_f32_16x16x32_bf16 v[12:15], v[144:147], v[194:197], 0
	v_mfma_f32_16x16x32_bf16 v[8:11], v[152:155], v[194:197], 0
	v_mfma_f32_16x16x32_bf16 v[4:7], v[144:147], v[202:205], 0
	v_mfma_f32_16x16x32_bf16 v[0:3], v[152:155], v[202:205], 0
	v_mfma_f32_16x16x32_bf16 v[28:31], v[148:151], v[174:177], v[28:31]
	v_mfma_f32_16x16x32_bf16 v[24:27], v[156:159], v[174:177], v[24:27]
	v_mfma_f32_16x16x32_bf16 v[20:23], v[148:151], v[184:187], v[20:23]
	v_mfma_f32_16x16x32_bf16 v[16:19], v[156:159], v[184:187], v[16:19]
	v_mfma_f32_16x16x32_bf16 v[12:15], v[148:151], v[198:201], v[12:15]
	v_mfma_f32_16x16x32_bf16 v[8:11], v[156:159], v[198:201], v[8:11]
	v_mfma_f32_16x16x32_bf16 v[4:7], v[148:151], v[206:209], v[4:7]
	v_mfma_f32_16x16x32_bf16 v[0:3], v[156:159], v[206:209], v[0:3]
	s_barrier
	s_setprio 0
	s_add_i32 s6, 0, 0x18000
	s_add_i32 s7, 0, 0x1c000
	v_add_u32_e32 v140, s6, v182
	v_add_u32_e32 v156, s7, v182
	ds_read_b128 v[128:131], v140
	ds_read_b128 v[132:135], v140 offset:1024
	ds_read_b128 v[136:139], v140 offset:2048
	ds_read_b128 v[140:143], v140 offset:3072
	ds_read_b128 v[144:147], v156
	ds_read_b128 v[148:151], v156 offset:1024
	ds_read_b128 v[152:155], v156 offset:2048
	ds_read_b128 v[156:159], v156 offset:3072
	s_add_u32 s4, s78, 0x40100
	s_addc_u32 s5, s79, 0
	s_mov_b32 m0, s1
	v_lshl_add_u64 v[214:215], s[4:5], 0, v[166:167]
	ds_read_b128 v[162:165], v183 offset:32768
	ds_read_b128 v[174:177], v183 offset:33792
	ds_read_b128 v[178:181], v183 offset:34816
	ds_read_b128 v[184:187], v183 offset:35840
	ds_read_b128 v[194:197], v183 offset:36864
	ds_read_b128 v[198:201], v183 offset:37888
	ds_read_b128 v[202:205], v183 offset:38912
	ds_read_b128 v[206:209], v183 offset:39936
	global_load_lds_dwordx4 v[214:215], off
	v_lshl_add_u64 v[214:215], s[4:5], 0, v[168:169]
	s_mov_b32 m0, s50
	s_nop 0
	global_load_lds_dwordx4 v[214:215], off
	s_waitcnt vmcnt(8) lgkmcnt(0)
	s_setprio 1
	s_barrier
	v_mfma_f32_16x16x32_bf16 v[124:127], v[128:131], v[162:165], v[124:127]
	v_mfma_f32_16x16x32_bf16 v[120:123], v[136:139], v[162:165], v[120:123]
	v_mfma_f32_16x16x32_bf16 v[116:119], v[128:131], v[178:181], v[116:119]
	v_mfma_f32_16x16x32_bf16 v[112:115], v[136:139], v[178:181], v[112:115]
	v_mfma_f32_16x16x32_bf16 v[108:111], v[128:131], v[194:197], v[108:111]
	v_mfma_f32_16x16x32_bf16 v[104:107], v[136:139], v[194:197], v[104:107]
	v_mfma_f32_16x16x32_bf16 v[100:103], v[128:131], v[202:205], v[100:103]
	v_mfma_f32_16x16x32_bf16 v[96:99], v[136:139], v[202:205], v[96:99]
	v_mfma_f32_16x16x32_bf16 v[124:127], v[132:135], v[174:177], v[124:127]
	v_mfma_f32_16x16x32_bf16 v[120:123], v[140:143], v[174:177], v[120:123]
	v_mfma_f32_16x16x32_bf16 v[116:119], v[132:135], v[184:187], v[116:119]
	v_mfma_f32_16x16x32_bf16 v[112:115], v[140:143], v[184:187], v[112:115]
	v_mfma_f32_16x16x32_bf16 v[108:111], v[132:135], v[198:201], v[108:111]
	v_mfma_f32_16x16x32_bf16 v[104:107], v[140:143], v[198:201], v[104:107]
	v_mfma_f32_16x16x32_bf16 v[100:103], v[132:135], v[206:209], v[100:103]
	v_mfma_f32_16x16x32_bf16 v[96:99], v[140:143], v[206:209], v[96:99]
	s_setprio 0
	s_setprio 1
	v_mfma_f32_16x16x32_bf16 v[92:95], v[144:147], v[162:165], v[92:95]
	v_mfma_f32_16x16x32_bf16 v[88:91], v[152:155], v[162:165], v[88:91]
	v_mfma_f32_16x16x32_bf16 v[84:87], v[144:147], v[178:181], v[84:87]
	v_mfma_f32_16x16x32_bf16 v[80:83], v[152:155], v[178:181], v[80:83]
	v_mfma_f32_16x16x32_bf16 v[76:79], v[144:147], v[194:197], v[76:79]
	v_mfma_f32_16x16x32_bf16 v[72:75], v[152:155], v[194:197], v[72:75]
	v_mfma_f32_16x16x32_bf16 v[68:71], v[144:147], v[202:205], v[68:71]
	v_mfma_f32_16x16x32_bf16 v[64:67], v[152:155], v[202:205], v[64:67]
	v_mfma_f32_16x16x32_bf16 v[92:95], v[148:151], v[174:177], v[92:95]
	v_mfma_f32_16x16x32_bf16 v[88:91], v[156:159], v[174:177], v[88:91]
	v_mfma_f32_16x16x32_bf16 v[84:87], v[148:151], v[184:187], v[84:87]
	v_mfma_f32_16x16x32_bf16 v[80:83], v[156:159], v[184:187], v[80:83]
	v_mfma_f32_16x16x32_bf16 v[76:79], v[148:151], v[198:201], v[76:79]
	v_mfma_f32_16x16x32_bf16 v[72:75], v[156:159], v[198:201], v[72:75]
	v_mfma_f32_16x16x32_bf16 v[68:71], v[148:151], v[206:209], v[68:71]
	v_mfma_f32_16x16x32_bf16 v[64:67], v[156:159], v[206:209], v[64:67]
	s_barrier
	s_setprio 0
	s_mov_b64 s[8:9], 0x180
	s_add_i32 s4, s6, s58
	v_lshl_add_u64 v[188:189], v[188:189], 0, s[8:9]
	s_mov_b32 m0, s4
	ds_read_b128 v[162:165], v183 offset:49152
	ds_read_b128 v[174:177], v183 offset:50176
	ds_read_b128 v[178:181], v183 offset:51200
	ds_read_b128 v[184:187], v183 offset:52224
	ds_read_b128 v[194:197], v183 offset:53248
	ds_read_b128 v[198:201], v183 offset:54272
	ds_read_b128 v[202:205], v183 offset:55296
	ds_read_b128 v[206:209], v183 offset:56320
	global_load_lds_dwordx4 v[188:189], off
	s_add_i32 m0, s4, 0x2000
	s_add_u32 s4, s76, 0x40180
	v_lshl_add_u64 v[188:189], v[190:191], 0, s[8:9]
	s_addc_u32 s5, s77, 0
	s_add_i32 s6, s7, s58
	global_load_lds_dwordx4 v[188:189], off
	v_lshl_add_u64 v[188:189], s[4:5], 0, v[172:173]
	s_mov_b32 m0, s6
	s_nop 0
	global_load_lds_dwordx4 v[188:189], off
	v_lshl_add_u64 v[188:189], s[4:5], 0, v[170:171]
	s_add_i32 m0, s6, 0x2000
	s_nop 0
	global_load_lds_dwordx4 v[188:189], off
	v_lshl_add_u64 v[188:189], v[210:211], 0, s[8:9]
	s_mov_b32 m0, s62
	s_nop 0
	global_load_lds_dwordx4 v[188:189], off
	v_lshl_add_u64 v[188:189], v[212:213], 0, s[8:9]
	s_mov_b32 m0, s63
	s_nop 0
	global_load_lds_dwordx4 v[188:189], off
	s_waitcnt vmcnt(8) lgkmcnt(0)
	s_setprio 1
	s_barrier
	v_mfma_f32_16x16x32_bf16 v[60:63], v[128:131], v[162:165], v[60:63]
	v_mfma_f32_16x16x32_bf16 v[56:59], v[136:139], v[162:165], v[56:59]
	v_mfma_f32_16x16x32_bf16 v[52:55], v[128:131], v[178:181], v[52:55]
	v_mfma_f32_16x16x32_bf16 v[48:51], v[136:139], v[178:181], v[48:51]
	v_mfma_f32_16x16x32_bf16 v[44:47], v[128:131], v[194:197], v[44:47]
	v_mfma_f32_16x16x32_bf16 v[40:43], v[136:139], v[194:197], v[40:43]
	v_mfma_f32_16x16x32_bf16 v[36:39], v[128:131], v[202:205], v[36:39]
	v_mfma_f32_16x16x32_bf16 v[32:35], v[136:139], v[202:205], v[32:35]
	v_mfma_f32_16x16x32_bf16 v[60:63], v[132:135], v[174:177], v[60:63]
	v_mfma_f32_16x16x32_bf16 v[56:59], v[140:143], v[174:177], v[56:59]
	v_mfma_f32_16x16x32_bf16 v[52:55], v[132:135], v[184:187], v[52:55]
	v_mfma_f32_16x16x32_bf16 v[48:51], v[140:143], v[184:187], v[48:51]
	v_mfma_f32_16x16x32_bf16 v[44:47], v[132:135], v[198:201], v[44:47]
	v_mfma_f32_16x16x32_bf16 v[40:43], v[140:143], v[198:201], v[40:43]
	v_mfma_f32_16x16x32_bf16 v[36:39], v[132:135], v[206:209], v[36:39]
	v_mfma_f32_16x16x32_bf16 v[32:35], v[140:143], v[206:209], v[32:35]
	s_setprio 0
	s_setprio 1
	v_mfma_f32_16x16x32_bf16 v[28:31], v[144:147], v[162:165], v[28:31]
	v_mfma_f32_16x16x32_bf16 v[24:27], v[152:155], v[162:165], v[24:27]
	v_mfma_f32_16x16x32_bf16 v[20:23], v[144:147], v[178:181], v[20:23]
	v_mfma_f32_16x16x32_bf16 v[16:19], v[152:155], v[178:181], v[16:19]
	v_mfma_f32_16x16x32_bf16 v[12:15], v[144:147], v[194:197], v[12:15]
	v_mfma_f32_16x16x32_bf16 v[8:11], v[152:155], v[194:197], v[8:11]
	v_mfma_f32_16x16x32_bf16 v[4:7], v[144:147], v[202:205], v[4:7]
	v_mfma_f32_16x16x32_bf16 v[0:3], v[152:155], v[202:205], v[0:3]
	v_mfma_f32_16x16x32_bf16 v[28:31], v[148:151], v[174:177], v[28:31]
	v_mfma_f32_16x16x32_bf16 v[24:27], v[156:159], v[174:177], v[24:27]
	v_mfma_f32_16x16x32_bf16 v[20:23], v[148:151], v[184:187], v[20:23]
	v_mfma_f32_16x16x32_bf16 v[16:19], v[156:159], v[184:187], v[16:19]
	v_mfma_f32_16x16x32_bf16 v[12:15], v[148:151], v[198:201], v[12:15]
	v_mfma_f32_16x16x32_bf16 v[8:11], v[156:159], v[198:201], v[8:11]
	v_mfma_f32_16x16x32_bf16 v[4:7], v[148:151], v[206:209], v[4:7]
	v_mfma_f32_16x16x32_bf16 v[0:3], v[156:159], v[206:209], v[0:3]
	s_barrier
	s_setprio 0
	s_mov_b32 s4, 2

.LBB0_1381:
	s_add_u32 s8, s43, s92
	s_addc_u32 s9, s44, 0
	s_add_u32 s47, s45, s92
	s_addc_u32 s48, s46, 0
	s_add_i32 s49, 0, 0x10000
	s_cmp_eq_u32 s92, s4
	s_cselect_b32 s23, s18, s9
	s_cselect_b32 s22, s19, s8
	s_cselect_b32 s9, s24, s48
	s_cselect_b32 s8, s25, s47
	s_add_i32 s47, 0, 0x14000
	v_add_u32_e32 v144, s49, v182
	v_add_u32_e32 v160, s47, v182
	ds_read_b128 v[132:135], v144
	ds_read_b128 v[136:139], v144 offset:1024
	ds_read_b128 v[140:143], v144 offset:2048
	ds_read_b128 v[144:147], v144 offset:3072
	ds_read_b128 v[148:151], v160
	ds_read_b128 v[152:155], v160 offset:1024
	ds_read_b128 v[156:159], v160 offset:2048
	ds_read_b128 v[162:165], v160 offset:3072
	v_lshl_add_u64 v[188:189], v[128:129], 0, s[92:93]
	s_add_i32 m0, s55, 0xc000
	ds_read_b128 v[174:177], v183
	ds_read_b128 v[178:181], v183 offset:1024
	ds_read_b128 v[184:187], v183 offset:2048
	ds_read_b128 v[194:197], v183 offset:3072
	ds_read_b128 v[198:201], v183 offset:4096
	ds_read_b128 v[202:205], v183 offset:5120
	ds_read_b128 v[206:209], v183 offset:6144
	ds_read_b128 v[210:213], v183 offset:7168
	global_load_lds_dwordx4 v[188:189], off
	v_lshl_add_u64 v[188:189], v[130:131], 0, s[92:93]
	s_add_i32 m0, s55, 0xe000
	s_nop 0
	global_load_lds_dwordx4 v[188:189], off
	s_waitcnt vmcnt(8) lgkmcnt(0)
	s_setprio 1
	s_barrier
	v_mfma_f32_16x16x32_bf16 v[124:127], v[132:135], v[174:177], v[124:127]
	v_mfma_f32_16x16x32_bf16 v[120:123], v[140:143], v[174:177], v[120:123]
	v_mfma_f32_16x16x32_bf16 v[116:119], v[132:135], v[184:187], v[116:119]
	v_mfma_f32_16x16x32_bf16 v[112:115], v[140:143], v[184:187], v[112:115]
	v_mfma_f32_16x16x32_bf16 v[108:111], v[132:135], v[198:201], v[108:111]
	v_mfma_f32_16x16x32_bf16 v[104:107], v[140:143], v[198:201], v[104:107]
	v_mfma_f32_16x16x32_bf16 v[100:103], v[132:135], v[206:209], v[100:103]
	v_mfma_f32_16x16x32_bf16 v[96:99], v[140:143], v[206:209], v[96:99]
	v_mfma_f32_16x16x32_bf16 v[124:127], v[136:139], v[178:181], v[124:127]
	v_mfma_f32_16x16x32_bf16 v[120:123], v[144:147], v[178:181], v[120:123]
	v_mfma_f32_16x16x32_bf16 v[116:119], v[136:139], v[194:197], v[116:119]
	v_mfma_f32_16x16x32_bf16 v[112:115], v[144:147], v[194:197], v[112:115]
	v_mfma_f32_16x16x32_bf16 v[108:111], v[136:139], v[202:205], v[108:111]
	v_mfma_f32_16x16x32_bf16 v[104:107], v[144:147], v[202:205], v[104:107]
	v_mfma_f32_16x16x32_bf16 v[100:103], v[136:139], v[210:213], v[100:103]
	v_mfma_f32_16x16x32_bf16 v[96:99], v[144:147], v[210:213], v[96:99]
	s_setprio 0
	s_setprio 1
	v_mfma_f32_16x16x32_bf16 v[92:95], v[148:151], v[174:177], v[92:95]
	v_mfma_f32_16x16x32_bf16 v[88:91], v[156:159], v[174:177], v[88:91]
	v_mfma_f32_16x16x32_bf16 v[84:87], v[148:151], v[184:187], v[84:87]
	v_mfma_f32_16x16x32_bf16 v[80:83], v[156:159], v[184:187], v[80:83]
	v_mfma_f32_16x16x32_bf16 v[76:79], v[148:151], v[198:201], v[76:79]
	v_mfma_f32_16x16x32_bf16 v[72:75], v[156:159], v[198:201], v[72:75]
	v_mfma_f32_16x16x32_bf16 v[68:71], v[148:151], v[206:209], v[68:71]
	v_mfma_f32_16x16x32_bf16 v[64:67], v[156:159], v[206:209], v[64:67]
	v_mfma_f32_16x16x32_bf16 v[92:95], v[152:155], v[178:181], v[92:95]
	v_mfma_f32_16x16x32_bf16 v[88:91], v[162:165], v[178:181], v[88:91]
	v_mfma_f32_16x16x32_bf16 v[84:87], v[152:155], v[194:197], v[84:87]
	v_mfma_f32_16x16x32_bf16 v[80:83], v[162:165], v[194:197], v[80:83]
	v_mfma_f32_16x16x32_bf16 v[76:79], v[152:155], v[202:205], v[76:79]
	v_mfma_f32_16x16x32_bf16 v[72:75], v[162:165], v[202:205], v[72:75]
	v_mfma_f32_16x16x32_bf16 v[68:71], v[152:155], v[210:213], v[68:71]
	v_mfma_f32_16x16x32_bf16 v[64:67], v[162:165], v[210:213], v[64:67]
	s_barrier
	s_setprio 0
	s_add_i32 s48, s49, s58
	v_lshl_add_u64 v[188:189], s[8:9], 0, v[172:173]
	s_mov_b32 m0, s48
	ds_read_b128 v[174:177], v183 offset:16384
	ds_read_b128 v[178:181], v183 offset:17408
	ds_read_b128 v[184:187], v183 offset:18432
	ds_read_b128 v[194:197], v183 offset:19456
	ds_read_b128 v[198:201], v183 offset:20480
	ds_read_b128 v[202:205], v183 offset:21504
	ds_read_b128 v[206:209], v183 offset:22528
	ds_read_b128 v[210:213], v183 offset:23552
	global_load_lds_dwordx4 v[188:189], off
	s_add_i32 m0, s48, 0x2000
	s_add_u32 s48, s8, 0x40000
	v_lshl_add_u64 v[190:191], s[8:9], 0, v[170:171]
	s_addc_u32 s49, s9, 0
	s_add_i32 s47, s47, s58
	global_load_lds_dwordx4 v[190:191], off
	v_lshl_add_u64 v[214:215], s[48:49], 0, v[172:173]
	s_mov_b32 m0, s47
	v_lshl_add_u64 v[216:217], s[22:23], 0, v[168:169]
	global_load_lds_dwordx4 v[214:215], off
	v_lshl_add_u64 v[214:215], s[48:49], 0, v[170:171]
	s_add_i32 m0, s47, 0x2000
	s_nop 0
	global_load_lds_dwordx4 v[214:215], off
	v_lshl_add_u64 v[214:215], s[22:23], 0, v[166:167]
	s_mov_b32 m0, s55
	s_nop 0
	global_load_lds_dwordx4 v[214:215], off
	s_mov_b32 m0, s59
	s_nop 0
	global_load_lds_dwordx4 v[216:217], off
	s_waitcnt vmcnt(8) lgkmcnt(0)
	s_setprio 1
	s_barrier
	v_mfma_f32_16x16x32_bf16 v[60:63], v[132:135], v[174:177], v[60:63]
	v_mfma_f32_16x16x32_bf16 v[56:59], v[140:143], v[174:177], v[56:59]
	v_mfma_f32_16x16x32_bf16 v[52:55], v[132:135], v[184:187], v[52:55]
	v_mfma_f32_16x16x32_bf16 v[48:51], v[140:143], v[184:187], v[48:51]
	v_mfma_f32_16x16x32_bf16 v[44:47], v[132:135], v[198:201], v[44:47]
	v_mfma_f32_16x16x32_bf16 v[40:43], v[140:143], v[198:201], v[40:43]
	v_mfma_f32_16x16x32_bf16 v[36:39], v[132:135], v[206:209], v[36:39]
	v_mfma_f32_16x16x32_bf16 v[32:35], v[140:143], v[206:209], v[32:35]
	v_mfma_f32_16x16x32_bf16 v[60:63], v[136:139], v[178:181], v[60:63]
	v_mfma_f32_16x16x32_bf16 v[56:59], v[144:147], v[178:181], v[56:59]
	v_mfma_f32_16x16x32_bf16 v[52:55], v[136:139], v[194:197], v[52:55]
	v_mfma_f32_16x16x32_bf16 v[48:51], v[144:147], v[194:197], v[48:51]
	v_mfma_f32_16x16x32_bf16 v[44:47], v[136:139], v[202:205], v[44:47]
	v_mfma_f32_16x16x32_bf16 v[40:43], v[144:147], v[202:205], v[40:43]
	v_mfma_f32_16x16x32_bf16 v[36:39], v[136:139], v[210:213], v[36:39]
	v_mfma_f32_16x16x32_bf16 v[32:35], v[144:147], v[210:213], v[32:35]
	s_setprio 0
	s_setprio 1
	v_mfma_f32_16x16x32_bf16 v[28:31], v[148:151], v[174:177], v[28:31]
	v_mfma_f32_16x16x32_bf16 v[24:27], v[156:159], v[174:177], v[24:27]
	v_mfma_f32_16x16x32_bf16 v[20:23], v[148:151], v[184:187], v[20:23]
	v_mfma_f32_16x16x32_bf16 v[16:19], v[156:159], v[184:187], v[16:19]
	v_mfma_f32_16x16x32_bf16 v[12:15], v[148:151], v[198:201], v[12:15]
	v_mfma_f32_16x16x32_bf16 v[8:11], v[156:159], v[198:201], v[8:11]
	v_mfma_f32_16x16x32_bf16 v[4:7], v[148:151], v[206:209], v[4:7]
	v_mfma_f32_16x16x32_bf16 v[0:3], v[156:159], v[206:209], v[0:3]
	v_mfma_f32_16x16x32_bf16 v[28:31], v[152:155], v[178:181], v[28:31]
	v_mfma_f32_16x16x32_bf16 v[24:27], v[162:165], v[178:181], v[24:27]
	v_mfma_f32_16x16x32_bf16 v[20:23], v[152:155], v[194:197], v[20:23]
	v_mfma_f32_16x16x32_bf16 v[16:19], v[162:165], v[194:197], v[16:19]
	v_mfma_f32_16x16x32_bf16 v[12:15], v[152:155], v[202:205], v[12:15]
	v_mfma_f32_16x16x32_bf16 v[8:11], v[162:165], v[202:205], v[8:11]
	v_mfma_f32_16x16x32_bf16 v[4:7], v[152:155], v[210:213], v[4:7]
	v_mfma_f32_16x16x32_bf16 v[0:3], v[162:165], v[210:213], v[0:3]
	s_barrier
	s_setprio 0
	s_add_i32 s47, 0, 0x18000
	s_add_i32 s48, 0, 0x1c000
	v_add_u32_e32 v144, s47, v182
	v_add_u32_e32 v160, s48, v182
	ds_read_b128 v[132:135], v144
	ds_read_b128 v[136:139], v144 offset:1024
	ds_read_b128 v[140:143], v144 offset:2048
	ds_read_b128 v[144:147], v144 offset:3072
	ds_read_b128 v[148:151], v160
	ds_read_b128 v[152:155], v160 offset:1024
	ds_read_b128 v[156:159], v160 offset:2048
	ds_read_b128 v[162:165], v160 offset:3072
	s_add_u32 s22, s22, 0x40000
	s_addc_u32 s23, s23, 0
	s_mov_b32 m0, s1
	v_lshl_add_u64 v[218:219], s[22:23], 0, v[166:167]
	ds_read_b128 v[174:177], v183 offset:32768
	ds_read_b128 v[178:181], v183 offset:33792
	ds_read_b128 v[184:187], v183 offset:34816
	ds_read_b128 v[194:197], v183 offset:35840
	ds_read_b128 v[198:201], v183 offset:36864
	ds_read_b128 v[202:205], v183 offset:37888
	ds_read_b128 v[206:209], v183 offset:38912
	ds_read_b128 v[210:213], v183 offset:39936
	global_load_lds_dwordx4 v[218:219], off
	v_lshl_add_u64 v[218:219], s[22:23], 0, v[168:169]
	s_mov_b32 m0, s50
	s_nop 0
	global_load_lds_dwordx4 v[218:219], off
	s_waitcnt vmcnt(8) lgkmcnt(0)
	s_setprio 1
	s_barrier
	v_mfma_f32_16x16x32_bf16 v[124:127], v[132:135], v[174:177], v[124:127]
	v_mfma_f32_16x16x32_bf16 v[120:123], v[140:143], v[174:177], v[120:123]
	v_mfma_f32_16x16x32_bf16 v[116:119], v[132:135], v[184:187], v[116:119]
	v_mfma_f32_16x16x32_bf16 v[112:115], v[140:143], v[184:187], v[112:115]
	v_mfma_f32_16x16x32_bf16 v[108:111], v[132:135], v[198:201], v[108:111]
	v_mfma_f32_16x16x32_bf16 v[104:107], v[140:143], v[198:201], v[104:107]
	v_mfma_f32_16x16x32_bf16 v[100:103], v[132:135], v[206:209], v[100:103]
	v_mfma_f32_16x16x32_bf16 v[96:99], v[140:143], v[206:209], v[96:99]
	v_mfma_f32_16x16x32_bf16 v[124:127], v[136:139], v[178:181], v[124:127]
	v_mfma_f32_16x16x32_bf16 v[120:123], v[144:147], v[178:181], v[120:123]
	v_mfma_f32_16x16x32_bf16 v[116:119], v[136:139], v[194:197], v[116:119]
	v_mfma_f32_16x16x32_bf16 v[112:115], v[144:147], v[194:197], v[112:115]
	v_mfma_f32_16x16x32_bf16 v[108:111], v[136:139], v[202:205], v[108:111]
	v_mfma_f32_16x16x32_bf16 v[104:107], v[144:147], v[202:205], v[104:107]
	v_mfma_f32_16x16x32_bf16 v[100:103], v[136:139], v[210:213], v[100:103]
	v_mfma_f32_16x16x32_bf16 v[96:99], v[144:147], v[210:213], v[96:99]
	s_setprio 0
	s_setprio 1
	v_mfma_f32_16x16x32_bf16 v[92:95], v[148:151], v[174:177], v[92:95]
	v_mfma_f32_16x16x32_bf16 v[88:91], v[156:159], v[174:177], v[88:91]
	v_mfma_f32_16x16x32_bf16 v[84:87], v[148:151], v[184:187], v[84:87]
	v_mfma_f32_16x16x32_bf16 v[80:83], v[156:159], v[184:187], v[80:83]
	v_mfma_f32_16x16x32_bf16 v[76:79], v[148:151], v[198:201], v[76:79]
	v_mfma_f32_16x16x32_bf16 v[72:75], v[156:159], v[198:201], v[72:75]
	v_mfma_f32_16x16x32_bf16 v[68:71], v[148:151], v[206:209], v[68:71]
	v_mfma_f32_16x16x32_bf16 v[64:67], v[156:159], v[206:209], v[64:67]
	v_mfma_f32_16x16x32_bf16 v[92:95], v[152:155], v[178:181], v[92:95]
	v_mfma_f32_16x16x32_bf16 v[88:91], v[162:165], v[178:181], v[88:91]
	v_mfma_f32_16x16x32_bf16 v[84:87], v[152:155], v[194:197], v[84:87]
	v_mfma_f32_16x16x32_bf16 v[80:83], v[162:165], v[194:197], v[80:83]
	v_mfma_f32_16x16x32_bf16 v[76:79], v[152:155], v[202:205], v[76:79]
	v_mfma_f32_16x16x32_bf16 v[72:75], v[162:165], v[202:205], v[72:75]
	v_mfma_f32_16x16x32_bf16 v[68:71], v[152:155], v[210:213], v[68:71]
	v_mfma_f32_16x16x32_bf16 v[64:67], v[162:165], v[210:213], v[64:67]
	s_barrier
	s_setprio 0
	s_add_i32 s22, s47, s58
	v_lshl_add_u64 v[188:189], v[188:189], 0, s[14:15]
	s_mov_b32 m0, s22
	ds_read_b128 v[174:177], v183 offset:49152
	ds_read_b128 v[178:181], v183 offset:50176
	ds_read_b128 v[184:187], v183 offset:51200
	ds_read_b128 v[194:197], v183 offset:52224
	ds_read_b128 v[198:201], v183 offset:53248
	ds_read_b128 v[202:205], v183 offset:54272
	ds_read_b128 v[206:209], v183 offset:55296
	ds_read_b128 v[210:213], v183 offset:56320
	global_load_lds_dwordx4 v[188:189], off
	s_add_i32 m0, s22, 0x2000
	s_add_u32 s8, s8, 0x40080
	v_lshl_add_u64 v[188:189], v[190:191], 0, s[14:15]
	s_addc_u32 s9, s9, 0
	s_add_i32 s22, s48, s58
	global_load_lds_dwordx4 v[188:189], off
	v_lshl_add_u64 v[188:189], s[8:9], 0, v[172:173]
	s_mov_b32 m0, s22
	s_nop 0
	global_load_lds_dwordx4 v[188:189], off
	v_lshl_add_u64 v[188:189], s[8:9], 0, v[170:171]
	s_add_i32 m0, s22, 0x2000
	s_nop 0
	global_load_lds_dwordx4 v[188:189], off
	v_lshl_add_u64 v[188:189], v[214:215], 0, s[14:15]
	s_mov_b32 m0, s62
	s_nop 0
	global_load_lds_dwordx4 v[188:189], off
	v_lshl_add_u64 v[188:189], v[216:217], 0, s[14:15]
	s_mov_b32 m0, s63
	s_nop 0
	global_load_lds_dwordx4 v[188:189], off
	s_waitcnt vmcnt(8) lgkmcnt(0)
	s_setprio 1
	s_barrier
	v_mfma_f32_16x16x32_bf16 v[60:63], v[132:135], v[174:177], v[60:63]
	v_mfma_f32_16x16x32_bf16 v[56:59], v[140:143], v[174:177], v[56:59]
	v_mfma_f32_16x16x32_bf16 v[52:55], v[132:135], v[184:187], v[52:55]
	v_mfma_f32_16x16x32_bf16 v[48:51], v[140:143], v[184:187], v[48:51]
	v_mfma_f32_16x16x32_bf16 v[44:47], v[132:135], v[198:201], v[44:47]
	v_mfma_f32_16x16x32_bf16 v[40:43], v[140:143], v[198:201], v[40:43]
	v_mfma_f32_16x16x32_bf16 v[36:39], v[132:135], v[206:209], v[36:39]
	v_mfma_f32_16x16x32_bf16 v[32:35], v[140:143], v[206:209], v[32:35]
	v_mfma_f32_16x16x32_bf16 v[60:63], v[136:139], v[178:181], v[60:63]
	v_mfma_f32_16x16x32_bf16 v[56:59], v[144:147], v[178:181], v[56:59]
	v_mfma_f32_16x16x32_bf16 v[52:55], v[136:139], v[194:197], v[52:55]
	v_mfma_f32_16x16x32_bf16 v[48:51], v[144:147], v[194:197], v[48:51]
	v_mfma_f32_16x16x32_bf16 v[44:47], v[136:139], v[202:205], v[44:47]
	v_mfma_f32_16x16x32_bf16 v[40:43], v[144:147], v[202:205], v[40:43]
	v_mfma_f32_16x16x32_bf16 v[36:39], v[136:139], v[210:213], v[36:39]
	v_mfma_f32_16x16x32_bf16 v[32:35], v[144:147], v[210:213], v[32:35]
	s_setprio 0
	s_setprio 1
	v_mfma_f32_16x16x32_bf16 v[28:31], v[148:151], v[174:177], v[28:31]
	v_mfma_f32_16x16x32_bf16 v[24:27], v[156:159], v[174:177], v[24:27]
	v_mfma_f32_16x16x32_bf16 v[20:23], v[148:151], v[184:187], v[20:23]
	v_mfma_f32_16x16x32_bf16 v[16:19], v[156:159], v[184:187], v[16:19]
	v_mfma_f32_16x16x32_bf16 v[12:15], v[148:151], v[198:201], v[12:15]
	v_mfma_f32_16x16x32_bf16 v[8:11], v[156:159], v[198:201], v[8:11]
	v_mfma_f32_16x16x32_bf16 v[4:7], v[148:151], v[206:209], v[4:7]
	v_mfma_f32_16x16x32_bf16 v[0:3], v[156:159], v[206:209], v[0:3]
	v_mfma_f32_16x16x32_bf16 v[28:31], v[152:155], v[178:181], v[28:31]
	v_mfma_f32_16x16x32_bf16 v[24:27], v[162:165], v[178:181], v[24:27]
	v_mfma_f32_16x16x32_bf16 v[20:23], v[152:155], v[194:197], v[20:23]
	v_mfma_f32_16x16x32_bf16 v[16:19], v[162:165], v[194:197], v[16:19]
	v_mfma_f32_16x16x32_bf16 v[12:15], v[152:155], v[202:205], v[12:15]
	v_mfma_f32_16x16x32_bf16 v[8:11], v[162:165], v[202:205], v[8:11]
	v_mfma_f32_16x16x32_bf16 v[4:7], v[152:155], v[210:213], v[4:7]
	v_mfma_f32_16x16x32_bf16 v[0:3], v[162:165], v[210:213], v[0:3]
	s_barrier
	s_setprio 0
	s_add_i32 s42, s42, 2
	s_add_u32 s43, s43, 0x100
	s_addc_u32 s44, s44, 0
	s_add_u32 s45, s45, 0x100
	s_addc_u32 s46, s46, 0
	s_add_u32 s4, s4, 0xffffff00
	s_addc_u32 s5, s5, -1
	v_lshl_add_u64 v[128:129], v[128:129], 0, s[16:17]
	s_cmp_gt_u32 s42, 13
	v_lshl_add_u64 v[130:131], v[130:131], 0, s[16:17]
	s_cbranch_scc0 .LBB0_1381
	s_and_b64 vcc, exec, s[70:71]
	s_cbranch_vccz .LBB0_1384
	s_barrier

.LBB0_1393:
	v_lshl_or_b32 v160, s73, 6, v169
	v_mov_b32_e32 v203, v167
	v_lshl_add_u32 v132, v160, 3, s67
	ds_read_b64 v[132:133], v132
	v_cmp_gt_u32_e64 s[46:47], 2, v169
	s_waitcnt lgkmcnt(0)
	v_pk_mul_f32 v[152:153], v[132:133], s[96:97] op_sel_hi:[1,0]
	v_fma_f32 v132, -v152, v152, v153
	v_max_f32_e32 v132, 0, v132
	v_add_f32_e32 v132, 0x3727c5ac, v132
	v_rsq_f32_e32 v180, v132
	ds_read_b128 v[132:135], v203 offset:2048
	ds_read_b128 v[136:139], v203 offset:2560
	ds_read_b128 v[144:147], v203 offset:2064
	ds_read_b128 v[148:151], v203 offset:2576
	v_mul_f32_e64 v188, v180, -v152
	ds_read_b128 v[152:155], v203 offset:3072
	ds_read_b128 v[176:179], v203 offset:3584
	s_waitcnt lgkmcnt(0)
	v_pk_fma_f32 v[132:133], v[132:133], v[188:189], v[136:137] op_sel_hi:[1,0,1]
	v_pk_fma_f32 v[134:135], v[134:135], v[188:189], v[138:139] op_sel_hi:[1,0,1]
	v_pk_fma_f32 v[136:137], v[144:145], v[188:189], v[148:149] op_sel_hi:[1,0,1]
	v_pk_fma_f32 v[138:139], v[146:147], v[188:189], v[150:151] op_sel_hi:[1,0,1]
	ds_read_b128 v[144:147], v203 offset:3088
	ds_read_b128 v[184:187], v203 offset:3600
	v_pk_fma_f32 v[132:133], v[124:125], v[180:181], v[132:133] op_sel_hi:[1,0,1]
	v_pk_fma_f32 v[134:135], v[126:127], v[180:181], v[134:135] op_sel_hi:[1,0,1]
	v_pk_fma_f32 v[136:137], v[120:121], v[180:181], v[136:137] op_sel_hi:[1,0,1]
	v_pk_fma_f32 v[138:139], v[122:123], v[180:181], v[138:139] op_sel_hi:[1,0,1]
	v_pk_fma_f32 v[148:149], v[152:153], v[188:189], v[176:177] op_sel_hi:[1,0,1]
	v_pk_fma_f32 v[150:151], v[154:155], v[188:189], v[178:179] op_sel_hi:[1,0,1]
	s_waitcnt lgkmcnt(0)
	v_pk_fma_f32 v[144:145], v[144:145], v[188:189], v[184:185] op_sel_hi:[1,0,1]
	v_pk_fma_f32 v[146:147], v[146:147], v[188:189], v[186:187] op_sel_hi:[1,0,1]
	s_and_b64 s[4:5], s[4:5], s[46:47]
	v_cmp_eq_u32_e64 s[42:43], 0, v169
	v_cmp_lt_u32_e32 vcc, 1, v169
	v_cmp_eq_u32_e64 s[44:45], 1, v169
	v_ashrrev_i32_e32 v175, 31, v174
	v_pk_fma_f32 v[150:151], v[94:95], v[180:181], v[150:151] op_sel_hi:[1,0,1]
	v_pk_fma_f32 v[144:145], v[88:89], v[180:181], v[144:145] op_sel_hi:[1,0,1]
	v_pk_fma_f32 v[146:147], v[90:91], v[180:181], v[146:147] op_sel_hi:[1,0,1]
	v_mov_b32_dpp v173, v132 row_ror:1 row_mask:0xf bank_mask:0xf
	v_mov_b32_dpp v185, v133 row_ror:1 row_mask:0xf bank_mask:0xf
	v_mov_b32_dpp v184, v132 row_ror:2 row_mask:0xf bank_mask:0xf
	v_mov_b32_dpp v186, v133 row_ror:2 row_mask:0xf bank_mask:0xf
	v_mov_b32_dpp v187, v134 row_ror:1 row_mask:0xf bank_mask:0xf
	v_mov_b32_dpp v194, v135 row_ror:1 row_mask:0xf bank_mask:0xf
	v_mov_b32_dpp v188, v134 row_ror:2 row_mask:0xf bank_mask:0xf
	v_mov_b32_dpp v189, v135 row_ror:2 row_mask:0xf bank_mask:0xf
	v_mov_b32_dpp v195, v136 row_ror:1 row_mask:0xf bank_mask:0xf
	v_mov_b32_dpp v197, v137 row_ror:1 row_mask:0xf bank_mask:0xf
	v_mov_b32_dpp v196, v136 row_ror:2 row_mask:0xf bank_mask:0xf
	v_mov_b32_dpp v198, v137 row_ror:2 row_mask:0xf bank_mask:0xf
	v_mov_b32_dpp v201, v138 row_ror:1 row_mask:0xf bank_mask:0xf
	v_mov_b32_dpp v202, v139 row_ror:1 row_mask:0xf bank_mask:0xf
	v_mov_b32_dpp v199, v138 row_ror:2 row_mask:0xf bank_mask:0xf
	v_mov_b32_dpp v200, v139 row_ror:2 row_mask:0xf bank_mask:0xf
	v_pk_fma_f32 v[148:149], v[92:93], v[180:181], v[148:149] op_sel_hi:[1,0,1]
	s_xor_b64 s[8:9], s[4:5], -1
	s_and_saveexec_b64 s[4:5], s[8:9]
	s_cbranch_execz .LBB0_1395
	ds_read_b128 v[178:181], v203 offset:1040
	ds_read_b128 v[204:207], v203 offset:528
	ds_read_b128 v[152:155], v203
	ds_read_b128 v[208:211], v203 offset:16
	ds_read_b128 v[212:215], v203 offset:1552
	v_cndmask_b32_e64 v158, v158, v164, s[44:45]
	v_cndmask_b32_e64 v159, v159, v165, s[44:45]
	v_cndmask_b32_e32 v159, v159, v200, vcc
	v_cndmask_b32_e32 v158, v158, v199, vcc
	v_cndmask_b32_e64 v177, v202, v165, s[42:43]
	v_cndmask_b32_e64 v176, v201, v164, s[42:43]
	s_waitcnt lgkmcnt(0)
	v_pk_fma_f32 v[158:159], v[158:159], v[210:211], v[214:215]
	v_cndmask_b32_e64 v156, v156, v162, s[44:45]
	v_pk_fma_f32 v[158:159], v[176:177], v[206:207], v[158:159]
	v_cndmask_b32_e64 v157, v157, v163, s[44:45]
	v_pk_fma_f32 v[158:159], v[138:139], v[180:181], v[158:159]
	v_cndmask_b32_e32 v157, v157, v198, vcc
	v_pk_mul_f32 v[164:165], v[146:147], v[158:159]
	v_pk_mul_f32 v[158:159], v[158:159], s[20:21] op_sel_hi:[1,0]
	v_cndmask_b32_e32 v156, v156, v196, vcc
	v_exp_f32_e32 v158, v158
	v_exp_f32_e32 v159, v159
	v_pk_fma_f32 v[156:157], v[156:157], v[208:209], v[212:213]
	v_cndmask_b32_e64 v130, v130, v142, s[44:45]
	v_cndmask_b32_e64 v131, v131, v143, s[44:45]
	v_pk_add_f32 v[158:159], v[158:159], 1.0 op_sel_hi:[1,0]
	v_cndmask_b32_e32 v131, v131, v189, vcc
	v_rcp_f32_e32 v158, v158
	v_rcp_f32_e32 v159, v159
	v_cndmask_b32_e32 v130, v130, v188, vcc
	v_cndmask_b32_e64 v181, v194, v143, s[42:43]
	v_cndmask_b32_e64 v180, v187, v142, s[42:43]
	v_pk_mul_f32 v[176:177], v[164:165], v[158:159]
	v_cndmask_b32_e64 v159, v197, v163, s[42:43]
	v_cndmask_b32_e64 v158, v195, v162, s[42:43]
	v_pk_fma_f32 v[156:157], v[158:159], v[204:205], v[156:157]
	ds_read_b128 v[204:207], v203 offset:1536
	v_pk_fma_f32 v[156:157], v[136:137], v[178:179], v[156:157]
	ds_read_b128 v[162:165], v203 offset:512
	v_pk_mul_f32 v[158:159], v[144:145], v[156:157]
	v_pk_mul_f32 v[156:157], v[156:157], s[20:21] op_sel_hi:[1,0]
	s_waitcnt lgkmcnt(0)
	v_pk_fma_f32 v[130:131], v[130:131], v[154:155], v[206:207]
	v_exp_f32_e32 v156, v156
	v_exp_f32_e32 v157, v157
	v_pk_fma_f32 v[130:131], v[180:181], v[164:165], v[130:131]
	v_cndmask_b32_e64 v128, v128, v140, s[44:45]
	v_cndmask_b32_e64 v129, v129, v141, s[44:45]
	v_pk_add_f32 v[156:157], v[156:157], 1.0 op_sel_hi:[1,0]
	v_cndmask_b32_e32 v129, v129, v186, vcc
	v_rcp_f32_e32 v156, v156
	v_rcp_f32_e32 v157, v157
	v_cndmask_b32_e32 v128, v128, v184, vcc
	v_pk_fma_f32 v[128:129], v[128:129], v[152:153], v[204:205]
	s_movk_i32 s8, 0x1600
	v_pk_mul_f32 v[178:179], v[158:159], v[156:157]
	ds_read_b128 v[156:159], v203 offset:1024
	s_waitcnt lgkmcnt(0)
	v_pk_fma_f32 v[130:131], v[134:135], v[158:159], v[130:131]
	s_nop 0
	v_pk_mul_f32 v[142:143], v[150:151], v[130:131]
	v_pk_mul_f32 v[130:131], v[130:131], s[20:21] op_sel_hi:[1,0]
	s_nop 0
	v_exp_f32_e32 v130, v130
	v_exp_f32_e32 v131, v131
	s_nop 0
	v_pk_add_f32 v[130:131], v[130:131], 1.0 op_sel_hi:[1,0]
	s_nop 0
	v_rcp_f32_e32 v130, v130
	v_rcp_f32_e32 v131, v131
	s_nop 0
	v_pk_mul_f32 v[130:131], v[142:143], v[130:131]
	v_cndmask_b32_e64 v143, v185, v141, s[42:43]
	v_cndmask_b32_e64 v142, v173, v140, s[42:43]
	v_pk_fma_f32 v[128:129], v[142:143], v[162:163], v[128:129]
	v_lshl_add_u32 v142, s56, 8, v160
	v_pk_fma_f32 v[128:129], v[132:133], v[156:157], v[128:129]
	s_nop 0
	v_pk_mul_f32 v[140:141], v[148:149], v[128:129]
	v_pk_mul_f32 v[128:129], v[128:129], s[20:21] op_sel_hi:[1,0]
	s_nop 0
	v_exp_f32_e32 v128, v128
	v_exp_f32_e32 v129, v129
	s_nop 0
	v_pk_add_f32 v[128:129], v[128:129], 1.0 op_sel_hi:[1,0]
	s_nop 0
	v_rcp_f32_e32 v128, v128
	v_rcp_f32_e32 v129, v129
	s_nop 0
	v_pk_mul_f32 v[128:129], v[140:141], v[128:129]
	v_mov_b64_e32 v[140:141], s[60:61]
	v_mad_i64_i32 v[140:141], s[8:9], v142, s8, v[140:141]
	v_cvt_pk_bf16_f32 v128, v128, v129
	v_cvt_pk_bf16_f32 v129, v130, v131
	v_cvt_pk_bf16_f32 v130, v178, v179
	v_cvt_pk_bf16_f32 v131, v176, v177
	v_lshl_add_u64 v[140:141], v[174:175], 1, v[140:141]
	global_store_dwordx4 v[140:141], v[128:131], off

.LBB0_1397:
	s_or_b64 exec, exec, s[4:5]
	v_or_b32_e32 v208, 16, v160
	v_mov_b32_e32 v209, v167
	v_lshl_add_u32 v128, v208, 3, s67
	ds_read_b64 v[136:137], v128
	ds_read_b128 v[128:131], v209 offset:2048
	ds_read_b128 v[132:135], v209 offset:2560
	ds_read_b128 v[142:145], v209 offset:2064
	ds_read_b128 v[146:149], v209 offset:2576
	s_waitcnt lgkmcnt(0)
	v_pk_mul_f32 v[136:137], v[136:137], s[96:97] op_sel_hi:[1,0]
	v_fma_f32 v137, -v136, v136, v137
	v_max_f32_e32 v137, 0, v137
	v_add_f32_e32 v137, 0x3727c5ac, v137
	v_rsq_f32_e32 v150, v137
	s_nop 0
	v_mul_f32_e64 v152, v150, -v136
	v_pk_fma_f32 v[128:129], v[128:129], v[152:153], v[132:133] op_sel_hi:[1,0,1]
	v_pk_fma_f32 v[130:131], v[130:131], v[152:153], v[134:135] op_sel_hi:[1,0,1]
	v_pk_fma_f32 v[136:137], v[116:117], v[150:151], v[128:129] op_sel_hi:[1,0,1]
	v_pk_fma_f32 v[128:129], v[142:143], v[152:153], v[146:147] op_sel_hi:[1,0,1]
	v_pk_fma_f32 v[140:141], v[118:119], v[150:151], v[130:131] op_sel_hi:[1,0,1]
	v_pk_fma_f32 v[180:181], v[112:113], v[150:151], v[128:129] op_sel_hi:[1,0,1]
	ds_read_b128 v[128:131], v209 offset:3072
	ds_read_b128 v[132:135], v209 offset:3584
	v_pk_fma_f32 v[138:139], v[144:145], v[152:153], v[148:149] op_sel_hi:[1,0,1]
	ds_read_b128 v[142:145], v209 offset:3088
	ds_read_b128 v[146:149], v209 offset:3600
	v_pk_fma_f32 v[190:191], v[114:115], v[150:151], v[138:139] op_sel_hi:[1,0,1]
	s_waitcnt lgkmcnt(0)
	v_pk_fma_f32 v[130:131], v[130:131], v[152:153], v[134:135] op_sel_hi:[1,0,1]
	v_pk_fma_f32 v[128:129], v[128:129], v[152:153], v[132:133] op_sel_hi:[1,0,1]
	v_pk_fma_f32 v[138:139], v[86:87], v[150:151], v[130:131] op_sel_hi:[1,0,1]
	v_pk_fma_f32 v[130:131], v[142:143], v[152:153], v[146:147] op_sel_hi:[1,0,1]
	v_pk_fma_f32 v[142:143], v[84:85], v[150:151], v[128:129] op_sel_hi:[1,0,1]
	v_pk_fma_f32 v[204:205], v[80:81], v[150:151], v[130:131] op_sel_hi:[1,0,1]
	v_pk_fma_f32 v[130:131], v[144:145], v[152:153], v[148:149] op_sel_hi:[1,0,1]
	ds_read_b128 v[132:135], v209 offset:1040
	v_pk_fma_f32 v[206:207], v[82:83], v[150:151], v[130:131] op_sel_hi:[1,0,1]
	ds_read_b128 v[144:147], v209 offset:16
	ds_read_b128 v[148:151], v209 offset:1552
	ds_read_b128 v[176:179], v209 offset:528
	ds_read_b128 v[128:131], v209
	v_mov_b32_dpp v210, v190 row_ror:1 row_mask:0xf bank_mask:0xf
	v_mov_b32_dpp v211, v191 row_ror:1 row_mask:0xf bank_mask:0xf
	v_mov_b32_dpp v212, v190 row_ror:2 row_mask:0xf bank_mask:0xf
	v_mov_b32_dpp v213, v191 row_ror:2 row_mask:0xf bank_mask:0xf
	v_cndmask_b32_e64 v203, v211, v202, s[42:43]
	v_cndmask_b32_e64 v202, v210, v201, s[42:43]
	v_cndmask_b32_e32 v201, v200, v213, vcc
	v_cndmask_b32_e32 v200, v199, v212, vcc
	v_mov_b32_dpp v163, v180 row_ror:2 row_mask:0xf bank_mask:0xf
	v_mov_b32_dpp v165, v181 row_ror:2 row_mask:0xf bank_mask:0xf
	s_waitcnt lgkmcnt(0)
	v_pk_fma_f32 v[146:147], v[200:201], v[146:147], v[150:151]
	v_mov_b32_dpp v162, v180 row_ror:1 row_mask:0xf bank_mask:0xf
	v_mov_b32_dpp v164, v181 row_ror:1 row_mask:0xf bank_mask:0xf
	v_pk_fma_f32 v[146:147], v[202:203], v[178:179], v[146:147]
	v_cndmask_b32_e32 v179, v198, v165, vcc
	v_cndmask_b32_e32 v178, v196, v163, vcc
	v_cndmask_b32_e64 v151, v164, v197, s[42:43]
	v_cndmask_b32_e64 v150, v162, v195, s[42:43]
	v_pk_fma_f32 v[144:145], v[178:179], v[144:145], v[148:149]
	v_pk_fma_f32 v[134:135], v[190:191], v[134:135], v[146:147]
	v_pk_fma_f32 v[144:145], v[150:151], v[176:177], v[144:145]
	v_pk_mul_f32 v[146:147], v[134:135], s[20:21] op_sel_hi:[1,0]
	v_pk_fma_f32 v[132:133], v[180:181], v[132:133], v[144:145]
	v_exp_f32_e32 v146, v146
	v_pk_mul_f32 v[144:145], v[132:133], s[20:21] op_sel_hi:[1,0]
	v_exp_f32_e32 v147, v147
	v_exp_f32_e32 v144, v144
	v_exp_f32_e32 v145, v145
	v_pk_mul_f32 v[134:135], v[206:207], v[134:135]
	v_pk_add_f32 v[146:147], v[146:147], 1.0 op_sel_hi:[1,0]
	v_pk_mul_f32 v[132:133], v[204:205], v[132:133]
	v_pk_add_f32 v[144:145], v[144:145], 1.0 op_sel_hi:[1,0]
	v_rcp_f32_e32 v146, v146
	v_rcp_f32_e32 v147, v147
	v_rcp_f32_e32 v148, v144
	v_rcp_f32_e32 v149, v145
	v_pk_mul_f32 v[144:145], v[134:135], v[146:147]
	v_pk_mul_f32 v[146:147], v[132:133], v[148:149]
	ds_read_b128 v[132:135], v209 offset:1024
	ds_read_b128 v[148:151], v209 offset:1536
	ds_read_b128 v[176:179], v209 offset:512
	v_mov_b32_dpp v157, v140 row_ror:2 row_mask:0xf bank_mask:0xf
	v_mov_b32_dpp v158, v141 row_ror:2 row_mask:0xf bank_mask:0xf
	v_mov_b32_dpp v156, v140 row_ror:1 row_mask:0xf bank_mask:0xf
	v_mov_b32_dpp v159, v141 row_ror:1 row_mask:0xf bank_mask:0xf
	v_cndmask_b32_e32 v189, v189, v158, vcc
	v_cndmask_b32_e32 v188, v188, v157, vcc
	v_mov_b32_dpp v153, v136 row_ror:2 row_mask:0xf bank_mask:0xf
	v_mov_b32_dpp v155, v137 row_ror:2 row_mask:0xf bank_mask:0xf
	v_cndmask_b32_e64 v181, v159, v194, s[42:43]
	v_cndmask_b32_e64 v180, v156, v187, s[42:43]
	s_waitcnt lgkmcnt(0)
	v_pk_fma_f32 v[130:131], v[188:189], v[130:131], v[150:151]
	v_mov_b32_dpp v152, v136 row_ror:1 row_mask:0xf bank_mask:0xf
	v_mov_b32_dpp v154, v137 row_ror:1 row_mask:0xf bank_mask:0xf
	v_pk_fma_f32 v[130:131], v[180:181], v[178:179], v[130:131]
	v_cndmask_b32_e32 v151, v186, v155, vcc
	v_cndmask_b32_e32 v150, v184, v153, vcc
	v_pk_fma_f32 v[130:131], v[140:141], v[134:135], v[130:131]
	v_cndmask_b32_e64 v141, v154, v185, s[42:43]
	v_cndmask_b32_e64 v140, v152, v173, s[42:43]
	v_pk_fma_f32 v[128:129], v[150:151], v[128:129], v[148:149]
	v_pk_mul_f32 v[134:135], v[130:131], s[20:21] op_sel_hi:[1,0]
	v_pk_fma_f32 v[128:129], v[140:141], v[176:177], v[128:129]
	v_exp_f32_e32 v134, v134
	v_pk_fma_f32 v[128:129], v[136:137], v[132:133], v[128:129]
	v_exp_f32_e32 v135, v135
	v_pk_mul_f32 v[132:133], v[128:129], s[20:21] op_sel_hi:[1,0]
	v_pk_mul_f32 v[128:129], v[142:143], v[128:129]
	v_exp_f32_e32 v132, v132
	v_exp_f32_e32 v133, v133
	v_pk_add_f32 v[134:135], v[134:135], 1.0 op_sel_hi:[1,0]
	s_lshl_b32 s4, s56, 8
	v_rcp_f32_e32 v134, v134
	v_pk_add_f32 v[132:133], v[132:133], 1.0 op_sel_hi:[1,0]
	v_rcp_f32_e32 v135, v135
	v_rcp_f32_e32 v132, v132
	v_rcp_f32_e32 v133, v133
	v_pk_mul_f32 v[130:131], v[138:139], v[130:131]
	v_mov_b64_e32 v[148:149], s[60:61]
	s_movk_i32 s19, 0x1600
	v_pk_mul_f32 v[128:129], v[128:129], v[132:133]
	v_add_u32_e32 v132, s4, v208
	v_pk_mul_f32 v[130:131], v[130:131], v[134:135]
	v_mad_i64_i32 v[132:133], s[8:9], v132, s19, v[148:149]
	v_lshlrev_b64 v[150:151], 1, v[174:175]
	v_cvt_pk_bf16_f32 v128, v128, v129
	v_cvt_pk_bf16_f32 v129, v130, v131
	v_cvt_pk_bf16_f32 v130, v146, v147
	v_cvt_pk_bf16_f32 v131, v144, v145
	v_lshl_add_u64 v[132:133], v[132:133], 0, v[150:151]
	v_or_b32_e32 v147, 32, v160
	global_store_dwordx4 v[132:133], v[128:131], off
	v_mov_b32_e32 v173, v167
	s_nop 0
	v_lshl_add_u32 v128, v147, 3, s67
	ds_read_b64 v[128:129], v128
	s_waitcnt lgkmcnt(0)
	v_pk_mul_f32 v[136:137], v[128:129], s[96:97] op_sel_hi:[1,0]
	v_fma_f32 v128, -v136, v136, v137
	v_max_f32_e32 v128, 0, v128
	v_add_f32_e32 v128, 0x3727c5ac, v128
	v_rsq_f32_e32 v180, v128
	ds_read_b128 v[128:131], v173 offset:2048
	ds_read_b128 v[132:135], v173 offset:2560
	ds_read_b128 v[138:141], v173 offset:2064
	ds_read_b128 v[142:145], v173 offset:2576
	v_mul_f32_e64 v146, v180, -v136
	s_waitcnt lgkmcnt(0)
	v_pk_fma_f32 v[128:129], v[128:129], v[146:147], v[132:133] op_sel_hi:[1,0,1]
	v_pk_fma_f32 v[132:133], v[108:109], v[180:181], v[128:129] op_sel_hi:[1,0,1]
	v_pk_fma_f32 v[128:129], v[130:131], v[146:147], v[134:135] op_sel_hi:[1,0,1]
	v_pk_fma_f32 v[134:135], v[140:141], v[146:147], v[144:145] op_sel_hi:[1,0,1]
	v_pk_fma_f32 v[136:137], v[110:111], v[180:181], v[128:129] op_sel_hi:[1,0,1]
	v_pk_fma_f32 v[128:129], v[138:139], v[146:147], v[142:143] op_sel_hi:[1,0,1]
	v_pk_fma_f32 v[190:191], v[106:107], v[180:181], v[134:135] op_sel_hi:[1,0,1]
	v_pk_fma_f32 v[188:189], v[104:105], v[180:181], v[128:129] op_sel_hi:[1,0,1]
	ds_read_b128 v[128:131], v173 offset:3072
	ds_read_b128 v[176:179], v173 offset:3584
	ds_read_b128 v[138:141], v173 offset:3088
	ds_read_b128 v[142:145], v173 offset:3600
	v_mov_b32_dpp v219, v190 row_ror:2 row_mask:0xf bank_mask:0xf
	v_mov_b32_dpp v220, v191 row_ror:2 row_mask:0xf bank_mask:0xf
	v_mov_b32_dpp v217, v190 row_ror:1 row_mask:0xf bank_mask:0xf
	s_waitcnt lgkmcnt(0)
	v_pk_fma_f32 v[130:131], v[130:131], v[146:147], v[178:179] op_sel_hi:[1,0,1]
	v_pk_fma_f32 v[128:129], v[128:129], v[146:147], v[176:177] op_sel_hi:[1,0,1]
	v_pk_fma_f32 v[134:135], v[78:79], v[180:181], v[130:131] op_sel_hi:[1,0,1]
	v_pk_fma_f32 v[130:131], v[138:139], v[146:147], v[142:143] op_sel_hi:[1,0,1]
	v_pk_fma_f32 v[138:139], v[76:77], v[180:181], v[128:129] op_sel_hi:[1,0,1]
	v_pk_fma_f32 v[198:199], v[72:73], v[180:181], v[130:131] op_sel_hi:[1,0,1]
	v_pk_fma_f32 v[130:131], v[140:141], v[146:147], v[144:145] op_sel_hi:[1,0,1]
	ds_read_b128 v[140:143], v173 offset:1040
	v_pk_fma_f32 v[200:201], v[74:75], v[180:181], v[130:131] op_sel_hi:[1,0,1]
	ds_read_b128 v[176:179], v173 offset:16
	ds_read_b128 v[184:187], v173 offset:1552
	ds_read_b128 v[194:197], v173 offset:528
	ds_read_b128 v[128:131], v173
	v_mov_b32_dpp v218, v191 row_ror:1 row_mask:0xf bank_mask:0xf
	v_cndmask_b32_e32 v203, v213, v220, vcc
	v_cndmask_b32_e32 v202, v212, v219, vcc
	v_mov_b32_dpp v214, v189 row_ror:1 row_mask:0xf bank_mask:0xf
	v_mov_b32_dpp v215, v188 row_ror:2 row_mask:0xf bank_mask:0xf
	v_mov_b32_dpp v216, v189 row_ror:2 row_mask:0xf bank_mask:0xf
	v_cndmask_b32_e64 v181, v218, v211, s[42:43]
	v_cndmask_b32_e64 v180, v217, v210, s[42:43]
	s_waitcnt lgkmcnt(0)
	v_pk_fma_f32 v[178:179], v[202:203], v[178:179], v[186:187]
	v_mov_b32_dpp v209, v188 row_ror:1 row_mask:0xf bank_mask:0xf
	v_pk_fma_f32 v[178:179], v[180:181], v[196:197], v[178:179]
	v_cndmask_b32_e64 v181, v214, v164, s[42:43]
	v_cndmask_b32_e32 v165, v165, v216, vcc
	v_cndmask_b32_e32 v164, v163, v215, vcc
	v_cndmask_b32_e64 v180, v209, v162, s[42:43]
	v_pk_fma_f32 v[162:163], v[164:165], v[176:177], v[184:185]
	v_pk_fma_f32 v[142:143], v[190:191], v[142:143], v[178:179]
	v_pk_fma_f32 v[162:163], v[180:181], v[194:195], v[162:163]
	v_pk_mul_f32 v[178:179], v[142:143], s[20:21] op_sel_hi:[1,0]
	v_pk_fma_f32 v[162:163], v[188:189], v[140:141], v[162:163]
	v_exp_f32_e32 v178, v178
	v_pk_mul_f32 v[140:141], v[162:163], s[20:21] op_sel_hi:[1,0]
	v_exp_f32_e32 v179, v179
	v_exp_f32_e32 v140, v140
	v_exp_f32_e32 v141, v141
	v_pk_add_f32 v[164:165], v[178:179], 1.0 op_sel_hi:[1,0]
	v_pk_add_f32 v[140:141], v[140:141], 1.0 op_sel_hi:[1,0]
	v_rcp_f32_e32 v164, v164
	v_rcp_f32_e32 v165, v165
	v_rcp_f32_e32 v176, v140
	v_rcp_f32_e32 v177, v141
	v_pk_mul_f32 v[140:141], v[200:201], v[142:143]
	v_pk_mul_f32 v[142:143], v[198:199], v[162:163]
	v_pk_mul_f32 v[140:141], v[140:141], v[164:165]
	v_pk_mul_f32 v[142:143], v[142:143], v[176:177]
	ds_read_b128 v[162:165], v173 offset:1024
	ds_read_b128 v[176:179], v173 offset:1536
	ds_read_b128 v[184:187], v173 offset:512
	v_mov_b32_dpp v146, v133 row_ror:1 row_mask:0xf bank_mask:0xf
	v_mov_b32_dpp v145, v132 row_ror:2 row_mask:0xf bank_mask:0xf
	v_mov_b32_dpp v204, v133 row_ror:2 row_mask:0xf bank_mask:0xf
	v_mov_b32_dpp v206, v137 row_ror:1 row_mask:0xf bank_mask:0xf
	v_mov_b32_dpp v207, v136 row_ror:2 row_mask:0xf bank_mask:0xf
	v_mov_b32_dpp v208, v137 row_ror:2 row_mask:0xf bank_mask:0xf
	v_mov_b32_dpp v144, v132 row_ror:1 row_mask:0xf bank_mask:0xf
	v_mov_b32_dpp v205, v136 row_ror:1 row_mask:0xf bank_mask:0xf
	v_cndmask_b32_e64 v181, v206, v159, s[42:43]
	v_cndmask_b32_e32 v159, v158, v208, vcc
	v_cndmask_b32_e32 v158, v157, v207, vcc
	v_cndmask_b32_e64 v157, v146, v154, s[42:43]
	v_cndmask_b32_e32 v155, v155, v204, vcc
	v_cndmask_b32_e32 v154, v153, v145, vcc
	v_cndmask_b32_e64 v180, v205, v156, s[42:43]
	v_cndmask_b32_e64 v156, v144, v152, s[42:43]
	s_waitcnt lgkmcnt(0)
	v_pk_fma_f32 v[128:129], v[154:155], v[128:129], v[176:177]
	v_pk_fma_f32 v[130:131], v[158:159], v[130:131], v[178:179]
	v_pk_fma_f32 v[128:129], v[156:157], v[184:185], v[128:129]
	v_pk_fma_f32 v[130:131], v[180:181], v[186:187], v[130:131]
	v_pk_fma_f32 v[128:129], v[132:133], v[162:163], v[128:129]
	v_pk_fma_f32 v[130:131], v[136:137], v[164:165], v[130:131]
	v_pk_mul_f32 v[132:133], v[128:129], s[20:21] op_sel_hi:[1,0]
	v_pk_mul_f32 v[136:137], v[130:131], s[20:21] op_sel_hi:[1,0]
	v_exp_f32_e32 v132, v132
	v_exp_f32_e32 v133, v133
	v_exp_f32_e32 v136, v136
	v_exp_f32_e32 v137, v137
	v_pk_mul_f32 v[128:129], v[138:139], v[128:129]
	v_pk_add_f32 v[132:133], v[132:133], 1.0 op_sel_hi:[1,0]
	v_pk_mul_f32 v[130:131], v[134:135], v[130:131]
	v_pk_add_f32 v[136:137], v[136:137], 1.0 op_sel_hi:[1,0]
	v_rcp_f32_e32 v132, v132
	v_rcp_f32_e32 v133, v133
	v_rcp_f32_e32 v136, v136
	v_rcp_f32_e32 v137, v137
	v_or_b32_e32 v173, 48, v160
	v_pk_mul_f32 v[128:129], v[128:129], v[132:133]
	v_add_u32_e32 v132, s4, v147
	v_pk_mul_f32 v[130:131], v[130:131], v[136:137]
	v_mad_i64_i32 v[132:133], s[8:9], v132, s19, v[148:149]
	v_cvt_pk_bf16_f32 v128, v128, v129
	v_cvt_pk_bf16_f32 v129, v130, v131
	v_cvt_pk_bf16_f32 v130, v142, v143
	v_cvt_pk_bf16_f32 v131, v140, v141
	v_lshl_add_u64 v[132:133], v[132:133], 0, v[150:151]
	global_store_dwordx4 v[132:133], v[128:131], off
	v_mov_b32_e32 v147, v167
	s_nop 0
	v_lshl_add_u32 v128, v173, 3, s67
	ds_read_b64 v[128:129], v128
	ds_read_b128 v[130:133], v147 offset:2048
	ds_read_b128 v[134:137], v147 offset:2560
	ds_read_b128 v[138:141], v147 offset:2064
	ds_read_b128 v[152:155], v147 offset:2576
	s_waitcnt lgkmcnt(0)
	v_pk_mul_f32 v[142:143], v[128:129], s[96:97] op_sel_hi:[1,0]
	v_fma_f32 v128, -v142, v142, v143
	v_max_f32_e32 v128, 0, v128
	v_add_f32_e32 v128, 0x3727c5ac, v128
	v_rsq_f32_e32 v156, v128
	s_nop 0
	v_mul_f32_e64 v142, v156, -v142
	v_pk_fma_f32 v[130:131], v[130:131], v[142:143], v[134:135] op_sel_hi:[1,0,1]
	v_pk_fma_f32 v[158:159], v[140:141], v[142:143], v[154:155] op_sel_hi:[1,0,1]
	v_pk_fma_f32 v[162:163], v[100:101], v[156:157], v[130:131] op_sel_hi:[1,0,1]
	v_pk_fma_f32 v[130:131], v[132:133], v[142:143], v[136:137] op_sel_hi:[1,0,1]
	v_pk_fma_f32 v[178:179], v[98:99], v[156:157], v[158:159] op_sel_hi:[1,0,1]
	v_pk_fma_f32 v[164:165], v[102:103], v[156:157], v[130:131] op_sel_hi:[1,0,1]
	v_pk_fma_f32 v[130:131], v[138:139], v[142:143], v[152:153] op_sel_hi:[1,0,1]
	v_mov_b32_dpp v190, v178 row_ror:2 row_mask:0xf bank_mask:0xf
	v_pk_fma_f32 v[176:177], v[96:97], v[156:157], v[130:131] op_sel_hi:[1,0,1]
	ds_read_b128 v[130:133], v147 offset:3072
	ds_read_b128 v[134:137], v147 offset:3584
	ds_read_b128 v[138:141], v147 offset:3088
	ds_read_b128 v[152:155], v147 offset:3600
	v_mov_b32_dpp v191, v179 row_ror:2 row_mask:0xf bank_mask:0xf
	v_cndmask_b32_e32 v191, v220, v191, vcc
	v_cndmask_b32_e32 v190, v219, v190, vcc
	s_waitcnt lgkmcnt(0)
	v_pk_fma_f32 v[132:133], v[132:133], v[142:143], v[136:137] op_sel_hi:[1,0,1]
	v_pk_fma_f32 v[130:131], v[130:131], v[142:143], v[134:135] op_sel_hi:[1,0,1]
	v_pk_fma_f32 v[180:181], v[70:71], v[156:157], v[132:133] op_sel_hi:[1,0,1]
	v_pk_fma_f32 v[132:133], v[138:139], v[142:143], v[152:153] op_sel_hi:[1,0,1]
	v_pk_fma_f32 v[184:185], v[64:65], v[156:157], v[132:133] op_sel_hi:[1,0,1]
	v_pk_fma_f32 v[132:133], v[140:141], v[142:143], v[154:155] op_sel_hi:[1,0,1]
	v_mov_b32_dpp v134, v178 row_ror:1 row_mask:0xf bank_mask:0xf
	v_mov_b32_dpp v135, v179 row_ror:1 row_mask:0xf bank_mask:0xf
	v_pk_fma_f32 v[142:143], v[66:67], v[156:157], v[132:133] op_sel_hi:[1,0,1]
	v_pk_fma_f32 v[186:187], v[68:69], v[156:157], v[130:131] op_sel_hi:[1,0,1]
	ds_read_b128 v[130:133], v147 offset:1040
	v_cndmask_b32_e64 v189, v135, v218, s[42:43]
	v_cndmask_b32_e64 v188, v134, v217, s[42:43]
	ds_read_b128 v[134:137], v147 offset:16
	ds_read_b128 v[138:141], v147 offset:1552
	ds_read_b128 v[152:155], v147 offset:528
	ds_read_b128 v[156:159], v147
	v_mov_b32_dpp v203, v176 row_ror:2 row_mask:0xf bank_mask:0xf
	v_mov_b32_dpp v210, v177 row_ror:2 row_mask:0xf bank_mask:0xf
	s_waitcnt lgkmcnt(0)
	v_pk_fma_f32 v[136:137], v[190:191], v[136:137], v[140:141]
	v_mov_b32_dpp v201, v176 row_ror:1 row_mask:0xf bank_mask:0xf
	v_mov_b32_dpp v202, v177 row_ror:1 row_mask:0xf bank_mask:0xf
	v_pk_fma_f32 v[136:137], v[188:189], v[154:155], v[136:137]
	v_cndmask_b32_e32 v155, v216, v210, vcc
	v_cndmask_b32_e32 v154, v215, v203, vcc
	v_cndmask_b32_e64 v141, v202, v214, s[42:43]
	v_cndmask_b32_e64 v140, v201, v209, s[42:43]
	v_pk_fma_f32 v[134:135], v[154:155], v[134:135], v[138:139]
	v_pk_fma_f32 v[132:133], v[178:179], v[132:133], v[136:137]
	v_pk_fma_f32 v[134:135], v[140:141], v[152:153], v[134:135]
	v_pk_mul_f32 v[136:137], v[132:133], s[20:21] op_sel_hi:[1,0]
	v_pk_fma_f32 v[130:131], v[176:177], v[130:131], v[134:135]
	v_exp_f32_e32 v136, v136
	v_pk_mul_f32 v[134:135], v[130:131], s[20:21] op_sel_hi:[1,0]
	v_exp_f32_e32 v137, v137
	v_exp_f32_e32 v134, v134
	v_exp_f32_e32 v135, v135
	v_pk_mul_f32 v[132:133], v[142:143], v[132:133]
	v_pk_add_f32 v[136:137], v[136:137], 1.0 op_sel_hi:[1,0]
	v_pk_mul_f32 v[130:131], v[184:185], v[130:131]
	v_pk_add_f32 v[134:135], v[134:135], 1.0 op_sel_hi:[1,0]
	v_rcp_f32_e32 v136, v136
	v_rcp_f32_e32 v137, v137
	v_rcp_f32_e32 v134, v134
	v_rcp_f32_e32 v135, v135
	v_pk_mul_f32 v[142:143], v[132:133], v[136:137]
	v_pk_mul_f32 v[152:153], v[130:131], v[134:135]
	ds_read_b128 v[130:133], v147 offset:1024
	ds_read_b128 v[134:137], v147 offset:1536
	ds_read_b128 v[138:141], v147 offset:512
	v_mov_b32_dpp v199, v164 row_ror:2 row_mask:0xf bank_mask:0xf
	v_mov_b32_dpp v200, v165 row_ror:2 row_mask:0xf bank_mask:0xf
	v_mov_b32_dpp v197, v164 row_ror:1 row_mask:0xf bank_mask:0xf
	v_mov_b32_dpp v198, v165 row_ror:1 row_mask:0xf bank_mask:0xf
	v_cndmask_b32_e32 v177, v208, v200, vcc
	v_cndmask_b32_e32 v176, v207, v199, vcc
	v_mov_b32_dpp v194, v163 row_ror:1 row_mask:0xf bank_mask:0xf
	v_mov_b32_dpp v195, v162 row_ror:2 row_mask:0xf bank_mask:0xf
	v_mov_b32_dpp v196, v163 row_ror:2 row_mask:0xf bank_mask:0xf
	v_cndmask_b32_e64 v155, v198, v206, s[42:43]
	v_cndmask_b32_e64 v154, v197, v205, s[42:43]
	s_waitcnt lgkmcnt(0)
	v_pk_fma_f32 v[136:137], v[176:177], v[158:159], v[136:137]
	v_mov_b32_dpp v129, v162 row_ror:1 row_mask:0xf bank_mask:0xf
	v_pk_fma_f32 v[136:137], v[154:155], v[140:141], v[136:137]
	v_cndmask_b32_e64 v141, v194, v146, s[42:43]
	v_cndmask_b32_e32 v147, v204, v196, vcc
	v_cndmask_b32_e32 v146, v145, v195, vcc
	v_cndmask_b32_e64 v140, v129, v144, s[42:43]
	v_pk_fma_f32 v[134:135], v[146:147], v[156:157], v[134:135]
	v_pk_fma_f32 v[132:133], v[164:165], v[132:133], v[136:137]
	v_pk_fma_f32 v[134:135], v[140:141], v[138:139], v[134:135]
	v_pk_mul_f32 v[136:137], v[132:133], s[20:21] op_sel_hi:[1,0]
	v_pk_fma_f32 v[130:131], v[162:163], v[130:131], v[134:135]
	v_exp_f32_e32 v136, v136
	v_pk_mul_f32 v[134:135], v[130:131], s[20:21] op_sel_hi:[1,0]
	v_exp_f32_e32 v137, v137
	v_exp_f32_e32 v134, v134
	v_exp_f32_e32 v135, v135
	s_xor_b64 s[8:9], s[48:49], -1
	v_pk_add_f32 v[136:137], v[136:137], 1.0 op_sel_hi:[1,0]
	v_cndmask_b32_e64 v128, 0, 1, s[8:9]
	v_pk_add_f32 v[134:135], v[134:135], 1.0 op_sel_hi:[1,0]
	v_rcp_f32_e32 v136, v136
	v_rcp_f32_e32 v137, v137
	v_rcp_f32_e32 v134, v134
	v_rcp_f32_e32 v135, v135
	s_and_b64 s[8:9], s[48:49], exec
	s_cselect_b32 s5, 2, 0
	v_or_b32_e32 v128, s5, v128
	v_pk_mul_f32 v[132:133], v[180:181], v[132:133]
	v_pk_mul_f32 v[130:131], v[186:187], v[130:131]
	v_add_u32_e32 v129, s4, v173
	v_lshlrev_b32_e32 v128, 10, v128
	v_pk_mul_f32 v[132:133], v[132:133], v[136:137]
	v_pk_mul_f32 v[130:131], v[130:131], v[134:135]
	v_mad_i64_i32 v[134:135], s[8:9], v129, s19, v[148:149]
	v_add_u32_e32 v128, 0, v128
	v_cvt_pk_bf16_f32 v130, v130, v131
	v_cvt_pk_bf16_f32 v131, v132, v133
	v_cvt_pk_bf16_f32 v132, v152, v153
	v_cvt_pk_bf16_f32 v133, v142, v143
	v_lshl_add_u64 v[134:135], v[134:135], 0, v[150:151]
	v_lshl_add_u32 v128, v171, 2, v128
	global_store_dwordx4 v[134:135], v[130:133], off
	v_add_u32_e32 v136, 0x20000, v128
	v_add_u32_e32 v214, 0x80, v160
	ds_read_b128 v[128:131], v136
	ds_read_b128 v[140:143], v136 offset:16
	ds_read_b128 v[132:135], v136 offset:512
	ds_read_b128 v[144:147], v136 offset:528
	v_mov_b32_e32 v215, v167
	v_lshl_add_u32 v136, v214, 3, s67
	ds_read_b64 v[136:137], v136
	s_waitcnt lgkmcnt(0)
	v_pk_mul_f32 v[156:157], v[136:137], s[96:97] op_sel_hi:[1,0]
	v_cndmask_b32_e64 v142, v142, v146, s[44:45]
	v_fma_f32 v136, -v156, v156, v157
	v_max_f32_e32 v136, 0, v136
	v_add_f32_e32 v136, 0x3727c5ac, v136
	v_rsq_f32_e32 v158, v136
	ds_read_b128 v[136:139], v215 offset:2048
	ds_read_b128 v[152:155], v215 offset:2560
	ds_read_b128 v[162:165], v215 offset:2064
	ds_read_b128 v[176:179], v215 offset:2576
	v_cndmask_b32_e64 v143, v143, v147, s[44:45]
	v_cndmask_b32_e64 v140, v140, v144, s[44:45]
	v_mul_f32_e64 v180, v158, -v156
	s_waitcnt lgkmcnt(0)
	v_pk_fma_f32 v[136:137], v[136:137], v[180:181], v[152:153] op_sel_hi:[1,0,1]
	v_cndmask_b32_e64 v141, v141, v145, s[44:45]
	v_pk_fma_f32 v[152:153], v[60:61], v[158:159], v[136:137] op_sel_hi:[1,0,1]
	v_pk_fma_f32 v[136:137], v[138:139], v[180:181], v[154:155] op_sel_hi:[1,0,1]
	v_pk_fma_f32 v[154:155], v[164:165], v[180:181], v[178:179] op_sel_hi:[1,0,1]
	v_pk_fma_f32 v[156:157], v[62:63], v[158:159], v[136:137] op_sel_hi:[1,0,1]
	v_pk_fma_f32 v[136:137], v[162:163], v[180:181], v[176:177] op_sel_hi:[1,0,1]
	v_pk_fma_f32 v[206:207], v[58:59], v[158:159], v[154:155] op_sel_hi:[1,0,1]
	v_pk_fma_f32 v[190:191], v[56:57], v[158:159], v[136:137] op_sel_hi:[1,0,1]
	ds_read_b128 v[136:139], v215 offset:3072
	ds_read_b128 v[184:187], v215 offset:3584
	ds_read_b128 v[162:165], v215 offset:3088
	ds_read_b128 v[176:179], v215 offset:3600
	v_mov_b32_dpp v188, v206 row_ror:2 row_mask:0xf bank_mask:0xf
	v_mov_b32_dpp v189, v207 row_ror:2 row_mask:0xf bank_mask:0xf
	v_mov_b32_dpp v216, v206 row_ror:1 row_mask:0xf bank_mask:0xf
	s_waitcnt lgkmcnt(0)
	v_pk_fma_f32 v[138:139], v[138:139], v[180:181], v[186:187] op_sel_hi:[1,0,1]
	v_pk_fma_f32 v[136:137], v[136:137], v[180:181], v[184:185] op_sel_hi:[1,0,1]
	v_pk_fma_f32 v[154:155], v[30:31], v[158:159], v[138:139] op_sel_hi:[1,0,1]
	v_pk_fma_f32 v[138:139], v[162:163], v[180:181], v[176:177] op_sel_hi:[1,0,1]
	v_pk_fma_f32 v[208:209], v[24:25], v[158:159], v[138:139] op_sel_hi:[1,0,1]
	v_pk_fma_f32 v[138:139], v[164:165], v[180:181], v[178:179] op_sel_hi:[1,0,1]
	ds_read_b128 v[162:165], v215 offset:1040
	v_pk_fma_f32 v[210:211], v[26:27], v[158:159], v[138:139] op_sel_hi:[1,0,1]
	v_pk_fma_f32 v[158:159], v[28:29], v[158:159], v[136:137] op_sel_hi:[1,0,1]
	ds_read_b128 v[194:197], v215 offset:528
	ds_read_b128 v[136:139], v215
	ds_read_b128 v[198:201], v215 offset:16
	ds_read_b128 v[202:205], v215 offset:1552
	v_mov_b32_dpp v217, v207 row_ror:1 row_mask:0xf bank_mask:0xf
	v_cndmask_b32_e32 v143, v143, v189, vcc
	v_cndmask_b32_e32 v142, v142, v188, vcc
	v_mov_b32_dpp v185, v190 row_ror:2 row_mask:0xf bank_mask:0xf
	v_mov_b32_dpp v187, v191 row_ror:2 row_mask:0xf bank_mask:0xf
	v_cndmask_b32_e64 v213, v217, v147, s[42:43]
	v_cndmask_b32_e64 v212, v216, v146, s[42:43]
	s_waitcnt lgkmcnt(0)
	v_pk_fma_f32 v[142:143], v[142:143], v[200:201], v[204:205]
	v_mov_b32_dpp v184, v190 row_ror:1 row_mask:0xf bank_mask:0xf
	v_mov_b32_dpp v186, v191 row_ror:1 row_mask:0xf bank_mask:0xf
	v_pk_fma_f32 v[142:143], v[212:213], v[196:197], v[142:143]
	v_cndmask_b32_e32 v141, v141, v187, vcc
	v_cndmask_b32_e32 v140, v140, v185, vcc
	v_pk_fma_f32 v[142:143], v[206:207], v[164:165], v[142:143]
	v_cndmask_b32_e64 v165, v186, v145, s[42:43]
	v_cndmask_b32_e64 v164, v184, v144, s[42:43]
	v_pk_fma_f32 v[140:141], v[140:141], v[198:199], v[202:203]
	v_pk_mul_f32 v[146:147], v[142:143], s[20:21] op_sel_hi:[1,0]
	v_pk_fma_f32 v[140:141], v[164:165], v[194:195], v[140:141]
	v_exp_f32_e32 v146, v146
	v_pk_fma_f32 v[140:141], v[190:191], v[162:163], v[140:141]
	v_exp_f32_e32 v147, v147
	v_pk_mul_f32 v[144:145], v[140:141], s[20:21] op_sel_hi:[1,0]
	v_pk_mul_f32 v[142:143], v[210:211], v[142:143]
	v_exp_f32_e32 v144, v144
	v_exp_f32_e32 v145, v145
	v_pk_add_f32 v[146:147], v[146:147], 1.0 op_sel_hi:[1,0]
	v_pk_mul_f32 v[140:141], v[208:209], v[140:141]
	v_rcp_f32_e32 v146, v146
	v_pk_add_f32 v[144:145], v[144:145], 1.0 op_sel_hi:[1,0]
	v_rcp_f32_e32 v147, v147
	v_rcp_f32_e32 v144, v144
	v_rcp_f32_e32 v145, v145
	v_pk_mul_f32 v[162:163], v[142:143], v[146:147]
	v_pk_mul_f32 v[164:165], v[140:141], v[144:145]
	ds_read_b128 v[140:143], v215 offset:1024
	ds_read_b128 v[144:147], v215 offset:512
	ds_read_b128 v[194:197], v215 offset:1536
	v_mov_b32_dpp v173, v152 row_ror:2 row_mask:0xf bank_mask:0xf
	v_mov_b32_dpp v177, v153 row_ror:2 row_mask:0xf bank_mask:0xf
	v_mov_b32_dpp v179, v156 row_ror:2 row_mask:0xf bank_mask:0xf
	v_mov_b32_dpp v180, v157 row_ror:2 row_mask:0xf bank_mask:0xf
	v_cndmask_b32_e64 v130, v130, v134, s[44:45]
	v_cndmask_b32_e64 v131, v131, v135, s[44:45]
	v_cndmask_b32_e64 v128, v128, v132, s[44:45]
	v_cndmask_b32_e64 v129, v129, v133, s[44:45]
	v_mov_b32_dpp v171, v152 row_ror:1 row_mask:0xf bank_mask:0xf
	v_mov_b32_dpp v176, v153 row_ror:1 row_mask:0xf bank_mask:0xf
	v_cndmask_b32_e32 v131, v131, v180, vcc
	v_cndmask_b32_e32 v130, v130, v179, vcc
	v_cndmask_b32_e32 v129, v129, v177, vcc
	v_cndmask_b32_e32 v128, v128, v173, vcc
	v_mov_b32_dpp v178, v156 row_ror:1 row_mask:0xf bank_mask:0xf
	v_mov_b32_dpp v181, v157 row_ror:1 row_mask:0xf bank_mask:0xf
	s_waitcnt lgkmcnt(0)
	v_pk_fma_f32 v[130:131], v[130:131], v[138:139], v[196:197]
	v_cndmask_b32_e64 v139, v176, v133, s[42:43]
	v_cndmask_b32_e64 v138, v171, v132, s[42:43]
	v_pk_fma_f32 v[128:129], v[128:129], v[136:137], v[194:195]
	v_cndmask_b32_e64 v191, v181, v135, s[42:43]
	v_cndmask_b32_e64 v190, v178, v134, s[42:43]
	v_pk_fma_f32 v[128:129], v[138:139], v[144:145], v[128:129]
	v_pk_fma_f32 v[130:131], v[190:191], v[146:147], v[130:131]
	v_pk_fma_f32 v[128:129], v[152:153], v[140:141], v[128:129]
	v_pk_fma_f32 v[130:131], v[156:157], v[142:143], v[130:131]
	v_pk_mul_f32 v[132:133], v[128:129], s[20:21] op_sel_hi:[1,0]
	v_pk_mul_f32 v[134:135], v[130:131], s[20:21] op_sel_hi:[1,0]
	v_exp_f32_e32 v132, v132
	v_exp_f32_e32 v133, v133
	v_exp_f32_e32 v134, v134
	v_exp_f32_e32 v135, v135
	v_pk_mul_f32 v[128:129], v[158:159], v[128:129]
	v_pk_add_f32 v[132:133], v[132:133], 1.0 op_sel_hi:[1,0]
	v_pk_mul_f32 v[130:131], v[154:155], v[130:131]
	v_pk_add_f32 v[134:135], v[134:135], 1.0 op_sel_hi:[1,0]
	v_rcp_f32_e32 v132, v132
	v_rcp_f32_e32 v133, v133
	v_rcp_f32_e32 v134, v134
	v_rcp_f32_e32 v135, v135
	v_add_u32_e32 v208, 0x90, v160
	v_pk_mul_f32 v[128:129], v[128:129], v[132:133]
	v_add_u32_e32 v132, s4, v214
	v_pk_mul_f32 v[130:131], v[130:131], v[134:135]
	v_mad_i64_i32 v[132:133], s[8:9], v132, s19, v[148:149]
	v_cvt_pk_bf16_f32 v128, v128, v129
	v_cvt_pk_bf16_f32 v129, v130, v131
	v_cvt_pk_bf16_f32 v130, v164, v165
	v_cvt_pk_bf16_f32 v131, v162, v163
	v_lshl_add_u64 v[132:133], v[132:133], 0, v[150:151]
	global_store_dwordx4 v[132:133], v[128:131], off
	v_mov_b32_e32 v209, v167
	s_nop 0
	v_lshl_add_u32 v128, v208, 3, s67
	ds_read_b64 v[128:129], v128
	s_waitcnt lgkmcnt(0)
	v_pk_mul_f32 v[136:137], v[128:129], s[96:97] op_sel_hi:[1,0]
	v_fma_f32 v128, -v136, v136, v137
	v_max_f32_e32 v128, 0, v128
	v_add_f32_e32 v128, 0x3727c5ac, v128
	v_rsq_f32_e32 v156, v128
	ds_read_b128 v[128:131], v209 offset:2048
	ds_read_b128 v[132:135], v209 offset:2560
	ds_read_b128 v[138:141], v209 offset:2064
	ds_read_b128 v[142:145], v209 offset:2576
	v_mul_f32_e64 v146, v156, -v136
	s_waitcnt lgkmcnt(0)
	v_pk_fma_f32 v[128:129], v[128:129], v[146:147], v[132:133] op_sel_hi:[1,0,1]
	v_mov_b32_e32 v218, v161
	v_pk_fma_f32 v[132:133], v[52:53], v[156:157], v[128:129] op_sel_hi:[1,0,1]
	v_pk_fma_f32 v[128:129], v[130:131], v[146:147], v[134:135] op_sel_hi:[1,0,1]
	v_pk_fma_f32 v[134:135], v[140:141], v[146:147], v[144:145] op_sel_hi:[1,0,1]
	v_pk_fma_f32 v[136:137], v[54:55], v[156:157], v[128:129] op_sel_hi:[1,0,1]
	v_pk_fma_f32 v[128:129], v[138:139], v[146:147], v[142:143] op_sel_hi:[1,0,1]
	v_pk_fma_f32 v[200:201], v[50:51], v[156:157], v[134:135] op_sel_hi:[1,0,1]
	v_pk_fma_f32 v[190:191], v[48:49], v[156:157], v[128:129] op_sel_hi:[1,0,1]
	ds_read_b128 v[128:131], v209 offset:3072
	ds_read_b128 v[152:155], v209 offset:3584
	ds_read_b128 v[138:141], v209 offset:3088
	ds_read_b128 v[142:145], v209 offset:3600
	v_mov_b32_dpp v214, v200 row_ror:2 row_mask:0xf bank_mask:0xf
	v_mov_b32_dpp v215, v201 row_ror:2 row_mask:0xf bank_mask:0xf
	v_mov_b32_dpp v210, v191 row_ror:1 row_mask:0xf bank_mask:0xf
	s_waitcnt lgkmcnt(0)
	v_pk_fma_f32 v[130:131], v[130:131], v[146:147], v[154:155] op_sel_hi:[1,0,1]
	v_pk_fma_f32 v[128:129], v[128:129], v[146:147], v[152:153] op_sel_hi:[1,0,1]
	v_pk_fma_f32 v[134:135], v[22:23], v[156:157], v[130:131] op_sel_hi:[1,0,1]
	v_pk_fma_f32 v[130:131], v[138:139], v[146:147], v[142:143] op_sel_hi:[1,0,1]
	v_pk_fma_f32 v[138:139], v[20:21], v[156:157], v[128:129] op_sel_hi:[1,0,1]
	v_pk_fma_f32 v[202:203], v[16:17], v[156:157], v[130:131] op_sel_hi:[1,0,1]
	v_pk_fma_f32 v[130:131], v[140:141], v[146:147], v[144:145] op_sel_hi:[1,0,1]
	ds_read_b128 v[140:143], v209 offset:1040
	v_pk_fma_f32 v[204:205], v[18:19], v[156:157], v[130:131] op_sel_hi:[1,0,1]
	ds_read_b128 v[156:159], v209 offset:16
	ds_read_b128 v[162:165], v209 offset:1552
	ds_read_b128 v[196:199], v209 offset:528
	ds_read_b128 v[128:131], v209
	v_mov_b32_dpp v195, v190 row_ror:2 row_mask:0xf bank_mask:0xf
	v_mov_b32_dpp v211, v191 row_ror:2 row_mask:0xf bank_mask:0xf
	v_cndmask_b32_e32 v189, v189, v215, vcc
	v_cndmask_b32_e32 v188, v188, v214, vcc
	v_mov_b32_dpp v194, v190 row_ror:1 row_mask:0xf bank_mask:0xf
	v_mov_b32_dpp v212, v200 row_ror:1 row_mask:0xf bank_mask:0xf
	v_mov_b32_dpp v213, v201 row_ror:1 row_mask:0xf bank_mask:0xf
	s_waitcnt lgkmcnt(0)
	v_pk_fma_f32 v[158:159], v[188:189], v[158:159], v[164:165]
	v_cndmask_b32_e64 v165, v210, v186, s[42:43]
	v_cndmask_b32_e32 v187, v187, v211, vcc
	v_cndmask_b32_e32 v186, v185, v195, vcc
	v_cndmask_b32_e64 v207, v213, v217, s[42:43]
	v_cndmask_b32_e64 v206, v212, v216, s[42:43]
	v_cndmask_b32_e64 v164, v194, v184, s[42:43]
	v_pk_fma_f32 v[156:157], v[186:187], v[156:157], v[162:163]
	v_pk_fma_f32 v[158:159], v[206:207], v[198:199], v[158:159]
	v_pk_fma_f32 v[156:157], v[164:165], v[196:197], v[156:157]
	v_pk_fma_f32 v[142:143], v[200:201], v[142:143], v[158:159]
	v_pk_fma_f32 v[156:157], v[190:191], v[140:141], v[156:157]
	v_pk_mul_f32 v[158:159], v[142:143], s[20:21] op_sel_hi:[1,0]
	v_pk_mul_f32 v[140:141], v[156:157], s[20:21] op_sel_hi:[1,0]
	v_exp_f32_e32 v158, v158
	v_exp_f32_e32 v159, v159
	v_exp_f32_e32 v140, v140
	v_exp_f32_e32 v141, v141
	v_pk_add_f32 v[158:159], v[158:159], 1.0 op_sel_hi:[1,0]
	v_pk_add_f32 v[140:141], v[140:141], 1.0 op_sel_hi:[1,0]
	v_rcp_f32_e32 v158, v158
	v_rcp_f32_e32 v159, v159
	v_rcp_f32_e32 v162, v140
	v_rcp_f32_e32 v163, v141
	v_pk_mul_f32 v[140:141], v[204:205], v[142:143]
	v_pk_mul_f32 v[142:143], v[202:203], v[156:157]
	v_pk_mul_f32 v[140:141], v[140:141], v[158:159]
	v_pk_mul_f32 v[142:143], v[142:143], v[162:163]
	ds_read_b128 v[156:159], v209 offset:1024
	ds_read_b128 v[162:165], v209 offset:1536
	ds_read_b128 v[184:187], v209 offset:512
	v_mov_b32_dpp v155, v137 row_ror:1 row_mask:0xf bank_mask:0xf
	v_mov_b32_dpp v153, v136 row_ror:2 row_mask:0xf bank_mask:0xf
	v_mov_b32_dpp v154, v137 row_ror:2 row_mask:0xf bank_mask:0xf
	v_mov_b32_dpp v152, v136 row_ror:1 row_mask:0xf bank_mask:0xf
	v_cndmask_b32_e64 v189, v155, v181, s[42:43]
	v_cndmask_b32_e32 v181, v180, v154, vcc
	v_cndmask_b32_e32 v180, v179, v153, vcc
	v_mov_b32_dpp v145, v132 row_ror:2 row_mask:0xf bank_mask:0xf
	v_mov_b32_dpp v147, v133 row_ror:2 row_mask:0xf bank_mask:0xf
	v_cndmask_b32_e64 v188, v152, v178, s[42:43]
	s_waitcnt lgkmcnt(0)
	v_pk_fma_f32 v[130:131], v[180:181], v[130:131], v[164:165]
	v_mov_b32_dpp v144, v132 row_ror:1 row_mask:0xf bank_mask:0xf
	v_mov_b32_dpp v146, v133 row_ror:1 row_mask:0xf bank_mask:0xf
	v_pk_fma_f32 v[130:131], v[188:189], v[186:187], v[130:131]
	v_cndmask_b32_e32 v165, v177, v147, vcc
	v_cndmask_b32_e32 v164, v173, v145, vcc
	v_pk_fma_f32 v[130:131], v[136:137], v[158:159], v[130:131]
	v_cndmask_b32_e64 v159, v146, v176, s[42:43]
	v_cndmask_b32_e64 v158, v144, v171, s[42:43]
	v_pk_fma_f32 v[128:129], v[164:165], v[128:129], v[162:163]
	v_pk_mul_f32 v[136:137], v[130:131], s[20:21] op_sel_hi:[1,0]
	v_pk_fma_f32 v[128:129], v[158:159], v[184:185], v[128:129]
	v_exp_f32_e32 v136, v136
	v_pk_fma_f32 v[128:129], v[132:133], v[156:157], v[128:129]
	v_exp_f32_e32 v137, v137
	v_pk_mul_f32 v[132:133], v[128:129], s[20:21] op_sel_hi:[1,0]
	v_pk_mul_f32 v[128:129], v[138:139], v[128:129]
	v_exp_f32_e32 v132, v132
	v_exp_f32_e32 v133, v133
	v_pk_add_f32 v[136:137], v[136:137], 1.0 op_sel_hi:[1,0]
	v_pk_mul_f32 v[130:131], v[134:135], v[130:131]
	v_rcp_f32_e32 v136, v136
	v_pk_add_f32 v[132:133], v[132:133], 1.0 op_sel_hi:[1,0]
	v_rcp_f32_e32 v137, v137
	v_rcp_f32_e32 v132, v132
	v_rcp_f32_e32 v133, v133
	v_add_u32_e32 v179, 0xa0, v160
	v_pk_mul_f32 v[130:131], v[130:131], v[136:137]
	v_mov_b32_e32 v216, v167
	v_pk_mul_f32 v[128:129], v[128:129], v[132:133]
	v_add_u32_e32 v132, s4, v208
	v_mad_i64_i32 v[132:133], s[8:9], v132, s19, v[148:149]
	v_cvt_pk_bf16_f32 v128, v128, v129
	v_cvt_pk_bf16_f32 v129, v130, v131
	v_cvt_pk_bf16_f32 v130, v142, v143
	v_cvt_pk_bf16_f32 v131, v140, v141
	v_lshl_add_u64 v[132:133], v[132:133], 0, v[150:151]
	global_store_dwordx4 v[132:133], v[128:131], off
	s_nop 1
	v_lshl_add_u32 v128, v179, 3, s67
	ds_read_b64 v[128:129], v128
	s_and_b64 s[24:25], s[86:87], s[48:49]
	s_waitcnt lgkmcnt(0)
	v_pk_mul_f32 v[136:137], v[128:129], s[96:97] op_sel_hi:[1,0]
	s_nop 0
	v_fma_f32 v128, -v136, v136, v137
	v_max_f32_e32 v128, 0, v128
	v_add_f32_e32 v128, 0x3727c5ac, v128
	v_rsq_f32_e32 v142, v128
	ds_read_b128 v[128:131], v216 offset:2048
	ds_read_b128 v[132:135], v216 offset:2560
	ds_read_b128 v[138:141], v216 offset:2064
	ds_read_b128 v[156:159], v216 offset:2576
	v_mul_f32_e64 v176, v142, -v136
	s_waitcnt lgkmcnt(0)
	v_pk_fma_f32 v[128:129], v[128:129], v[176:177], v[132:133] op_sel_hi:[1,0,1]
	s_nop 0
	v_pk_fma_f32 v[132:133], v[44:45], v[142:143], v[128:129] op_sel_hi:[1,0,1]
	v_pk_fma_f32 v[128:129], v[130:131], v[176:177], v[134:135] op_sel_hi:[1,0,1]
	v_pk_fma_f32 v[134:135], v[140:141], v[176:177], v[158:159] op_sel_hi:[1,0,1]
	v_pk_fma_f32 v[136:137], v[46:47], v[142:143], v[128:129] op_sel_hi:[1,0,1]
	v_pk_fma_f32 v[128:129], v[138:139], v[176:177], v[156:157] op_sel_hi:[1,0,1]
	v_pk_fma_f32 v[188:189], v[42:43], v[142:143], v[134:135] op_sel_hi:[1,0,1]
	v_pk_fma_f32 v[180:181], v[40:41], v[142:143], v[128:129] op_sel_hi:[1,0,1]
	ds_read_b128 v[128:131], v216 offset:3072
	ds_read_b128 v[162:165], v216 offset:3584
	ds_read_b128 v[138:141], v216 offset:3088
	ds_read_b128 v[156:159], v216 offset:3600
	v_mov_b32_dpp v218, v133 row_ror:1 row_mask:0xf bank_mask:0xf
	v_mov_b32_dpp v219, v133 row_ror:2 row_mask:0xf bank_mask:0xf
	v_mov_b32_dpp v173, v136 row_ror:2 row_mask:0xf bank_mask:0xf
	s_waitcnt lgkmcnt(0)
	v_pk_fma_f32 v[130:131], v[130:131], v[176:177], v[164:165] op_sel_hi:[1,0,1]
	v_pk_fma_f32 v[128:129], v[128:129], v[176:177], v[162:163] op_sel_hi:[1,0,1]
	v_pk_fma_f32 v[134:135], v[14:15], v[142:143], v[130:131] op_sel_hi:[1,0,1]
	v_pk_fma_f32 v[130:131], v[138:139], v[176:177], v[156:157] op_sel_hi:[1,0,1]
	v_pk_fma_f32 v[190:191], v[8:9], v[142:143], v[130:131] op_sel_hi:[1,0,1]
	v_pk_fma_f32 v[130:131], v[140:141], v[176:177], v[158:159] op_sel_hi:[1,0,1]
	v_pk_fma_f32 v[204:205], v[10:11], v[142:143], v[130:131] op_sel_hi:[1,0,1]
	v_pk_fma_f32 v[138:139], v[12:13], v[142:143], v[128:129] op_sel_hi:[1,0,1]
	ds_read_b128 v[140:143], v216 offset:1040
	ds_read_b128 v[184:187], v216 offset:16
	ds_read_b128 v[196:199], v216 offset:1552
	ds_read_b128 v[200:203], v216 offset:528
	ds_read_b128 v[128:131], v216
	v_mov_b32_dpp v156, v188 row_ror:2 row_mask:0xf bank_mask:0xf
	v_mov_b32_dpp v157, v189 row_ror:2 row_mask:0xf bank_mask:0xf
	v_mov_b32_dpp v158, v188 row_ror:1 row_mask:0xf bank_mask:0xf
	v_mov_b32_dpp v159, v189 row_ror:1 row_mask:0xf bank_mask:0xf
	v_cndmask_b32_e32 v209, v215, v157, vcc
	v_cndmask_b32_e32 v208, v214, v156, vcc
	v_mov_b32_dpp v163, v180 row_ror:2 row_mask:0xf bank_mask:0xf
	v_mov_b32_dpp v164, v181 row_ror:2 row_mask:0xf bank_mask:0xf
	v_cndmask_b32_e64 v207, v159, v213, s[42:43]
	v_cndmask_b32_e64 v206, v158, v212, s[42:43]
	s_waitcnt lgkmcnt(0)
	v_pk_fma_f32 v[186:187], v[208:209], v[186:187], v[198:199]
	v_mov_b32_dpp v162, v180 row_ror:1 row_mask:0xf bank_mask:0xf
	v_mov_b32_dpp v165, v181 row_ror:1 row_mask:0xf bank_mask:0xf
	v_pk_fma_f32 v[186:187], v[206:207], v[202:203], v[186:187]
	v_cndmask_b32_e32 v199, v211, v164, vcc
	v_cndmask_b32_e32 v198, v195, v163, vcc
	v_pk_fma_f32 v[142:143], v[188:189], v[142:143], v[186:187]
	v_cndmask_b32_e64 v189, v165, v210, s[42:43]
	v_cndmask_b32_e64 v188, v162, v194, s[42:43]
	v_pk_fma_f32 v[184:185], v[198:199], v[184:185], v[196:197]
	v_pk_mul_f32 v[186:187], v[142:143], s[20:21] op_sel_hi:[1,0]
	v_pk_fma_f32 v[184:185], v[188:189], v[200:201], v[184:185]
	v_exp_f32_e32 v186, v186
	v_pk_fma_f32 v[180:181], v[180:181], v[140:141], v[184:185]
	v_exp_f32_e32 v187, v187
	v_pk_mul_f32 v[140:141], v[180:181], s[20:21] op_sel_hi:[1,0]
	v_exp_f32_e32 v140, v140
	v_exp_f32_e32 v141, v141
	v_pk_add_f32 v[184:185], v[186:187], 1.0 op_sel_hi:[1,0]
	v_rcp_f32_e32 v184, v184
	v_pk_add_f32 v[140:141], v[140:141], 1.0 op_sel_hi:[1,0]
	v_rcp_f32_e32 v185, v185
	v_rcp_f32_e32 v186, v140
	v_rcp_f32_e32 v187, v141
	v_pk_mul_f32 v[140:141], v[204:205], v[142:143]
	v_pk_mul_f32 v[142:143], v[190:191], v[180:181]
	v_pk_mul_f32 v[140:141], v[140:141], v[184:185]
	v_pk_mul_f32 v[142:143], v[142:143], v[186:187]
	ds_read_b128 v[184:187], v216 offset:1024
	ds_read_b128 v[194:197], v216 offset:1536
	ds_read_b128 v[198:201], v216 offset:512
	v_mov_b32_dpp v177, v132 row_ror:2 row_mask:0xf bank_mask:0xf
	v_mov_b32_dpp v176, v137 row_ror:1 row_mask:0xf bank_mask:0xf
	v_mov_b32_dpp v178, v137 row_ror:2 row_mask:0xf bank_mask:0xf
	v_mov_b32_dpp v217, v132 row_ror:1 row_mask:0xf bank_mask:0xf
	v_mov_b32_dpp v171, v136 row_ror:1 row_mask:0xf bank_mask:0xf
	v_cndmask_b32_e64 v181, v176, v155, s[42:43]
	v_cndmask_b32_e32 v155, v154, v178, vcc
	v_cndmask_b32_e32 v154, v153, v173, vcc
	v_cndmask_b32_e64 v153, v218, v146, s[42:43]
	v_cndmask_b32_e32 v147, v147, v219, vcc
	v_cndmask_b32_e32 v146, v145, v177, vcc
	v_cndmask_b32_e64 v180, v171, v152, s[42:43]
	v_cndmask_b32_e64 v152, v217, v144, s[42:43]
	s_waitcnt lgkmcnt(0)
	v_pk_fma_f32 v[128:129], v[146:147], v[128:129], v[194:195]
	v_pk_fma_f32 v[130:131], v[154:155], v[130:131], v[196:197]
	v_pk_fma_f32 v[128:129], v[152:153], v[198:199], v[128:129]
	v_pk_fma_f32 v[130:131], v[180:181], v[200:201], v[130:131]
	v_pk_fma_f32 v[128:129], v[132:133], v[184:185], v[128:129]
	v_pk_fma_f32 v[130:131], v[136:137], v[186:187], v[130:131]
	v_pk_mul_f32 v[132:133], v[128:129], s[20:21] op_sel_hi:[1,0]
	v_pk_mul_f32 v[136:137], v[130:131], s[20:21] op_sel_hi:[1,0]
	v_exp_f32_e32 v132, v132
	v_exp_f32_e32 v133, v133
	v_exp_f32_e32 v136, v136
	v_exp_f32_e32 v137, v137
	v_pk_mul_f32 v[128:129], v[138:139], v[128:129]
	v_pk_add_f32 v[132:133], v[132:133], 1.0 op_sel_hi:[1,0]
	v_pk_mul_f32 v[130:131], v[134:135], v[130:131]
	v_pk_add_f32 v[136:137], v[136:137], 1.0 op_sel_hi:[1,0]
	v_rcp_f32_e32 v132, v132
	v_rcp_f32_e32 v133, v133
	v_rcp_f32_e32 v136, v136
	v_rcp_f32_e32 v137, v137
	v_add_u32_e32 v200, 0xb0, v160
	v_pk_mul_f32 v[128:129], v[128:129], v[132:133]
	v_add_u32_e32 v132, s4, v179
	v_pk_mul_f32 v[130:131], v[130:131], v[136:137]
	v_mad_i64_i32 v[132:133], s[8:9], v132, s19, v[148:149]
	v_cvt_pk_bf16_f32 v128, v128, v129
	v_cvt_pk_bf16_f32 v129, v130, v131
	v_cvt_pk_bf16_f32 v130, v142, v143
	v_cvt_pk_bf16_f32 v131, v140, v141
	v_lshl_add_u64 v[132:133], v[132:133], 0, v[150:151]
	global_store_dwordx4 v[132:133], v[128:131], off
	v_mov_b32_e32 v201, v167
	s_nop 0
	v_lshl_add_u32 v128, v200, 3, s67
	ds_read_b64 v[128:129], v128
	s_waitcnt lgkmcnt(0)
	v_pk_mul_f32 v[144:145], v[128:129], s[96:97] op_sel_hi:[1,0]
	v_fma_f32 v128, -v144, v144, v145
	v_max_f32_e32 v128, 0, v128
	v_add_f32_e32 v128, 0x3727c5ac, v128
	v_rsq_f32_e32 v160, v128
	ds_read_b128 v[128:131], v201 offset:2048
	ds_read_b128 v[132:135], v201 offset:2560
	ds_read_b128 v[136:139], v201 offset:2064
	ds_read_b128 v[140:143], v201 offset:2576
	v_mul_f32_e64 v180, v160, -v144
	s_waitcnt lgkmcnt(0)
	v_pk_fma_f32 v[128:129], v[128:129], v[180:181], v[132:133] op_sel_hi:[1,0,1]
	v_pk_fma_f32 v[130:131], v[130:131], v[180:181], v[134:135] op_sel_hi:[1,0,1]
	v_pk_fma_f32 v[132:133], v[136:137], v[180:181], v[140:141] op_sel_hi:[1,0,1]
	ds_read_b128 v[144:147], v201 offset:3072
	ds_read_b128 v[152:155], v201 offset:3584
	v_pk_fma_f32 v[134:135], v[138:139], v[180:181], v[142:143] op_sel_hi:[1,0,1]
	ds_read_b128 v[136:139], v201 offset:3088
	ds_read_b128 v[140:143], v201 offset:3600
	v_pk_fma_f32 v[128:129], v[36:37], v[160:161], v[128:129] op_sel_hi:[1,0,1]
	v_pk_fma_f32 v[130:131], v[38:39], v[160:161], v[130:131] op_sel_hi:[1,0,1]
	s_waitcnt lgkmcnt(0)
	v_pk_fma_f32 v[152:153], v[144:145], v[180:181], v[152:153] op_sel_hi:[1,0,1]
	v_pk_fma_f32 v[144:145], v[146:147], v[180:181], v[154:155] op_sel_hi:[1,0,1]
	v_pk_fma_f32 v[136:137], v[136:137], v[180:181], v[140:141] op_sel_hi:[1,0,1]
	v_pk_fma_f32 v[188:189], v[6:7], v[160:161], v[144:145] op_sel_hi:[1,0,1]
	v_pk_fma_f32 v[144:145], v[0:1], v[160:161], v[136:137] op_sel_hi:[1,0,1]
	v_pk_fma_f32 v[136:137], v[138:139], v[180:181], v[142:143] op_sel_hi:[1,0,1]
	v_pk_fma_f32 v[180:181], v[4:5], v[160:161], v[152:153] op_sel_hi:[1,0,1]
	v_pk_fma_f32 v[146:147], v[2:3], v[160:161], v[136:137] op_sel_hi:[1,0,1]
	ds_read_b128 v[140:143], v201 offset:1024
	v_mov_b32_dpp v136, v128 row_ror:1 row_mask:0xf bank_mask:0xf
	v_mov_b32_dpp v137, v129 row_ror:1 row_mask:0xf bank_mask:0xf
	v_cndmask_b32_e64 v191, v137, v218, s[42:43]
	v_cndmask_b32_e64 v190, v136, v217, s[42:43]
	ds_read_b128 v[152:155], v201
	ds_read_b128 v[184:187], v201 offset:1536
	ds_read_b128 v[194:197], v201 offset:512
	ds_read_b128 v[136:139], v201 offset:16
	v_mov_b32_dpp v179, v128 row_ror:2 row_mask:0xf bank_mask:0xf
	v_mov_b32_dpp v198, v129 row_ror:2 row_mask:0xf bank_mask:0xf
	v_mov_b32_dpp v204, v130 row_ror:2 row_mask:0xf bank_mask:0xf
	v_mov_b32_dpp v205, v131 row_ror:2 row_mask:0xf bank_mask:0xf
	v_cndmask_b32_e32 v199, v219, v198, vcc
	v_cndmask_b32_e32 v198, v177, v179, vcc
	v_mov_b32_dpp v202, v130 row_ror:1 row_mask:0xf bank_mask:0xf
	v_mov_b32_dpp v203, v131 row_ror:1 row_mask:0xf bank_mask:0xf
	s_waitcnt lgkmcnt(0)
	v_pk_fma_f32 v[152:153], v[198:199], v[152:153], v[184:185]
	v_cndmask_b32_e32 v179, v178, v205, vcc
	v_cndmask_b32_e32 v178, v173, v204, vcc
	v_pk_fma_f32 v[152:153], v[190:191], v[194:195], v[152:153]
	v_cndmask_b32_e64 v177, v203, v176, s[42:43]
	v_cndmask_b32_e64 v176, v202, v171, s[42:43]
	v_pk_fma_f32 v[154:155], v[178:179], v[154:155], v[186:187]
	v_pk_fma_f32 v[140:141], v[128:129], v[140:141], v[152:153]
	v_pk_fma_f32 v[154:155], v[176:177], v[196:197], v[154:155]
	v_pk_mul_f32 v[152:153], v[140:141], s[20:21] op_sel_hi:[1,0]
	v_pk_fma_f32 v[142:143], v[130:131], v[142:143], v[154:155]
	v_exp_f32_e32 v152, v152
	v_exp_f32_e32 v153, v153
	v_pk_mul_f32 v[154:155], v[142:143], s[20:21] op_sel_hi:[1,0]
	v_pk_mul_f32 v[140:141], v[180:181], v[140:141]
	v_exp_f32_e32 v154, v154
	v_exp_f32_e32 v155, v155
	v_pk_add_f32 v[152:153], v[152:153], 1.0 op_sel_hi:[1,0]
	v_pk_fma_f32 v[132:133], v[32:33], v[160:161], v[132:133] op_sel_hi:[1,0,1]
	v_rcp_f32_e32 v152, v152
	v_rcp_f32_e32 v153, v153
	v_pk_add_f32 v[154:155], v[154:155], 1.0 op_sel_hi:[1,0]
	v_rcp_f32_e32 v154, v154
	v_rcp_f32_e32 v155, v155
	v_pk_mul_f32 v[152:153], v[140:141], v[152:153]
	v_pk_mul_f32 v[140:141], v[188:189], v[142:143]
	v_pk_mul_f32 v[154:155], v[140:141], v[154:155]
	ds_read_b128 v[140:143], v201 offset:1040
	ds_read_b128 v[176:179], v201 offset:1552
	ds_read_b128 v[184:187], v201 offset:528
	v_mov_b32_dpp v207, v133 row_ror:1 row_mask:0xf bank_mask:0xf
	v_mov_b32_dpp v208, v132 row_ror:2 row_mask:0xf bank_mask:0xf
	v_mov_b32_dpp v209, v133 row_ror:2 row_mask:0xf bank_mask:0xf
	v_pk_fma_f32 v[134:135], v[34:35], v[160:161], v[134:135] op_sel_hi:[1,0,1]
	v_mov_b32_dpp v206, v132 row_ror:1 row_mask:0xf bank_mask:0xf
	v_cndmask_b32_e64 v181, v207, v165, s[42:43]
	v_cndmask_b32_e32 v165, v164, v209, vcc
	v_cndmask_b32_e32 v164, v163, v208, vcc
	v_mov_b32_dpp v212, v134 row_ror:2 row_mask:0xf bank_mask:0xf
	v_mov_b32_dpp v213, v135 row_ror:2 row_mask:0xf bank_mask:0xf
	v_cndmask_b32_e64 v180, v206, v162, s[42:43]
	s_waitcnt lgkmcnt(0)
	v_pk_fma_f32 v[136:137], v[164:165], v[136:137], v[176:177]
	v_mov_b32_dpp v210, v134 row_ror:1 row_mask:0xf bank_mask:0xf
	v_mov_b32_dpp v211, v135 row_ror:1 row_mask:0xf bank_mask:0xf
	v_pk_fma_f32 v[136:137], v[180:181], v[184:185], v[136:137]
	v_cndmask_b32_e32 v157, v157, v213, vcc
	v_cndmask_b32_e32 v156, v156, v212, vcc
	v_pk_fma_f32 v[136:137], v[132:133], v[140:141], v[136:137]
	v_cndmask_b32_e64 v159, v211, v159, s[42:43]
	v_cndmask_b32_e64 v158, v210, v158, s[42:43]
	v_pk_fma_f32 v[138:139], v[156:157], v[138:139], v[178:179]
	v_pk_mul_f32 v[140:141], v[136:137], s[20:21] op_sel_hi:[1,0]
	v_pk_fma_f32 v[138:139], v[158:159], v[186:187], v[138:139]
	v_exp_f32_e32 v140, v140
	v_exp_f32_e32 v141, v141
	v_pk_fma_f32 v[138:139], v[134:135], v[142:143], v[138:139]
	v_pk_mul_f32 v[136:137], v[144:145], v[136:137]
	v_pk_mul_f32 v[142:143], v[138:139], s[20:21] op_sel_hi:[1,0]
	v_pk_add_f32 v[140:141], v[140:141], 1.0 op_sel_hi:[1,0]
	v_exp_f32_e32 v142, v142
	v_exp_f32_e32 v143, v143
	v_rcp_f32_e32 v140, v140
	v_rcp_f32_e32 v141, v141
	s_mov_b64 s[8:9], 0
	v_pk_add_f32 v[142:143], v[142:143], 1.0 op_sel_hi:[1,0]
	v_pk_mul_f32 v[140:141], v[136:137], v[140:141]
	v_rcp_f32_e32 v142, v142
	v_rcp_f32_e32 v143, v143
	v_pk_mul_f32 v[136:137], v[146:147], v[138:139]
	v_cvt_pk_bf16_f32 v138, v140, v141
	v_add_u32_e32 v140, s4, v200
	v_pk_mul_f32 v[142:143], v[136:137], v[142:143]
	v_mad_i64_i32 v[140:141], s[4:5], v140, s19, v[148:149]
	v_cvt_pk_bf16_f32 v136, v152, v153
	v_cvt_pk_bf16_f32 v137, v154, v155
	v_cvt_pk_bf16_f32 v139, v142, v143
	v_lshl_add_u64 v[140:141], v[140:141], 0, v[150:151]
	s_mov_b64 s[4:5], 0
	global_store_dwordx4 v[140:141], v[136:139], off
	s_and_saveexec_b64 s[22:23], s[24:25]
	s_cbranch_execz .LBB0_1401
	v_readlane_b32 s8, v255, 10
	s_mov_b32 s42, s57
	v_add_u32_e32 v160, -14, v169
	s_ashr_i32 s57, s56, 31
	v_readlane_b32 s9, v255, 11
	v_lshl_add_u64 v[136:137], s[56:57], 1, v[160:161]
	s_movk_i32 s19, 0x2c00
	v_mov_b64_e32 v[138:139], s[8:9]
	v_mad_u64_u32 v[138:139], s[8:9], v136, s19, v[138:139]
	v_mad_i32_i24 v139, v137, s19, v139
	v_lshl_add_u64 v[136:137], v[174:175], 2, v[138:139]
	s_cmp_eq_u32 s18, 7
	s_mov_b64 s[24:25], 0
	global_store_dwordx4 v[136:137], v[128:131], off
	global_store_dwordx4 v[136:137], v[132:135], off offset:16
	s_cbranch_scc0 .LBB0_1400
	s_ashr_i32 s8, s56, 3
	s_ashr_i32 s9, s8, 31
	s_mov_b64 s[24:25], -1

.LBB0_1402:
	s_lshl_b32 s23, s73, 6
	v_or_b32_e32 v162, s23, v169
	v_mov_b32_e32 v160, v167
	v_lshl_add_u32 v128, v162, 3, s67
	ds_read_b64 v[128:129], v128
	s_lshl_b32 s22, s56, 8
	s_add_i32 s23, s23, s22
	s_add_i32 s4, s23, 0xffff0000
	s_ashr_i32 s4, s4, 4
	s_waitcnt lgkmcnt(0)
	v_pk_mul_f32 v[144:145], v[128:129], s[96:97] op_sel_hi:[1,0]
	s_mul_i32 s8, s4, 0x5800
	v_fma_f32 v128, -v144, v144, v145
	v_max_f32_e32 v128, 0, v128
	v_add_f32_e32 v128, 0x3727c5ac, v128
	v_rsq_f32_e32 v152, v128
	ds_read_b128 v[128:131], v160 offset:2048
	ds_read_b128 v[132:135], v160 offset:2064
	ds_read_b128 v[136:139], v160 offset:2560
	ds_read_b128 v[140:143], v160 offset:2576
	s_mul_hi_i32 s5, s4, 0x5800
	s_add_u32 s8, s51, s8
	v_mul_f32_e64 v154, v152, -v144
	s_waitcnt lgkmcnt(0)
	v_pk_fma_f32 v[128:129], v[128:129], v[154:155], v[136:137] op_sel_hi:[1,0,1]
	v_pk_fma_f32 v[130:131], v[130:131], v[154:155], v[138:139] op_sel_hi:[1,0,1]
	v_pk_fma_f32 v[132:133], v[132:133], v[154:155], v[140:141] op_sel_hi:[1,0,1]
	v_pk_fma_f32 v[134:135], v[134:135], v[154:155], v[142:143] op_sel_hi:[1,0,1]
	ds_read_b128 v[136:139], v160 offset:3072
	ds_read_b128 v[144:147], v160 offset:3088
	ds_read_b128 v[140:143], v160 offset:3584
	ds_read_b128 v[148:151], v160 offset:3600
	v_ashrrev_i32_e32 v175, 31, v174
	s_addc_u32 s9, s83, s5
	v_pk_fma_f32 v[128:129], v[124:125], v[152:153], v[128:129] op_sel_hi:[1,0,1]
	s_waitcnt lgkmcnt(0)
	v_pk_fma_f32 v[140:141], v[136:137], v[154:155], v[140:141] op_sel_hi:[1,0,1]
	v_pk_fma_f32 v[136:137], v[138:139], v[154:155], v[142:143] op_sel_hi:[1,0,1]
	v_pk_fma_f32 v[138:139], v[146:147], v[154:155], v[150:151] op_sel_hi:[1,0,1]
	v_pk_fma_f32 v[142:143], v[94:95], v[152:153], v[136:137] op_sel_hi:[1,0,1]
	v_pk_fma_f32 v[136:137], v[144:145], v[154:155], v[148:149] op_sel_hi:[1,0,1]
	v_pk_fma_f32 v[130:131], v[126:127], v[152:153], v[130:131] op_sel_hi:[1,0,1]
	v_pk_fma_f32 v[132:133], v[120:121], v[152:153], v[132:133] op_sel_hi:[1,0,1]
	v_pk_fma_f32 v[134:135], v[122:123], v[152:153], v[134:135] op_sel_hi:[1,0,1]
	v_pk_fma_f32 v[136:137], v[88:89], v[152:153], v[136:137] op_sel_hi:[1,0,1]
	v_pk_fma_f32 v[138:139], v[90:91], v[152:153], v[138:139] op_sel_hi:[1,0,1]
	v_pk_fma_f32 v[140:141], v[92:93], v[152:153], v[140:141] op_sel_hi:[1,0,1]
	v_lshl_add_u64 v[152:153], v[174:175], 2, s[8:9]
	global_load_dwordx4 v[144:147], v[152:153], off offset:16
	global_load_dwordx4 v[148:151], v[152:153], off
	v_lshl_add_u64 v[156:157], v[152:153], 0, s[34:35]
	v_add_co_u32_e64 v152, s[48:49], s33, v152
	v_cmp_eq_u32_e64 s[42:43], 1, v169
	s_nop 0
	v_addc_co_u32_e64 v153, s[48:49], 0, v153, s[48:49]
	global_load_dwordx4 v[152:155], v[152:153], off offset:3072
	s_nop 0
	global_load_dwordx4 v[156:159], v[156:157], off offset:16
	v_cmp_lt_u32_e32 vcc, 1, v169
	v_mov_b32_dpp v179, v128 row_ror:2 row_mask:0xf bank_mask:0xf
	v_mov_b32_dpp v185, v129 row_ror:2 row_mask:0xf bank_mask:0xf
	v_mov_b32_dpp v164, v132 row_ror:2 row_mask:0xf bank_mask:0xf
	v_mov_b32_dpp v177, v133 row_ror:2 row_mask:0xf bank_mask:0xf
	v_cmp_eq_u32_e64 s[44:45], 0, v169
	v_mov_b32_dpp v187, v128 row_ror:1 row_mask:0xf bank_mask:0xf
	v_mov_b32_dpp v188, v129 row_ror:1 row_mask:0xf bank_mask:0xf
	v_mov_b32_dpp v180, v130 row_ror:1 row_mask:0xf bank_mask:0xf
	v_mov_b32_dpp v186, v131 row_ror:1 row_mask:0xf bank_mask:0xf
	v_mov_b32_dpp v173, v130 row_ror:2 row_mask:0xf bank_mask:0xf
	v_mov_b32_dpp v181, v131 row_ror:2 row_mask:0xf bank_mask:0xf
	v_mov_b32_dpp v176, v132 row_ror:1 row_mask:0xf bank_mask:0xf
	v_mov_b32_dpp v184, v133 row_ror:1 row_mask:0xf bank_mask:0xf
	v_mov_b32_dpp v165, v134 row_ror:1 row_mask:0xf bank_mask:0xf
	v_mov_b32_dpp v178, v135 row_ror:1 row_mask:0xf bank_mask:0xf
	v_mov_b32_dpp v163, v134 row_ror:2 row_mask:0xf bank_mask:0xf
	v_mov_b32_dpp v171, v135 row_ror:2 row_mask:0xf bank_mask:0xf
	s_movk_i32 s5, 0x1600
	s_cmp_eq_u32 s73, 0
	v_cmp_gt_u32_e64 s[46:47], 2, v169
	s_waitcnt vmcnt(0)
	v_cndmask_b32_e64 v148, v148, v152, s[42:43]
	v_cndmask_b32_e64 v149, v149, v153, s[42:43]
	v_cndmask_b32_e64 v144, v144, v156, s[42:43]
	v_cndmask_b32_e64 v145, v145, v157, s[42:43]
	v_cndmask_b32_e32 v191, v149, v185, vcc
	v_cndmask_b32_e32 v190, v148, v179, vcc
	v_cndmask_b32_e64 v148, v150, v154, s[42:43]
	v_cndmask_b32_e64 v149, v151, v155, s[42:43]
	v_cndmask_b32_e32 v207, v145, v177, vcc
	v_cndmask_b32_e32 v206, v144, v164, vcc
	v_cndmask_b32_e64 v144, v146, v158, s[42:43]
	v_cndmask_b32_e64 v145, v147, v159, s[42:43]
	v_cndmask_b32_e64 v189, v188, v153, s[44:45]
	v_cndmask_b32_e64 v188, v187, v152, s[44:45]
	v_cndmask_b32_e64 v203, v186, v155, s[44:45]
	v_cndmask_b32_e64 v202, v180, v154, s[44:45]
	v_cndmask_b32_e32 v181, v149, v181, vcc
	v_cndmask_b32_e32 v180, v148, v173, vcc
	v_cndmask_b32_e64 v205, v184, v157, s[44:45]
	v_cndmask_b32_e64 v204, v176, v156, s[44:45]
	v_cndmask_b32_e64 v209, v178, v159, s[44:45]
	v_cndmask_b32_e64 v208, v165, v158, s[44:45]
	v_cndmask_b32_e32 v165, v145, v171, vcc
	v_cndmask_b32_e32 v164, v144, v163, vcc
	ds_read_b128 v[144:147], v160
	ds_read_b128 v[148:151], v160 offset:16
	ds_read_b128 v[152:155], v160 offset:512
	ds_read_b128 v[156:159], v160 offset:528
	ds_read_b128 v[176:179], v160 offset:1024
	ds_read_b128 v[184:187], v160 offset:1040
	ds_read_b128 v[194:197], v160 offset:1536
	ds_read_b128 v[198:201], v160 offset:1552
	s_waitcnt lgkmcnt(1)
	v_pk_fma_f32 v[144:145], v[144:145], v[190:191], v[194:195]
	s_nop 0
	v_pk_fma_f32 v[144:145], v[188:189], v[152:153], v[144:145]
	v_pk_fma_f32 v[146:147], v[146:147], v[180:181], v[196:197]
	v_pk_fma_f32 v[144:145], v[128:129], v[176:177], v[144:145]
	v_pk_fma_f32 v[146:147], v[202:203], v[154:155], v[146:147]
	v_pk_mul_f32 v[152:153], v[144:145], s[20:21] op_sel_hi:[1,0]
	v_pk_mul_f32 v[144:145], v[140:141], v[144:145]
	v_exp_f32_e32 v152, v152
	v_exp_f32_e32 v153, v153
	v_pk_fma_f32 v[146:147], v[130:131], v[178:179], v[146:147]
	s_waitcnt lgkmcnt(0)
	v_pk_fma_f32 v[148:149], v[148:149], v[206:207], v[198:199]
	v_pk_fma_f32 v[150:151], v[150:151], v[164:165], v[200:201]
	v_pk_add_f32 v[152:153], v[152:153], 1.0 op_sel_hi:[1,0]
	v_pk_fma_f32 v[148:149], v[204:205], v[156:157], v[148:149]
	v_rcp_f32_e32 v152, v152
	v_rcp_f32_e32 v153, v153
	v_pk_fma_f32 v[148:149], v[132:133], v[184:185], v[148:149]
	v_pk_fma_f32 v[150:151], v[208:209], v[158:159], v[150:151]
	v_pk_mul_f32 v[144:145], v[144:145], v[152:153]
	v_pk_mul_f32 v[152:153], v[146:147], s[20:21] op_sel_hi:[1,0]
	v_pk_mul_f32 v[146:147], v[142:143], v[146:147]
	v_exp_f32_e32 v152, v152
	v_exp_f32_e32 v153, v153
	v_pk_fma_f32 v[150:151], v[134:135], v[186:187], v[150:151]
	v_cvt_pk_bf16_f32 v144, v144, v145
	v_pk_add_f32 v[152:153], v[152:153], 1.0 op_sel_hi:[1,0]
	s_nop 0
	v_rcp_f32_e32 v152, v152
	v_rcp_f32_e32 v153, v153
	s_nop 0
	v_pk_mul_f32 v[146:147], v[146:147], v[152:153]
	v_pk_mul_f32 v[152:153], v[148:149], s[20:21] op_sel_hi:[1,0]
	v_pk_mul_f32 v[148:149], v[136:137], v[148:149]
	v_exp_f32_e32 v152, v152
	v_exp_f32_e32 v153, v153
	v_cvt_pk_bf16_f32 v145, v146, v147
	v_pk_add_f32 v[152:153], v[152:153], 1.0 op_sel_hi:[1,0]
	s_nop 0
	v_rcp_f32_e32 v152, v152
	v_rcp_f32_e32 v153, v153
	s_nop 0
	v_pk_mul_f32 v[148:149], v[148:149], v[152:153]
	v_pk_mul_f32 v[152:153], v[150:151], s[20:21] op_sel_hi:[1,0]
	v_pk_mul_f32 v[150:151], v[138:139], v[150:151]
	v_exp_f32_e32 v152, v152
	v_exp_f32_e32 v153, v153
	v_cvt_pk_bf16_f32 v146, v148, v149
	v_mov_b64_e32 v[148:149], s[60:61]
	v_pk_add_f32 v[152:153], v[152:153], 1.0 op_sel_hi:[1,0]
	s_nop 0
	v_rcp_f32_e32 v152, v152
	v_rcp_f32_e32 v153, v153
	s_nop 0
	v_pk_mul_f32 v[150:151], v[150:151], v[152:153]
	s_nop 0
	v_cvt_pk_bf16_f32 v147, v150, v151
	v_add_u32_e32 v150, s22, v162
	v_mad_i64_i32 v[148:149], s[8:9], v150, s5, v[148:149]
	s_cselect_b64 s[8:9], -1, 0
	v_lshl_add_u64 v[148:149], v[174:175], 1, v[148:149]
	s_and_b64 s[18:19], s[8:9], s[46:47]
	global_store_dwordx4 v[148:149], v[144:147], off
	s_and_saveexec_b64 s[8:9], s[18:19]
	s_cbranch_execz .LBB0_1404
	v_readlane_b32 s18, v255, 6
	v_readlane_b32 s19, v255, 7
	v_lshl_or_b32 v150, s56, 1, v169
	s_movk_i32 s5, 0x2c00
	v_mov_b64_e32 v[144:145], s[18:19]
	v_mad_u64_u32 v[144:145], s[18:19], v150, s5, v[144:145]
	v_readlane_b32 s18, v255, 8
	v_readlane_b32 s19, v255, 9
	v_lshlrev_b64 v[146:147], 2, v[174:175]
	v_lshl_add_u64 v[144:145], v[144:145], 0, v[146:147]
	v_mov_b64_e32 v[148:149], s[18:19]
	v_mad_u64_u32 v[148:149], s[18:19], v150, s5, v[148:149]
	v_lshl_add_u64 v[146:147], v[148:149], 0, v[146:147]
	global_store_dwordx4 v[144:145], v[128:131], off
	global_store_dwordx4 v[144:145], v[132:135], off offset:16
	global_store_dwordx4 v[146:147], v[140:143], off
	global_store_dwordx4 v[146:147], v[136:139], off offset:16

.LBB0_1406:
	s_or_b64 exec, exec, s[8:9]
	v_or_b32_e32 v163, 16, v162
	v_mov_b32_e32 v164, v167
	v_lshl_add_u32 v128, v163, 3, s67
	ds_read_b64 v[128:129], v128
	s_add_i32 s4, s23, 0xffff0010
	s_ashr_i32 s4, s4, 4
	s_mul_i32 s8, s4, 0x5800
	s_mul_hi_i32 s5, s4, 0x5800
	s_waitcnt lgkmcnt(0)
	v_pk_mul_f32 v[144:145], v[128:129], s[96:97] op_sel_hi:[1,0]
	s_add_u32 s8, s51, s8
	v_fma_f32 v128, -v144, v144, v145
	v_max_f32_e32 v128, 0, v128
	v_add_f32_e32 v128, 0x3727c5ac, v128
	v_rsq_f32_e32 v158, v128
	ds_read_b128 v[128:131], v164 offset:2048
	ds_read_b128 v[136:139], v164 offset:2064
	ds_read_b128 v[132:135], v164 offset:2560
	ds_read_b128 v[140:143], v164 offset:2576
	s_addc_u32 s9, s83, s5
	v_mul_f32_e64 v152, v158, -v144
	s_waitcnt lgkmcnt(1)
	v_pk_fma_f32 v[128:129], v[128:129], v[152:153], v[132:133] op_sel_hi:[1,0,1]
	v_pk_fma_f32 v[132:133], v[116:117], v[158:159], v[128:129] op_sel_hi:[1,0,1]
	v_pk_fma_f32 v[128:129], v[130:131], v[152:153], v[134:135] op_sel_hi:[1,0,1]
	s_waitcnt lgkmcnt(0)
	v_pk_fma_f32 v[130:131], v[138:139], v[152:153], v[142:143] op_sel_hi:[1,0,1]
	v_pk_fma_f32 v[134:135], v[118:119], v[158:159], v[128:129] op_sel_hi:[1,0,1]
	v_pk_fma_f32 v[128:129], v[136:137], v[152:153], v[140:141] op_sel_hi:[1,0,1]
	ds_read_b128 v[136:139], v164 offset:3072
	ds_read_b128 v[140:143], v164 offset:3088
	ds_read_b128 v[144:147], v164 offset:3584
	ds_read_b128 v[148:151], v164 offset:3600
	v_pk_fma_f32 v[128:129], v[112:113], v[158:159], v[128:129] op_sel_hi:[1,0,1]
	v_pk_fma_f32 v[130:131], v[114:115], v[158:159], v[130:131] op_sel_hi:[1,0,1]
	s_waitcnt lgkmcnt(1)
	v_pk_fma_f32 v[138:139], v[138:139], v[152:153], v[146:147] op_sel_hi:[1,0,1]
	v_pk_fma_f32 v[136:137], v[136:137], v[152:153], v[144:145] op_sel_hi:[1,0,1]
	v_pk_fma_f32 v[156:157], v[86:87], v[158:159], v[138:139] op_sel_hi:[1,0,1]
	s_waitcnt lgkmcnt(0)
	v_pk_fma_f32 v[138:139], v[140:141], v[152:153], v[148:149] op_sel_hi:[1,0,1]
	v_lshl_add_u64 v[144:145], v[174:175], 2, s[8:9]
	v_pk_fma_f32 v[154:155], v[80:81], v[158:159], v[138:139] op_sel_hi:[1,0,1]
	v_pk_fma_f32 v[138:139], v[142:143], v[152:153], v[150:151] op_sel_hi:[1,0,1]
	v_lshl_add_u64 v[146:147], v[144:145], 0, s[34:35]
	v_pk_fma_f32 v[152:153], v[82:83], v[158:159], v[138:139] op_sel_hi:[1,0,1]
	v_pk_fma_f32 v[158:159], v[84:85], v[158:159], v[136:137] op_sel_hi:[1,0,1]
	global_load_dwordx4 v[136:139], v[144:145], off offset:16
	global_load_dwordx4 v[140:143], v[144:145], off
	v_add_co_u32_e64 v144, s[46:47], s33, v144
	s_nop 0
	s_nop 0
	v_addc_co_u32_e64 v145, s[46:47], 0, v145, s[46:47]
	global_load_dwordx4 v[148:151], v[144:145], off offset:3072
	s_nop 0
	global_load_dwordx4 v[144:147], v[146:147], off offset:16
	v_mov_b32_dpp v189, v133 row_ror:1 row_mask:0xf bank_mask:0xf
	v_mov_b32_dpp v185, v132 row_ror:2 row_mask:0xf bank_mask:0xf
	v_mov_b32_dpp v188, v133 row_ror:2 row_mask:0xf bank_mask:0xf
	v_mov_b32_dpp v169, v128 row_ror:2 row_mask:0xf bank_mask:0xf
	v_mov_b32_dpp v178, v129 row_ror:2 row_mask:0xf bank_mask:0xf
	v_mov_b32_dpp v187, v132 row_ror:1 row_mask:0xf bank_mask:0xf
	v_mov_b32_dpp v180, v134 row_ror:1 row_mask:0xf bank_mask:0xf
	v_mov_b32_dpp v186, v135 row_ror:1 row_mask:0xf bank_mask:0xf
	v_mov_b32_dpp v176, v134 row_ror:2 row_mask:0xf bank_mask:0xf
	v_mov_b32_dpp v181, v135 row_ror:2 row_mask:0xf bank_mask:0xf
	v_mov_b32_dpp v177, v128 row_ror:1 row_mask:0xf bank_mask:0xf
	v_mov_b32_dpp v184, v129 row_ror:1 row_mask:0xf bank_mask:0xf
	v_mov_b32_dpp v171, v130 row_ror:1 row_mask:0xf bank_mask:0xf
	v_mov_b32_dpp v179, v131 row_ror:1 row_mask:0xf bank_mask:0xf
	v_mov_b32_dpp v165, v130 row_ror:2 row_mask:0xf bank_mask:0xf
	v_mov_b32_dpp v173, v131 row_ror:2 row_mask:0xf bank_mask:0xf
	s_movk_i32 s5, 0x1600
	s_waitcnt vmcnt(1)
	v_cndmask_b32_e64 v140, v140, v148, s[42:43]
	v_cndmask_b32_e64 v141, v141, v149, s[42:43]
	s_waitcnt vmcnt(0)
	v_cndmask_b32_e64 v136, v136, v144, s[42:43]
	v_cndmask_b32_e64 v137, v137, v145, s[42:43]
	v_cndmask_b32_e64 v191, v189, v149, s[44:45]
	v_cndmask_b32_e32 v189, v141, v188, vcc
	v_cndmask_b32_e32 v188, v140, v185, vcc
	v_cndmask_b32_e64 v140, v142, v150, s[42:43]
	v_cndmask_b32_e64 v141, v143, v151, s[42:43]
	v_cndmask_b32_e32 v207, v137, v178, vcc
	v_cndmask_b32_e32 v206, v136, v169, vcc
	v_cndmask_b32_e64 v136, v138, v146, s[42:43]
	v_cndmask_b32_e64 v137, v139, v147, s[42:43]
	v_cndmask_b32_e64 v190, v187, v148, s[44:45]
	v_cndmask_b32_e64 v203, v186, v151, s[44:45]
	v_cndmask_b32_e64 v202, v180, v150, s[44:45]
	v_cndmask_b32_e32 v181, v141, v181, vcc
	v_cndmask_b32_e32 v180, v140, v176, vcc
	v_cndmask_b32_e64 v205, v184, v145, s[44:45]
	v_cndmask_b32_e64 v204, v177, v144, s[44:45]
	v_cndmask_b32_e64 v209, v179, v147, s[44:45]
	v_cndmask_b32_e64 v208, v171, v146, s[44:45]
	v_cndmask_b32_e32 v211, v137, v173, vcc
	v_cndmask_b32_e32 v210, v136, v165, vcc
	ds_read_b128 v[136:139], v164
	ds_read_b128 v[140:143], v164 offset:16
	ds_read_b128 v[144:147], v164 offset:512
	ds_read_b128 v[148:151], v164 offset:528
	ds_read_b128 v[176:179], v164 offset:1024
	ds_read_b128 v[184:187], v164 offset:1040
	ds_read_b128 v[194:197], v164 offset:1536
	ds_read_b128 v[198:201], v164 offset:1552
	s_waitcnt lgkmcnt(1)
	v_pk_fma_f32 v[136:137], v[136:137], v[188:189], v[194:195]
	s_nop 0
	v_pk_fma_f32 v[136:137], v[190:191], v[144:145], v[136:137]
	v_pk_fma_f32 v[138:139], v[138:139], v[180:181], v[196:197]
	v_pk_fma_f32 v[136:137], v[132:133], v[176:177], v[136:137]
	v_pk_fma_f32 v[138:139], v[202:203], v[146:147], v[138:139]
	v_pk_mul_f32 v[144:145], v[136:137], s[20:21] op_sel_hi:[1,0]
	v_pk_mul_f32 v[136:137], v[158:159], v[136:137]
	v_exp_f32_e32 v144, v144
	v_exp_f32_e32 v145, v145
	v_pk_fma_f32 v[138:139], v[134:135], v[178:179], v[138:139]
	s_waitcnt lgkmcnt(0)
	v_pk_fma_f32 v[140:141], v[140:141], v[206:207], v[198:199]
	v_pk_fma_f32 v[142:143], v[142:143], v[210:211], v[200:201]
	v_pk_add_f32 v[144:145], v[144:145], 1.0 op_sel_hi:[1,0]
	v_pk_fma_f32 v[140:141], v[204:205], v[148:149], v[140:141]
	v_rcp_f32_e32 v144, v144
	v_rcp_f32_e32 v145, v145
	v_pk_fma_f32 v[140:141], v[128:129], v[184:185], v[140:141]
	v_pk_fma_f32 v[142:143], v[208:209], v[150:151], v[142:143]
	v_pk_mul_f32 v[136:137], v[136:137], v[144:145]
	v_pk_mul_f32 v[144:145], v[138:139], s[20:21] op_sel_hi:[1,0]
	v_pk_mul_f32 v[138:139], v[156:157], v[138:139]
	v_exp_f32_e32 v144, v144
	v_exp_f32_e32 v145, v145
	v_pk_fma_f32 v[142:143], v[130:131], v[186:187], v[142:143]
	v_cvt_pk_bf16_f32 v136, v136, v137
	v_pk_add_f32 v[144:145], v[144:145], 1.0 op_sel_hi:[1,0]
	s_nop 0
	v_rcp_f32_e32 v144, v144
	v_rcp_f32_e32 v145, v145
	s_nop 0
	v_pk_mul_f32 v[138:139], v[138:139], v[144:145]
	v_pk_mul_f32 v[144:145], v[140:141], s[20:21] op_sel_hi:[1,0]
	v_pk_mul_f32 v[140:141], v[154:155], v[140:141]
	v_exp_f32_e32 v144, v144
	v_exp_f32_e32 v145, v145
	v_cvt_pk_bf16_f32 v137, v138, v139
	v_pk_add_f32 v[144:145], v[144:145], 1.0 op_sel_hi:[1,0]
	s_nop 0
	v_rcp_f32_e32 v144, v144
	v_rcp_f32_e32 v145, v145
	s_nop 0
	v_pk_mul_f32 v[140:141], v[140:141], v[144:145]
	v_pk_mul_f32 v[144:145], v[142:143], s[20:21] op_sel_hi:[1,0]
	v_pk_mul_f32 v[142:143], v[152:153], v[142:143]
	v_exp_f32_e32 v144, v144
	v_exp_f32_e32 v145, v145
	v_cvt_pk_bf16_f32 v138, v140, v141
	v_mov_b64_e32 v[140:141], s[60:61]
	v_pk_add_f32 v[144:145], v[144:145], 1.0 op_sel_hi:[1,0]
	s_nop 0
	v_rcp_f32_e32 v144, v144
	v_rcp_f32_e32 v145, v145
	s_nop 0
	v_pk_mul_f32 v[142:143], v[142:143], v[144:145]
	s_nop 0
	v_cvt_pk_bf16_f32 v139, v142, v143
	v_add_u32_e32 v142, s22, v163
	v_mad_i64_i32 v[140:141], s[8:9], v142, s5, v[140:141]
	v_lshl_add_u64 v[140:141], v[174:175], 1, v[140:141]
	global_store_dwordx4 v[140:141], v[136:139], off
	s_and_saveexec_b64 s[8:9], s[86:87]
	s_cbranch_execz .LBB0_1408
	s_ashr_i32 s5, s4, 31
	v_lshl_add_u64 v[136:137], s[4:5], 1, v[160:161]
	v_mov_b64_e32 v[138:139], s[68:69]
	s_movk_i32 s18, 0x2c00
	v_mad_u64_u32 v[138:139], s[4:5], v136, s18, v[138:139]
	v_mad_i32_i24 v139, v137, s18, v139
	v_lshl_add_u64 v[136:137], v[174:175], 2, v[138:139]
	global_store_dwordx4 v[136:137], v[132:135], off
	global_store_dwordx4 v[136:137], v[128:131], off offset:16
.LBB0_1408:
	s_or_b64 exec, exec, s[8:9]
	v_or_b32_e32 v163, 32, v162
	v_mov_b32_e32 v164, v167
	v_lshl_add_u32 v128, v163, 3, s67
	ds_read_b64 v[128:129], v128
	s_add_i32 s4, s23, 0xffff0020
	s_ashr_i32 s4, s4, 4
	s_mul_i32 s8, s4, 0x5800
	s_mul_hi_i32 s5, s4, 0x5800
	s_waitcnt lgkmcnt(0)
	v_pk_mul_f32 v[144:145], v[128:129], s[96:97] op_sel_hi:[1,0]
	s_add_u32 s8, s51, s8
	v_fma_f32 v128, -v144, v144, v145
	v_max_f32_e32 v128, 0, v128
	v_add_f32_e32 v128, 0x3727c5ac, v128
	v_rsq_f32_e32 v158, v128
	ds_read_b128 v[128:131], v164 offset:2048
	ds_read_b128 v[136:139], v164 offset:2064
	ds_read_b128 v[132:135], v164 offset:2560
	ds_read_b128 v[140:143], v164 offset:2576
	s_addc_u32 s9, s83, s5
	v_mul_f32_e64 v152, v158, -v144
	s_waitcnt lgkmcnt(1)
	v_pk_fma_f32 v[128:129], v[128:129], v[152:153], v[132:133] op_sel_hi:[1,0,1]
	v_pk_fma_f32 v[132:133], v[108:109], v[158:159], v[128:129] op_sel_hi:[1,0,1]
	v_pk_fma_f32 v[128:129], v[130:131], v[152:153], v[134:135] op_sel_hi:[1,0,1]
	s_waitcnt lgkmcnt(0)
	v_pk_fma_f32 v[130:131], v[138:139], v[152:153], v[142:143] op_sel_hi:[1,0,1]
	v_pk_fma_f32 v[134:135], v[110:111], v[158:159], v[128:129] op_sel_hi:[1,0,1]
	v_pk_fma_f32 v[128:129], v[136:137], v[152:153], v[140:141] op_sel_hi:[1,0,1]
	ds_read_b128 v[136:139], v164 offset:3072
	ds_read_b128 v[140:143], v164 offset:3088
	ds_read_b128 v[144:147], v164 offset:3584
	ds_read_b128 v[148:151], v164 offset:3600
	v_pk_fma_f32 v[128:129], v[104:105], v[158:159], v[128:129] op_sel_hi:[1,0,1]
	v_pk_fma_f32 v[130:131], v[106:107], v[158:159], v[130:131] op_sel_hi:[1,0,1]
	s_waitcnt lgkmcnt(1)
	v_pk_fma_f32 v[138:139], v[138:139], v[152:153], v[146:147] op_sel_hi:[1,0,1]
	v_pk_fma_f32 v[136:137], v[136:137], v[152:153], v[144:145] op_sel_hi:[1,0,1]
	v_pk_fma_f32 v[156:157], v[78:79], v[158:159], v[138:139] op_sel_hi:[1,0,1]
	s_waitcnt lgkmcnt(0)
	v_pk_fma_f32 v[138:139], v[140:141], v[152:153], v[148:149] op_sel_hi:[1,0,1]
	v_lshl_add_u64 v[144:145], v[174:175], 2, s[8:9]
	v_pk_fma_f32 v[154:155], v[72:73], v[158:159], v[138:139] op_sel_hi:[1,0,1]
	v_pk_fma_f32 v[138:139], v[142:143], v[152:153], v[150:151] op_sel_hi:[1,0,1]
	v_lshl_add_u64 v[146:147], v[144:145], 0, s[34:35]
	v_pk_fma_f32 v[152:153], v[74:75], v[158:159], v[138:139] op_sel_hi:[1,0,1]
	v_pk_fma_f32 v[158:159], v[76:77], v[158:159], v[136:137] op_sel_hi:[1,0,1]
	global_load_dwordx4 v[136:139], v[144:145], off offset:16
	global_load_dwordx4 v[140:143], v[144:145], off
	v_add_co_u32_e64 v144, s[46:47], s33, v144
	s_nop 0
	s_nop 0
	v_addc_co_u32_e64 v145, s[46:47], 0, v145, s[46:47]
	global_load_dwordx4 v[148:151], v[144:145], off offset:3072
	s_nop 0
	global_load_dwordx4 v[144:147], v[146:147], off offset:16
	v_mov_b32_dpp v189, v133 row_ror:1 row_mask:0xf bank_mask:0xf
	v_mov_b32_dpp v185, v132 row_ror:2 row_mask:0xf bank_mask:0xf
	v_mov_b32_dpp v188, v133 row_ror:2 row_mask:0xf bank_mask:0xf
	v_mov_b32_dpp v169, v128 row_ror:2 row_mask:0xf bank_mask:0xf
	v_mov_b32_dpp v178, v129 row_ror:2 row_mask:0xf bank_mask:0xf
	v_mov_b32_dpp v187, v132 row_ror:1 row_mask:0xf bank_mask:0xf
	v_mov_b32_dpp v180, v134 row_ror:1 row_mask:0xf bank_mask:0xf
	v_mov_b32_dpp v186, v135 row_ror:1 row_mask:0xf bank_mask:0xf
	v_mov_b32_dpp v176, v134 row_ror:2 row_mask:0xf bank_mask:0xf
	v_mov_b32_dpp v181, v135 row_ror:2 row_mask:0xf bank_mask:0xf
	v_mov_b32_dpp v177, v128 row_ror:1 row_mask:0xf bank_mask:0xf
	v_mov_b32_dpp v184, v129 row_ror:1 row_mask:0xf bank_mask:0xf
	v_mov_b32_dpp v171, v130 row_ror:1 row_mask:0xf bank_mask:0xf
	v_mov_b32_dpp v179, v131 row_ror:1 row_mask:0xf bank_mask:0xf
	v_mov_b32_dpp v165, v130 row_ror:2 row_mask:0xf bank_mask:0xf
	v_mov_b32_dpp v173, v131 row_ror:2 row_mask:0xf bank_mask:0xf
	s_movk_i32 s5, 0x1600
	s_waitcnt vmcnt(1)
	v_cndmask_b32_e64 v140, v140, v148, s[42:43]
	v_cndmask_b32_e64 v141, v141, v149, s[42:43]
	s_waitcnt vmcnt(0)
	v_cndmask_b32_e64 v136, v136, v144, s[42:43]
	v_cndmask_b32_e64 v137, v137, v145, s[42:43]
	v_cndmask_b32_e64 v191, v189, v149, s[44:45]
	v_cndmask_b32_e32 v189, v141, v188, vcc
	v_cndmask_b32_e32 v188, v140, v185, vcc
	v_cndmask_b32_e64 v140, v142, v150, s[42:43]
	v_cndmask_b32_e64 v141, v143, v151, s[42:43]
	v_cndmask_b32_e32 v207, v137, v178, vcc
	v_cndmask_b32_e32 v206, v136, v169, vcc
	v_cndmask_b32_e64 v136, v138, v146, s[42:43]
	v_cndmask_b32_e64 v137, v139, v147, s[42:43]
	v_cndmask_b32_e64 v190, v187, v148, s[44:45]
	v_cndmask_b32_e64 v203, v186, v151, s[44:45]
	v_cndmask_b32_e64 v202, v180, v150, s[44:45]
	v_cndmask_b32_e32 v181, v141, v181, vcc
	v_cndmask_b32_e32 v180, v140, v176, vcc
	v_cndmask_b32_e64 v205, v184, v145, s[44:45]
	v_cndmask_b32_e64 v204, v177, v144, s[44:45]
	v_cndmask_b32_e64 v209, v179, v147, s[44:45]
	v_cndmask_b32_e64 v208, v171, v146, s[44:45]
	v_cndmask_b32_e32 v211, v137, v173, vcc
	v_cndmask_b32_e32 v210, v136, v165, vcc
	ds_read_b128 v[136:139], v164
	ds_read_b128 v[140:143], v164 offset:16
	ds_read_b128 v[144:147], v164 offset:512
	ds_read_b128 v[148:151], v164 offset:528
	ds_read_b128 v[176:179], v164 offset:1024
	ds_read_b128 v[184:187], v164 offset:1040
	ds_read_b128 v[194:197], v164 offset:1536
	ds_read_b128 v[198:201], v164 offset:1552
	s_waitcnt lgkmcnt(1)
	v_pk_fma_f32 v[136:137], v[136:137], v[188:189], v[194:195]
	s_nop 0
	v_pk_fma_f32 v[136:137], v[190:191], v[144:145], v[136:137]
	v_pk_fma_f32 v[138:139], v[138:139], v[180:181], v[196:197]
	v_pk_fma_f32 v[136:137], v[132:133], v[176:177], v[136:137]
	v_pk_fma_f32 v[138:139], v[202:203], v[146:147], v[138:139]
	v_pk_mul_f32 v[144:145], v[136:137], s[20:21] op_sel_hi:[1,0]
	v_pk_mul_f32 v[136:137], v[158:159], v[136:137]
	v_exp_f32_e32 v144, v144
	v_exp_f32_e32 v145, v145
	v_pk_fma_f32 v[138:139], v[134:135], v[178:179], v[138:139]
	s_waitcnt lgkmcnt(0)
	v_pk_fma_f32 v[140:141], v[140:141], v[206:207], v[198:199]
	v_pk_fma_f32 v[142:143], v[142:143], v[210:211], v[200:201]
	v_pk_add_f32 v[144:145], v[144:145], 1.0 op_sel_hi:[1,0]
	v_pk_fma_f32 v[140:141], v[204:205], v[148:149], v[140:141]
	v_rcp_f32_e32 v144, v144
	v_rcp_f32_e32 v145, v145
	v_pk_fma_f32 v[140:141], v[128:129], v[184:185], v[140:141]
	v_pk_fma_f32 v[142:143], v[208:209], v[150:151], v[142:143]
	v_pk_mul_f32 v[136:137], v[136:137], v[144:145]
	v_pk_mul_f32 v[144:145], v[138:139], s[20:21] op_sel_hi:[1,0]
	v_pk_mul_f32 v[138:139], v[156:157], v[138:139]
	v_exp_f32_e32 v144, v144
	v_exp_f32_e32 v145, v145
	v_pk_fma_f32 v[142:143], v[130:131], v[186:187], v[142:143]
	v_cvt_pk_bf16_f32 v136, v136, v137
	v_pk_add_f32 v[144:145], v[144:145], 1.0 op_sel_hi:[1,0]
	s_nop 0
	v_rcp_f32_e32 v144, v144
	v_rcp_f32_e32 v145, v145
	s_nop 0
	v_pk_mul_f32 v[138:139], v[138:139], v[144:145]
	v_pk_mul_f32 v[144:145], v[140:141], s[20:21] op_sel_hi:[1,0]
	v_pk_mul_f32 v[140:141], v[154:155], v[140:141]
	v_exp_f32_e32 v144, v144
	v_exp_f32_e32 v145, v145
	v_cvt_pk_bf16_f32 v137, v138, v139
	v_pk_add_f32 v[144:145], v[144:145], 1.0 op_sel_hi:[1,0]
	s_nop 0
	v_rcp_f32_e32 v144, v144
	v_rcp_f32_e32 v145, v145
	s_nop 0
	v_pk_mul_f32 v[140:141], v[140:141], v[144:145]
	v_pk_mul_f32 v[144:145], v[142:143], s[20:21] op_sel_hi:[1,0]
	v_pk_mul_f32 v[142:143], v[152:153], v[142:143]
	v_exp_f32_e32 v144, v144
	v_exp_f32_e32 v145, v145
	v_cvt_pk_bf16_f32 v138, v140, v141
	v_mov_b64_e32 v[140:141], s[60:61]
	v_pk_add_f32 v[144:145], v[144:145], 1.0 op_sel_hi:[1,0]
	s_nop 0
	v_rcp_f32_e32 v144, v144
	v_rcp_f32_e32 v145, v145
	s_nop 0
	v_pk_mul_f32 v[142:143], v[142:143], v[144:145]
	s_nop 0
	v_cvt_pk_bf16_f32 v139, v142, v143
	v_add_u32_e32 v142, s22, v163
	v_mad_i64_i32 v[140:141], s[8:9], v142, s5, v[140:141]
	v_lshl_add_u64 v[140:141], v[174:175], 1, v[140:141]
	global_store_dwordx4 v[140:141], v[136:139], off
	s_and_saveexec_b64 s[8:9], s[86:87]
	s_cbranch_execz .LBB0_1410
	s_ashr_i32 s5, s4, 31
	v_lshl_add_u64 v[136:137], s[4:5], 1, v[160:161]
	v_mov_b64_e32 v[138:139], s[68:69]
	s_movk_i32 s18, 0x2c00
	v_mad_u64_u32 v[138:139], s[4:5], v136, s18, v[138:139]
	v_mad_i32_i24 v139, v137, s18, v139
	v_lshl_add_u64 v[136:137], v[174:175], 2, v[138:139]
	global_store_dwordx4 v[136:137], v[132:135], off
	global_store_dwordx4 v[136:137], v[128:131], off offset:16
.LBB0_1410:
	s_or_b64 exec, exec, s[8:9]
	v_or_b32_e32 v163, 48, v162
	v_mov_b32_e32 v164, v167
	v_lshl_add_u32 v128, v163, 3, s67
	ds_read_b64 v[128:129], v128
	s_add_i32 s4, s23, 0xffff0030
	s_ashr_i32 s4, s4, 4
	s_mul_i32 s8, s4, 0x5800
	s_mul_hi_i32 s5, s4, 0x5800
	s_waitcnt lgkmcnt(0)
	v_pk_mul_f32 v[144:145], v[128:129], s[96:97] op_sel_hi:[1,0]
	s_add_u32 s8, s51, s8
	v_fma_f32 v128, -v144, v144, v145
	v_max_f32_e32 v128, 0, v128
	v_add_f32_e32 v128, 0x3727c5ac, v128
	v_rsq_f32_e32 v158, v128
	ds_read_b128 v[128:131], v164 offset:2048
	ds_read_b128 v[136:139], v164 offset:2064
	ds_read_b128 v[132:135], v164 offset:2560
	ds_read_b128 v[140:143], v164 offset:2576
	s_addc_u32 s9, s83, s5
	v_mul_f32_e64 v152, v158, -v144
	s_waitcnt lgkmcnt(1)
	v_pk_fma_f32 v[128:129], v[128:129], v[152:153], v[132:133] op_sel_hi:[1,0,1]
	v_pk_fma_f32 v[132:133], v[100:101], v[158:159], v[128:129] op_sel_hi:[1,0,1]
	v_pk_fma_f32 v[128:129], v[130:131], v[152:153], v[134:135] op_sel_hi:[1,0,1]
	s_waitcnt lgkmcnt(0)
	v_pk_fma_f32 v[130:131], v[138:139], v[152:153], v[142:143] op_sel_hi:[1,0,1]
	v_pk_fma_f32 v[134:135], v[102:103], v[158:159], v[128:129] op_sel_hi:[1,0,1]
	v_pk_fma_f32 v[128:129], v[136:137], v[152:153], v[140:141] op_sel_hi:[1,0,1]
	ds_read_b128 v[136:139], v164 offset:3072
	ds_read_b128 v[140:143], v164 offset:3088
	ds_read_b128 v[144:147], v164 offset:3584
	ds_read_b128 v[148:151], v164 offset:3600
	v_pk_fma_f32 v[128:129], v[96:97], v[158:159], v[128:129] op_sel_hi:[1,0,1]
	v_pk_fma_f32 v[130:131], v[98:99], v[158:159], v[130:131] op_sel_hi:[1,0,1]
	s_waitcnt lgkmcnt(1)
	v_pk_fma_f32 v[138:139], v[138:139], v[152:153], v[146:147] op_sel_hi:[1,0,1]
	v_pk_fma_f32 v[136:137], v[136:137], v[152:153], v[144:145] op_sel_hi:[1,0,1]
	v_pk_fma_f32 v[156:157], v[70:71], v[158:159], v[138:139] op_sel_hi:[1,0,1]
	s_waitcnt lgkmcnt(0)
	v_pk_fma_f32 v[138:139], v[140:141], v[152:153], v[148:149] op_sel_hi:[1,0,1]
	v_lshl_add_u64 v[144:145], v[174:175], 2, s[8:9]
	v_pk_fma_f32 v[154:155], v[64:65], v[158:159], v[138:139] op_sel_hi:[1,0,1]
	v_pk_fma_f32 v[138:139], v[142:143], v[152:153], v[150:151] op_sel_hi:[1,0,1]
	v_lshl_add_u64 v[146:147], v[144:145], 0, s[34:35]
	v_pk_fma_f32 v[152:153], v[66:67], v[158:159], v[138:139] op_sel_hi:[1,0,1]
	v_pk_fma_f32 v[158:159], v[68:69], v[158:159], v[136:137] op_sel_hi:[1,0,1]
	global_load_dwordx4 v[136:139], v[144:145], off offset:16
	global_load_dwordx4 v[140:143], v[144:145], off
	v_add_co_u32_e64 v144, s[46:47], s33, v144
	s_nop 0
	s_nop 0
	v_addc_co_u32_e64 v145, s[46:47], 0, v145, s[46:47]
	global_load_dwordx4 v[148:151], v[144:145], off offset:3072
	s_nop 0
	global_load_dwordx4 v[144:147], v[146:147], off offset:16
	v_mov_b32_dpp v189, v133 row_ror:1 row_mask:0xf bank_mask:0xf
	v_mov_b32_dpp v185, v132 row_ror:2 row_mask:0xf bank_mask:0xf
	v_mov_b32_dpp v188, v133 row_ror:2 row_mask:0xf bank_mask:0xf
	v_mov_b32_dpp v169, v128 row_ror:2 row_mask:0xf bank_mask:0xf
	v_mov_b32_dpp v178, v129 row_ror:2 row_mask:0xf bank_mask:0xf
	v_mov_b32_dpp v187, v132 row_ror:1 row_mask:0xf bank_mask:0xf
	v_mov_b32_dpp v180, v134 row_ror:1 row_mask:0xf bank_mask:0xf
	v_mov_b32_dpp v186, v135 row_ror:1 row_mask:0xf bank_mask:0xf
	v_mov_b32_dpp v176, v134 row_ror:2 row_mask:0xf bank_mask:0xf
	v_mov_b32_dpp v181, v135 row_ror:2 row_mask:0xf bank_mask:0xf
	v_mov_b32_dpp v177, v128 row_ror:1 row_mask:0xf bank_mask:0xf
	v_mov_b32_dpp v184, v129 row_ror:1 row_mask:0xf bank_mask:0xf
	v_mov_b32_dpp v171, v130 row_ror:1 row_mask:0xf bank_mask:0xf
	v_mov_b32_dpp v179, v131 row_ror:1 row_mask:0xf bank_mask:0xf
	v_mov_b32_dpp v165, v130 row_ror:2 row_mask:0xf bank_mask:0xf
	v_mov_b32_dpp v173, v131 row_ror:2 row_mask:0xf bank_mask:0xf
	s_movk_i32 s5, 0x1600
	s_waitcnt vmcnt(1)
	v_cndmask_b32_e64 v140, v140, v148, s[42:43]
	v_cndmask_b32_e64 v141, v141, v149, s[42:43]
	s_waitcnt vmcnt(0)
	v_cndmask_b32_e64 v136, v136, v144, s[42:43]
	v_cndmask_b32_e64 v137, v137, v145, s[42:43]
	v_cndmask_b32_e64 v191, v189, v149, s[44:45]
	v_cndmask_b32_e32 v189, v141, v188, vcc
	v_cndmask_b32_e32 v188, v140, v185, vcc
	v_cndmask_b32_e64 v140, v142, v150, s[42:43]
	v_cndmask_b32_e64 v141, v143, v151, s[42:43]
	v_cndmask_b32_e32 v207, v137, v178, vcc
	v_cndmask_b32_e32 v206, v136, v169, vcc
	v_cndmask_b32_e64 v136, v138, v146, s[42:43]
	v_cndmask_b32_e64 v137, v139, v147, s[42:43]
	v_cndmask_b32_e64 v190, v187, v148, s[44:45]
	v_cndmask_b32_e64 v203, v186, v151, s[44:45]
	v_cndmask_b32_e64 v202, v180, v150, s[44:45]
	v_cndmask_b32_e32 v181, v141, v181, vcc
	v_cndmask_b32_e32 v180, v140, v176, vcc
	v_cndmask_b32_e64 v205, v184, v145, s[44:45]
	v_cndmask_b32_e64 v204, v177, v144, s[44:45]
	v_cndmask_b32_e64 v209, v179, v147, s[44:45]
	v_cndmask_b32_e64 v208, v171, v146, s[44:45]
	v_cndmask_b32_e32 v211, v137, v173, vcc
	v_cndmask_b32_e32 v210, v136, v165, vcc
	ds_read_b128 v[136:139], v164
	ds_read_b128 v[140:143], v164 offset:16
	ds_read_b128 v[144:147], v164 offset:512
	ds_read_b128 v[148:151], v164 offset:528
	ds_read_b128 v[176:179], v164 offset:1024
	ds_read_b128 v[184:187], v164 offset:1040
	ds_read_b128 v[194:197], v164 offset:1536
	ds_read_b128 v[198:201], v164 offset:1552
	s_waitcnt lgkmcnt(1)
	v_pk_fma_f32 v[136:137], v[136:137], v[188:189], v[194:195]
	s_nop 0
	v_pk_fma_f32 v[136:137], v[190:191], v[144:145], v[136:137]
	v_pk_fma_f32 v[138:139], v[138:139], v[180:181], v[196:197]
	v_pk_fma_f32 v[136:137], v[132:133], v[176:177], v[136:137]
	v_pk_fma_f32 v[138:139], v[202:203], v[146:147], v[138:139]
	v_pk_mul_f32 v[144:145], v[136:137], s[20:21] op_sel_hi:[1,0]
	v_pk_mul_f32 v[136:137], v[158:159], v[136:137]
	v_exp_f32_e32 v144, v144
	v_exp_f32_e32 v145, v145
	v_pk_fma_f32 v[138:139], v[134:135], v[178:179], v[138:139]
	s_waitcnt lgkmcnt(0)
	v_pk_fma_f32 v[140:141], v[140:141], v[206:207], v[198:199]
	v_pk_fma_f32 v[142:143], v[142:143], v[210:211], v[200:201]
	v_pk_add_f32 v[144:145], v[144:145], 1.0 op_sel_hi:[1,0]
	v_pk_fma_f32 v[140:141], v[204:205], v[148:149], v[140:141]
	v_rcp_f32_e32 v144, v144
	v_rcp_f32_e32 v145, v145
	v_pk_fma_f32 v[140:141], v[128:129], v[184:185], v[140:141]
	v_pk_fma_f32 v[142:143], v[208:209], v[150:151], v[142:143]
	v_pk_mul_f32 v[136:137], v[136:137], v[144:145]
	v_pk_mul_f32 v[144:145], v[138:139], s[20:21] op_sel_hi:[1,0]
	v_pk_mul_f32 v[138:139], v[156:157], v[138:139]
	v_exp_f32_e32 v144, v144
	v_exp_f32_e32 v145, v145
	v_pk_fma_f32 v[142:143], v[130:131], v[186:187], v[142:143]
	v_cvt_pk_bf16_f32 v136, v136, v137
	v_pk_add_f32 v[144:145], v[144:145], 1.0 op_sel_hi:[1,0]
	s_nop 0
	v_rcp_f32_e32 v144, v144
	v_rcp_f32_e32 v145, v145
	s_nop 0
	v_pk_mul_f32 v[138:139], v[138:139], v[144:145]
	v_pk_mul_f32 v[144:145], v[140:141], s[20:21] op_sel_hi:[1,0]
	v_pk_mul_f32 v[140:141], v[154:155], v[140:141]
	v_exp_f32_e32 v144, v144
	v_exp_f32_e32 v145, v145
	v_cvt_pk_bf16_f32 v137, v138, v139
	v_pk_add_f32 v[144:145], v[144:145], 1.0 op_sel_hi:[1,0]
	s_nop 0
	v_rcp_f32_e32 v144, v144
	v_rcp_f32_e32 v145, v145
	s_nop 0
	v_pk_mul_f32 v[140:141], v[140:141], v[144:145]
	v_pk_mul_f32 v[144:145], v[142:143], s[20:21] op_sel_hi:[1,0]
	v_pk_mul_f32 v[142:143], v[152:153], v[142:143]
	v_exp_f32_e32 v144, v144
	v_exp_f32_e32 v145, v145
	v_cvt_pk_bf16_f32 v138, v140, v141
	v_mov_b64_e32 v[140:141], s[60:61]
	v_pk_add_f32 v[144:145], v[144:145], 1.0 op_sel_hi:[1,0]
	s_nop 0
	v_rcp_f32_e32 v144, v144
	v_rcp_f32_e32 v145, v145
	s_nop 0
	v_pk_mul_f32 v[142:143], v[142:143], v[144:145]
	s_nop 0
	v_cvt_pk_bf16_f32 v139, v142, v143
	v_add_u32_e32 v142, s22, v163
	v_mad_i64_i32 v[140:141], s[8:9], v142, s5, v[140:141]
	v_lshl_add_u64 v[140:141], v[174:175], 1, v[140:141]
	global_store_dwordx4 v[140:141], v[136:139], off
	s_and_saveexec_b64 s[8:9], s[86:87]
	s_cbranch_execz .LBB0_1412
	s_ashr_i32 s5, s4, 31
	v_lshl_add_u64 v[136:137], s[4:5], 1, v[160:161]
	v_mov_b64_e32 v[138:139], s[68:69]
	s_movk_i32 s18, 0x2c00
	v_mad_u64_u32 v[138:139], s[4:5], v136, s18, v[138:139]
	v_mad_i32_i24 v139, v137, s18, v139
	v_lshl_add_u64 v[136:137], v[174:175], 2, v[138:139]
	global_store_dwordx4 v[136:137], v[132:135], off
	global_store_dwordx4 v[136:137], v[128:131], off offset:16
.LBB0_1412:
	s_or_b64 exec, exec, s[8:9]
	v_add_u32_e32 v163, 0x80, v162
	v_mov_b32_e32 v164, v167
	v_lshl_add_u32 v128, v163, 3, s67
	ds_read_b64 v[128:129], v128
	s_add_i32 s4, s23, 0xffff0080
	s_ashr_i32 s4, s4, 4
	s_mul_i32 s8, s4, 0x5800
	s_mul_hi_i32 s5, s4, 0x5800
	s_waitcnt lgkmcnt(0)
	v_pk_mul_f32 v[144:145], v[128:129], s[96:97] op_sel_hi:[1,0]
	s_add_u32 s8, s51, s8
	v_fma_f32 v128, -v144, v144, v145
	v_max_f32_e32 v128, 0, v128
	v_add_f32_e32 v128, 0x3727c5ac, v128
	v_rsq_f32_e32 v158, v128
	ds_read_b128 v[128:131], v164 offset:2048
	ds_read_b128 v[136:139], v164 offset:2064
	ds_read_b128 v[132:135], v164 offset:2560
	ds_read_b128 v[140:143], v164 offset:2576
	s_addc_u32 s9, s83, s5
	v_mul_f32_e64 v152, v158, -v144
	s_waitcnt lgkmcnt(1)
	v_pk_fma_f32 v[128:129], v[128:129], v[152:153], v[132:133] op_sel_hi:[1,0,1]
	v_pk_fma_f32 v[132:133], v[60:61], v[158:159], v[128:129] op_sel_hi:[1,0,1]
	v_pk_fma_f32 v[128:129], v[130:131], v[152:153], v[134:135] op_sel_hi:[1,0,1]
	s_waitcnt lgkmcnt(0)
	v_pk_fma_f32 v[130:131], v[138:139], v[152:153], v[142:143] op_sel_hi:[1,0,1]
	v_pk_fma_f32 v[134:135], v[62:63], v[158:159], v[128:129] op_sel_hi:[1,0,1]
	v_pk_fma_f32 v[128:129], v[136:137], v[152:153], v[140:141] op_sel_hi:[1,0,1]
	ds_read_b128 v[136:139], v164 offset:3072
	ds_read_b128 v[140:143], v164 offset:3088
	ds_read_b128 v[144:147], v164 offset:3584
	ds_read_b128 v[148:151], v164 offset:3600
	v_pk_fma_f32 v[128:129], v[56:57], v[158:159], v[128:129] op_sel_hi:[1,0,1]
	v_pk_fma_f32 v[130:131], v[58:59], v[158:159], v[130:131] op_sel_hi:[1,0,1]
	s_waitcnt lgkmcnt(1)
	v_pk_fma_f32 v[138:139], v[138:139], v[152:153], v[146:147] op_sel_hi:[1,0,1]
	v_pk_fma_f32 v[136:137], v[136:137], v[152:153], v[144:145] op_sel_hi:[1,0,1]
	v_pk_fma_f32 v[156:157], v[30:31], v[158:159], v[138:139] op_sel_hi:[1,0,1]
	s_waitcnt lgkmcnt(0)
	v_pk_fma_f32 v[138:139], v[140:141], v[152:153], v[148:149] op_sel_hi:[1,0,1]
	v_lshl_add_u64 v[144:145], v[174:175], 2, s[8:9]
	v_pk_fma_f32 v[154:155], v[24:25], v[158:159], v[138:139] op_sel_hi:[1,0,1]
	v_pk_fma_f32 v[138:139], v[142:143], v[152:153], v[150:151] op_sel_hi:[1,0,1]
	v_lshl_add_u64 v[146:147], v[144:145], 0, s[34:35]
	v_pk_fma_f32 v[152:153], v[26:27], v[158:159], v[138:139] op_sel_hi:[1,0,1]
	v_pk_fma_f32 v[158:159], v[28:29], v[158:159], v[136:137] op_sel_hi:[1,0,1]
	global_load_dwordx4 v[136:139], v[144:145], off offset:16
	global_load_dwordx4 v[140:143], v[144:145], off
	v_add_co_u32_e64 v144, s[46:47], s33, v144
	s_nop 0
	s_nop 0
	v_addc_co_u32_e64 v145, s[46:47], 0, v145, s[46:47]
	global_load_dwordx4 v[148:151], v[144:145], off offset:3072
	s_nop 0
	global_load_dwordx4 v[144:147], v[146:147], off offset:16
	v_mov_b32_dpp v189, v133 row_ror:1 row_mask:0xf bank_mask:0xf
	v_mov_b32_dpp v185, v132 row_ror:2 row_mask:0xf bank_mask:0xf
	v_mov_b32_dpp v188, v133 row_ror:2 row_mask:0xf bank_mask:0xf
	v_mov_b32_dpp v169, v128 row_ror:2 row_mask:0xf bank_mask:0xf
	v_mov_b32_dpp v178, v129 row_ror:2 row_mask:0xf bank_mask:0xf
	v_mov_b32_dpp v187, v132 row_ror:1 row_mask:0xf bank_mask:0xf
	v_mov_b32_dpp v180, v134 row_ror:1 row_mask:0xf bank_mask:0xf
	v_mov_b32_dpp v186, v135 row_ror:1 row_mask:0xf bank_mask:0xf
	v_mov_b32_dpp v176, v134 row_ror:2 row_mask:0xf bank_mask:0xf
	v_mov_b32_dpp v181, v135 row_ror:2 row_mask:0xf bank_mask:0xf
	v_mov_b32_dpp v177, v128 row_ror:1 row_mask:0xf bank_mask:0xf
	v_mov_b32_dpp v184, v129 row_ror:1 row_mask:0xf bank_mask:0xf
	v_mov_b32_dpp v171, v130 row_ror:1 row_mask:0xf bank_mask:0xf
	v_mov_b32_dpp v179, v131 row_ror:1 row_mask:0xf bank_mask:0xf
	v_mov_b32_dpp v165, v130 row_ror:2 row_mask:0xf bank_mask:0xf
	v_mov_b32_dpp v173, v131 row_ror:2 row_mask:0xf bank_mask:0xf
	s_movk_i32 s5, 0x1600
	s_waitcnt vmcnt(1)
	v_cndmask_b32_e64 v140, v140, v148, s[42:43]
	v_cndmask_b32_e64 v141, v141, v149, s[42:43]
	s_waitcnt vmcnt(0)
	v_cndmask_b32_e64 v136, v136, v144, s[42:43]
	v_cndmask_b32_e64 v137, v137, v145, s[42:43]
	v_cndmask_b32_e64 v191, v189, v149, s[44:45]
	v_cndmask_b32_e32 v189, v141, v188, vcc
	v_cndmask_b32_e32 v188, v140, v185, vcc
	v_cndmask_b32_e64 v140, v142, v150, s[42:43]
	v_cndmask_b32_e64 v141, v143, v151, s[42:43]
	v_cndmask_b32_e32 v207, v137, v178, vcc
	v_cndmask_b32_e32 v206, v136, v169, vcc
	v_cndmask_b32_e64 v136, v138, v146, s[42:43]
	v_cndmask_b32_e64 v137, v139, v147, s[42:43]
	v_cndmask_b32_e64 v190, v187, v148, s[44:45]
	v_cndmask_b32_e64 v203, v186, v151, s[44:45]
	v_cndmask_b32_e64 v202, v180, v150, s[44:45]
	v_cndmask_b32_e32 v181, v141, v181, vcc
	v_cndmask_b32_e32 v180, v140, v176, vcc
	v_cndmask_b32_e64 v205, v184, v145, s[44:45]
	v_cndmask_b32_e64 v204, v177, v144, s[44:45]
	v_cndmask_b32_e64 v209, v179, v147, s[44:45]
	v_cndmask_b32_e64 v208, v171, v146, s[44:45]
	v_cndmask_b32_e32 v211, v137, v173, vcc
	v_cndmask_b32_e32 v210, v136, v165, vcc
	ds_read_b128 v[136:139], v164
	ds_read_b128 v[140:143], v164 offset:16
	ds_read_b128 v[144:147], v164 offset:512
	ds_read_b128 v[148:151], v164 offset:528
	ds_read_b128 v[176:179], v164 offset:1024
	ds_read_b128 v[184:187], v164 offset:1040
	ds_read_b128 v[194:197], v164 offset:1536
	ds_read_b128 v[198:201], v164 offset:1552
	s_waitcnt lgkmcnt(1)
	v_pk_fma_f32 v[136:137], v[136:137], v[188:189], v[194:195]
	s_nop 0
	v_pk_fma_f32 v[136:137], v[190:191], v[144:145], v[136:137]
	v_pk_fma_f32 v[138:139], v[138:139], v[180:181], v[196:197]
	v_pk_fma_f32 v[136:137], v[132:133], v[176:177], v[136:137]
	v_pk_fma_f32 v[138:139], v[202:203], v[146:147], v[138:139]
	v_pk_mul_f32 v[144:145], v[136:137], s[20:21] op_sel_hi:[1,0]
	v_pk_mul_f32 v[136:137], v[158:159], v[136:137]
	v_exp_f32_e32 v144, v144
	v_exp_f32_e32 v145, v145
	v_pk_fma_f32 v[138:139], v[134:135], v[178:179], v[138:139]
	s_waitcnt lgkmcnt(0)
	v_pk_fma_f32 v[140:141], v[140:141], v[206:207], v[198:199]
	v_pk_fma_f32 v[142:143], v[142:143], v[210:211], v[200:201]
	v_pk_add_f32 v[144:145], v[144:145], 1.0 op_sel_hi:[1,0]
	v_pk_fma_f32 v[140:141], v[204:205], v[148:149], v[140:141]
	v_rcp_f32_e32 v144, v144
	v_rcp_f32_e32 v145, v145
	v_pk_fma_f32 v[140:141], v[128:129], v[184:185], v[140:141]
	v_pk_fma_f32 v[142:143], v[208:209], v[150:151], v[142:143]
	v_pk_mul_f32 v[136:137], v[136:137], v[144:145]
	v_pk_mul_f32 v[144:145], v[138:139], s[20:21] op_sel_hi:[1,0]
	v_pk_mul_f32 v[138:139], v[156:157], v[138:139]
	v_exp_f32_e32 v144, v144
	v_exp_f32_e32 v145, v145
	v_pk_fma_f32 v[142:143], v[130:131], v[186:187], v[142:143]
	v_cvt_pk_bf16_f32 v136, v136, v137
	v_pk_add_f32 v[144:145], v[144:145], 1.0 op_sel_hi:[1,0]
	s_nop 0
	v_rcp_f32_e32 v144, v144
	v_rcp_f32_e32 v145, v145
	s_nop 0
	v_pk_mul_f32 v[138:139], v[138:139], v[144:145]
	v_pk_mul_f32 v[144:145], v[140:141], s[20:21] op_sel_hi:[1,0]
	v_pk_mul_f32 v[140:141], v[154:155], v[140:141]
	v_exp_f32_e32 v144, v144
	v_exp_f32_e32 v145, v145
	v_cvt_pk_bf16_f32 v137, v138, v139
	v_pk_add_f32 v[144:145], v[144:145], 1.0 op_sel_hi:[1,0]
	s_nop 0
	v_rcp_f32_e32 v144, v144
	v_rcp_f32_e32 v145, v145
	s_nop 0
	v_pk_mul_f32 v[140:141], v[140:141], v[144:145]
	v_pk_mul_f32 v[144:145], v[142:143], s[20:21] op_sel_hi:[1,0]
	v_pk_mul_f32 v[142:143], v[152:153], v[142:143]
	v_exp_f32_e32 v144, v144
	v_exp_f32_e32 v145, v145
	v_cvt_pk_bf16_f32 v138, v140, v141
	v_mov_b64_e32 v[140:141], s[60:61]
	v_pk_add_f32 v[144:145], v[144:145], 1.0 op_sel_hi:[1,0]
	s_nop 0
	v_rcp_f32_e32 v144, v144
	v_rcp_f32_e32 v145, v145
	s_nop 0
	v_pk_mul_f32 v[142:143], v[142:143], v[144:145]
	s_nop 0
	v_cvt_pk_bf16_f32 v139, v142, v143
	v_add_u32_e32 v142, s22, v163
	v_mad_i64_i32 v[140:141], s[8:9], v142, s5, v[140:141]
	v_lshl_add_u64 v[140:141], v[174:175], 1, v[140:141]
	global_store_dwordx4 v[140:141], v[136:139], off
	s_and_saveexec_b64 s[8:9], s[86:87]
	s_cbranch_execz .LBB0_1414
	s_ashr_i32 s5, s4, 31
	v_lshl_add_u64 v[136:137], s[4:5], 1, v[160:161]
	v_mov_b64_e32 v[138:139], s[68:69]
	s_movk_i32 s18, 0x2c00
	v_mad_u64_u32 v[138:139], s[4:5], v136, s18, v[138:139]
	v_mad_i32_i24 v139, v137, s18, v139
	v_lshl_add_u64 v[136:137], v[174:175], 2, v[138:139]
	global_store_dwordx4 v[136:137], v[132:135], off
	global_store_dwordx4 v[136:137], v[128:131], off offset:16
.LBB0_1414:
	s_or_b64 exec, exec, s[8:9]
	v_add_u32_e32 v163, 0x90, v162
	v_mov_b32_e32 v164, v167
	v_lshl_add_u32 v128, v163, 3, s67
	ds_read_b64 v[128:129], v128
	s_add_i32 s4, s23, 0xffff0090
	s_ashr_i32 s4, s4, 4
	s_mul_i32 s8, s4, 0x5800
	s_mul_hi_i32 s5, s4, 0x5800
	s_waitcnt lgkmcnt(0)
	v_pk_mul_f32 v[144:145], v[128:129], s[96:97] op_sel_hi:[1,0]
	s_add_u32 s8, s51, s8
	v_fma_f32 v128, -v144, v144, v145
	v_max_f32_e32 v128, 0, v128
	v_add_f32_e32 v128, 0x3727c5ac, v128
	v_rsq_f32_e32 v158, v128
	ds_read_b128 v[128:131], v164 offset:2048
	ds_read_b128 v[136:139], v164 offset:2064
	ds_read_b128 v[132:135], v164 offset:2560
	ds_read_b128 v[140:143], v164 offset:2576
	s_addc_u32 s9, s83, s5
	v_mul_f32_e64 v152, v158, -v144
	s_waitcnt lgkmcnt(1)
	v_pk_fma_f32 v[128:129], v[128:129], v[152:153], v[132:133] op_sel_hi:[1,0,1]
	v_pk_fma_f32 v[132:133], v[52:53], v[158:159], v[128:129] op_sel_hi:[1,0,1]
	v_pk_fma_f32 v[128:129], v[130:131], v[152:153], v[134:135] op_sel_hi:[1,0,1]
	s_waitcnt lgkmcnt(0)
	v_pk_fma_f32 v[130:131], v[138:139], v[152:153], v[142:143] op_sel_hi:[1,0,1]
	v_pk_fma_f32 v[134:135], v[54:55], v[158:159], v[128:129] op_sel_hi:[1,0,1]
	v_pk_fma_f32 v[128:129], v[136:137], v[152:153], v[140:141] op_sel_hi:[1,0,1]
	ds_read_b128 v[136:139], v164 offset:3072
	ds_read_b128 v[140:143], v164 offset:3088
	ds_read_b128 v[144:147], v164 offset:3584
	ds_read_b128 v[148:151], v164 offset:3600
	v_pk_fma_f32 v[128:129], v[48:49], v[158:159], v[128:129] op_sel_hi:[1,0,1]
	v_pk_fma_f32 v[130:131], v[50:51], v[158:159], v[130:131] op_sel_hi:[1,0,1]
	s_waitcnt lgkmcnt(1)
	v_pk_fma_f32 v[138:139], v[138:139], v[152:153], v[146:147] op_sel_hi:[1,0,1]
	v_pk_fma_f32 v[136:137], v[136:137], v[152:153], v[144:145] op_sel_hi:[1,0,1]
	v_pk_fma_f32 v[156:157], v[22:23], v[158:159], v[138:139] op_sel_hi:[1,0,1]
	s_waitcnt lgkmcnt(0)
	v_pk_fma_f32 v[138:139], v[140:141], v[152:153], v[148:149] op_sel_hi:[1,0,1]
	v_lshl_add_u64 v[144:145], v[174:175], 2, s[8:9]
	v_pk_fma_f32 v[154:155], v[16:17], v[158:159], v[138:139] op_sel_hi:[1,0,1]
	v_pk_fma_f32 v[138:139], v[142:143], v[152:153], v[150:151] op_sel_hi:[1,0,1]
	v_lshl_add_u64 v[146:147], v[144:145], 0, s[34:35]
	v_pk_fma_f32 v[152:153], v[18:19], v[158:159], v[138:139] op_sel_hi:[1,0,1]
	v_pk_fma_f32 v[158:159], v[20:21], v[158:159], v[136:137] op_sel_hi:[1,0,1]
	global_load_dwordx4 v[136:139], v[144:145], off offset:16
	global_load_dwordx4 v[140:143], v[144:145], off
	v_add_co_u32_e64 v144, s[46:47], s33, v144
	s_nop 0
	s_nop 0
	v_addc_co_u32_e64 v145, s[46:47], 0, v145, s[46:47]
	global_load_dwordx4 v[148:151], v[144:145], off offset:3072
	s_nop 0
	global_load_dwordx4 v[144:147], v[146:147], off offset:16
	v_mov_b32_dpp v189, v133 row_ror:1 row_mask:0xf bank_mask:0xf
	v_mov_b32_dpp v185, v132 row_ror:2 row_mask:0xf bank_mask:0xf
	v_mov_b32_dpp v188, v133 row_ror:2 row_mask:0xf bank_mask:0xf
	v_mov_b32_dpp v169, v128 row_ror:2 row_mask:0xf bank_mask:0xf
	v_mov_b32_dpp v178, v129 row_ror:2 row_mask:0xf bank_mask:0xf
	v_mov_b32_dpp v187, v132 row_ror:1 row_mask:0xf bank_mask:0xf
	v_mov_b32_dpp v180, v134 row_ror:1 row_mask:0xf bank_mask:0xf
	v_mov_b32_dpp v186, v135 row_ror:1 row_mask:0xf bank_mask:0xf
	v_mov_b32_dpp v176, v134 row_ror:2 row_mask:0xf bank_mask:0xf
	v_mov_b32_dpp v181, v135 row_ror:2 row_mask:0xf bank_mask:0xf
	v_mov_b32_dpp v177, v128 row_ror:1 row_mask:0xf bank_mask:0xf
	v_mov_b32_dpp v184, v129 row_ror:1 row_mask:0xf bank_mask:0xf
	v_mov_b32_dpp v171, v130 row_ror:1 row_mask:0xf bank_mask:0xf
	v_mov_b32_dpp v179, v131 row_ror:1 row_mask:0xf bank_mask:0xf
	v_mov_b32_dpp v165, v130 row_ror:2 row_mask:0xf bank_mask:0xf
	v_mov_b32_dpp v173, v131 row_ror:2 row_mask:0xf bank_mask:0xf
	s_movk_i32 s5, 0x1600
	s_waitcnt vmcnt(1)
	v_cndmask_b32_e64 v140, v140, v148, s[42:43]
	v_cndmask_b32_e64 v141, v141, v149, s[42:43]
	s_waitcnt vmcnt(0)
	v_cndmask_b32_e64 v136, v136, v144, s[42:43]
	v_cndmask_b32_e64 v137, v137, v145, s[42:43]
	v_cndmask_b32_e64 v191, v189, v149, s[44:45]
	v_cndmask_b32_e32 v189, v141, v188, vcc
	v_cndmask_b32_e32 v188, v140, v185, vcc
	v_cndmask_b32_e64 v140, v142, v150, s[42:43]
	v_cndmask_b32_e64 v141, v143, v151, s[42:43]
	v_cndmask_b32_e32 v207, v137, v178, vcc
	v_cndmask_b32_e32 v206, v136, v169, vcc
	v_cndmask_b32_e64 v136, v138, v146, s[42:43]
	v_cndmask_b32_e64 v137, v139, v147, s[42:43]
	v_cndmask_b32_e64 v190, v187, v148, s[44:45]
	v_cndmask_b32_e64 v203, v186, v151, s[44:45]
	v_cndmask_b32_e64 v202, v180, v150, s[44:45]
	v_cndmask_b32_e32 v181, v141, v181, vcc
	v_cndmask_b32_e32 v180, v140, v176, vcc
	v_cndmask_b32_e64 v205, v184, v145, s[44:45]
	v_cndmask_b32_e64 v204, v177, v144, s[44:45]
	v_cndmask_b32_e64 v209, v179, v147, s[44:45]
	v_cndmask_b32_e64 v208, v171, v146, s[44:45]
	v_cndmask_b32_e32 v211, v137, v173, vcc
	v_cndmask_b32_e32 v210, v136, v165, vcc
	ds_read_b128 v[136:139], v164
	ds_read_b128 v[140:143], v164 offset:16
	ds_read_b128 v[144:147], v164 offset:512
	ds_read_b128 v[148:151], v164 offset:528
	ds_read_b128 v[176:179], v164 offset:1024
	ds_read_b128 v[184:187], v164 offset:1040
	ds_read_b128 v[194:197], v164 offset:1536
	ds_read_b128 v[198:201], v164 offset:1552
	s_waitcnt lgkmcnt(1)
	v_pk_fma_f32 v[136:137], v[136:137], v[188:189], v[194:195]
	s_nop 0
	v_pk_fma_f32 v[136:137], v[190:191], v[144:145], v[136:137]
	v_pk_fma_f32 v[138:139], v[138:139], v[180:181], v[196:197]
	v_pk_fma_f32 v[136:137], v[132:133], v[176:177], v[136:137]
	v_pk_fma_f32 v[138:139], v[202:203], v[146:147], v[138:139]
	v_pk_mul_f32 v[144:145], v[136:137], s[20:21] op_sel_hi:[1,0]
	v_pk_mul_f32 v[136:137], v[158:159], v[136:137]
	v_exp_f32_e32 v144, v144
	v_exp_f32_e32 v145, v145
	v_pk_fma_f32 v[138:139], v[134:135], v[178:179], v[138:139]
	s_waitcnt lgkmcnt(0)
	v_pk_fma_f32 v[140:141], v[140:141], v[206:207], v[198:199]
	v_pk_fma_f32 v[142:143], v[142:143], v[210:211], v[200:201]
	v_pk_add_f32 v[144:145], v[144:145], 1.0 op_sel_hi:[1,0]
	v_pk_fma_f32 v[140:141], v[204:205], v[148:149], v[140:141]
	v_rcp_f32_e32 v144, v144
	v_rcp_f32_e32 v145, v145
	v_pk_fma_f32 v[140:141], v[128:129], v[184:185], v[140:141]
	v_pk_fma_f32 v[142:143], v[208:209], v[150:151], v[142:143]
	v_pk_mul_f32 v[136:137], v[136:137], v[144:145]
	v_pk_mul_f32 v[144:145], v[138:139], s[20:21] op_sel_hi:[1,0]
	v_pk_mul_f32 v[138:139], v[156:157], v[138:139]
	v_exp_f32_e32 v144, v144
	v_exp_f32_e32 v145, v145
	v_pk_fma_f32 v[142:143], v[130:131], v[186:187], v[142:143]
	v_cvt_pk_bf16_f32 v136, v136, v137
	v_pk_add_f32 v[144:145], v[144:145], 1.0 op_sel_hi:[1,0]
	s_nop 0
	v_rcp_f32_e32 v144, v144
	v_rcp_f32_e32 v145, v145
	s_nop 0
	v_pk_mul_f32 v[138:139], v[138:139], v[144:145]
	v_pk_mul_f32 v[144:145], v[140:141], s[20:21] op_sel_hi:[1,0]
	v_pk_mul_f32 v[140:141], v[154:155], v[140:141]
	v_exp_f32_e32 v144, v144
	v_exp_f32_e32 v145, v145
	v_cvt_pk_bf16_f32 v137, v138, v139
	v_pk_add_f32 v[144:145], v[144:145], 1.0 op_sel_hi:[1,0]
	s_nop 0
	v_rcp_f32_e32 v144, v144
	v_rcp_f32_e32 v145, v145
	s_nop 0
	v_pk_mul_f32 v[140:141], v[140:141], v[144:145]
	v_pk_mul_f32 v[144:145], v[142:143], s[20:21] op_sel_hi:[1,0]
	v_pk_mul_f32 v[142:143], v[152:153], v[142:143]
	v_exp_f32_e32 v144, v144
	v_exp_f32_e32 v145, v145
	v_cvt_pk_bf16_f32 v138, v140, v141
	v_mov_b64_e32 v[140:141], s[60:61]
	v_pk_add_f32 v[144:145], v[144:145], 1.0 op_sel_hi:[1,0]
	s_nop 0
	v_rcp_f32_e32 v144, v144
	v_rcp_f32_e32 v145, v145
	s_nop 0
	v_pk_mul_f32 v[142:143], v[142:143], v[144:145]
	s_nop 0
	v_cvt_pk_bf16_f32 v139, v142, v143
	v_add_u32_e32 v142, s22, v163
	v_mad_i64_i32 v[140:141], s[8:9], v142, s5, v[140:141]
	v_lshl_add_u64 v[140:141], v[174:175], 1, v[140:141]
	global_store_dwordx4 v[140:141], v[136:139], off
	s_and_saveexec_b64 s[8:9], s[86:87]
	s_cbranch_execz .LBB0_1416
	s_ashr_i32 s5, s4, 31
	v_lshl_add_u64 v[136:137], s[4:5], 1, v[160:161]
	v_mov_b64_e32 v[138:139], s[68:69]
	s_movk_i32 s18, 0x2c00
	v_mad_u64_u32 v[138:139], s[4:5], v136, s18, v[138:139]
	v_mad_i32_i24 v139, v137, s18, v139
	v_lshl_add_u64 v[136:137], v[174:175], 2, v[138:139]
	global_store_dwordx4 v[136:137], v[132:135], off
	global_store_dwordx4 v[136:137], v[128:131], off offset:16
.LBB0_1416:
	s_or_b64 exec, exec, s[8:9]
	v_add_u32_e32 v163, 0xa0, v162
	v_mov_b32_e32 v164, v167
	v_lshl_add_u32 v128, v163, 3, s67
	ds_read_b64 v[128:129], v128
	s_add_i32 s4, s23, 0xffff00a0
	s_ashr_i32 s4, s4, 4
	s_mul_i32 s8, s4, 0x5800
	s_mul_hi_i32 s5, s4, 0x5800
	s_waitcnt lgkmcnt(0)
	v_pk_mul_f32 v[144:145], v[128:129], s[96:97] op_sel_hi:[1,0]
	s_add_u32 s8, s51, s8
	v_fma_f32 v128, -v144, v144, v145
	v_max_f32_e32 v128, 0, v128
	v_add_f32_e32 v128, 0x3727c5ac, v128
	v_rsq_f32_e32 v158, v128
	ds_read_b128 v[128:131], v164 offset:2048
	ds_read_b128 v[136:139], v164 offset:2064
	ds_read_b128 v[132:135], v164 offset:2560
	ds_read_b128 v[140:143], v164 offset:2576
	s_addc_u32 s9, s83, s5
	v_mul_f32_e64 v152, v158, -v144
	s_waitcnt lgkmcnt(1)
	v_pk_fma_f32 v[128:129], v[128:129], v[152:153], v[132:133] op_sel_hi:[1,0,1]
	v_pk_fma_f32 v[132:133], v[44:45], v[158:159], v[128:129] op_sel_hi:[1,0,1]
	v_pk_fma_f32 v[128:129], v[130:131], v[152:153], v[134:135] op_sel_hi:[1,0,1]
	s_waitcnt lgkmcnt(0)
	v_pk_fma_f32 v[130:131], v[138:139], v[152:153], v[142:143] op_sel_hi:[1,0,1]
	v_pk_fma_f32 v[134:135], v[46:47], v[158:159], v[128:129] op_sel_hi:[1,0,1]
	v_pk_fma_f32 v[128:129], v[136:137], v[152:153], v[140:141] op_sel_hi:[1,0,1]
	ds_read_b128 v[136:139], v164 offset:3072
	ds_read_b128 v[140:143], v164 offset:3088
	ds_read_b128 v[144:147], v164 offset:3584
	ds_read_b128 v[148:151], v164 offset:3600
	v_pk_fma_f32 v[128:129], v[40:41], v[158:159], v[128:129] op_sel_hi:[1,0,1]
	v_pk_fma_f32 v[130:131], v[42:43], v[158:159], v[130:131] op_sel_hi:[1,0,1]
	s_waitcnt lgkmcnt(1)
	v_pk_fma_f32 v[138:139], v[138:139], v[152:153], v[146:147] op_sel_hi:[1,0,1]
	v_pk_fma_f32 v[136:137], v[136:137], v[152:153], v[144:145] op_sel_hi:[1,0,1]
	v_pk_fma_f32 v[156:157], v[14:15], v[158:159], v[138:139] op_sel_hi:[1,0,1]
	s_waitcnt lgkmcnt(0)
	v_pk_fma_f32 v[138:139], v[140:141], v[152:153], v[148:149] op_sel_hi:[1,0,1]
	v_lshl_add_u64 v[144:145], v[174:175], 2, s[8:9]
	v_pk_fma_f32 v[154:155], v[8:9], v[158:159], v[138:139] op_sel_hi:[1,0,1]
	v_pk_fma_f32 v[138:139], v[142:143], v[152:153], v[150:151] op_sel_hi:[1,0,1]
	v_lshl_add_u64 v[146:147], v[144:145], 0, s[34:35]
	v_pk_fma_f32 v[152:153], v[10:11], v[158:159], v[138:139] op_sel_hi:[1,0,1]
	v_pk_fma_f32 v[158:159], v[12:13], v[158:159], v[136:137] op_sel_hi:[1,0,1]
	global_load_dwordx4 v[136:139], v[144:145], off offset:16
	global_load_dwordx4 v[140:143], v[144:145], off
	v_add_co_u32_e64 v144, s[46:47], s33, v144
	s_nop 0
	s_nop 0
	v_addc_co_u32_e64 v145, s[46:47], 0, v145, s[46:47]
	global_load_dwordx4 v[148:151], v[144:145], off offset:3072
	s_nop 0
	global_load_dwordx4 v[144:147], v[146:147], off offset:16
	v_mov_b32_dpp v189, v133 row_ror:1 row_mask:0xf bank_mask:0xf
	v_mov_b32_dpp v185, v132 row_ror:2 row_mask:0xf bank_mask:0xf
	v_mov_b32_dpp v188, v133 row_ror:2 row_mask:0xf bank_mask:0xf
	v_mov_b32_dpp v169, v128 row_ror:2 row_mask:0xf bank_mask:0xf
	v_mov_b32_dpp v178, v129 row_ror:2 row_mask:0xf bank_mask:0xf
	v_mov_b32_dpp v187, v132 row_ror:1 row_mask:0xf bank_mask:0xf
	v_mov_b32_dpp v180, v134 row_ror:1 row_mask:0xf bank_mask:0xf
	v_mov_b32_dpp v186, v135 row_ror:1 row_mask:0xf bank_mask:0xf
	v_mov_b32_dpp v176, v134 row_ror:2 row_mask:0xf bank_mask:0xf
	v_mov_b32_dpp v181, v135 row_ror:2 row_mask:0xf bank_mask:0xf
	v_mov_b32_dpp v177, v128 row_ror:1 row_mask:0xf bank_mask:0xf
	v_mov_b32_dpp v184, v129 row_ror:1 row_mask:0xf bank_mask:0xf
	v_mov_b32_dpp v171, v130 row_ror:1 row_mask:0xf bank_mask:0xf
	v_mov_b32_dpp v179, v131 row_ror:1 row_mask:0xf bank_mask:0xf
	v_mov_b32_dpp v165, v130 row_ror:2 row_mask:0xf bank_mask:0xf
	v_mov_b32_dpp v173, v131 row_ror:2 row_mask:0xf bank_mask:0xf
	s_movk_i32 s5, 0x1600
	s_waitcnt vmcnt(1)
	v_cndmask_b32_e64 v140, v140, v148, s[42:43]
	v_cndmask_b32_e64 v141, v141, v149, s[42:43]
	s_waitcnt vmcnt(0)
	v_cndmask_b32_e64 v136, v136, v144, s[42:43]
	v_cndmask_b32_e64 v137, v137, v145, s[42:43]
	v_cndmask_b32_e64 v191, v189, v149, s[44:45]
	v_cndmask_b32_e32 v189, v141, v188, vcc
	v_cndmask_b32_e32 v188, v140, v185, vcc
	v_cndmask_b32_e64 v140, v142, v150, s[42:43]
	v_cndmask_b32_e64 v141, v143, v151, s[42:43]
	v_cndmask_b32_e32 v207, v137, v178, vcc
	v_cndmask_b32_e32 v206, v136, v169, vcc
	v_cndmask_b32_e64 v136, v138, v146, s[42:43]
	v_cndmask_b32_e64 v137, v139, v147, s[42:43]
	v_cndmask_b32_e64 v190, v187, v148, s[44:45]
	v_cndmask_b32_e64 v203, v186, v151, s[44:45]
	v_cndmask_b32_e64 v202, v180, v150, s[44:45]
	v_cndmask_b32_e32 v181, v141, v181, vcc
	v_cndmask_b32_e32 v180, v140, v176, vcc
	v_cndmask_b32_e64 v205, v184, v145, s[44:45]
	v_cndmask_b32_e64 v204, v177, v144, s[44:45]
	v_cndmask_b32_e64 v209, v179, v147, s[44:45]
	v_cndmask_b32_e64 v208, v171, v146, s[44:45]
	v_cndmask_b32_e32 v211, v137, v173, vcc
	v_cndmask_b32_e32 v210, v136, v165, vcc
	ds_read_b128 v[136:139], v164
	ds_read_b128 v[140:143], v164 offset:16
	ds_read_b128 v[144:147], v164 offset:512
	ds_read_b128 v[148:151], v164 offset:528
	ds_read_b128 v[176:179], v164 offset:1024
	ds_read_b128 v[184:187], v164 offset:1040
	ds_read_b128 v[194:197], v164 offset:1536
	ds_read_b128 v[198:201], v164 offset:1552
	s_waitcnt lgkmcnt(1)
	v_pk_fma_f32 v[136:137], v[136:137], v[188:189], v[194:195]
	s_nop 0
	v_pk_fma_f32 v[136:137], v[190:191], v[144:145], v[136:137]
	v_pk_fma_f32 v[138:139], v[138:139], v[180:181], v[196:197]
	v_pk_fma_f32 v[136:137], v[132:133], v[176:177], v[136:137]
	v_pk_fma_f32 v[138:139], v[202:203], v[146:147], v[138:139]
	v_pk_mul_f32 v[144:145], v[136:137], s[20:21] op_sel_hi:[1,0]
	v_pk_mul_f32 v[136:137], v[158:159], v[136:137]
	v_exp_f32_e32 v144, v144
	v_exp_f32_e32 v145, v145
	v_pk_fma_f32 v[138:139], v[134:135], v[178:179], v[138:139]
	s_waitcnt lgkmcnt(0)
	v_pk_fma_f32 v[140:141], v[140:141], v[206:207], v[198:199]
	v_pk_fma_f32 v[142:143], v[142:143], v[210:211], v[200:201]
	v_pk_add_f32 v[144:145], v[144:145], 1.0 op_sel_hi:[1,0]
	v_pk_fma_f32 v[140:141], v[204:205], v[148:149], v[140:141]
	v_rcp_f32_e32 v144, v144
	v_rcp_f32_e32 v145, v145
	v_pk_fma_f32 v[140:141], v[128:129], v[184:185], v[140:141]
	v_pk_fma_f32 v[142:143], v[208:209], v[150:151], v[142:143]
	v_pk_mul_f32 v[136:137], v[136:137], v[144:145]
	v_pk_mul_f32 v[144:145], v[138:139], s[20:21] op_sel_hi:[1,0]
	v_pk_mul_f32 v[138:139], v[156:157], v[138:139]
	v_exp_f32_e32 v144, v144
	v_exp_f32_e32 v145, v145
	v_pk_fma_f32 v[142:143], v[130:131], v[186:187], v[142:143]
	v_cvt_pk_bf16_f32 v136, v136, v137
	v_pk_add_f32 v[144:145], v[144:145], 1.0 op_sel_hi:[1,0]
	s_nop 0
	v_rcp_f32_e32 v144, v144
	v_rcp_f32_e32 v145, v145
	s_nop 0
	v_pk_mul_f32 v[138:139], v[138:139], v[144:145]
	v_pk_mul_f32 v[144:145], v[140:141], s[20:21] op_sel_hi:[1,0]
	v_pk_mul_f32 v[140:141], v[154:155], v[140:141]
	v_exp_f32_e32 v144, v144
	v_exp_f32_e32 v145, v145
	v_cvt_pk_bf16_f32 v137, v138, v139
	v_pk_add_f32 v[144:145], v[144:145], 1.0 op_sel_hi:[1,0]
	s_nop 0
	v_rcp_f32_e32 v144, v144
	v_rcp_f32_e32 v145, v145
	s_nop 0
	v_pk_mul_f32 v[140:141], v[140:141], v[144:145]
	v_pk_mul_f32 v[144:145], v[142:143], s[20:21] op_sel_hi:[1,0]
	v_pk_mul_f32 v[142:143], v[152:153], v[142:143]
	v_exp_f32_e32 v144, v144
	v_exp_f32_e32 v145, v145
	v_cvt_pk_bf16_f32 v138, v140, v141
	v_mov_b64_e32 v[140:141], s[60:61]
	v_pk_add_f32 v[144:145], v[144:145], 1.0 op_sel_hi:[1,0]
	s_nop 0
	v_rcp_f32_e32 v144, v144
	v_rcp_f32_e32 v145, v145
	s_nop 0
	v_pk_mul_f32 v[142:143], v[142:143], v[144:145]
	s_nop 0
	v_cvt_pk_bf16_f32 v139, v142, v143
	v_add_u32_e32 v142, s22, v163
	v_mad_i64_i32 v[140:141], s[8:9], v142, s5, v[140:141]
	v_lshl_add_u64 v[140:141], v[174:175], 1, v[140:141]
	global_store_dwordx4 v[140:141], v[136:139], off
	s_and_saveexec_b64 s[8:9], s[86:87]
	s_cbranch_execz .LBB0_1418
	s_ashr_i32 s5, s4, 31
	v_lshl_add_u64 v[136:137], s[4:5], 1, v[160:161]
	v_mov_b64_e32 v[138:139], s[68:69]
	s_movk_i32 s18, 0x2c00
	v_mad_u64_u32 v[138:139], s[4:5], v136, s18, v[138:139]
	v_mad_i32_i24 v139, v137, s18, v139
	v_lshl_add_u64 v[136:137], v[174:175], 2, v[138:139]
	global_store_dwordx4 v[136:137], v[132:135], off
	global_store_dwordx4 v[136:137], v[128:131], off offset:16
.LBB0_1418:
	s_or_b64 exec, exec, s[8:9]
	v_add_u32_e32 v162, 0xb0, v162
	v_lshl_add_u32 v128, v162, 3, s67
	ds_read_b64 v[128:129], v128
	s_cmp_eq_u32 s73, 1
	s_cselect_b64 s[4:5], -1, 0
	s_add_i32 s23, s23, 0xffff00b0
	s_ashr_i32 s8, s23, 4
	s_waitcnt lgkmcnt(0)
	v_pk_mul_f32 v[144:145], v[128:129], s[96:97] op_sel_hi:[1,0]
	s_mul_i32 s18, s8, 0x5800
	v_fma_f32 v128, -v144, v144, v145
	v_max_f32_e32 v128, 0, v128
	v_add_f32_e32 v128, 0x3727c5ac, v128
	v_rsq_f32_e32 v158, v128
	ds_read_b128 v[128:131], v167 offset:2048
	ds_read_b128 v[132:135], v167 offset:2064
	ds_read_b128 v[136:139], v167 offset:2560
	ds_read_b128 v[140:143], v167 offset:2576
	s_mul_hi_i32 s9, s8, 0x5800
	s_add_u32 s18, s51, s18
	v_mul_f32_e64 v152, v158, -v144
	s_waitcnt lgkmcnt(1)
	v_pk_fma_f32 v[128:129], v[128:129], v[152:153], v[136:137] op_sel_hi:[1,0,1]
	v_pk_fma_f32 v[130:131], v[130:131], v[152:153], v[138:139] op_sel_hi:[1,0,1]
	s_waitcnt lgkmcnt(0)
	v_pk_fma_f32 v[132:133], v[132:133], v[152:153], v[140:141] op_sel_hi:[1,0,1]
	v_pk_fma_f32 v[134:135], v[134:135], v[152:153], v[142:143] op_sel_hi:[1,0,1]
	ds_read_b128 v[136:139], v167 offset:3072
	ds_read_b128 v[140:143], v167 offset:3088
	ds_read_b128 v[144:147], v167 offset:3584
	ds_read_b128 v[148:151], v167 offset:3600
	s_addc_u32 s19, s83, s9
	v_pk_fma_f32 v[128:129], v[36:37], v[158:159], v[128:129] op_sel_hi:[1,0,1]
	v_pk_fma_f32 v[130:131], v[38:39], v[158:159], v[130:131] op_sel_hi:[1,0,1]
	s_waitcnt lgkmcnt(1)
	v_pk_fma_f32 v[138:139], v[138:139], v[152:153], v[146:147] op_sel_hi:[1,0,1]
	v_pk_fma_f32 v[136:137], v[136:137], v[152:153], v[144:145] op_sel_hi:[1,0,1]
	v_pk_fma_f32 v[156:157], v[6:7], v[158:159], v[138:139] op_sel_hi:[1,0,1]
	s_waitcnt lgkmcnt(0)
	v_pk_fma_f32 v[138:139], v[140:141], v[152:153], v[148:149] op_sel_hi:[1,0,1]
	v_lshl_add_u64 v[144:145], v[174:175], 2, s[18:19]
	v_pk_fma_f32 v[154:155], v[0:1], v[158:159], v[138:139] op_sel_hi:[1,0,1]
	v_pk_fma_f32 v[138:139], v[142:143], v[152:153], v[150:151] op_sel_hi:[1,0,1]
	v_pk_fma_f32 v[132:133], v[32:33], v[158:159], v[132:133] op_sel_hi:[1,0,1]
	v_pk_fma_f32 v[134:135], v[34:35], v[158:159], v[134:135] op_sel_hi:[1,0,1]
	v_pk_fma_f32 v[152:153], v[2:3], v[158:159], v[138:139] op_sel_hi:[1,0,1]
	v_pk_fma_f32 v[158:159], v[4:5], v[158:159], v[136:137] op_sel_hi:[1,0,1]
	global_load_dwordx4 v[136:139], v[144:145], off offset:16
	global_load_dwordx4 v[140:143], v[144:145], off
	v_lshl_add_u64 v[146:147], v[144:145], 0, s[34:35]
	v_add_co_u32_e64 v144, s[46:47], s33, v144
	s_nop 0
	s_nop 0
	v_addc_co_u32_e64 v145, s[46:47], 0, v145, s[46:47]
	global_load_dwordx4 v[148:151], v[144:145], off offset:3072
	s_nop 0
	global_load_dwordx4 v[144:147], v[146:147], off offset:16
	v_mov_b32_dpp v181, v128 row_ror:2 row_mask:0xf bank_mask:0xf
	v_mov_b32_dpp v186, v129 row_ror:2 row_mask:0xf bank_mask:0xf
	v_mov_b32_dpp v164, v132 row_ror:2 row_mask:0xf bank_mask:0xf
	v_mov_b32_dpp v176, v133 row_ror:2 row_mask:0xf bank_mask:0xf
	v_mov_b32_dpp v185, v128 row_ror:1 row_mask:0xf bank_mask:0xf
	v_mov_b32_dpp v187, v129 row_ror:1 row_mask:0xf bank_mask:0xf
	v_mov_b32_dpp v178, v130 row_ror:1 row_mask:0xf bank_mask:0xf
	v_mov_b32_dpp v184, v131 row_ror:1 row_mask:0xf bank_mask:0xf
	v_mov_b32_dpp v171, v130 row_ror:2 row_mask:0xf bank_mask:0xf
	v_mov_b32_dpp v179, v131 row_ror:2 row_mask:0xf bank_mask:0xf
	v_mov_b32_dpp v173, v132 row_ror:1 row_mask:0xf bank_mask:0xf
	v_mov_b32_dpp v180, v133 row_ror:1 row_mask:0xf bank_mask:0xf
	v_mov_b32_dpp v165, v134 row_ror:1 row_mask:0xf bank_mask:0xf
	v_mov_b32_dpp v177, v135 row_ror:1 row_mask:0xf bank_mask:0xf
	v_mov_b32_dpp v163, v134 row_ror:2 row_mask:0xf bank_mask:0xf
	v_mov_b32_dpp v169, v135 row_ror:2 row_mask:0xf bank_mask:0xf
	s_movk_i32 s9, 0x1600
	s_waitcnt vmcnt(1)
	v_cndmask_b32_e64 v140, v140, v148, s[42:43]
	v_cndmask_b32_e64 v141, v141, v149, s[42:43]
	s_waitcnt vmcnt(0)
	v_cndmask_b32_e64 v136, v136, v144, s[42:43]
	v_cndmask_b32_e64 v137, v137, v145, s[42:43]
	v_cndmask_b32_e32 v191, v141, v186, vcc
	v_cndmask_b32_e32 v190, v140, v181, vcc
	v_cndmask_b32_e64 v140, v142, v150, s[42:43]
	v_cndmask_b32_e64 v141, v143, v151, s[42:43]
	v_cndmask_b32_e32 v207, v137, v176, vcc
	v_cndmask_b32_e32 v206, v136, v164, vcc
	v_cndmask_b32_e64 v136, v138, v146, s[42:43]
	v_cndmask_b32_e64 v137, v139, v147, s[42:43]
	v_cndmask_b32_e64 v189, v187, v149, s[44:45]
	v_cndmask_b32_e64 v188, v185, v148, s[44:45]
	v_cndmask_b32_e64 v203, v184, v151, s[44:45]
	v_cndmask_b32_e64 v202, v178, v150, s[44:45]
	v_cndmask_b32_e32 v205, v141, v179, vcc
	v_cndmask_b32_e32 v204, v140, v171, vcc
	v_cndmask_b32_e64 v181, v180, v145, s[44:45]
	v_cndmask_b32_e64 v180, v173, v144, s[44:45]
	v_cndmask_b32_e64 v209, v177, v147, s[44:45]
	v_cndmask_b32_e64 v208, v165, v146, s[44:45]
	v_cndmask_b32_e32 v165, v137, v169, vcc
	v_cndmask_b32_e32 v164, v136, v163, vcc
	ds_read_b128 v[136:139], v167
	ds_read_b128 v[140:143], v167 offset:16
	ds_read_b128 v[144:147], v167 offset:512
	ds_read_b128 v[148:151], v167 offset:528
	ds_read_b128 v[176:179], v167 offset:1024
	ds_read_b128 v[184:187], v167 offset:1040
	ds_read_b128 v[194:197], v167 offset:1536
	ds_read_b128 v[198:201], v167 offset:1552
	s_waitcnt lgkmcnt(1)
	v_pk_fma_f32 v[136:137], v[136:137], v[190:191], v[194:195]
	s_nop 0
	v_pk_fma_f32 v[136:137], v[188:189], v[144:145], v[136:137]
	v_pk_fma_f32 v[138:139], v[138:139], v[204:205], v[196:197]
	v_pk_fma_f32 v[136:137], v[128:129], v[176:177], v[136:137]
	v_pk_fma_f32 v[138:139], v[202:203], v[146:147], v[138:139]
	v_pk_mul_f32 v[144:145], v[136:137], s[20:21] op_sel_hi:[1,0]
	v_pk_mul_f32 v[136:137], v[158:159], v[136:137]
	v_exp_f32_e32 v144, v144
	v_exp_f32_e32 v145, v145
	v_pk_fma_f32 v[138:139], v[130:131], v[178:179], v[138:139]
	s_waitcnt lgkmcnt(0)
	v_pk_fma_f32 v[140:141], v[140:141], v[206:207], v[198:199]
	v_pk_fma_f32 v[142:143], v[142:143], v[164:165], v[200:201]
	v_pk_add_f32 v[144:145], v[144:145], 1.0 op_sel_hi:[1,0]
	v_pk_fma_f32 v[140:141], v[180:181], v[148:149], v[140:141]
	v_rcp_f32_e32 v144, v144
	v_rcp_f32_e32 v145, v145
	v_pk_fma_f32 v[140:141], v[132:133], v[184:185], v[140:141]
	v_pk_fma_f32 v[142:143], v[208:209], v[150:151], v[142:143]
	v_pk_mul_f32 v[136:137], v[136:137], v[144:145]
	v_pk_mul_f32 v[144:145], v[138:139], s[20:21] op_sel_hi:[1,0]
	v_pk_mul_f32 v[138:139], v[156:157], v[138:139]
	v_exp_f32_e32 v144, v144
	v_exp_f32_e32 v145, v145
	v_pk_fma_f32 v[142:143], v[134:135], v[186:187], v[142:143]
	v_cvt_pk_bf16_f32 v136, v136, v137
	v_pk_add_f32 v[144:145], v[144:145], 1.0 op_sel_hi:[1,0]
	s_nop 0
	v_rcp_f32_e32 v144, v144
	v_rcp_f32_e32 v145, v145
	s_nop 0
	v_pk_mul_f32 v[138:139], v[138:139], v[144:145]
	v_pk_mul_f32 v[144:145], v[140:141], s[20:21] op_sel_hi:[1,0]
	v_pk_mul_f32 v[140:141], v[154:155], v[140:141]
	v_exp_f32_e32 v144, v144
	v_exp_f32_e32 v145, v145
	v_cvt_pk_bf16_f32 v137, v138, v139
	v_pk_add_f32 v[144:145], v[144:145], 1.0 op_sel_hi:[1,0]
	s_nop 0
	v_rcp_f32_e32 v144, v144
	v_rcp_f32_e32 v145, v145
	s_nop 0
	v_pk_mul_f32 v[140:141], v[140:141], v[144:145]
	v_pk_mul_f32 v[144:145], v[142:143], s[20:21] op_sel_hi:[1,0]
	v_pk_mul_f32 v[142:143], v[152:153], v[142:143]
	v_exp_f32_e32 v144, v144
	v_exp_f32_e32 v145, v145
	v_cvt_pk_bf16_f32 v138, v140, v141
	v_mov_b64_e32 v[140:141], s[60:61]
	v_pk_add_f32 v[144:145], v[144:145], 1.0 op_sel_hi:[1,0]
	s_nop 0
	v_rcp_f32_e32 v144, v144
	v_rcp_f32_e32 v145, v145
	s_nop 0
	v_pk_mul_f32 v[142:143], v[142:143], v[144:145]
	s_nop 0
	v_cvt_pk_bf16_f32 v139, v142, v143
	v_add_u32_e32 v142, s22, v162
	v_mad_i64_i32 v[140:141], s[18:19], v142, s9, v[140:141]
	v_lshl_add_u64 v[140:141], v[174:175], 1, v[140:141]
	s_and_b64 s[18:19], s[86:87], s[4:5]
	global_store_dwordx4 v[140:141], v[136:139], off
	s_and_saveexec_b64 s[4:5], s[18:19]
	s_cbranch_execz .LBB0_1420
	v_readlane_b32 s18, v255, 10
	v_readlane_b32 s19, v255, 11
	v_lshl_add_u32 v138, s56, 1, v160
	s_movk_i32 s9, 0x2c00
	v_mov_b64_e32 v[136:137], s[18:19]
	v_mad_u64_u32 v[136:137], s[18:19], v138, s9, v[136:137]
	v_lshl_add_u64 v[136:137], v[174:175], 2, v[136:137]
	global_store_dwordx4 v[136:137], v[128:131], off
	global_store_dwordx4 v[136:137], v[132:135], off offset:16

.LBB0_1567:
.LBB0_1568:
	s_add_i32 s19, 0, 0x10000
	s_add_i32 s36, 0, 0x14000
	v_add_u32_e32 v12, s19, v174
	v_add_u32_e32 v28, s36, v174
	ds_read_b128 v[0:3], v12
	ds_read_b128 v[4:7], v12 offset:1024
	ds_read_b128 v[8:11], v12 offset:2048
	ds_read_b128 v[12:15], v12 offset:3072
	ds_read_b128 v[16:19], v28
	ds_read_b128 v[20:23], v28 offset:1024
	ds_read_b128 v[24:27], v28 offset:2048
	ds_read_b128 v[28:31], v28 offset:3072
	s_add_u32 s24, s22, 0xb0080
	s_addc_u32 s25, s23, 0
	s_waitcnt vmcnt(0)
	v_lshl_add_u64 v[64:65], s[24:25], 0, v[128:129]
	s_add_i32 m0, s73, 0xc000
	ds_read_b128 v[32:35], v175
	ds_read_b128 v[36:39], v175 offset:1024
	ds_read_b128 v[40:43], v175 offset:2048
	ds_read_b128 v[44:47], v175 offset:3072
	ds_read_b128 v[48:51], v175 offset:4096
	ds_read_b128 v[52:55], v175 offset:5120
	ds_read_b128 v[56:59], v175 offset:6144
	ds_read_b128 v[60:63], v175 offset:7168
	global_load_lds_dwordx4 v[64:65], off
	v_lshl_add_u64 v[64:65], s[24:25], 0, v[132:133]
	s_add_i32 m0, s73, 0xe000
	s_nop 0
	global_load_lds_dwordx4 v[64:65], off
	s_waitcnt vmcnt(40) lgkmcnt(0)
	s_setprio 1
	s_barrier
	v_mfma_f32_16x16x32_bf16 v[64:67], v[0:3], v[32:35], 0
	v_mfma_f32_16x16x32_bf16 v[68:71], v[8:11], v[32:35], 0
	v_mfma_f32_16x16x32_bf16 v[72:75], v[0:3], v[40:43], 0
	v_mfma_f32_16x16x32_bf16 v[76:79], v[8:11], v[40:43], 0
	v_mfma_f32_16x16x32_bf16 v[80:83], v[0:3], v[48:51], 0
	v_mfma_f32_16x16x32_bf16 v[84:87], v[8:11], v[48:51], 0
	v_mfma_f32_16x16x32_bf16 v[88:91], v[0:3], v[56:59], 0
	v_mfma_f32_16x16x32_bf16 v[92:95], v[8:11], v[56:59], 0
	v_mfma_f32_16x16x32_bf16 v[64:67], v[4:7], v[36:39], v[64:67]
	v_mfma_f32_16x16x32_bf16 v[68:71], v[12:15], v[36:39], v[68:71]
	v_mfma_f32_16x16x32_bf16 v[72:75], v[4:7], v[44:47], v[72:75]
	v_mfma_f32_16x16x32_bf16 v[76:79], v[12:15], v[44:47], v[76:79]
	v_mfma_f32_16x16x32_bf16 v[80:83], v[4:7], v[52:55], v[80:83]
	v_mfma_f32_16x16x32_bf16 v[84:87], v[12:15], v[52:55], v[84:87]
	v_mfma_f32_16x16x32_bf16 v[88:91], v[4:7], v[60:63], v[88:91]
	v_mfma_f32_16x16x32_bf16 v[92:95], v[12:15], v[60:63], v[92:95]
	s_setprio 0
	s_setprio 1
	v_mfma_f32_16x16x32_bf16 v[96:99], v[16:19], v[32:35], 0
	v_mfma_f32_16x16x32_bf16 v[32:35], v[24:27], v[32:35], 0
	v_mfma_f32_16x16x32_bf16 v[96:99], v[20:23], v[36:39], v[96:99]
	v_mfma_f32_16x16x32_bf16 v[32:35], v[28:31], v[36:39], v[32:35]
	v_mfma_f32_16x16x32_bf16 v[36:39], v[16:19], v[40:43], 0
	v_mfma_f32_16x16x32_bf16 v[40:43], v[24:27], v[40:43], 0
	v_mfma_f32_16x16x32_bf16 v[36:39], v[20:23], v[44:47], v[36:39]
	v_mfma_f32_16x16x32_bf16 v[40:43], v[28:31], v[44:47], v[40:43]
	v_mfma_f32_16x16x32_bf16 v[44:47], v[16:19], v[48:51], 0
	v_mfma_f32_16x16x32_bf16 v[48:51], v[24:27], v[48:51], 0
	v_mfma_f32_16x16x32_bf16 v[44:47], v[20:23], v[52:55], v[44:47]
	v_mfma_f32_16x16x32_bf16 v[48:51], v[28:31], v[52:55], v[48:51]
	v_mfma_f32_16x16x32_bf16 v[52:55], v[16:19], v[56:59], 0
	v_mfma_f32_16x16x32_bf16 v[52:55], v[20:23], v[60:63], v[52:55]
	v_mfma_f32_16x16x32_bf16 v[56:59], v[24:27], v[56:59], 0
	v_mfma_f32_16x16x32_bf16 v[134:137], v[28:31], v[60:63], v[56:59]
	s_barrier
	s_setprio 0
	v_lshl_add_u64 v[158:159], s[8:9], 0, v[130:131]
	s_add_i32 s19, s19, s72
	v_lshl_add_u64 v[124:125], v[158:159], 0, s[16:17]
	s_mov_b32 m0, s19
	s_nop 0
	ds_read_b128 v[56:59], v175 offset:16384
	ds_read_b128 v[60:63], v175 offset:17408
	ds_read_b128 v[100:103], v175 offset:18432
	ds_read_b128 v[104:107], v175 offset:19456
	ds_read_b128 v[108:111], v175 offset:20480
	ds_read_b128 v[112:115], v175 offset:21504
	ds_read_b128 v[116:119], v175 offset:22528
	ds_read_b128 v[120:123], v175 offset:23552
	global_load_lds_dwordx4 v[124:125], off
	s_add_i32 m0, s19, 0x2000
	v_lshl_add_u64 v[188:189], s[8:9], 0, v[160:161]
	s_add_u32 s24, s8, 0xb0100
	v_lshl_add_u64 v[124:125], v[188:189], 0, s[16:17]
	s_addc_u32 s25, s9, 0
	s_add_i32 s19, s36, s72
	global_load_lds_dwordx4 v[124:125], off
	v_lshl_add_u64 v[124:125], s[24:25], 0, v[130:131]
	s_mov_b32 m0, s19
	v_lshl_add_u64 v[190:191], s[22:23], 0, v[128:129]
	global_load_lds_dwordx4 v[124:125], off
	v_lshl_add_u64 v[124:125], s[24:25], 0, v[160:161]
	s_add_i32 m0, s19, 0x2000
	v_lshl_add_u64 v[246:247], s[22:23], 0, v[132:133]
	global_load_lds_dwordx4 v[124:125], off
	v_lshl_add_u64 v[124:125], v[190:191], 0, s[16:17]
	s_mov_b32 m0, s73
	s_nop 0
	global_load_lds_dwordx4 v[124:125], off
	v_lshl_add_u64 v[124:125], v[246:247], 0, s[16:17]
	s_mov_b32 m0, s74
	s_nop 0
	global_load_lds_dwordx4 v[124:125], off
	s_waitcnt vmcnt(40) lgkmcnt(0)
	s_setprio 1
	s_barrier
	v_mfma_f32_16x16x32_bf16 v[124:127], v[0:3], v[56:59], 0
	v_mfma_f32_16x16x32_bf16 v[138:141], v[4:7], v[60:63], v[124:127]
	v_mfma_f32_16x16x32_bf16 v[124:127], v[8:11], v[56:59], 0
	v_mfma_f32_16x16x32_bf16 v[142:145], v[12:15], v[60:63], v[124:127]
	v_mfma_f32_16x16x32_bf16 v[124:127], v[0:3], v[100:103], 0
	v_mfma_f32_16x16x32_bf16 v[146:149], v[4:7], v[104:107], v[124:127]
	v_mfma_f32_16x16x32_bf16 v[124:127], v[8:11], v[100:103], 0
	v_mfma_f32_16x16x32_bf16 v[150:153], v[12:15], v[104:107], v[124:127]
	v_mfma_f32_16x16x32_bf16 v[124:127], v[0:3], v[108:111], 0
	v_mfma_f32_16x16x32_bf16 v[0:3], v[0:3], v[116:119], 0
	v_mfma_f32_16x16x32_bf16 v[154:157], v[4:7], v[112:115], v[124:127]
	v_mfma_f32_16x16x32_bf16 v[0:3], v[4:7], v[120:123], v[0:3]
	v_mfma_f32_16x16x32_bf16 v[4:7], v[8:11], v[116:119], 0
	v_mfma_f32_16x16x32_bf16 v[124:127], v[8:11], v[108:111], 0
	v_mfma_f32_16x16x32_bf16 v[4:7], v[12:15], v[120:123], v[4:7]
	v_mfma_f32_16x16x32_bf16 v[162:165], v[12:15], v[112:115], v[124:127]
	s_setprio 0
	s_setprio 1
	v_mfma_f32_16x16x32_bf16 v[8:11], v[16:19], v[56:59], 0
	v_mfma_f32_16x16x32_bf16 v[166:169], v[20:23], v[60:63], v[8:11]
	v_mfma_f32_16x16x32_bf16 v[8:11], v[24:27], v[56:59], 0
	v_mfma_f32_16x16x32_bf16 v[170:173], v[28:31], v[60:63], v[8:11]
	v_mfma_f32_16x16x32_bf16 v[8:11], v[16:19], v[100:103], 0
	v_mfma_f32_16x16x32_bf16 v[176:179], v[20:23], v[104:107], v[8:11]
	v_mfma_f32_16x16x32_bf16 v[8:11], v[24:27], v[100:103], 0
	v_mfma_f32_16x16x32_bf16 v[180:183], v[28:31], v[104:107], v[8:11]
	v_mfma_f32_16x16x32_bf16 v[8:11], v[16:19], v[108:111], 0
	v_mfma_f32_16x16x32_bf16 v[184:187], v[20:23], v[112:115], v[8:11]
	v_mfma_f32_16x16x32_bf16 v[8:11], v[24:27], v[108:111], 0
	v_mfma_f32_16x16x32_bf16 v[194:197], v[28:31], v[112:115], v[8:11]
	v_mfma_f32_16x16x32_bf16 v[8:11], v[16:19], v[116:119], 0
	v_mfma_f32_16x16x32_bf16 v[198:201], v[20:23], v[120:123], v[8:11]
	v_mfma_f32_16x16x32_bf16 v[8:11], v[24:27], v[116:119], 0
	v_mfma_f32_16x16x32_bf16 v[202:205], v[28:31], v[120:123], v[8:11]
	s_barrier
	s_setprio 0
	s_add_i32 s19, 0, 0x18000
	v_add_u32_e32 v16, s19, v174
	s_add_i32 s36, 0, 0x1c000
	s_nop 1
	ds_read_b128 v[8:11], v16
	ds_read_b128 v[12:15], v16 offset:1024
	ds_read_b128 v[28:31], v16 offset:2048
	ds_read_b128 v[206:209], v16 offset:3072
	v_add_u32_e32 v16, s36, v174
	ds_read_b128 v[210:213], v16
	ds_read_b128 v[214:217], v16 offset:1024
	ds_read_b128 v[218:221], v16 offset:2048
	ds_read_b128 v[222:225], v16 offset:3072
	s_add_u32 s24, s22, 0xb0100
	s_addc_u32 s25, s23, 0
	s_mov_b32 m0, s75
	v_lshl_add_u64 v[100:101], s[24:25], 0, v[128:129]
	ds_read_b128 v[16:19], v175 offset:32768
	ds_read_b128 v[20:23], v175 offset:33792
	ds_read_b128 v[24:27], v175 offset:34816
	ds_read_b128 v[56:59], v175 offset:35840
	ds_read_b128 v[60:63], v175 offset:36864
	ds_read_b128 v[226:229], v175 offset:37888
	ds_read_b128 v[230:233], v175 offset:38912
	ds_read_b128 v[234:237], v175 offset:39936
	global_load_lds_dwordx4 v[100:101], off
	v_lshl_add_u64 v[100:101], s[24:25], 0, v[132:133]
	s_mov_b32 m0, s76
	s_nop 0
	global_load_lds_dwordx4 v[100:101], off
	s_waitcnt vmcnt(8) lgkmcnt(0)
	s_setprio 1
	s_barrier
	v_mfma_f32_16x16x32_bf16 v[64:67], v[8:11], v[16:19], v[64:67]
	v_mfma_f32_16x16x32_bf16 v[124:127], v[12:15], v[20:23], v[64:67]
	v_mfma_f32_16x16x32_bf16 v[64:67], v[28:31], v[16:19], v[68:71]
	v_mfma_f32_16x16x32_bf16 v[120:123], v[206:209], v[20:23], v[64:67]
	v_mfma_f32_16x16x32_bf16 v[64:67], v[8:11], v[24:27], v[72:75]
	v_mfma_f32_16x16x32_bf16 v[116:119], v[12:15], v[56:59], v[64:67]
	v_mfma_f32_16x16x32_bf16 v[64:67], v[28:31], v[24:27], v[76:79]
	v_mfma_f32_16x16x32_bf16 v[112:115], v[206:209], v[56:59], v[64:67]
	v_mfma_f32_16x16x32_bf16 v[64:67], v[8:11], v[60:63], v[80:83]
	v_mfma_f32_16x16x32_bf16 v[108:111], v[12:15], v[226:229], v[64:67]
	v_mfma_f32_16x16x32_bf16 v[64:67], v[28:31], v[60:63], v[84:87]
	v_mfma_f32_16x16x32_bf16 v[104:107], v[206:209], v[226:229], v[64:67]
	v_mfma_f32_16x16x32_bf16 v[64:67], v[8:11], v[230:233], v[88:91]
	v_mfma_f32_16x16x32_bf16 v[100:103], v[12:15], v[234:237], v[64:67]
	v_mfma_f32_16x16x32_bf16 v[64:67], v[28:31], v[230:233], v[92:95]
	v_mfma_f32_16x16x32_bf16 v[92:95], v[206:209], v[234:237], v[64:67]
	s_setprio 0
	s_setprio 1
	v_mfma_f32_16x16x32_bf16 v[64:67], v[210:213], v[16:19], v[96:99]
	v_mfma_f32_16x16x32_bf16 v[16:19], v[218:221], v[16:19], v[32:35]
	v_mfma_f32_16x16x32_bf16 v[76:79], v[222:225], v[20:23], v[16:19]
	v_mfma_f32_16x16x32_bf16 v[16:19], v[210:213], v[24:27], v[36:39]
	v_mfma_f32_16x16x32_bf16 v[72:75], v[214:217], v[56:59], v[16:19]
	v_mfma_f32_16x16x32_bf16 v[16:19], v[218:221], v[24:27], v[40:43]
	v_mfma_f32_16x16x32_bf16 v[68:71], v[222:225], v[56:59], v[16:19]
	v_mfma_f32_16x16x32_bf16 v[16:19], v[210:213], v[60:63], v[44:47]
	v_mfma_f32_16x16x32_bf16 v[80:83], v[214:217], v[20:23], v[64:67]
	v_mfma_f32_16x16x32_bf16 v[64:67], v[214:217], v[226:229], v[16:19]
	v_mfma_f32_16x16x32_bf16 v[16:19], v[218:221], v[60:63], v[48:51]
	v_mfma_f32_16x16x32_bf16 v[60:63], v[222:225], v[226:229], v[16:19]
	v_mfma_f32_16x16x32_bf16 v[16:19], v[210:213], v[230:233], v[52:55]
	v_mfma_f32_16x16x32_bf16 v[56:59], v[214:217], v[234:237], v[16:19]
	v_mfma_f32_16x16x32_bf16 v[16:19], v[218:221], v[230:233], v[134:137]
	v_mfma_f32_16x16x32_bf16 v[48:51], v[222:225], v[234:237], v[16:19]
	s_barrier
	s_setprio 0
	s_mov_b64 s[80:81], 0x180
	s_add_i32 s19, s19, s72
	s_nop 2
	v_lshl_add_u64 v[16:17], v[158:159], 0, s[80:81]
	s_mov_b32 m0, s19
	ds_read_b128 v[32:35], v175 offset:49152
	ds_read_b128 v[36:39], v175 offset:50176
	ds_read_b128 v[134:137], v175 offset:51200
	ds_read_b128 v[226:229], v175 offset:52224
	ds_read_b128 v[230:233], v175 offset:53248
	ds_read_b128 v[234:237], v175 offset:54272
	ds_read_b128 v[238:241], v175 offset:55296
	ds_read_b128 v[242:245], v175 offset:56320
	global_load_lds_dwordx4 v[16:17], off
	s_add_i32 m0, s19, 0x2000
	s_add_u32 s24, s8, 0xb0180
	v_lshl_add_u64 v[16:17], v[188:189], 0, s[80:81]
	s_addc_u32 s25, s9, 0
	s_add_i32 s19, s36, s72
	global_load_lds_dwordx4 v[16:17], off
	v_lshl_add_u64 v[16:17], s[24:25], 0, v[130:131]
	s_mov_b32 m0, s19
	s_nop 0
	global_load_lds_dwordx4 v[16:17], off
	v_lshl_add_u64 v[16:17], s[24:25], 0, v[160:161]
	s_add_i32 m0, s19, 0x2000
	s_nop 0
	global_load_lds_dwordx4 v[16:17], off
	v_lshl_add_u64 v[16:17], v[190:191], 0, s[80:81]
	s_mov_b32 m0, s78
	s_nop 0
	global_load_lds_dwordx4 v[16:17], off
	v_lshl_add_u64 v[16:17], v[246:247], 0, s[80:81]
	s_mov_b32 m0, s79
	v_mov_b32_e32 v247, 0x77
	global_load_lds_dwordx4 v[16:17], off
	s_waitcnt vmcnt(8)
	s_waitcnt lgkmcnt(0)
	v_mov_b32_e32 v246, 0x7c
	s_barrier
	s_setprio 1
	s_waitcnt lgkmcnt(0)
	v_mfma_f32_16x16x32_bf16 v[16:19], v[8:11], v[32:35], v[138:141]
	v_mfma_f32_16x16x32_bf16 v[96:99], v[12:15], v[36:39], v[16:19]
	v_mfma_f32_16x16x32_bf16 v[16:19], v[28:31], v[32:35], v[142:145]
	v_mfma_f32_16x16x32_bf16 v[88:91], v[206:209], v[36:39], v[16:19]
	v_mfma_f32_16x16x32_bf16 v[16:19], v[8:11], v[134:137], v[146:149]
	v_mfma_f32_16x16x32_bf16 v[84:87], v[12:15], v[226:229], v[16:19]
	v_mfma_f32_16x16x32_bf16 v[16:19], v[28:31], v[134:137], v[150:153]
	v_mfma_f32_16x16x32_bf16 v[24:27], v[206:209], v[226:229], v[16:19]
	v_mfma_f32_16x16x32_bf16 v[16:19], v[8:11], v[230:233], v[154:157]
	v_mfma_f32_16x16x32_bf16 v[0:3], v[8:11], v[238:241], v[0:3]
	v_mfma_f32_16x16x32_bf16 v[20:23], v[12:15], v[234:237], v[16:19]
	v_mfma_f32_16x16x32_bf16 v[16:19], v[28:31], v[230:233], v[162:165]
	v_mfma_f32_16x16x32_bf16 v[12:15], v[12:15], v[242:245], v[0:3]
	v_mfma_f32_16x16x32_bf16 v[0:3], v[28:31], v[238:241], v[4:7]
	v_mfma_f32_16x16x32_bf16 v[16:19], v[206:209], v[234:237], v[16:19]
	v_mfma_f32_16x16x32_bf16 v[8:11], v[206:209], v[242:245], v[0:3]
	s_setprio 0
	s_setprio 1
	v_mfma_f32_16x16x32_bf16 v[0:3], v[210:213], v[32:35], v[166:169]
	v_mfma_f32_16x16x32_bf16 v[52:55], v[214:217], v[36:39], v[0:3]
	v_mfma_f32_16x16x32_bf16 v[0:3], v[218:221], v[32:35], v[170:173]
	v_mfma_f32_16x16x32_bf16 v[44:47], v[222:225], v[36:39], v[0:3]
	v_mfma_f32_16x16x32_bf16 v[0:3], v[210:213], v[134:137], v[176:179]
	v_mfma_f32_16x16x32_bf16 v[40:43], v[214:217], v[226:229], v[0:3]
	v_mfma_f32_16x16x32_bf16 v[0:3], v[218:221], v[134:137], v[180:183]
	v_mfma_f32_16x16x32_bf16 v[36:39], v[222:225], v[226:229], v[0:3]
	v_mfma_f32_16x16x32_bf16 v[0:3], v[210:213], v[230:233], v[184:187]
	v_mfma_f32_16x16x32_bf16 v[32:35], v[214:217], v[234:237], v[0:3]
	v_mfma_f32_16x16x32_bf16 v[0:3], v[218:221], v[230:233], v[194:197]
	v_mfma_f32_16x16x32_bf16 v[28:31], v[222:225], v[234:237], v[0:3]
	v_mfma_f32_16x16x32_bf16 v[0:3], v[210:213], v[238:241], v[198:201]
	v_mfma_f32_16x16x32_bf16 v[4:7], v[214:217], v[242:245], v[0:3]
	v_mfma_f32_16x16x32_bf16 v[0:3], v[218:221], v[238:241], v[202:205]
	v_mov_b32_e32 v241, 0x7f
	v_mfma_f32_16x16x32_bf16 v[0:3], v[222:225], v[242:245], v[0:3]
	v_mov_b32_e32 v245, 0x7d
	v_mov_b32_e32 v244, 0x7e
	v_mov_b64_e32 v[242:243], 0x400
	s_setprio 0
	s_barrier
	s_mov_b32 s24, 2

.LBB0_1570:
	s_add_u32 s22, s36, s92
	s_addc_u32 s23, s37, 0
	s_add_u32 s80, s67, s92
	s_addc_u32 s87, s81, 0
	s_add_i32 s88, 0, 0x10000
	s_cmp_eq_u32 s92, s8
	s_cselect_b32 s25, s41, s23
	s_cselect_b32 s24, s40, s22
	s_cselect_b32 s23, s69, s87
	s_cselect_b32 s22, s68, s80
	s_add_i32 s80, 0, 0x14000
	v_add_u32_e32 v150, s88, v174
	v_add_u32_e32 v158, s80, v174
	ds_read_b128 v[138:141], v150
	ds_read_b128 v[142:145], v150 offset:1024
	ds_read_b128 v[146:149], v150 offset:2048
	ds_read_b128 v[150:153], v150 offset:3072
	ds_read_b128 v[154:157], v158
	ds_read_b128 v[162:165], v158 offset:1024
	ds_read_b128 v[166:169], v158 offset:2048
	ds_read_b128 v[170:173], v158 offset:3072
	v_lshl_add_u64 v[158:159], v[134:135], 0, s[92:93]
	s_add_i32 m0, s73, 0xc000
	ds_read_b128 v[176:179], v175
	ds_read_b128 v[180:183], v175 offset:1024
	ds_read_b128 v[184:187], v175 offset:2048
	ds_read_b128 v[194:197], v175 offset:3072
	ds_read_b128 v[198:201], v175 offset:4096
	ds_read_b128 v[202:205], v175 offset:5120
	ds_read_b128 v[206:209], v175 offset:6144
	ds_read_b128 v[210:213], v175 offset:7168
	global_load_lds_dwordx4 v[158:159], off
	v_lshl_add_u64 v[158:159], v[136:137], 0, s[92:93]
	s_add_i32 m0, s73, 0xe000
	s_nop 0
	global_load_lds_dwordx4 v[158:159], off
	s_waitcnt vmcnt(8) lgkmcnt(0)
	s_setprio 1
	s_barrier
	v_mfma_f32_16x16x32_bf16 v[124:127], v[138:141], v[176:179], v[124:127]
	v_mfma_f32_16x16x32_bf16 v[120:123], v[146:149], v[176:179], v[120:123]
	v_mfma_f32_16x16x32_bf16 v[116:119], v[138:141], v[184:187], v[116:119]
	v_mfma_f32_16x16x32_bf16 v[112:115], v[146:149], v[184:187], v[112:115]
	v_mfma_f32_16x16x32_bf16 v[108:111], v[138:141], v[198:201], v[108:111]
	v_mfma_f32_16x16x32_bf16 v[104:107], v[146:149], v[198:201], v[104:107]
	v_mfma_f32_16x16x32_bf16 v[100:103], v[138:141], v[206:209], v[100:103]
	v_mfma_f32_16x16x32_bf16 v[92:95], v[146:149], v[206:209], v[92:95]
	v_mfma_f32_16x16x32_bf16 v[124:127], v[142:145], v[180:183], v[124:127]
	v_mfma_f32_16x16x32_bf16 v[120:123], v[150:153], v[180:183], v[120:123]
	v_mfma_f32_16x16x32_bf16 v[116:119], v[142:145], v[194:197], v[116:119]
	v_mfma_f32_16x16x32_bf16 v[112:115], v[150:153], v[194:197], v[112:115]
	v_mfma_f32_16x16x32_bf16 v[108:111], v[142:145], v[202:205], v[108:111]
	v_mfma_f32_16x16x32_bf16 v[104:107], v[150:153], v[202:205], v[104:107]
	v_mfma_f32_16x16x32_bf16 v[100:103], v[142:145], v[210:213], v[100:103]
	v_mfma_f32_16x16x32_bf16 v[92:95], v[150:153], v[210:213], v[92:95]
	s_setprio 0
	s_setprio 1
	v_mfma_f32_16x16x32_bf16 v[80:83], v[154:157], v[176:179], v[80:83]
	v_mfma_f32_16x16x32_bf16 v[76:79], v[166:169], v[176:179], v[76:79]
	v_mfma_f32_16x16x32_bf16 v[72:75], v[154:157], v[184:187], v[72:75]
	v_mfma_f32_16x16x32_bf16 v[68:71], v[166:169], v[184:187], v[68:71]
	v_mfma_f32_16x16x32_bf16 v[64:67], v[154:157], v[198:201], v[64:67]
	v_mfma_f32_16x16x32_bf16 v[60:63], v[166:169], v[198:201], v[60:63]
	v_mfma_f32_16x16x32_bf16 v[56:59], v[154:157], v[206:209], v[56:59]
	v_mfma_f32_16x16x32_bf16 v[48:51], v[166:169], v[206:209], v[48:51]
	v_mfma_f32_16x16x32_bf16 v[80:83], v[162:165], v[180:183], v[80:83]
	v_mfma_f32_16x16x32_bf16 v[76:79], v[170:173], v[180:183], v[76:79]
	v_mfma_f32_16x16x32_bf16 v[72:75], v[162:165], v[194:197], v[72:75]
	v_mfma_f32_16x16x32_bf16 v[68:71], v[170:173], v[194:197], v[68:71]
	v_mfma_f32_16x16x32_bf16 v[64:67], v[162:165], v[202:205], v[64:67]
	v_mfma_f32_16x16x32_bf16 v[60:63], v[170:173], v[202:205], v[60:63]
	v_mfma_f32_16x16x32_bf16 v[56:59], v[162:165], v[210:213], v[56:59]
	v_mfma_f32_16x16x32_bf16 v[48:51], v[170:173], v[210:213], v[48:51]
	s_barrier
	s_setprio 0
	s_add_i32 s87, s88, s72
	v_lshl_add_u64 v[158:159], s[22:23], 0, v[130:131]
	s_mov_b32 m0, s87
	ds_read_b128 v[176:179], v175 offset:16384
	ds_read_b128 v[180:183], v175 offset:17408
	ds_read_b128 v[184:187], v175 offset:18432
	ds_read_b128 v[194:197], v175 offset:19456
	ds_read_b128 v[198:201], v175 offset:20480
	ds_read_b128 v[202:205], v175 offset:21504
	ds_read_b128 v[206:209], v175 offset:22528
	ds_read_b128 v[210:213], v175 offset:23552
	global_load_lds_dwordx4 v[158:159], off
	s_add_i32 m0, s87, 0x2000
	s_add_u32 s88, s22, 0xb0000
	v_lshl_add_u64 v[188:189], s[22:23], 0, v[160:161]
	s_addc_u32 s89, s23, 0
	s_add_i32 s80, s80, s72
	global_load_lds_dwordx4 v[188:189], off
	v_lshl_add_u64 v[190:191], s[88:89], 0, v[130:131]
	s_mov_b32 m0, s80
	v_lshl_add_u64 v[214:215], s[24:25], 0, v[132:133]
	global_load_lds_dwordx4 v[190:191], off
	v_lshl_add_u64 v[190:191], s[88:89], 0, v[160:161]
	s_add_i32 m0, s80, 0x2000
	s_nop 0
	global_load_lds_dwordx4 v[190:191], off
	v_lshl_add_u64 v[190:191], s[24:25], 0, v[128:129]
	s_mov_b32 m0, s73
	s_nop 0
	global_load_lds_dwordx4 v[190:191], off
	s_mov_b32 m0, s74
	s_nop 0
	global_load_lds_dwordx4 v[214:215], off
	s_waitcnt vmcnt(8) lgkmcnt(0)
	s_setprio 1
	s_barrier
	v_mfma_f32_16x16x32_bf16 v[96:99], v[138:141], v[176:179], v[96:99]
	v_mfma_f32_16x16x32_bf16 v[88:91], v[146:149], v[176:179], v[88:91]
	v_mfma_f32_16x16x32_bf16 v[84:87], v[138:141], v[184:187], v[84:87]
	v_mfma_f32_16x16x32_bf16 v[24:27], v[146:149], v[184:187], v[24:27]
	v_mfma_f32_16x16x32_bf16 v[20:23], v[138:141], v[198:201], v[20:23]
	v_mfma_f32_16x16x32_bf16 v[16:19], v[146:149], v[198:201], v[16:19]
	v_mfma_f32_16x16x32_bf16 v[12:15], v[138:141], v[206:209], v[12:15]
	v_mfma_f32_16x16x32_bf16 v[8:11], v[146:149], v[206:209], v[8:11]
	v_mfma_f32_16x16x32_bf16 v[96:99], v[142:145], v[180:183], v[96:99]
	v_mfma_f32_16x16x32_bf16 v[88:91], v[150:153], v[180:183], v[88:91]
	v_mfma_f32_16x16x32_bf16 v[84:87], v[142:145], v[194:197], v[84:87]
	v_mfma_f32_16x16x32_bf16 v[24:27], v[150:153], v[194:197], v[24:27]
	v_mfma_f32_16x16x32_bf16 v[20:23], v[142:145], v[202:205], v[20:23]
	v_mfma_f32_16x16x32_bf16 v[16:19], v[150:153], v[202:205], v[16:19]
	v_mfma_f32_16x16x32_bf16 v[12:15], v[142:145], v[210:213], v[12:15]
	v_mfma_f32_16x16x32_bf16 v[8:11], v[150:153], v[210:213], v[8:11]
	s_setprio 0
	s_setprio 1
	v_mfma_f32_16x16x32_bf16 v[52:55], v[154:157], v[176:179], v[52:55]
	v_mfma_f32_16x16x32_bf16 v[44:47], v[166:169], v[176:179], v[44:47]
	v_mfma_f32_16x16x32_bf16 v[40:43], v[154:157], v[184:187], v[40:43]
	v_mfma_f32_16x16x32_bf16 v[36:39], v[166:169], v[184:187], v[36:39]
	v_mfma_f32_16x16x32_bf16 v[32:35], v[154:157], v[198:201], v[32:35]
	v_mfma_f32_16x16x32_bf16 v[28:31], v[166:169], v[198:201], v[28:31]
	v_mfma_f32_16x16x32_bf16 v[4:7], v[154:157], v[206:209], v[4:7]
	v_mfma_f32_16x16x32_bf16 v[0:3], v[166:169], v[206:209], v[0:3]
	v_mfma_f32_16x16x32_bf16 v[52:55], v[162:165], v[180:183], v[52:55]
	v_mfma_f32_16x16x32_bf16 v[44:47], v[170:173], v[180:183], v[44:47]
	v_mfma_f32_16x16x32_bf16 v[40:43], v[162:165], v[194:197], v[40:43]
	v_mfma_f32_16x16x32_bf16 v[36:39], v[170:173], v[194:197], v[36:39]
	v_mfma_f32_16x16x32_bf16 v[32:35], v[162:165], v[202:205], v[32:35]
	v_mfma_f32_16x16x32_bf16 v[28:31], v[170:173], v[202:205], v[28:31]
	v_mfma_f32_16x16x32_bf16 v[4:7], v[162:165], v[210:213], v[4:7]
	v_mfma_f32_16x16x32_bf16 v[0:3], v[170:173], v[210:213], v[0:3]
	s_barrier
	s_setprio 0
	s_add_i32 s80, 0, 0x18000
	s_add_i32 s87, 0, 0x1c000
	v_add_u32_e32 v150, s80, v174
	v_add_u32_e32 v170, s87, v174
	ds_read_b128 v[138:141], v150
	ds_read_b128 v[142:145], v150 offset:1024
	ds_read_b128 v[146:149], v150 offset:2048
	ds_read_b128 v[150:153], v150 offset:3072
	ds_read_b128 v[154:157], v170
	ds_read_b128 v[162:165], v170 offset:1024
	ds_read_b128 v[166:169], v170 offset:2048
	ds_read_b128 v[170:173], v170 offset:3072
	s_add_u32 s24, s24, 0xb0000
	s_addc_u32 s25, s25, 0
	s_mov_b32 m0, s75
	v_lshl_add_u64 v[216:217], s[24:25], 0, v[128:129]
	ds_read_b128 v[176:179], v175 offset:32768
	ds_read_b128 v[180:183], v175 offset:33792
	ds_read_b128 v[184:187], v175 offset:34816
	ds_read_b128 v[194:197], v175 offset:35840
	ds_read_b128 v[198:201], v175 offset:36864
	ds_read_b128 v[202:205], v175 offset:37888
	ds_read_b128 v[206:209], v175 offset:38912
	ds_read_b128 v[210:213], v175 offset:39936
	global_load_lds_dwordx4 v[216:217], off
	v_lshl_add_u64 v[216:217], s[24:25], 0, v[132:133]
	s_mov_b32 m0, s76
	s_nop 0
	global_load_lds_dwordx4 v[216:217], off
	s_waitcnt vmcnt(8) lgkmcnt(0)
	s_setprio 1
	s_barrier
	v_mfma_f32_16x16x32_bf16 v[124:127], v[138:141], v[176:179], v[124:127]
	v_mfma_f32_16x16x32_bf16 v[120:123], v[146:149], v[176:179], v[120:123]
	v_mfma_f32_16x16x32_bf16 v[116:119], v[138:141], v[184:187], v[116:119]
	v_mfma_f32_16x16x32_bf16 v[112:115], v[146:149], v[184:187], v[112:115]
	v_mfma_f32_16x16x32_bf16 v[108:111], v[138:141], v[198:201], v[108:111]
	v_mfma_f32_16x16x32_bf16 v[104:107], v[146:149], v[198:201], v[104:107]
	v_mfma_f32_16x16x32_bf16 v[100:103], v[138:141], v[206:209], v[100:103]
	v_mfma_f32_16x16x32_bf16 v[92:95], v[146:149], v[206:209], v[92:95]
	v_mfma_f32_16x16x32_bf16 v[124:127], v[142:145], v[180:183], v[124:127]
	v_mfma_f32_16x16x32_bf16 v[120:123], v[150:153], v[180:183], v[120:123]
	v_mfma_f32_16x16x32_bf16 v[116:119], v[142:145], v[194:197], v[116:119]
	v_mfma_f32_16x16x32_bf16 v[112:115], v[150:153], v[194:197], v[112:115]
	v_mfma_f32_16x16x32_bf16 v[108:111], v[142:145], v[202:205], v[108:111]
	v_mfma_f32_16x16x32_bf16 v[104:107], v[150:153], v[202:205], v[104:107]
	v_mfma_f32_16x16x32_bf16 v[100:103], v[142:145], v[210:213], v[100:103]
	v_mfma_f32_16x16x32_bf16 v[92:95], v[150:153], v[210:213], v[92:95]
	s_setprio 0
	s_setprio 1
	v_mfma_f32_16x16x32_bf16 v[80:83], v[154:157], v[176:179], v[80:83]
	v_mfma_f32_16x16x32_bf16 v[76:79], v[166:169], v[176:179], v[76:79]
	v_mfma_f32_16x16x32_bf16 v[72:75], v[154:157], v[184:187], v[72:75]
	v_mfma_f32_16x16x32_bf16 v[68:71], v[166:169], v[184:187], v[68:71]
	v_mfma_f32_16x16x32_bf16 v[64:67], v[154:157], v[198:201], v[64:67]
	v_mfma_f32_16x16x32_bf16 v[60:63], v[166:169], v[198:201], v[60:63]
	v_mfma_f32_16x16x32_bf16 v[56:59], v[154:157], v[206:209], v[56:59]
	v_mfma_f32_16x16x32_bf16 v[48:51], v[166:169], v[206:209], v[48:51]
	v_mfma_f32_16x16x32_bf16 v[80:83], v[162:165], v[180:183], v[80:83]
	v_mfma_f32_16x16x32_bf16 v[76:79], v[170:173], v[180:183], v[76:79]
	v_mfma_f32_16x16x32_bf16 v[72:75], v[162:165], v[194:197], v[72:75]
	v_mfma_f32_16x16x32_bf16 v[68:71], v[170:173], v[194:197], v[68:71]
	v_mfma_f32_16x16x32_bf16 v[64:67], v[162:165], v[202:205], v[64:67]
	v_mfma_f32_16x16x32_bf16 v[60:63], v[170:173], v[202:205], v[60:63]
	v_mfma_f32_16x16x32_bf16 v[56:59], v[162:165], v[210:213], v[56:59]
	v_mfma_f32_16x16x32_bf16 v[48:51], v[170:173], v[210:213], v[48:51]
	s_barrier
	s_setprio 0
	s_add_i32 s24, s80, s72
	v_lshl_add_u64 v[158:159], v[158:159], 0, s[14:15]
	s_mov_b32 m0, s24
	ds_read_b128 v[176:179], v175 offset:49152
	ds_read_b128 v[180:183], v175 offset:50176
	ds_read_b128 v[184:187], v175 offset:51200
	ds_read_b128 v[194:197], v175 offset:52224
	ds_read_b128 v[198:201], v175 offset:53248
	ds_read_b128 v[202:205], v175 offset:54272
	ds_read_b128 v[206:209], v175 offset:55296
	ds_read_b128 v[210:213], v175 offset:56320
	global_load_lds_dwordx4 v[158:159], off
	s_add_i32 m0, s24, 0x2000
	s_add_u32 s22, s22, 0xb0080
	v_lshl_add_u64 v[158:159], v[188:189], 0, s[14:15]
	s_addc_u32 s23, s23, 0
	s_add_i32 s24, s87, s72
	global_load_lds_dwordx4 v[158:159], off
	v_lshl_add_u64 v[158:159], s[22:23], 0, v[130:131]
	s_mov_b32 m0, s24
	s_nop 0
	global_load_lds_dwordx4 v[158:159], off
	v_lshl_add_u64 v[158:159], s[22:23], 0, v[160:161]
	s_add_i32 m0, s24, 0x2000
	s_nop 0
	global_load_lds_dwordx4 v[158:159], off
	v_lshl_add_u64 v[158:159], v[190:191], 0, s[14:15]
	s_mov_b32 m0, s78
	s_nop 0
	global_load_lds_dwordx4 v[158:159], off
	v_lshl_add_u64 v[158:159], v[214:215], 0, s[14:15]
	s_mov_b32 m0, s79
	s_nop 0
	global_load_lds_dwordx4 v[158:159], off
	s_waitcnt vmcnt(8) lgkmcnt(0)
	s_setprio 1
	s_barrier
	v_mfma_f32_16x16x32_bf16 v[96:99], v[138:141], v[176:179], v[96:99]
	v_mfma_f32_16x16x32_bf16 v[88:91], v[146:149], v[176:179], v[88:91]
	v_mfma_f32_16x16x32_bf16 v[84:87], v[138:141], v[184:187], v[84:87]
	v_mfma_f32_16x16x32_bf16 v[24:27], v[146:149], v[184:187], v[24:27]
	v_mfma_f32_16x16x32_bf16 v[20:23], v[138:141], v[198:201], v[20:23]
	v_mfma_f32_16x16x32_bf16 v[16:19], v[146:149], v[198:201], v[16:19]
	v_mfma_f32_16x16x32_bf16 v[12:15], v[138:141], v[206:209], v[12:15]
	v_mfma_f32_16x16x32_bf16 v[8:11], v[146:149], v[206:209], v[8:11]
	v_mfma_f32_16x16x32_bf16 v[96:99], v[142:145], v[180:183], v[96:99]
	v_mfma_f32_16x16x32_bf16 v[88:91], v[150:153], v[180:183], v[88:91]
	v_mfma_f32_16x16x32_bf16 v[84:87], v[142:145], v[194:197], v[84:87]
	v_mfma_f32_16x16x32_bf16 v[24:27], v[150:153], v[194:197], v[24:27]
	v_mfma_f32_16x16x32_bf16 v[20:23], v[142:145], v[202:205], v[20:23]
	v_mfma_f32_16x16x32_bf16 v[16:19], v[150:153], v[202:205], v[16:19]
	v_mfma_f32_16x16x32_bf16 v[12:15], v[142:145], v[210:213], v[12:15]
	v_mfma_f32_16x16x32_bf16 v[8:11], v[150:153], v[210:213], v[8:11]
	s_setprio 0
	s_setprio 1
	v_mfma_f32_16x16x32_bf16 v[52:55], v[154:157], v[176:179], v[52:55]
	v_mfma_f32_16x16x32_bf16 v[44:47], v[166:169], v[176:179], v[44:47]
	v_mfma_f32_16x16x32_bf16 v[40:43], v[154:157], v[184:187], v[40:43]
	v_mfma_f32_16x16x32_bf16 v[36:39], v[166:169], v[184:187], v[36:39]
	v_mfma_f32_16x16x32_bf16 v[32:35], v[154:157], v[198:201], v[32:35]
	v_mfma_f32_16x16x32_bf16 v[28:31], v[166:169], v[198:201], v[28:31]
	v_mfma_f32_16x16x32_bf16 v[4:7], v[154:157], v[206:209], v[4:7]
	v_mfma_f32_16x16x32_bf16 v[0:3], v[166:169], v[206:209], v[0:3]
	v_mfma_f32_16x16x32_bf16 v[52:55], v[162:165], v[180:183], v[52:55]
	v_mfma_f32_16x16x32_bf16 v[44:47], v[170:173], v[180:183], v[44:47]
	v_mfma_f32_16x16x32_bf16 v[40:43], v[162:165], v[194:197], v[40:43]
	v_mfma_f32_16x16x32_bf16 v[36:39], v[170:173], v[194:197], v[36:39]
	v_mfma_f32_16x16x32_bf16 v[32:35], v[162:165], v[202:205], v[32:35]
	v_mfma_f32_16x16x32_bf16 v[28:31], v[170:173], v[202:205], v[28:31]
	v_mfma_f32_16x16x32_bf16 v[4:7], v[162:165], v[210:213], v[4:7]
	v_mfma_f32_16x16x32_bf16 v[0:3], v[170:173], v[210:213], v[0:3]
	s_barrier
	s_setprio 0
	s_add_i32 s19, s19, 2
	s_add_u32 s36, s36, 0x100
	s_addc_u32 s37, s37, 0
	s_add_u32 s67, s67, 0x100
	s_addc_u32 s81, s81, 0
	s_add_u32 s8, s8, 0xffffff00
	s_addc_u32 s9, s9, -1
	v_lshl_add_u64 v[134:135], v[134:135], 0, s[16:17]
	s_cmp_gt_u32 s19, 41
	v_lshl_add_u64 v[136:137], v[136:137], 0, s[16:17]
	s_cbranch_scc0 .LBB0_1570
	s_and_b64 vcc, exec, s[64:65]
	s_cbranch_vccz .LBB0_1573
	s_barrier
